# reciprocal in epilogues: exp result clamped to 2^126 (finite) so rcp + Newton needs no v_div_fixup (a quarter-rate op)
# baseline (speedup 1.0000x reference)
; __device__ __forceinline__ float sigmoidf_(float x) { return 1.0f / (1.0f + __expf(-x)); }
; __device__ __forceinline__ void phase0(const Params& p, unsigned char* lds) {
;     ...
;         for (int it = blockIdx.x; it < 768; it += gridDim.x) {
;             const int kc = it & 15, nc = (it >> 4) % 12, s = it / 192; const int k0 = kc * 128;
;             { const int b = tid >> 7, kk = tid & 127; const float cv = p.c[b * 2048 + k0 + kk]; sc[tid] = cv * sigmoidf_(cv); }
;             __syncthreads();
;             const int n = nc * 512 + tid; const float* W = p.ada_w + ((size_t)s * 2048 + k0) * 6144 + n;
.LBB0_5:
	s_and_b32 s21, s20, 15
	v_lshl_or_b32 v2, s21, 7, v12
	v_ashrrev_i32_e32 v3, 31, v2
	v_lshl_add_u64 v[2:3], v[2:3], 2, s[38:39]
	global_load_dword v5, v[2:3], off
	s_and_b32 s23, s19, 15
	s_ashr_i32 s24, s20, 4
	s_mul_hi_i32 s25, s20, 0x2aaaaaab
	s_mul_i32 s26, s23, 0x300000
	s_mul_hi_i32 s23, s24, 0x2aaaaaab
	s_lshr_b32 s27, s25, 31
	s_ashr_i32 s25, s25, 5
	s_lshr_b32 s28, s23, 31
	s_lshr_b32 s29, s23, 1
	s_add_i32 s23, s25, s27
	s_add_i32 s25, s29, s28
	s_mul_i32 s25, s25, 12
	s_mul_i32 s28, s23, 0x3000000
	s_sub_i32 s24, s24, s25
	s_mul_hi_i32 s27, s23, 0x3000000
	v_lshl_add_u32 v2, s24, 9, v1
	s_add_u32 s24, s28, s26
	s_addc_u32 s25, s27, 0
	s_add_u32 s24, s40, s24
	v_mov_b32_e32 v6, 0
	v_ashrrev_i32_e32 v3, 31, v2
	s_addc_u32 s25, s41, s25
	s_mov_b64 s[4:5], 0
	s_mov_b32 s22, 0
	v_mov_b32_e32 v7, v6
	v_mov_b32_e32 v4, v6
	s_waitcnt vmcnt(0)
	v_mul_f32_e32 v8, 0xbfb8aa3b, v5
	v_exp_f32_e32 v8, v8
	s_nop 0
	v_min_f32_e32 v8, 0x7e800000, v8
	v_add_f32_e32 v10, 1.0, v8
	v_rcp_f32_e32 v14, v10
	v_lshl_add_u64 v[8:9], v[2:3], 2, s[24:25]
	v_fma_f32 v16, -v10, v14, 1.0
	v_fma_f32 v10, v16, v14, v14
	v_mul_f32_e32 v5, v5, v10
	ds_write_b32 v13, v5
	v_mov_b32_e32 v5, v6
	s_waitcnt lgkmcnt(0)
	s_barrier

; __device__ __forceinline__ float sigmoidf_(float x) { return 1.0f / (1.0f + __expf(-x)); }
; __device__ __forceinline__ void phase_prep(const Params& p, unsigned char* lds) {
;     ...
;             for (int j = 0; j < 8; ++j) { const float a = (float)z1[j]; const float zs = a + (0.5f * ((float)z0[j] + (float)z2[j]) - a) * p.rwkv_mu[zc + j];
;                 v[j] = grp < 12 ? tanhf(zs) : (grp < 24 ? zs : sigmoidf_(zs)); }
.LBB0_292:
	s_or_b64 exec, exec, s[16:17]
	global_load_dword v36, v[16:17], off
	s_waitcnt vmcnt(1)
	v_cvt_f32_f16_e32 v37, v8
	v_cvt_f32_f16_e32 v40, v4
	v_add_f32_e32 v37, v37, v40
	v_fma_mix_f32 v37, v37, s30, -v0 op_sel_hi:[0,0,1]
	s_waitcnt vmcnt(0)
	v_fma_mix_f32 v36, v36, v37, v0 op_sel_hi:[0,0,1]
	s_and_saveexec_b64 s[16:17], s[6:7]
	s_xor_b64 s[16:17], exec, s[16:17]
	s_cbranch_execz .LBB0_296
	s_and_saveexec_b64 s[28:29], s[4:5]
	s_cbranch_execz .LBB0_295
	v_mul_f32_e32 v36, 0xbfb8aa3b, v36
	v_exp_f32_e32 v36, v36
	s_nop 0
	v_min_f32_e32 v36, 0x7e800000, v36
	v_add_f32_e32 v36, 1.0, v36
	v_rcp_f32_e32 v40, v36
	s_nop 0
	v_fma_f32 v42, -v36, v40, 1.0
	v_fma_f32 v36, v42, v40, v40

; __device__ __forceinline__ float sigmoidf_(float x) { return 1.0f / (1.0f + __expf(-x)); }
; __device__ __forceinline__ void phase_prep(const Params& p, unsigned char* lds) {
;     ...
;             for (int j = 0; j < 8; ++j) { const float a = (float)z1[j]; const float zs = a + (0.5f * ((float)z0[j] + (float)z2[j]) - a) * p.rwkv_mu[zc + j];
;                 v[j] = grp < 12 ? tanhf(zs) : (grp < 24 ? zs : sigmoidf_(zs)); }
.LBB0_302:
	s_or_b64 exec, exec, s[16:17]
	global_load_dword v37, v[18:19], off
	v_cvt_f32_f16_sdwa v8, v8 dst_sel:DWORD dst_unused:UNUSED_PAD src0_sel:WORD_1
	v_cvt_f32_f16_sdwa v4, v4 dst_sel:DWORD dst_unused:UNUSED_PAD src0_sel:WORD_1
	v_add_f32_e32 v4, v8, v4
	v_fma_mix_f32 v4, v4, s30, -v0 op_sel:[0,0,1] op_sel_hi:[0,0,1]
	s_waitcnt vmcnt(0)
	v_fma_mix_f32 v0, v4, v37, v0 op_sel:[0,0,1] op_sel_hi:[0,0,1]
	s_and_saveexec_b64 s[16:17], s[6:7]
	s_xor_b64 s[16:17], exec, s[16:17]
	s_cbranch_execz .LBB0_306
	s_and_saveexec_b64 s[28:29], s[4:5]
	s_cbranch_execz .LBB0_305
	v_mul_f32_e32 v0, 0xbfb8aa3b, v0
	v_exp_f32_e32 v0, v0
	s_nop 0
	v_min_f32_e32 v0, 0x7e800000, v0
	v_add_f32_e32 v0, 1.0, v0
	v_rcp_f32_e32 v8, v0
	s_nop 0
	v_fma_f32 v40, -v0, v8, 1.0
	v_fma_f32 v0, v40, v8, v8

; __device__ __forceinline__ float sigmoidf_(float x) { return 1.0f / (1.0f + __expf(-x)); }
; __device__ __forceinline__ void phase_prep(const Params& p, unsigned char* lds) {
;     ...
;             for (int j = 0; j < 8; ++j) { const float a = (float)z1[j]; const float zs = a + (0.5f * ((float)z0[j] + (float)z2[j]) - a) * p.rwkv_mu[zc + j];
;                 v[j] = grp < 12 ? tanhf(zs) : (grp < 24 ? zs : sigmoidf_(zs)); }
.LBB0_312:
	s_or_b64 exec, exec, s[16:17]
	global_load_dword v4, v[20:21], off
	v_cvt_f32_f16_e32 v8, v9
	v_cvt_f32_f16_e32 v37, v5
	v_add_f32_e32 v8, v8, v37
	v_fma_mix_f32 v8, v8, s30, -v1 op_sel_hi:[0,0,1]
	s_waitcnt vmcnt(0)
	v_fma_mix_f32 v4, v8, v4, v1 op_sel_hi:[0,0,1]
	s_and_saveexec_b64 s[16:17], s[6:7]
	s_xor_b64 s[16:17], exec, s[16:17]
	s_cbranch_execz .LBB0_316
	s_and_saveexec_b64 s[28:29], s[4:5]
	s_cbranch_execz .LBB0_315
	v_mul_f32_e32 v4, 0xbfb8aa3b, v4
	v_exp_f32_e32 v4, v4
	s_nop 0
	v_min_f32_e32 v4, 0x7e800000, v4
	v_add_f32_e32 v4, 1.0, v4
	v_rcp_f32_e32 v37, v4
	s_nop 0
	v_fma_f32 v41, -v4, v37, 1.0
	v_fma_f32 v4, v41, v37, v37

; __device__ __forceinline__ float sigmoidf_(float x) { return 1.0f / (1.0f + __expf(-x)); }
; __device__ __forceinline__ void phase_prep(const Params& p, unsigned char* lds) {
;     ...
;             for (int j = 0; j < 8; ++j) { const float a = (float)z1[j]; const float zs = a + (0.5f * ((float)z0[j] + (float)z2[j]) - a) * p.rwkv_mu[zc + j];
;                 v[j] = grp < 12 ? tanhf(zs) : (grp < 24 ? zs : sigmoidf_(zs)); }
.LBB0_322:
	s_or_b64 exec, exec, s[16:17]
	global_load_dword v8, v[22:23], off
	v_cvt_f32_f16_sdwa v9, v9 dst_sel:DWORD dst_unused:UNUSED_PAD src0_sel:WORD_1
	v_cvt_f32_f16_sdwa v5, v5 dst_sel:DWORD dst_unused:UNUSED_PAD src0_sel:WORD_1
	v_add_f32_e32 v5, v9, v5
	v_fma_mix_f32 v5, v5, s30, -v1 op_sel:[0,0,1] op_sel_hi:[0,0,1]
	s_waitcnt vmcnt(0)
	v_fma_mix_f32 v1, v5, v8, v1 op_sel:[0,0,1] op_sel_hi:[0,0,1]
	s_and_saveexec_b64 s[16:17], s[6:7]
	s_xor_b64 s[16:17], exec, s[16:17]
	s_cbranch_execz .LBB0_326
	s_and_saveexec_b64 s[28:29], s[4:5]
	s_cbranch_execz .LBB0_325
	v_mul_f32_e32 v1, 0xbfb8aa3b, v1
	v_exp_f32_e32 v1, v1
	s_nop 0
	v_min_f32_e32 v1, 0x7e800000, v1
	v_add_f32_e32 v1, 1.0, v1
	v_rcp_f32_e32 v8, v1
	s_nop 0
	v_fma_f32 v37, -v1, v8, 1.0
	v_fma_f32 v1, v37, v8, v8

; __device__ __forceinline__ float sigmoidf_(float x) { return 1.0f / (1.0f + __expf(-x)); }
; __device__ __forceinline__ void phase_prep(const Params& p, unsigned char* lds) {
;     ...
;             for (int j = 0; j < 8; ++j) { const float a = (float)z1[j]; const float zs = a + (0.5f * ((float)z0[j] + (float)z2[j]) - a) * p.rwkv_mu[zc + j];
;                 v[j] = grp < 12 ? tanhf(zs) : (grp < 24 ? zs : sigmoidf_(zs)); }
.LBB0_332:
	s_or_b64 exec, exec, s[16:17]
	global_load_dword v5, v[24:25], off
	v_cvt_f32_f16_e32 v8, v10
	v_cvt_f32_f16_e32 v9, v6
	v_add_f32_e32 v8, v8, v9
	v_fma_mix_f32 v8, v8, s30, -v2 op_sel_hi:[0,0,1]
	s_waitcnt vmcnt(0)
	v_fma_mix_f32 v5, v8, v5, v2 op_sel_hi:[0,0,1]
	s_and_saveexec_b64 s[16:17], s[6:7]
	s_xor_b64 s[16:17], exec, s[16:17]
	s_cbranch_execz .LBB0_336
	s_and_saveexec_b64 s[28:29], s[4:5]
	s_cbranch_execz .LBB0_335
	v_mul_f32_e32 v5, 0xbfb8aa3b, v5
	v_exp_f32_e32 v5, v5
	s_nop 0
	v_min_f32_e32 v5, 0x7e800000, v5
	v_add_f32_e32 v5, 1.0, v5
	v_rcp_f32_e32 v9, v5
	s_nop 0
	v_fma_f32 v40, -v5, v9, 1.0
	v_fma_f32 v5, v40, v9, v9

; __device__ __forceinline__ float sigmoidf_(float x) { return 1.0f / (1.0f + __expf(-x)); }
; __device__ __forceinline__ void phase_prep(const Params& p, unsigned char* lds) {
;     ...
;             for (int j = 0; j < 8; ++j) { const float a = (float)z1[j]; const float zs = a + (0.5f * ((float)z0[j] + (float)z2[j]) - a) * p.rwkv_mu[zc + j];
;                 v[j] = grp < 12 ? tanhf(zs) : (grp < 24 ? zs : sigmoidf_(zs)); }
.LBB0_342:
	s_or_b64 exec, exec, s[16:17]
	global_load_dword v8, v[26:27], off
	v_cvt_f32_f16_sdwa v9, v10 dst_sel:DWORD dst_unused:UNUSED_PAD src0_sel:WORD_1
	v_cvt_f32_f16_sdwa v6, v6 dst_sel:DWORD dst_unused:UNUSED_PAD src0_sel:WORD_1
	v_add_f32_e32 v6, v9, v6
	v_fma_mix_f32 v6, v6, s30, -v2 op_sel:[0,0,1] op_sel_hi:[0,0,1]
	s_waitcnt vmcnt(0)
	v_fma_mix_f32 v2, v6, v8, v2 op_sel:[0,0,1] op_sel_hi:[0,0,1]
	s_and_saveexec_b64 s[16:17], s[6:7]
	s_xor_b64 s[16:17], exec, s[16:17]
	s_cbranch_execz .LBB0_346
	s_and_saveexec_b64 s[28:29], s[4:5]
	s_cbranch_execz .LBB0_345
	v_mul_f32_e32 v2, 0xbfb8aa3b, v2
	v_exp_f32_e32 v2, v2
	s_nop 0
	v_min_f32_e32 v2, 0x7e800000, v2
	v_add_f32_e32 v2, 1.0, v2
	v_rcp_f32_e32 v8, v2
	s_nop 0
	v_fma_f32 v10, -v2, v8, 1.0
	v_fma_f32 v2, v10, v8, v8

; __device__ __forceinline__ float sigmoidf_(float x) { return 1.0f / (1.0f + __expf(-x)); }
; __device__ __forceinline__ void phase_prep(const Params& p, unsigned char* lds) {
;     ...
;             for (int j = 0; j < 8; ++j) { const float a = (float)z1[j]; const float zs = a + (0.5f * ((float)z0[j] + (float)z2[j]) - a) * p.rwkv_mu[zc + j];
;                 v[j] = grp < 12 ? tanhf(zs) : (grp < 24 ? zs : sigmoidf_(zs)); }
.LBB0_352:
	s_or_b64 exec, exec, s[16:17]
	global_load_dword v6, v[28:29], off
	v_cvt_f32_f16_e32 v8, v11
	v_cvt_f32_f16_e32 v9, v7
	v_add_f32_e32 v8, v8, v9
	v_fma_mix_f32 v8, v8, s30, -v3 op_sel_hi:[0,0,1]
	s_waitcnt vmcnt(0)
	v_fma_mix_f32 v6, v8, v6, v3 op_sel_hi:[0,0,1]
	s_and_saveexec_b64 s[16:17], s[6:7]
	s_xor_b64 s[16:17], exec, s[16:17]
	s_cbranch_execz .LBB0_356
	s_and_saveexec_b64 s[28:29], s[4:5]
	s_cbranch_execz .LBB0_355
	v_mul_f32_e32 v6, 0xbfb8aa3b, v6
	v_exp_f32_e32 v6, v6
	s_nop 0
	v_min_f32_e32 v6, 0x7e800000, v6
	v_add_f32_e32 v6, 1.0, v6
	v_rcp_f32_e32 v9, v6
	s_nop 0
	v_fma_f32 v37, -v6, v9, 1.0
	v_fma_f32 v6, v37, v9, v9

; __device__ __forceinline__ float sigmoidf_(float x) { return 1.0f / (1.0f + __expf(-x)); }
; __device__ __forceinline__ void phase_prep(const Params& p, unsigned char* lds) {
;     ...
;             for (int j = 0; j < 8; ++j) { const float a = (float)z1[j]; const float zs = a + (0.5f * ((float)z0[j] + (float)z2[j]) - a) * p.rwkv_mu[zc + j];
;                 v[j] = grp < 12 ? tanhf(zs) : (grp < 24 ? zs : sigmoidf_(zs)); }
.LBB0_362:
	s_or_b64 exec, exec, s[16:17]
	global_load_dword v8, v[30:31], off
	v_cvt_f32_f16_sdwa v9, v11 dst_sel:DWORD dst_unused:UNUSED_PAD src0_sel:WORD_1
	v_cvt_f32_f16_sdwa v7, v7 dst_sel:DWORD dst_unused:UNUSED_PAD src0_sel:WORD_1
	v_add_f32_e32 v7, v9, v7
	v_fma_mix_f32 v7, v7, s30, -v3 op_sel:[0,0,1] op_sel_hi:[0,0,1]
	s_waitcnt vmcnt(0)
	v_fma_mix_f32 v3, v7, v8, v3 op_sel:[0,0,1] op_sel_hi:[0,0,1]
	s_and_saveexec_b64 s[16:17], s[6:7]
	s_xor_b64 s[16:17], exec, s[16:17]
	s_cbranch_execz .LBB0_366
	s_and_saveexec_b64 s[28:29], s[4:5]
	s_cbranch_execz .LBB0_365
	v_mul_f32_e32 v3, 0xbfb8aa3b, v3
	v_exp_f32_e32 v3, v3
	s_nop 0
	v_min_f32_e32 v3, 0x7e800000, v3
	v_add_f32_e32 v3, 1.0, v3
	v_rcp_f32_e32 v8, v3
	s_nop 0
	v_fma_f32 v10, -v3, v8, 1.0
	v_fma_f32 v3, v10, v8, v8

; __device__ __forceinline__ float sigmoidf_(float x) { return 1.0f / (1.0f + __expf(-x)); }
;     __device__ __forceinline__ void operator()(const f32x4 (&acc)[2][2][4][2], const Unit& u, int wr, int wc, int fr, int fq) const {
;     ...
;                         for (int i = 0; i < 4; ++i) { float xv = acc[ai][bj][m][n][i] + bv[bj][n][i]; float r;
;                             if (type < 2) { const float sg = sigmoidf_(xv); r = -expm1f(-0.606531f * sg); }
;                             else if (type == 2) r = sigmoidf_(xv);
.LBB0_468:
	s_waitcnt vmcnt(0)
	v_add_f32_e32 v140, v140, v32
	s_mov_b64 s[52:53], -1
	s_and_b64 vcc, exec, s[38:39]
	s_cbranch_vccz .LBB0_472
	s_and_b64 vcc, exec, s[6:7]
	v_mov_b32_e32 v152, v140
	s_cbranch_vccnz .LBB0_471
	v_mul_f32_e32 v152, 0xbfb8aa3b, v140
	v_exp_f32_e32 v152, v152
	s_nop 0
	v_min_f32_e32 v152, 0x7e800000, v152
	v_add_f32_e32 v152, 1.0, v152
	v_rcp_f32_e32 v163, v152
	s_nop 0
	v_fma_f32 v175, -v152, v163, 1.0
	v_fma_f32 v152, v175, v163, v163

; __device__ __forceinline__ float sigmoidf_(float x) { return 1.0f / (1.0f + __expf(-x)); }
;     __device__ __forceinline__ void operator()(const f32x4 (&acc)[2][2][4][2], const Unit& u, int wr, int wc, int fr, int fq) const {
;     ...
;                         for (int i = 0; i < 4; ++i) { float xv = acc[ai][bj][m][n][i] + bv[bj][n][i]; float r;
;                             if (type < 2) { const float sg = sigmoidf_(xv); r = -expm1f(-0.606531f * sg); }
;                             else if (type == 2) r = sigmoidf_(xv);
;                             else r = xv;
;                             v[4 * n + i] = (f16)r; }
.LBB0_473:
	v_mul_f32_e32 v140, 0xbfb8aa3b, v140
	v_exp_f32_e32 v140, v140
	s_nop 0
	v_min_f32_e32 v140, 0x7e800000, v140
	v_add_f32_e32 v140, 1.0, v140
	v_rcp_f32_e32 v162, v140
	s_nop 0
	v_fma_f32 v174, -v140, v162, 1.0
	v_fma_f32 v140, v174, v162, v162
	v_mul_f32_e32 v140, 0xbf1b459e, v140
	v_mul_f32_e32 v152, 0x3fb8aa3b, v140
	v_exp_f32_e32 v152, v152
	s_nop 0
	v_sub_f32_e32 v152, 1.0, v152
.LBB0_474:
	v_add_f32_e32 v140, v141, v33
	s_and_b64 vcc, exec, s[8:9]
	s_mov_b64 s[38:39], -1
	s_cbranch_vccnz .LBB0_478
	s_and_b64 vcc, exec, s[6:7]
	v_mov_b32_e32 v162, v140
	s_cbranch_vccnz .LBB0_477
	v_mul_f32_e32 v141, 0xbfb8aa3b, v140
	v_exp_f32_e32 v141, v141
	s_nop 0
	v_min_f32_e32 v141, 0x7e800000, v141
	v_add_f32_e32 v141, 1.0, v141
	v_rcp_f32_e32 v163, v141
	s_nop 0
	v_fma_f32 v175, -v141, v163, 1.0
	v_fma_f32 v162, v175, v163, v163

; __device__ __forceinline__ float sigmoidf_(float x) { return 1.0f / (1.0f + __expf(-x)); }
;     __device__ __forceinline__ void operator()(const f32x4 (&acc)[2][2][4][2], const Unit& u, int wr, int wc, int fr, int fq) const {
;     ...
;                         for (int i = 0; i < 4; ++i) { float xv = acc[ai][bj][m][n][i] + bv[bj][n][i]; float r;
;                             if (type < 2) { const float sg = sigmoidf_(xv); r = -expm1f(-0.606531f * sg); }
;                             else if (type == 2) r = sigmoidf_(xv);
;                             else r = xv;
;                             v[4 * n + i] = (f16)r; }
.LBB0_479:
	v_mul_f32_e32 v140, 0xbfb8aa3b, v140
	v_exp_f32_e32 v140, v140
	s_nop 0
	v_min_f32_e32 v140, 0x7e800000, v140
	v_add_f32_e32 v140, 1.0, v140
	v_rcp_f32_e32 v162, v140
	s_nop 0
	v_fma_f32 v174, -v140, v162, 1.0
	v_fma_f32 v140, v174, v162, v162
	v_mul_f32_e32 v140, 0xbf1b459e, v140
	v_mul_f32_e32 v141, 0x3fb8aa3b, v140
	v_exp_f32_e32 v141, v141
	s_nop 0
	v_sub_f32_e32 v162, 1.0, v141
.LBB0_480:
	v_add_f32_e32 v140, v142, v34
	s_and_b64 vcc, exec, s[8:9]
	s_mov_b64 s[38:39], -1
	s_cbranch_vccnz .LBB0_484
	s_and_b64 vcc, exec, s[6:7]
	v_mov_b32_e32 v142, v140
	s_cbranch_vccnz .LBB0_483
	v_mul_f32_e32 v141, 0xbfb8aa3b, v140
	v_exp_f32_e32 v141, v141
	s_nop 0
	v_min_f32_e32 v141, 0x7e800000, v141
	v_add_f32_e32 v141, 1.0, v141
	v_rcp_f32_e32 v163, v141
	s_nop 0
	v_fma_f32 v175, -v141, v163, 1.0
	v_fma_f32 v142, v175, v163, v163

; __device__ __forceinline__ float sigmoidf_(float x) { return 1.0f / (1.0f + __expf(-x)); }
;     __device__ __forceinline__ void operator()(const f32x4 (&acc)[2][2][4][2], const Unit& u, int wr, int wc, int fr, int fq) const {
;     ...
;                         for (int i = 0; i < 4; ++i) { float xv = acc[ai][bj][m][n][i] + bv[bj][n][i]; float r;
;                             if (type < 2) { const float sg = sigmoidf_(xv); r = -expm1f(-0.606531f * sg); }
;                             else if (type == 2) r = sigmoidf_(xv);
;                             else r = xv;
;                             v[4 * n + i] = (f16)r; }
.LBB0_485:
	v_mul_f32_e32 v140, 0xbfb8aa3b, v140
	v_exp_f32_e32 v140, v140
	s_nop 0
	v_min_f32_e32 v140, 0x7e800000, v140
	v_add_f32_e32 v140, 1.0, v140
	v_rcp_f32_e32 v142, v140
	s_nop 0
	v_fma_f32 v174, -v140, v142, 1.0
	v_fma_f32 v140, v174, v142, v142
	v_mul_f32_e32 v140, 0xbf1b459e, v140
	v_mul_f32_e32 v141, 0x3fb8aa3b, v140
	v_exp_f32_e32 v141, v141
	s_nop 0
	v_sub_f32_e32 v142, 1.0, v141
.LBB0_486:
	v_add_f32_e32 v140, v143, v35
	s_and_b64 vcc, exec, s[8:9]
	s_mov_b64 s[38:39], -1
	s_cbranch_vccnz .LBB0_490
	s_and_b64 vcc, exec, s[6:7]
	v_mov_b32_e32 v143, v140
	s_cbranch_vccnz .LBB0_489
	v_mul_f32_e32 v141, 0xbfb8aa3b, v140
	v_exp_f32_e32 v141, v141
	s_nop 0
	v_min_f32_e32 v141, 0x7e800000, v141
	v_add_f32_e32 v141, 1.0, v141
	v_rcp_f32_e32 v163, v141
	s_nop 0
	v_fma_f32 v175, -v141, v163, 1.0
	v_fma_f32 v143, v175, v163, v163

; __device__ __forceinline__ float sigmoidf_(float x) { return 1.0f / (1.0f + __expf(-x)); }
;     __device__ __forceinline__ void operator()(const f32x4 (&acc)[2][2][4][2], const Unit& u, int wr, int wc, int fr, int fq) const {
;     ...
;                         for (int i = 0; i < 4; ++i) { float xv = acc[ai][bj][m][n][i] + bv[bj][n][i]; float r;
;                             if (type < 2) { const float sg = sigmoidf_(xv); r = -expm1f(-0.606531f * sg); }
;                             else if (type == 2) r = sigmoidf_(xv);
;                             else r = xv;
;                             v[4 * n + i] = (f16)r; }
.LBB0_491:
	v_mul_f32_e32 v140, 0xbfb8aa3b, v140
	v_exp_f32_e32 v140, v140
	s_nop 0
	v_min_f32_e32 v140, 0x7e800000, v140
	v_add_f32_e32 v140, 1.0, v140
	v_rcp_f32_e32 v143, v140
	s_nop 0
	v_fma_f32 v174, -v140, v143, 1.0
	v_fma_f32 v140, v174, v143, v143
	v_mul_f32_e32 v140, 0xbf1b459e, v140
	v_mul_f32_e32 v141, 0x3fb8aa3b, v140
	v_exp_f32_e32 v141, v141
	s_nop 0
	v_sub_f32_e32 v143, 1.0, v141
.LBB0_492:
	v_add_f32_e32 v136, v136, v28
	s_and_b64 vcc, exec, s[8:9]
	s_mov_b64 s[38:39], -1
	s_cbranch_vccnz .LBB0_496
	s_and_b64 vcc, exec, s[6:7]
	v_mov_b32_e32 v163, v136
	s_cbranch_vccnz .LBB0_495
	v_mul_f32_e32 v140, 0xbfb8aa3b, v136
	v_exp_f32_e32 v140, v140
	s_nop 0
	v_min_f32_e32 v140, 0x7e800000, v140
	v_add_f32_e32 v140, 1.0, v140
	v_rcp_f32_e32 v163, v140
	s_nop 0
	v_fma_f32 v175, -v140, v163, 1.0
	v_fma_f32 v163, v175, v163, v163

; __device__ __forceinline__ float sigmoidf_(float x) { return 1.0f / (1.0f + __expf(-x)); }
;     __device__ __forceinline__ void operator()(const f32x4 (&acc)[2][2][4][2], const Unit& u, int wr, int wc, int fr, int fq) const {
;     ...
;                         for (int i = 0; i < 4; ++i) { float xv = acc[ai][bj][m][n][i] + bv[bj][n][i]; float r;
;                             if (type < 2) { const float sg = sigmoidf_(xv); r = -expm1f(-0.606531f * sg); }
;                             else if (type == 2) r = sigmoidf_(xv);
;                             else r = xv;
;                             v[4 * n + i] = (f16)r; }
.LBB0_497:
	v_mul_f32_e32 v136, 0xbfb8aa3b, v136
	v_exp_f32_e32 v136, v136
	s_nop 0
	v_min_f32_e32 v136, 0x7e800000, v136
	v_add_f32_e32 v136, 1.0, v136
	v_rcp_f32_e32 v141, v136
	s_nop 0
	v_fma_f32 v174, -v136, v141, 1.0
	v_fma_f32 v136, v174, v141, v141
	v_mul_f32_e32 v136, 0xbf1b459e, v136
	v_mul_f32_e32 v140, 0x3fb8aa3b, v136
	v_exp_f32_e32 v140, v140
	s_nop 0
	v_sub_f32_e32 v163, 1.0, v140
.LBB0_498:
	v_add_f32_e32 v136, v137, v29
	s_and_b64 vcc, exec, s[8:9]
	s_mov_b64 s[38:39], -1
	s_cbranch_vccnz .LBB0_502
	s_and_b64 vcc, exec, s[6:7]
	v_mov_b32_e32 v174, v136
	s_cbranch_vccnz .LBB0_501
	v_mul_f32_e32 v137, 0xbfb8aa3b, v136
	v_exp_f32_e32 v137, v137
	s_nop 0
	v_min_f32_e32 v137, 0x7e800000, v137
	v_add_f32_e32 v137, 1.0, v137
	v_rcp_f32_e32 v141, v137
	s_nop 0
	v_fma_f32 v175, -v137, v141, 1.0
	v_fma_f32 v174, v175, v141, v141

; __device__ __forceinline__ float sigmoidf_(float x) { return 1.0f / (1.0f + __expf(-x)); }
;     __device__ __forceinline__ void operator()(const f32x4 (&acc)[2][2][4][2], const Unit& u, int wr, int wc, int fr, int fq) const {
;     ...
;                         for (int i = 0; i < 4; ++i) { float xv = acc[ai][bj][m][n][i] + bv[bj][n][i]; float r;
;                             if (type < 2) { const float sg = sigmoidf_(xv); r = -expm1f(-0.606531f * sg); }
;                             else if (type == 2) r = sigmoidf_(xv);
;                             else r = xv;
;                             v[4 * n + i] = (f16)r; }
.LBB0_503:
	v_mul_f32_e32 v136, 0xbfb8aa3b, v136
	v_exp_f32_e32 v136, v136
	s_nop 0
	v_min_f32_e32 v136, 0x7e800000, v136
	v_add_f32_e32 v136, 1.0, v136
	v_rcp_f32_e32 v140, v136
	s_nop 0
	v_fma_f32 v174, -v136, v140, 1.0
	v_fma_f32 v136, v174, v140, v140
	v_mul_f32_e32 v136, 0xbf1b459e, v136
	v_mul_f32_e32 v137, 0x3fb8aa3b, v136
	v_exp_f32_e32 v137, v137
	s_nop 0
	v_sub_f32_e32 v174, 1.0, v137
.LBB0_504:
	v_add_f32_e32 v136, v138, v30
	s_and_b64 vcc, exec, s[8:9]
	s_mov_b64 s[38:39], -1
	s_cbranch_vccnz .LBB0_508
	s_and_b64 vcc, exec, s[6:7]
	v_mov_b32_e32 v175, v136
	s_cbranch_vccnz .LBB0_507
	v_mul_f32_e32 v137, 0xbfb8aa3b, v136
	v_exp_f32_e32 v137, v137
	s_nop 0
	v_min_f32_e32 v137, 0x7e800000, v137
	v_add_f32_e32 v137, 1.0, v137
	v_rcp_f32_e32 v140, v137
	s_nop 0
	v_fma_f32 v175, -v137, v140, 1.0
	v_fma_f32 v175, v175, v140, v140

; __device__ __forceinline__ float sigmoidf_(float x) { return 1.0f / (1.0f + __expf(-x)); }
;     __device__ __forceinline__ void operator()(const f32x4 (&acc)[2][2][4][2], const Unit& u, int wr, int wc, int fr, int fq) const {
;     ...
;                         for (int i = 0; i < 4; ++i) { float xv = acc[ai][bj][m][n][i] + bv[bj][n][i]; float r;
;                             if (type < 2) { const float sg = sigmoidf_(xv); r = -expm1f(-0.606531f * sg); }
;                             else if (type == 2) r = sigmoidf_(xv);
;                             else r = xv;
;                             v[4 * n + i] = (f16)r; }
.LBB0_509:
	v_mul_f32_e32 v136, 0xbfb8aa3b, v136
	v_exp_f32_e32 v136, v136
	s_nop 0
	v_min_f32_e32 v136, 0x7e800000, v136
	v_add_f32_e32 v136, 1.0, v136
	v_rcp_f32_e32 v138, v136
	s_nop 0
	v_fma_f32 v141, -v136, v138, 1.0
	v_fma_f32 v136, v141, v138, v138
	v_mul_f32_e32 v136, 0xbf1b459e, v136
	v_mul_f32_e32 v137, 0x3fb8aa3b, v136
	v_exp_f32_e32 v137, v137
	s_nop 0
	v_sub_f32_e32 v175, 1.0, v137
.LBB0_510:
	v_add_f32_e32 v136, v139, v31
	s_and_b64 vcc, exec, s[8:9]
	s_mov_b64 s[38:39], -1
	s_cbranch_vccnz .LBB0_514
	s_and_b64 vcc, exec, s[6:7]
	v_mov_b32_e32 v176, v136
	s_cbranch_vccnz .LBB0_513
	v_mul_f32_e32 v137, 0xbfb8aa3b, v136
	v_exp_f32_e32 v137, v137
	s_nop 0
	v_min_f32_e32 v137, 0x7e800000, v137
	v_add_f32_e32 v137, 1.0, v137
	v_rcp_f32_e32 v139, v137
	s_nop 0
	v_fma_f32 v141, -v137, v139, 1.0
	v_fma_f32 v176, v141, v139, v139

; __device__ __forceinline__ float sigmoidf_(float x) { return 1.0f / (1.0f + __expf(-x)); }
;     __device__ __forceinline__ void operator()(const f32x4 (&acc)[2][2][4][2], const Unit& u, int wr, int wc, int fr, int fq) const {
;     ...
;                         for (int i = 0; i < 4; ++i) { float xv = acc[ai][bj][m][n][i] + bv[bj][n][i]; float r;
;                             if (type < 2) { const float sg = sigmoidf_(xv); r = -expm1f(-0.606531f * sg); }
;                             else if (type == 2) r = sigmoidf_(xv);
;                             else r = xv;
;                             v[4 * n + i] = (f16)r; }
;                     *(f16x8*)(rowp + bj * 128) = v; } }
.LBB0_515:
	v_mul_f32_e32 v136, 0xbfb8aa3b, v136
	v_exp_f32_e32 v136, v136
	s_nop 0
	v_min_f32_e32 v136, 0x7e800000, v136
	v_add_f32_e32 v136, 1.0, v136
	v_rcp_f32_e32 v138, v136
	s_nop 0
	v_fma_f32 v140, -v136, v138, 1.0
	v_fma_f32 v136, v140, v138, v138
	v_mul_f32_e32 v136, 0xbf1b459e, v136
	v_mul_f32_e32 v137, 0x3fb8aa3b, v136
	v_exp_f32_e32 v137, v137
	s_nop 0
	v_sub_f32_e32 v176, 1.0, v137
.LBB0_516:
	v_lshl_add_u32 v138, s36, 8, v164
	v_ashrrev_i32_e32 v139, 31, v138
	v_or_b32_e32 v136, s2, v166
	v_lshlrev_b64 v[140:141], 13, v[138:139]
	v_ashrrev_i32_e32 v137, 31, v136
	v_lshl_add_u64 v[140:141], s[28:29], 0, v[140:141]
	v_lshl_add_u64 v[140:141], v[136:137], 1, v[140:141]
	v_cvt_pk_f16_f32 v177, v175, v176
	v_cvt_pk_f16_f32 v176, v163, v174
	v_cvt_pk_f16_f32 v175, v142, v143
	v_cvt_pk_f16_f32 v174, v152, v162
	v_add_f32_e32 v142, v132, v20
	s_and_b64 vcc, exec, s[8:9]
	s_mov_b64 s[14:15], -1
	global_store_dwordx4 v[140:141], v[174:177], off
	s_cbranch_vccnz .LBB0_520
	s_and_b64 vcc, exec, s[6:7]
	v_mov_b32_e32 v132, v142
	s_cbranch_vccnz .LBB0_519
	v_mul_f32_e32 v132, 0xbfb8aa3b, v142
	v_exp_f32_e32 v132, v132
	s_nop 0
	v_min_f32_e32 v132, 0x7e800000, v132
	v_add_f32_e32 v132, 1.0, v132
	v_rcp_f32_e32 v152, v132
	s_nop 0
	v_fma_f32 v163, -v132, v152, 1.0
	v_fma_f32 v132, v163, v152, v152

; __device__ __forceinline__ float sigmoidf_(float x) { return 1.0f / (1.0f + __expf(-x)); }
;     __device__ __forceinline__ void operator()(const f32x4 (&acc)[2][2][4][2], const Unit& u, int wr, int wc, int fr, int fq) const {
;     ...
;                         for (int i = 0; i < 4; ++i) { float xv = acc[ai][bj][m][n][i] + bv[bj][n][i]; float r;
;                             if (type < 2) { const float sg = sigmoidf_(xv); r = -expm1f(-0.606531f * sg); }
;                             else if (type == 2) r = sigmoidf_(xv);
;                             else r = xv;
;                             v[4 * n + i] = (f16)r; }
.LBB0_521:
	v_mul_f32_e32 v132, 0xbfb8aa3b, v142
	v_exp_f32_e32 v132, v132
	s_nop 0
	v_min_f32_e32 v132, 0x7e800000, v132
	v_add_f32_e32 v132, 1.0, v132
	v_rcp_f32_e32 v143, v132
	s_nop 0
	v_fma_f32 v162, -v132, v143, 1.0
	v_fma_f32 v132, v162, v143, v143
	v_mul_f32_e32 v132, 0xbf1b459e, v132
	v_mul_f32_e32 v142, 0x3fb8aa3b, v132
	v_exp_f32_e32 v142, v142
	s_nop 0
	v_sub_f32_e32 v132, 1.0, v142
.LBB0_522:
	v_add_f32_e32 v142, v133, v21
	s_and_b64 vcc, exec, s[8:9]
	s_mov_b64 s[14:15], -1
	s_cbranch_vccnz .LBB0_526
	s_and_b64 vcc, exec, s[6:7]
	v_mov_b32_e32 v133, v142
	s_cbranch_vccnz .LBB0_525
	v_mul_f32_e32 v133, 0xbfb8aa3b, v142
	v_exp_f32_e32 v133, v133
	s_nop 0
	v_min_f32_e32 v133, 0x7e800000, v133
	v_add_f32_e32 v133, 1.0, v133
	v_rcp_f32_e32 v152, v133
	s_nop 0
	v_fma_f32 v163, -v133, v152, 1.0
	v_fma_f32 v133, v163, v152, v152

; __device__ __forceinline__ float sigmoidf_(float x) { return 1.0f / (1.0f + __expf(-x)); }
;     __device__ __forceinline__ void operator()(const f32x4 (&acc)[2][2][4][2], const Unit& u, int wr, int wc, int fr, int fq) const {
;     ...
;                         for (int i = 0; i < 4; ++i) { float xv = acc[ai][bj][m][n][i] + bv[bj][n][i]; float r;
;                             if (type < 2) { const float sg = sigmoidf_(xv); r = -expm1f(-0.606531f * sg); }
;                             else if (type == 2) r = sigmoidf_(xv);
;                             else r = xv;
;                             v[4 * n + i] = (f16)r; }
.LBB0_527:
	v_mul_f32_e32 v133, 0xbfb8aa3b, v142
	v_exp_f32_e32 v133, v133
	s_nop 0
	v_min_f32_e32 v133, 0x7e800000, v133
	v_add_f32_e32 v133, 1.0, v133
	v_rcp_f32_e32 v143, v133
	s_nop 0
	v_fma_f32 v162, -v133, v143, 1.0
	v_fma_f32 v133, v162, v143, v143
	v_mul_f32_e32 v133, 0xbf1b459e, v133
	v_mul_f32_e32 v142, 0x3fb8aa3b, v133
	v_exp_f32_e32 v142, v142
	s_nop 0
	v_sub_f32_e32 v133, 1.0, v142
.LBB0_528:
	v_add_f32_e32 v142, v134, v22
	s_and_b64 vcc, exec, s[8:9]
	s_mov_b64 s[14:15], -1
	s_cbranch_vccnz .LBB0_532
	s_and_b64 vcc, exec, s[6:7]
	v_mov_b32_e32 v134, v142
	s_cbranch_vccnz .LBB0_531
	v_mul_f32_e32 v134, 0xbfb8aa3b, v142
	v_exp_f32_e32 v134, v134
	s_nop 0
	v_min_f32_e32 v134, 0x7e800000, v134
	v_add_f32_e32 v134, 1.0, v134
	v_rcp_f32_e32 v152, v134
	s_nop 0
	v_fma_f32 v163, -v134, v152, 1.0
	v_fma_f32 v134, v163, v152, v152

; __device__ __forceinline__ float sigmoidf_(float x) { return 1.0f / (1.0f + __expf(-x)); }
;     __device__ __forceinline__ void operator()(const f32x4 (&acc)[2][2][4][2], const Unit& u, int wr, int wc, int fr, int fq) const {
;     ...
;                         for (int i = 0; i < 4; ++i) { float xv = acc[ai][bj][m][n][i] + bv[bj][n][i]; float r;
;                             if (type < 2) { const float sg = sigmoidf_(xv); r = -expm1f(-0.606531f * sg); }
;                             else if (type == 2) r = sigmoidf_(xv);
;                             else r = xv;
;                             v[4 * n + i] = (f16)r; }
.LBB0_533:
	v_mul_f32_e32 v134, 0xbfb8aa3b, v142
	v_exp_f32_e32 v134, v134
	s_nop 0
	v_min_f32_e32 v134, 0x7e800000, v134
	v_add_f32_e32 v134, 1.0, v134
	v_rcp_f32_e32 v143, v134
	s_nop 0
	v_fma_f32 v162, -v134, v143, 1.0
	v_fma_f32 v134, v162, v143, v143
	v_mul_f32_e32 v134, 0xbf1b459e, v134
	v_mul_f32_e32 v142, 0x3fb8aa3b, v134
	v_exp_f32_e32 v142, v142
	s_nop 0
	v_sub_f32_e32 v134, 1.0, v142
.LBB0_534:
	v_add_f32_e32 v142, v135, v23
	s_and_b64 vcc, exec, s[8:9]
	s_mov_b64 s[14:15], -1
	s_cbranch_vccnz .LBB0_538
	s_and_b64 vcc, exec, s[6:7]
	v_mov_b32_e32 v135, v142
	s_cbranch_vccnz .LBB0_537
	v_mul_f32_e32 v135, 0xbfb8aa3b, v142
	v_exp_f32_e32 v135, v135
	s_nop 0
	v_min_f32_e32 v135, 0x7e800000, v135
	v_add_f32_e32 v135, 1.0, v135
	v_rcp_f32_e32 v152, v135
	s_nop 0
	v_fma_f32 v163, -v135, v152, 1.0
	v_fma_f32 v135, v163, v152, v152

; __device__ __forceinline__ float sigmoidf_(float x) { return 1.0f / (1.0f + __expf(-x)); }
;     __device__ __forceinline__ void operator()(const f32x4 (&acc)[2][2][4][2], const Unit& u, int wr, int wc, int fr, int fq) const {
;     ...
;                         for (int i = 0; i < 4; ++i) { float xv = acc[ai][bj][m][n][i] + bv[bj][n][i]; float r;
;                             if (type < 2) { const float sg = sigmoidf_(xv); r = -expm1f(-0.606531f * sg); }
;                             else if (type == 2) r = sigmoidf_(xv);
;                             else r = xv;
;                             v[4 * n + i] = (f16)r; }
.LBB0_539:
	v_mul_f32_e32 v135, 0xbfb8aa3b, v142
	v_exp_f32_e32 v135, v135
	s_nop 0
	v_min_f32_e32 v135, 0x7e800000, v135
	v_add_f32_e32 v135, 1.0, v135
	v_rcp_f32_e32 v143, v135
	s_nop 0
	v_fma_f32 v162, -v135, v143, 1.0
	v_fma_f32 v135, v162, v143, v143
	v_mul_f32_e32 v135, 0xbf1b459e, v135
	v_mul_f32_e32 v142, 0x3fb8aa3b, v135
	v_exp_f32_e32 v142, v142
	s_nop 0
	v_sub_f32_e32 v135, 1.0, v142
.LBB0_540:
	v_add_f32_e32 v142, v128, v12
	s_and_b64 vcc, exec, s[8:9]
	s_mov_b64 s[14:15], -1
	s_cbranch_vccnz .LBB0_544
	s_and_b64 vcc, exec, s[6:7]
	v_mov_b32_e32 v128, v142
	s_cbranch_vccnz .LBB0_543
	v_mul_f32_e32 v128, 0xbfb8aa3b, v142
	v_exp_f32_e32 v128, v128
	s_nop 0
	v_min_f32_e32 v128, 0x7e800000, v128
	v_add_f32_e32 v128, 1.0, v128
	v_rcp_f32_e32 v152, v128
	s_nop 0
	v_fma_f32 v163, -v128, v152, 1.0
	v_fma_f32 v128, v163, v152, v152

; __device__ __forceinline__ float sigmoidf_(float x) { return 1.0f / (1.0f + __expf(-x)); }
;     __device__ __forceinline__ void operator()(const f32x4 (&acc)[2][2][4][2], const Unit& u, int wr, int wc, int fr, int fq) const {
;     ...
;                         for (int i = 0; i < 4; ++i) { float xv = acc[ai][bj][m][n][i] + bv[bj][n][i]; float r;
;                             if (type < 2) { const float sg = sigmoidf_(xv); r = -expm1f(-0.606531f * sg); }
;                             else if (type == 2) r = sigmoidf_(xv);
;                             else r = xv;
;                             v[4 * n + i] = (f16)r; }
.LBB0_545:
	v_mul_f32_e32 v128, 0xbfb8aa3b, v142
	v_exp_f32_e32 v128, v128
	s_nop 0
	v_min_f32_e32 v128, 0x7e800000, v128
	v_add_f32_e32 v128, 1.0, v128
	v_rcp_f32_e32 v143, v128
	s_nop 0
	v_fma_f32 v162, -v128, v143, 1.0
	v_fma_f32 v128, v162, v143, v143
	v_mul_f32_e32 v128, 0xbf1b459e, v128
	v_mul_f32_e32 v142, 0x3fb8aa3b, v128
	v_exp_f32_e32 v142, v142
	s_nop 0
	v_sub_f32_e32 v128, 1.0, v142
.LBB0_546:
	v_add_f32_e32 v142, v129, v13
	s_and_b64 vcc, exec, s[8:9]
	s_mov_b64 s[14:15], -1
	s_cbranch_vccnz .LBB0_550
	s_and_b64 vcc, exec, s[6:7]
	v_mov_b32_e32 v129, v142
	s_cbranch_vccnz .LBB0_549
	v_mul_f32_e32 v129, 0xbfb8aa3b, v142
	v_exp_f32_e32 v129, v129
	s_nop 0
	v_min_f32_e32 v129, 0x7e800000, v129
	v_add_f32_e32 v129, 1.0, v129
	v_rcp_f32_e32 v152, v129
	s_nop 0
	v_fma_f32 v163, -v129, v152, 1.0
	v_fma_f32 v129, v163, v152, v152

; __device__ __forceinline__ float sigmoidf_(float x) { return 1.0f / (1.0f + __expf(-x)); }
;     __device__ __forceinline__ void operator()(const f32x4 (&acc)[2][2][4][2], const Unit& u, int wr, int wc, int fr, int fq) const {
;     ...
;                         for (int i = 0; i < 4; ++i) { float xv = acc[ai][bj][m][n][i] + bv[bj][n][i]; float r;
;                             if (type < 2) { const float sg = sigmoidf_(xv); r = -expm1f(-0.606531f * sg); }
;                             else if (type == 2) r = sigmoidf_(xv);
;                             else r = xv;
;                             v[4 * n + i] = (f16)r; }
.LBB0_551:
	v_mul_f32_e32 v129, 0xbfb8aa3b, v142
	v_exp_f32_e32 v129, v129
	s_nop 0
	v_min_f32_e32 v129, 0x7e800000, v129
	v_add_f32_e32 v129, 1.0, v129
	v_rcp_f32_e32 v143, v129
	s_nop 0
	v_fma_f32 v162, -v129, v143, 1.0
	v_fma_f32 v129, v162, v143, v143
	v_mul_f32_e32 v129, 0xbf1b459e, v129
	v_mul_f32_e32 v142, 0x3fb8aa3b, v129
	v_exp_f32_e32 v142, v142
	s_nop 0
	v_sub_f32_e32 v129, 1.0, v142
.LBB0_552:
	v_add_f32_e32 v142, v130, v14
	s_and_b64 vcc, exec, s[8:9]
	s_mov_b64 s[14:15], -1
	s_cbranch_vccnz .LBB0_556
	s_and_b64 vcc, exec, s[6:7]
	v_mov_b32_e32 v130, v142
	s_cbranch_vccnz .LBB0_555
	v_mul_f32_e32 v130, 0xbfb8aa3b, v142
	v_exp_f32_e32 v130, v130
	s_nop 0
	v_min_f32_e32 v130, 0x7e800000, v130
	v_add_f32_e32 v130, 1.0, v130
	v_rcp_f32_e32 v152, v130
	s_nop 0
	v_fma_f32 v163, -v130, v152, 1.0
	v_fma_f32 v130, v163, v152, v152

; __device__ __forceinline__ float sigmoidf_(float x) { return 1.0f / (1.0f + __expf(-x)); }
;     __device__ __forceinline__ void operator()(const f32x4 (&acc)[2][2][4][2], const Unit& u, int wr, int wc, int fr, int fq) const {
;     ...
;                         for (int i = 0; i < 4; ++i) { float xv = acc[ai][bj][m][n][i] + bv[bj][n][i]; float r;
;                             if (type < 2) { const float sg = sigmoidf_(xv); r = -expm1f(-0.606531f * sg); }
;                             else if (type == 2) r = sigmoidf_(xv);
;                             else r = xv;
;                             v[4 * n + i] = (f16)r; }
.LBB0_557:
	v_mul_f32_e32 v130, 0xbfb8aa3b, v142
	v_exp_f32_e32 v130, v130
	s_nop 0
	v_min_f32_e32 v130, 0x7e800000, v130
	v_add_f32_e32 v130, 1.0, v130
	v_rcp_f32_e32 v143, v130
	s_nop 0
	v_fma_f32 v162, -v130, v143, 1.0
	v_fma_f32 v130, v162, v143, v143
	v_mul_f32_e32 v130, 0xbf1b459e, v130
	v_mul_f32_e32 v142, 0x3fb8aa3b, v130
	v_exp_f32_e32 v142, v142
	s_nop 0
	v_sub_f32_e32 v130, 1.0, v142
.LBB0_558:
	v_add_f32_e32 v131, v131, v15
	s_and_b64 vcc, exec, s[8:9]
	s_mov_b64 s[14:15], -1
	s_cbranch_vccnz .LBB0_562
	s_and_b64 vcc, exec, s[6:7]
	v_mov_b32_e32 v142, v131
	s_cbranch_vccnz .LBB0_561
	v_mul_f32_e32 v142, 0xbfb8aa3b, v131
	v_exp_f32_e32 v142, v142
	s_nop 0
	v_min_f32_e32 v142, 0x7e800000, v142
	v_add_f32_e32 v142, 1.0, v142
	v_rcp_f32_e32 v152, v142
	s_nop 0
	v_fma_f32 v163, -v142, v152, 1.0
	v_fma_f32 v142, v163, v152, v152

; __device__ __forceinline__ float sigmoidf_(float x) { return 1.0f / (1.0f + __expf(-x)); }
;     __device__ __forceinline__ void operator()(const f32x4 (&acc)[2][2][4][2], const Unit& u, int wr, int wc, int fr, int fq) const {
;     ...
;                         for (int i = 0; i < 4; ++i) { float xv = acc[ai][bj][m][n][i] + bv[bj][n][i]; float r;
;                             if (type < 2) { const float sg = sigmoidf_(xv); r = -expm1f(-0.606531f * sg); }
;                             else if (type == 2) r = sigmoidf_(xv);
;                             else r = xv;
;                             v[4 * n + i] = (f16)r; }
;                     *(f16x8*)(rowp + bj * 128) = v; } }
.LBB0_563:
	v_mul_f32_e32 v131, 0xbfb8aa3b, v131
	v_exp_f32_e32 v131, v131
	s_nop 0
	v_min_f32_e32 v131, 0x7e800000, v131
	v_add_f32_e32 v131, 1.0, v131
	v_rcp_f32_e32 v143, v131
	s_nop 0
	v_fma_f32 v162, -v131, v143, 1.0
	v_fma_f32 v131, v162, v143, v143
	v_mul_f32_e32 v131, 0xbf1b459e, v131
	v_mul_f32_e32 v142, 0x3fb8aa3b, v131
	v_exp_f32_e32 v142, v142
	s_nop 0
	v_sub_f32_e32 v142, 1.0, v142
.LBB0_564:
	v_cvt_pk_f16_f32 v131, v130, v142
	v_cvt_pk_f16_f32 v130, v128, v129
	v_cvt_pk_f16_f32 v129, v134, v135
	v_cvt_pk_f16_f32 v128, v132, v133
	global_store_dwordx4 v[140:141], v[128:131], off offset:256
	s_and_b64 vcc, exec, s[8:9]
	s_mov_b64 s[14:15], -1
	v_add_f32_e32 v128, v124, v32
	s_cbranch_vccnz .LBB0_568
	s_and_b64 vcc, exec, s[6:7]
	v_mov_b32_e32 v124, v128
	s_cbranch_vccnz .LBB0_567
	v_mul_f32_e32 v124, 0xbfb8aa3b, v128
	v_exp_f32_e32 v124, v124
	s_nop 0
	v_min_f32_e32 v124, 0x7e800000, v124
	v_add_f32_e32 v124, 1.0, v124
	v_rcp_f32_e32 v130, v124
	s_nop 0
	v_fma_f32 v132, -v124, v130, 1.0
	v_fma_f32 v124, v132, v130, v130

; __device__ __forceinline__ float sigmoidf_(float x) { return 1.0f / (1.0f + __expf(-x)); }
;     __device__ __forceinline__ void operator()(const f32x4 (&acc)[2][2][4][2], const Unit& u, int wr, int wc, int fr, int fq) const {
;     ...
;                         for (int i = 0; i < 4; ++i) { float xv = acc[ai][bj][m][n][i] + bv[bj][n][i]; float r;
;                             if (type < 2) { const float sg = sigmoidf_(xv); r = -expm1f(-0.606531f * sg); }
;                             else if (type == 2) r = sigmoidf_(xv);
;                             else r = xv;
;                             v[4 * n + i] = (f16)r; }
.LBB0_569:
	v_mul_f32_e32 v124, 0xbfb8aa3b, v128
	v_exp_f32_e32 v124, v124
	s_nop 0
	v_min_f32_e32 v124, 0x7e800000, v124
	v_add_f32_e32 v124, 1.0, v124
	v_rcp_f32_e32 v129, v124
	s_nop 0
	v_fma_f32 v131, -v124, v129, 1.0
	v_fma_f32 v124, v131, v129, v129
	v_mul_f32_e32 v124, 0xbf1b459e, v124
	v_mul_f32_e32 v128, 0x3fb8aa3b, v124
	v_exp_f32_e32 v128, v128
	s_nop 0
	v_sub_f32_e32 v124, 1.0, v128
.LBB0_570:
	v_add_f32_e32 v128, v125, v33
	s_and_b64 vcc, exec, s[8:9]
	s_mov_b64 s[14:15], -1
	s_cbranch_vccnz .LBB0_574
	s_and_b64 vcc, exec, s[6:7]
	v_mov_b32_e32 v125, v128
	s_cbranch_vccnz .LBB0_573
	v_mul_f32_e32 v125, 0xbfb8aa3b, v128
	v_exp_f32_e32 v125, v125
	s_nop 0
	v_min_f32_e32 v125, 0x7e800000, v125
	v_add_f32_e32 v125, 1.0, v125
	v_rcp_f32_e32 v130, v125
	s_nop 0
	v_fma_f32 v132, -v125, v130, 1.0
	v_fma_f32 v125, v132, v130, v130

; __device__ __forceinline__ float sigmoidf_(float x) { return 1.0f / (1.0f + __expf(-x)); }
;     __device__ __forceinline__ void operator()(const f32x4 (&acc)[2][2][4][2], const Unit& u, int wr, int wc, int fr, int fq) const {
;     ...
;                         for (int i = 0; i < 4; ++i) { float xv = acc[ai][bj][m][n][i] + bv[bj][n][i]; float r;
;                             if (type < 2) { const float sg = sigmoidf_(xv); r = -expm1f(-0.606531f * sg); }
;                             else if (type == 2) r = sigmoidf_(xv);
;                             else r = xv;
;                             v[4 * n + i] = (f16)r; }
.LBB0_575:
	v_mul_f32_e32 v125, 0xbfb8aa3b, v128
	v_exp_f32_e32 v125, v125
	s_nop 0
	v_min_f32_e32 v125, 0x7e800000, v125
	v_add_f32_e32 v125, 1.0, v125
	v_rcp_f32_e32 v129, v125
	s_nop 0
	v_fma_f32 v131, -v125, v129, 1.0
	v_fma_f32 v125, v131, v129, v129
	v_mul_f32_e32 v125, 0xbf1b459e, v125
	v_mul_f32_e32 v128, 0x3fb8aa3b, v125
	v_exp_f32_e32 v128, v128
	s_nop 0
	v_sub_f32_e32 v125, 1.0, v128
.LBB0_576:
	v_add_f32_e32 v128, v126, v34
	s_and_b64 vcc, exec, s[8:9]
	s_mov_b64 s[14:15], -1
	s_cbranch_vccnz .LBB0_580
	s_and_b64 vcc, exec, s[6:7]
	v_mov_b32_e32 v126, v128
	s_cbranch_vccnz .LBB0_579
	v_mul_f32_e32 v126, 0xbfb8aa3b, v128
	v_exp_f32_e32 v126, v126
	s_nop 0
	v_min_f32_e32 v126, 0x7e800000, v126
	v_add_f32_e32 v126, 1.0, v126
	v_rcp_f32_e32 v130, v126
	s_nop 0
	v_fma_f32 v132, -v126, v130, 1.0
	v_fma_f32 v126, v132, v130, v130

; __device__ __forceinline__ float sigmoidf_(float x) { return 1.0f / (1.0f + __expf(-x)); }
;     __device__ __forceinline__ void operator()(const f32x4 (&acc)[2][2][4][2], const Unit& u, int wr, int wc, int fr, int fq) const {
;     ...
;                         for (int i = 0; i < 4; ++i) { float xv = acc[ai][bj][m][n][i] + bv[bj][n][i]; float r;
;                             if (type < 2) { const float sg = sigmoidf_(xv); r = -expm1f(-0.606531f * sg); }
;                             else if (type == 2) r = sigmoidf_(xv);
;                             else r = xv;
;                             v[4 * n + i] = (f16)r; }
.LBB0_581:
	v_mul_f32_e32 v126, 0xbfb8aa3b, v128
	v_exp_f32_e32 v126, v126
	s_nop 0
	v_min_f32_e32 v126, 0x7e800000, v126
	v_add_f32_e32 v126, 1.0, v126
	v_rcp_f32_e32 v129, v126
	s_nop 0
	v_fma_f32 v131, -v126, v129, 1.0
	v_fma_f32 v126, v131, v129, v129
	v_mul_f32_e32 v126, 0xbf1b459e, v126
	v_mul_f32_e32 v128, 0x3fb8aa3b, v126
	v_exp_f32_e32 v128, v128
	s_nop 0
	v_sub_f32_e32 v126, 1.0, v128
.LBB0_582:
	v_add_f32_e32 v128, v127, v35
	s_and_b64 vcc, exec, s[8:9]
	s_mov_b64 s[14:15], -1
	s_cbranch_vccnz .LBB0_586
	s_and_b64 vcc, exec, s[6:7]
	v_mov_b32_e32 v127, v128
	s_cbranch_vccnz .LBB0_585
	v_mul_f32_e32 v127, 0xbfb8aa3b, v128
	v_exp_f32_e32 v127, v127
	s_nop 0
	v_min_f32_e32 v127, 0x7e800000, v127
	v_add_f32_e32 v127, 1.0, v127
	v_rcp_f32_e32 v130, v127
	s_nop 0
	v_fma_f32 v132, -v127, v130, 1.0
	v_fma_f32 v127, v132, v130, v130

; __device__ __forceinline__ float sigmoidf_(float x) { return 1.0f / (1.0f + __expf(-x)); }
;     __device__ __forceinline__ void operator()(const f32x4 (&acc)[2][2][4][2], const Unit& u, int wr, int wc, int fr, int fq) const {
;     ...
;                         for (int i = 0; i < 4; ++i) { float xv = acc[ai][bj][m][n][i] + bv[bj][n][i]; float r;
;                             if (type < 2) { const float sg = sigmoidf_(xv); r = -expm1f(-0.606531f * sg); }
;                             else if (type == 2) r = sigmoidf_(xv);
;                             else r = xv;
;                             v[4 * n + i] = (f16)r; }
.LBB0_587:
	v_mul_f32_e32 v127, 0xbfb8aa3b, v128
	v_exp_f32_e32 v127, v127
	s_nop 0
	v_min_f32_e32 v127, 0x7e800000, v127
	v_add_f32_e32 v127, 1.0, v127
	v_rcp_f32_e32 v129, v127
	s_nop 0
	v_fma_f32 v131, -v127, v129, 1.0
	v_fma_f32 v127, v131, v129, v129
	v_mul_f32_e32 v127, 0xbf1b459e, v127
	v_mul_f32_e32 v128, 0x3fb8aa3b, v127
	v_exp_f32_e32 v128, v128
	s_nop 0
	v_sub_f32_e32 v127, 1.0, v128
.LBB0_588:
	v_add_f32_e32 v120, v120, v28
	s_and_b64 vcc, exec, s[8:9]
	s_mov_b64 s[14:15], -1
	s_cbranch_vccnz .LBB0_592
	s_and_b64 vcc, exec, s[6:7]
	v_mov_b32_e32 v128, v120
	s_cbranch_vccnz .LBB0_591
	v_mul_f32_e32 v128, 0xbfb8aa3b, v120
	v_exp_f32_e32 v128, v128
	s_nop 0
	v_min_f32_e32 v128, 0x7e800000, v128
	v_add_f32_e32 v128, 1.0, v128
	v_rcp_f32_e32 v130, v128
	s_nop 0
	v_fma_f32 v132, -v128, v130, 1.0
	v_fma_f32 v128, v132, v130, v130

; __device__ __forceinline__ float sigmoidf_(float x) { return 1.0f / (1.0f + __expf(-x)); }
;     __device__ __forceinline__ void operator()(const f32x4 (&acc)[2][2][4][2], const Unit& u, int wr, int wc, int fr, int fq) const {
;     ...
;                         for (int i = 0; i < 4; ++i) { float xv = acc[ai][bj][m][n][i] + bv[bj][n][i]; float r;
;                             if (type < 2) { const float sg = sigmoidf_(xv); r = -expm1f(-0.606531f * sg); }
;                             else if (type == 2) r = sigmoidf_(xv);
;                             else r = xv;
;                             v[4 * n + i] = (f16)r; }
.LBB0_593:
	v_mul_f32_e32 v120, 0xbfb8aa3b, v120
	v_exp_f32_e32 v120, v120
	s_nop 0
	v_min_f32_e32 v120, 0x7e800000, v120
	v_add_f32_e32 v120, 1.0, v120
	v_rcp_f32_e32 v129, v120
	s_nop 0
	v_fma_f32 v131, -v120, v129, 1.0
	v_fma_f32 v120, v131, v129, v129
	v_mul_f32_e32 v120, 0xbf1b459e, v120
	v_mul_f32_e32 v128, 0x3fb8aa3b, v120
	v_exp_f32_e32 v128, v128
	s_nop 0
	v_sub_f32_e32 v128, 1.0, v128
.LBB0_594:
	v_add_f32_e32 v120, v121, v29
	s_and_b64 vcc, exec, s[8:9]
	s_mov_b64 s[14:15], -1
	s_cbranch_vccnz .LBB0_598
	s_and_b64 vcc, exec, s[6:7]
	v_mov_b32_e32 v129, v120
	s_cbranch_vccnz .LBB0_597
	v_mul_f32_e32 v121, 0xbfb8aa3b, v120
	v_exp_f32_e32 v121, v121
	s_nop 0
	v_min_f32_e32 v121, 0x7e800000, v121
	v_add_f32_e32 v121, 1.0, v121
	v_rcp_f32_e32 v130, v121
	s_nop 0
	v_fma_f32 v132, -v121, v130, 1.0
	v_fma_f32 v129, v132, v130, v130

; __device__ __forceinline__ float sigmoidf_(float x) { return 1.0f / (1.0f + __expf(-x)); }
;     __device__ __forceinline__ void operator()(const f32x4 (&acc)[2][2][4][2], const Unit& u, int wr, int wc, int fr, int fq) const {
;     ...
;                         for (int i = 0; i < 4; ++i) { float xv = acc[ai][bj][m][n][i] + bv[bj][n][i]; float r;
;                             if (type < 2) { const float sg = sigmoidf_(xv); r = -expm1f(-0.606531f * sg); }
;                             else if (type == 2) r = sigmoidf_(xv);
;                             else r = xv;
;                             v[4 * n + i] = (f16)r; }
.LBB0_599:
	v_mul_f32_e32 v120, 0xbfb8aa3b, v120
	v_exp_f32_e32 v120, v120
	s_nop 0
	v_min_f32_e32 v120, 0x7e800000, v120
	v_add_f32_e32 v120, 1.0, v120
	v_rcp_f32_e32 v129, v120
	s_nop 0
	v_fma_f32 v131, -v120, v129, 1.0
	v_fma_f32 v120, v131, v129, v129
	v_mul_f32_e32 v120, 0xbf1b459e, v120
	v_mul_f32_e32 v121, 0x3fb8aa3b, v120
	v_exp_f32_e32 v121, v121
	s_nop 0
	v_sub_f32_e32 v129, 1.0, v121
.LBB0_600:
	v_add_f32_e32 v120, v122, v30
	s_and_b64 vcc, exec, s[8:9]
	s_mov_b64 s[14:15], -1
	s_cbranch_vccnz .LBB0_604
	s_and_b64 vcc, exec, s[6:7]
	v_mov_b32_e32 v122, v120
	s_cbranch_vccnz .LBB0_603
	v_mul_f32_e32 v121, 0xbfb8aa3b, v120
	v_exp_f32_e32 v121, v121
	s_nop 0
	v_min_f32_e32 v121, 0x7e800000, v121
	v_add_f32_e32 v121, 1.0, v121
	v_rcp_f32_e32 v130, v121
	s_nop 0
	v_fma_f32 v132, -v121, v130, 1.0
	v_fma_f32 v122, v132, v130, v130

; __device__ __forceinline__ float sigmoidf_(float x) { return 1.0f / (1.0f + __expf(-x)); }
;     __device__ __forceinline__ void operator()(const f32x4 (&acc)[2][2][4][2], const Unit& u, int wr, int wc, int fr, int fq) const {
;     ...
;                         for (int i = 0; i < 4; ++i) { float xv = acc[ai][bj][m][n][i] + bv[bj][n][i]; float r;
;                             if (type < 2) { const float sg = sigmoidf_(xv); r = -expm1f(-0.606531f * sg); }
;                             else if (type == 2) r = sigmoidf_(xv);
;                             else r = xv;
;                             v[4 * n + i] = (f16)r; }
.LBB0_605:
	v_mul_f32_e32 v120, 0xbfb8aa3b, v120
	v_exp_f32_e32 v120, v120
	s_nop 0
	v_min_f32_e32 v120, 0x7e800000, v120
	v_add_f32_e32 v120, 1.0, v120
	v_rcp_f32_e32 v122, v120
	s_nop 0
	v_fma_f32 v131, -v120, v122, 1.0
	v_fma_f32 v120, v131, v122, v122
	v_mul_f32_e32 v120, 0xbf1b459e, v120
	v_mul_f32_e32 v121, 0x3fb8aa3b, v120
	v_exp_f32_e32 v121, v121
	s_nop 0
	v_sub_f32_e32 v122, 1.0, v121
.LBB0_606:
	v_add_f32_e32 v120, v123, v31
	s_and_b64 vcc, exec, s[8:9]
	s_mov_b64 s[14:15], -1
	s_cbranch_vccnz .LBB0_610
	s_and_b64 vcc, exec, s[6:7]
	v_mov_b32_e32 v123, v120
	s_cbranch_vccnz .LBB0_609
	v_mul_f32_e32 v121, 0xbfb8aa3b, v120
	v_exp_f32_e32 v121, v121
	s_nop 0
	v_min_f32_e32 v121, 0x7e800000, v121
	v_add_f32_e32 v121, 1.0, v121
	v_rcp_f32_e32 v130, v121
	s_nop 0
	v_fma_f32 v132, -v121, v130, 1.0
	v_fma_f32 v123, v132, v130, v130

; __device__ __forceinline__ float sigmoidf_(float x) { return 1.0f / (1.0f + __expf(-x)); }
;     __device__ __forceinline__ void operator()(const f32x4 (&acc)[2][2][4][2], const Unit& u, int wr, int wc, int fr, int fq) const {
;     ...
;                         for (int i = 0; i < 4; ++i) { float xv = acc[ai][bj][m][n][i] + bv[bj][n][i]; float r;
;                             if (type < 2) { const float sg = sigmoidf_(xv); r = -expm1f(-0.606531f * sg); }
;                             else if (type == 2) r = sigmoidf_(xv);
;                             else r = xv;
;                             v[4 * n + i] = (f16)r; }
;                     *(f16x8*)(rowp + bj * 128) = v; } }
.LBB0_611:
	v_mul_f32_e32 v120, 0xbfb8aa3b, v120
	v_exp_f32_e32 v120, v120
	s_nop 0
	v_min_f32_e32 v120, 0x7e800000, v120
	v_add_f32_e32 v120, 1.0, v120
	v_rcp_f32_e32 v123, v120
	s_nop 0
	v_fma_f32 v131, -v120, v123, 1.0
	v_fma_f32 v120, v131, v123, v123
	v_mul_f32_e32 v120, 0xbf1b459e, v120
	v_mul_f32_e32 v121, 0x3fb8aa3b, v120
	v_exp_f32_e32 v121, v121
	s_nop 0
	v_sub_f32_e32 v123, 1.0, v121
.LBB0_612:
	v_or_b32_e32 v120, 16, v138
	v_ashrrev_i32_e32 v121, 31, v120
	v_lshlrev_b64 v[120:121], 13, v[120:121]
	v_lshl_add_u64 v[120:121], s[28:29], 0, v[120:121]
	v_lshl_add_u64 v[120:121], v[136:137], 1, v[120:121]
	v_cvt_pk_f16_f32 v131, v122, v123
	v_cvt_pk_f16_f32 v130, v128, v129
	v_cvt_pk_f16_f32 v129, v126, v127
	v_cvt_pk_f16_f32 v128, v124, v125
	v_add_f32_e32 v122, v116, v20
	s_and_b64 vcc, exec, s[8:9]
	s_mov_b64 s[14:15], -1
	global_store_dwordx4 v[120:121], v[128:131], off
	s_cbranch_vccnz .LBB0_616
	s_and_b64 vcc, exec, s[6:7]
	v_mov_b32_e32 v116, v122
	s_cbranch_vccnz .LBB0_615
	v_mul_f32_e32 v116, 0xbfb8aa3b, v122
	v_exp_f32_e32 v116, v116
	s_nop 0
	v_min_f32_e32 v116, 0x7e800000, v116
	v_add_f32_e32 v116, 1.0, v116
	v_rcp_f32_e32 v124, v116
	s_nop 0
	v_fma_f32 v126, -v116, v124, 1.0
	v_fma_f32 v116, v126, v124, v124

; __device__ __forceinline__ float sigmoidf_(float x) { return 1.0f / (1.0f + __expf(-x)); }
;     __device__ __forceinline__ void operator()(const f32x4 (&acc)[2][2][4][2], const Unit& u, int wr, int wc, int fr, int fq) const {
;     ...
;                         for (int i = 0; i < 4; ++i) { float xv = acc[ai][bj][m][n][i] + bv[bj][n][i]; float r;
;                             if (type < 2) { const float sg = sigmoidf_(xv); r = -expm1f(-0.606531f * sg); }
;                             else if (type == 2) r = sigmoidf_(xv);
;                             else r = xv;
;                             v[4 * n + i] = (f16)r; }
.LBB0_617:
	v_mul_f32_e32 v116, 0xbfb8aa3b, v122
	v_exp_f32_e32 v116, v116
	s_nop 0
	v_min_f32_e32 v116, 0x7e800000, v116
	v_add_f32_e32 v116, 1.0, v116
	v_rcp_f32_e32 v123, v116
	s_nop 0
	v_fma_f32 v125, -v116, v123, 1.0
	v_fma_f32 v116, v125, v123, v123
	v_mul_f32_e32 v116, 0xbf1b459e, v116
	v_mul_f32_e32 v122, 0x3fb8aa3b, v116
	v_exp_f32_e32 v122, v122
	s_nop 0
	v_sub_f32_e32 v116, 1.0, v122
.LBB0_618:
	v_add_f32_e32 v122, v117, v21
	s_and_b64 vcc, exec, s[8:9]
	s_mov_b64 s[14:15], -1
	s_cbranch_vccnz .LBB0_622
	s_and_b64 vcc, exec, s[6:7]
	v_mov_b32_e32 v117, v122
	s_cbranch_vccnz .LBB0_621
	v_mul_f32_e32 v117, 0xbfb8aa3b, v122
	v_exp_f32_e32 v117, v117
	s_nop 0
	v_min_f32_e32 v117, 0x7e800000, v117
	v_add_f32_e32 v117, 1.0, v117
	v_rcp_f32_e32 v124, v117
	s_nop 0
	v_fma_f32 v126, -v117, v124, 1.0
	v_fma_f32 v117, v126, v124, v124

; __device__ __forceinline__ float sigmoidf_(float x) { return 1.0f / (1.0f + __expf(-x)); }
;     __device__ __forceinline__ void operator()(const f32x4 (&acc)[2][2][4][2], const Unit& u, int wr, int wc, int fr, int fq) const {
;     ...
;                         for (int i = 0; i < 4; ++i) { float xv = acc[ai][bj][m][n][i] + bv[bj][n][i]; float r;
;                             if (type < 2) { const float sg = sigmoidf_(xv); r = -expm1f(-0.606531f * sg); }
;                             else if (type == 2) r = sigmoidf_(xv);
;                             else r = xv;
;                             v[4 * n + i] = (f16)r; }
.LBB0_623:
	v_mul_f32_e32 v117, 0xbfb8aa3b, v122
	v_exp_f32_e32 v117, v117
	s_nop 0
	v_min_f32_e32 v117, 0x7e800000, v117
	v_add_f32_e32 v117, 1.0, v117
	v_rcp_f32_e32 v123, v117
	s_nop 0
	v_fma_f32 v125, -v117, v123, 1.0
	v_fma_f32 v117, v125, v123, v123
	v_mul_f32_e32 v117, 0xbf1b459e, v117
	v_mul_f32_e32 v122, 0x3fb8aa3b, v117
	v_exp_f32_e32 v122, v122
	s_nop 0
	v_sub_f32_e32 v117, 1.0, v122
.LBB0_624:
	v_add_f32_e32 v122, v118, v22
	s_and_b64 vcc, exec, s[8:9]
	s_mov_b64 s[14:15], -1
	s_cbranch_vccnz .LBB0_628
	s_and_b64 vcc, exec, s[6:7]
	v_mov_b32_e32 v118, v122
	s_cbranch_vccnz .LBB0_627
	v_mul_f32_e32 v118, 0xbfb8aa3b, v122
	v_exp_f32_e32 v118, v118
	s_nop 0
	v_min_f32_e32 v118, 0x7e800000, v118
	v_add_f32_e32 v118, 1.0, v118
	v_rcp_f32_e32 v124, v118
	s_nop 0
	v_fma_f32 v126, -v118, v124, 1.0
	v_fma_f32 v118, v126, v124, v124

; __device__ __forceinline__ float sigmoidf_(float x) { return 1.0f / (1.0f + __expf(-x)); }
;     __device__ __forceinline__ void operator()(const f32x4 (&acc)[2][2][4][2], const Unit& u, int wr, int wc, int fr, int fq) const {
;     ...
;                         for (int i = 0; i < 4; ++i) { float xv = acc[ai][bj][m][n][i] + bv[bj][n][i]; float r;
;                             if (type < 2) { const float sg = sigmoidf_(xv); r = -expm1f(-0.606531f * sg); }
;                             else if (type == 2) r = sigmoidf_(xv);
;                             else r = xv;
;                             v[4 * n + i] = (f16)r; }
.LBB0_629:
	v_mul_f32_e32 v118, 0xbfb8aa3b, v122
	v_exp_f32_e32 v118, v118
	s_nop 0
	v_min_f32_e32 v118, 0x7e800000, v118
	v_add_f32_e32 v118, 1.0, v118
	v_rcp_f32_e32 v123, v118
	s_nop 0
	v_fma_f32 v125, -v118, v123, 1.0
	v_fma_f32 v118, v125, v123, v123
	v_mul_f32_e32 v118, 0xbf1b459e, v118
	v_mul_f32_e32 v122, 0x3fb8aa3b, v118
	v_exp_f32_e32 v122, v122
	s_nop 0
	v_sub_f32_e32 v118, 1.0, v122
.LBB0_630:
	v_add_f32_e32 v122, v119, v23
	s_and_b64 vcc, exec, s[8:9]
	s_mov_b64 s[14:15], -1
	s_cbranch_vccnz .LBB0_634
	s_and_b64 vcc, exec, s[6:7]
	v_mov_b32_e32 v119, v122
	s_cbranch_vccnz .LBB0_633
	v_mul_f32_e32 v119, 0xbfb8aa3b, v122
	v_exp_f32_e32 v119, v119
	s_nop 0
	v_min_f32_e32 v119, 0x7e800000, v119
	v_add_f32_e32 v119, 1.0, v119
	v_rcp_f32_e32 v124, v119
	s_nop 0
	v_fma_f32 v126, -v119, v124, 1.0
	v_fma_f32 v119, v126, v124, v124

; __device__ __forceinline__ float sigmoidf_(float x) { return 1.0f / (1.0f + __expf(-x)); }
;     __device__ __forceinline__ void operator()(const f32x4 (&acc)[2][2][4][2], const Unit& u, int wr, int wc, int fr, int fq) const {
;     ...
;                         for (int i = 0; i < 4; ++i) { float xv = acc[ai][bj][m][n][i] + bv[bj][n][i]; float r;
;                             if (type < 2) { const float sg = sigmoidf_(xv); r = -expm1f(-0.606531f * sg); }
;                             else if (type == 2) r = sigmoidf_(xv);
;                             else r = xv;
;                             v[4 * n + i] = (f16)r; }
.LBB0_635:
	v_mul_f32_e32 v119, 0xbfb8aa3b, v122
	v_exp_f32_e32 v119, v119
	s_nop 0
	v_min_f32_e32 v119, 0x7e800000, v119
	v_add_f32_e32 v119, 1.0, v119
	v_rcp_f32_e32 v123, v119
	s_nop 0
	v_fma_f32 v125, -v119, v123, 1.0
	v_fma_f32 v119, v125, v123, v123
	v_mul_f32_e32 v119, 0xbf1b459e, v119
	v_mul_f32_e32 v122, 0x3fb8aa3b, v119
	v_exp_f32_e32 v122, v122
	s_nop 0
	v_sub_f32_e32 v119, 1.0, v122
.LBB0_636:
	v_add_f32_e32 v122, v112, v12
	s_and_b64 vcc, exec, s[8:9]
	s_mov_b64 s[14:15], -1
	s_cbranch_vccnz .LBB0_640
	s_and_b64 vcc, exec, s[6:7]
	v_mov_b32_e32 v112, v122
	s_cbranch_vccnz .LBB0_639
	v_mul_f32_e32 v112, 0xbfb8aa3b, v122
	v_exp_f32_e32 v112, v112
	s_nop 0
	v_min_f32_e32 v112, 0x7e800000, v112
	v_add_f32_e32 v112, 1.0, v112
	v_rcp_f32_e32 v124, v112
	s_nop 0
	v_fma_f32 v126, -v112, v124, 1.0
	v_fma_f32 v112, v126, v124, v124

; __device__ __forceinline__ float sigmoidf_(float x) { return 1.0f / (1.0f + __expf(-x)); }
;     __device__ __forceinline__ void operator()(const f32x4 (&acc)[2][2][4][2], const Unit& u, int wr, int wc, int fr, int fq) const {
;     ...
;                         for (int i = 0; i < 4; ++i) { float xv = acc[ai][bj][m][n][i] + bv[bj][n][i]; float r;
;                             if (type < 2) { const float sg = sigmoidf_(xv); r = -expm1f(-0.606531f * sg); }
;                             else if (type == 2) r = sigmoidf_(xv);
;                             else r = xv;
;                             v[4 * n + i] = (f16)r; }
.LBB0_641:
	v_mul_f32_e32 v112, 0xbfb8aa3b, v122
	v_exp_f32_e32 v112, v112
	s_nop 0
	v_min_f32_e32 v112, 0x7e800000, v112
	v_add_f32_e32 v112, 1.0, v112
	v_rcp_f32_e32 v123, v112
	s_nop 0
	v_fma_f32 v125, -v112, v123, 1.0
	v_fma_f32 v112, v125, v123, v123
	v_mul_f32_e32 v112, 0xbf1b459e, v112
	v_mul_f32_e32 v122, 0x3fb8aa3b, v112
	v_exp_f32_e32 v122, v122
	s_nop 0
	v_sub_f32_e32 v112, 1.0, v122
.LBB0_642:
	v_add_f32_e32 v122, v113, v13
	s_and_b64 vcc, exec, s[8:9]
	s_mov_b64 s[14:15], -1
	s_cbranch_vccnz .LBB0_646
	s_and_b64 vcc, exec, s[6:7]
	v_mov_b32_e32 v113, v122
	s_cbranch_vccnz .LBB0_645
	v_mul_f32_e32 v113, 0xbfb8aa3b, v122
	v_exp_f32_e32 v113, v113
	s_nop 0
	v_min_f32_e32 v113, 0x7e800000, v113
	v_add_f32_e32 v113, 1.0, v113
	v_rcp_f32_e32 v124, v113
	s_nop 0
	v_fma_f32 v126, -v113, v124, 1.0
	v_fma_f32 v113, v126, v124, v124

; __device__ __forceinline__ float sigmoidf_(float x) { return 1.0f / (1.0f + __expf(-x)); }
;     __device__ __forceinline__ void operator()(const f32x4 (&acc)[2][2][4][2], const Unit& u, int wr, int wc, int fr, int fq) const {
;     ...
;                         for (int i = 0; i < 4; ++i) { float xv = acc[ai][bj][m][n][i] + bv[bj][n][i]; float r;
;                             if (type < 2) { const float sg = sigmoidf_(xv); r = -expm1f(-0.606531f * sg); }
;                             else if (type == 2) r = sigmoidf_(xv);
;                             else r = xv;
;                             v[4 * n + i] = (f16)r; }
.LBB0_647:
	v_mul_f32_e32 v113, 0xbfb8aa3b, v122
	v_exp_f32_e32 v113, v113
	s_nop 0
	v_min_f32_e32 v113, 0x7e800000, v113
	v_add_f32_e32 v113, 1.0, v113
	v_rcp_f32_e32 v123, v113
	s_nop 0
	v_fma_f32 v125, -v113, v123, 1.0
	v_fma_f32 v113, v125, v123, v123
	v_mul_f32_e32 v113, 0xbf1b459e, v113
	v_mul_f32_e32 v122, 0x3fb8aa3b, v113
	v_exp_f32_e32 v122, v122
	s_nop 0
	v_sub_f32_e32 v113, 1.0, v122
.LBB0_648:
	v_add_f32_e32 v122, v114, v14
	s_and_b64 vcc, exec, s[8:9]
	s_mov_b64 s[14:15], -1
	s_cbranch_vccnz .LBB0_652
	s_and_b64 vcc, exec, s[6:7]
	v_mov_b32_e32 v114, v122
	s_cbranch_vccnz .LBB0_651
	v_mul_f32_e32 v114, 0xbfb8aa3b, v122
	v_exp_f32_e32 v114, v114
	s_nop 0
	v_min_f32_e32 v114, 0x7e800000, v114
	v_add_f32_e32 v114, 1.0, v114
	v_rcp_f32_e32 v124, v114
	s_nop 0
	v_fma_f32 v126, -v114, v124, 1.0
	v_fma_f32 v114, v126, v124, v124

; __device__ __forceinline__ float sigmoidf_(float x) { return 1.0f / (1.0f + __expf(-x)); }
;     __device__ __forceinline__ void operator()(const f32x4 (&acc)[2][2][4][2], const Unit& u, int wr, int wc, int fr, int fq) const {
;     ...
;                         for (int i = 0; i < 4; ++i) { float xv = acc[ai][bj][m][n][i] + bv[bj][n][i]; float r;
;                             if (type < 2) { const float sg = sigmoidf_(xv); r = -expm1f(-0.606531f * sg); }
;                             else if (type == 2) r = sigmoidf_(xv);
;                             else r = xv;
;                             v[4 * n + i] = (f16)r; }
.LBB0_653:
	v_mul_f32_e32 v114, 0xbfb8aa3b, v122
	v_exp_f32_e32 v114, v114
	s_nop 0
	v_min_f32_e32 v114, 0x7e800000, v114
	v_add_f32_e32 v114, 1.0, v114
	v_rcp_f32_e32 v123, v114
	s_nop 0
	v_fma_f32 v125, -v114, v123, 1.0
	v_fma_f32 v114, v125, v123, v123
	v_mul_f32_e32 v114, 0xbf1b459e, v114
	v_mul_f32_e32 v122, 0x3fb8aa3b, v114
	v_exp_f32_e32 v122, v122
	s_nop 0
	v_sub_f32_e32 v114, 1.0, v122
.LBB0_654:
	v_add_f32_e32 v115, v115, v15
	s_and_b64 vcc, exec, s[8:9]
	s_mov_b64 s[14:15], -1
	s_cbranch_vccnz .LBB0_658
	s_and_b64 vcc, exec, s[6:7]
	v_mov_b32_e32 v122, v115
	s_cbranch_vccnz .LBB0_657
	v_mul_f32_e32 v122, 0xbfb8aa3b, v115
	v_exp_f32_e32 v122, v122
	s_nop 0
	v_min_f32_e32 v122, 0x7e800000, v122
	v_add_f32_e32 v122, 1.0, v122
	v_rcp_f32_e32 v124, v122
	s_nop 0
	v_fma_f32 v126, -v122, v124, 1.0
	v_fma_f32 v122, v126, v124, v124

; __device__ __forceinline__ float sigmoidf_(float x) { return 1.0f / (1.0f + __expf(-x)); }
;     __device__ __forceinline__ void operator()(const f32x4 (&acc)[2][2][4][2], const Unit& u, int wr, int wc, int fr, int fq) const {
;     ...
;                         for (int i = 0; i < 4; ++i) { float xv = acc[ai][bj][m][n][i] + bv[bj][n][i]; float r;
;                             if (type < 2) { const float sg = sigmoidf_(xv); r = -expm1f(-0.606531f * sg); }
;                             else if (type == 2) r = sigmoidf_(xv);
;                             else r = xv;
;                             v[4 * n + i] = (f16)r; }
;                     *(f16x8*)(rowp + bj * 128) = v; } }
.LBB0_659:
	v_mul_f32_e32 v115, 0xbfb8aa3b, v115
	v_exp_f32_e32 v115, v115
	s_nop 0
	v_min_f32_e32 v115, 0x7e800000, v115
	v_add_f32_e32 v115, 1.0, v115
	v_rcp_f32_e32 v123, v115
	s_nop 0
	v_fma_f32 v125, -v115, v123, 1.0
	v_fma_f32 v115, v125, v123, v123
	v_mul_f32_e32 v115, 0xbf1b459e, v115
	v_mul_f32_e32 v122, 0x3fb8aa3b, v115
	v_exp_f32_e32 v122, v122
	s_nop 0
	v_sub_f32_e32 v122, 1.0, v122
.LBB0_660:
	v_cvt_pk_f16_f32 v115, v114, v122
	v_cvt_pk_f16_f32 v114, v112, v113
	v_cvt_pk_f16_f32 v113, v118, v119
	v_cvt_pk_f16_f32 v112, v116, v117
	global_store_dwordx4 v[120:121], v[112:115], off offset:256
	s_and_b64 vcc, exec, s[8:9]
	s_mov_b64 s[14:15], -1
	v_add_f32_e32 v112, v108, v32
	s_cbranch_vccnz .LBB0_664
	s_and_b64 vcc, exec, s[6:7]
	v_mov_b32_e32 v108, v112
	s_cbranch_vccnz .LBB0_663
	v_mul_f32_e32 v108, 0xbfb8aa3b, v112
	v_exp_f32_e32 v108, v108
	s_nop 0
	v_min_f32_e32 v108, 0x7e800000, v108
	v_add_f32_e32 v108, 1.0, v108
	v_rcp_f32_e32 v114, v108
	s_nop 0
	v_fma_f32 v116, -v108, v114, 1.0
	v_fma_f32 v108, v116, v114, v114

; __device__ __forceinline__ float sigmoidf_(float x) { return 1.0f / (1.0f + __expf(-x)); }
;     __device__ __forceinline__ void operator()(const f32x4 (&acc)[2][2][4][2], const Unit& u, int wr, int wc, int fr, int fq) const {
;     ...
;                         for (int i = 0; i < 4; ++i) { float xv = acc[ai][bj][m][n][i] + bv[bj][n][i]; float r;
;                             if (type < 2) { const float sg = sigmoidf_(xv); r = -expm1f(-0.606531f * sg); }
;                             else if (type == 2) r = sigmoidf_(xv);
;                             else r = xv;
;                             v[4 * n + i] = (f16)r; }
.LBB0_665:
	v_mul_f32_e32 v108, 0xbfb8aa3b, v112
	v_exp_f32_e32 v108, v108
	s_nop 0
	v_min_f32_e32 v108, 0x7e800000, v108
	v_add_f32_e32 v108, 1.0, v108
	v_rcp_f32_e32 v113, v108
	s_nop 0
	v_fma_f32 v115, -v108, v113, 1.0
	v_fma_f32 v108, v115, v113, v113
	v_mul_f32_e32 v108, 0xbf1b459e, v108
	v_mul_f32_e32 v112, 0x3fb8aa3b, v108
	v_exp_f32_e32 v112, v112
	s_nop 0
	v_sub_f32_e32 v108, 1.0, v112
.LBB0_666:
	v_add_f32_e32 v112, v109, v33
	s_and_b64 vcc, exec, s[8:9]
	s_mov_b64 s[14:15], -1
	s_cbranch_vccnz .LBB0_670
	s_and_b64 vcc, exec, s[6:7]
	v_mov_b32_e32 v109, v112
	s_cbranch_vccnz .LBB0_669
	v_mul_f32_e32 v109, 0xbfb8aa3b, v112
	v_exp_f32_e32 v109, v109
	s_nop 0
	v_min_f32_e32 v109, 0x7e800000, v109
	v_add_f32_e32 v109, 1.0, v109
	v_rcp_f32_e32 v114, v109
	s_nop 0
	v_fma_f32 v116, -v109, v114, 1.0
	v_fma_f32 v109, v116, v114, v114

; __device__ __forceinline__ float sigmoidf_(float x) { return 1.0f / (1.0f + __expf(-x)); }
;     __device__ __forceinline__ void operator()(const f32x4 (&acc)[2][2][4][2], const Unit& u, int wr, int wc, int fr, int fq) const {
;     ...
;                         for (int i = 0; i < 4; ++i) { float xv = acc[ai][bj][m][n][i] + bv[bj][n][i]; float r;
;                             if (type < 2) { const float sg = sigmoidf_(xv); r = -expm1f(-0.606531f * sg); }
;                             else if (type == 2) r = sigmoidf_(xv);
;                             else r = xv;
;                             v[4 * n + i] = (f16)r; }
.LBB0_671:
	v_mul_f32_e32 v109, 0xbfb8aa3b, v112
	v_exp_f32_e32 v109, v109
	s_nop 0
	v_min_f32_e32 v109, 0x7e800000, v109
	v_add_f32_e32 v109, 1.0, v109
	v_rcp_f32_e32 v113, v109
	s_nop 0
	v_fma_f32 v115, -v109, v113, 1.0
	v_fma_f32 v109, v115, v113, v113
	v_mul_f32_e32 v109, 0xbf1b459e, v109
	v_mul_f32_e32 v112, 0x3fb8aa3b, v109
	v_exp_f32_e32 v112, v112
	s_nop 0
	v_sub_f32_e32 v109, 1.0, v112
.LBB0_672:
	v_add_f32_e32 v112, v110, v34
	s_and_b64 vcc, exec, s[8:9]
	s_mov_b64 s[14:15], -1
	s_cbranch_vccnz .LBB0_676
	s_and_b64 vcc, exec, s[6:7]
	v_mov_b32_e32 v110, v112
	s_cbranch_vccnz .LBB0_675
	v_mul_f32_e32 v110, 0xbfb8aa3b, v112
	v_exp_f32_e32 v110, v110
	s_nop 0
	v_min_f32_e32 v110, 0x7e800000, v110
	v_add_f32_e32 v110, 1.0, v110
	v_rcp_f32_e32 v114, v110
	s_nop 0
	v_fma_f32 v116, -v110, v114, 1.0
	v_fma_f32 v110, v116, v114, v114

; __device__ __forceinline__ float sigmoidf_(float x) { return 1.0f / (1.0f + __expf(-x)); }
;     __device__ __forceinline__ void operator()(const f32x4 (&acc)[2][2][4][2], const Unit& u, int wr, int wc, int fr, int fq) const {
;     ...
;                         for (int i = 0; i < 4; ++i) { float xv = acc[ai][bj][m][n][i] + bv[bj][n][i]; float r;
;                             if (type < 2) { const float sg = sigmoidf_(xv); r = -expm1f(-0.606531f * sg); }
;                             else if (type == 2) r = sigmoidf_(xv);
;                             else r = xv;
;                             v[4 * n + i] = (f16)r; }
.LBB0_677:
	v_mul_f32_e32 v110, 0xbfb8aa3b, v112
	v_exp_f32_e32 v110, v110
	s_nop 0
	v_min_f32_e32 v110, 0x7e800000, v110
	v_add_f32_e32 v110, 1.0, v110
	v_rcp_f32_e32 v113, v110
	s_nop 0
	v_fma_f32 v115, -v110, v113, 1.0
	v_fma_f32 v110, v115, v113, v113
	v_mul_f32_e32 v110, 0xbf1b459e, v110
	v_mul_f32_e32 v112, 0x3fb8aa3b, v110
	v_exp_f32_e32 v112, v112
	s_nop 0
	v_sub_f32_e32 v110, 1.0, v112
.LBB0_678:
	v_add_f32_e32 v112, v111, v35
	s_and_b64 vcc, exec, s[8:9]
	s_mov_b64 s[14:15], -1
	s_cbranch_vccnz .LBB0_682
	s_and_b64 vcc, exec, s[6:7]
	v_mov_b32_e32 v111, v112
	s_cbranch_vccnz .LBB0_681
	v_mul_f32_e32 v111, 0xbfb8aa3b, v112
	v_exp_f32_e32 v111, v111
	s_nop 0
	v_min_f32_e32 v111, 0x7e800000, v111
	v_add_f32_e32 v111, 1.0, v111
	v_rcp_f32_e32 v114, v111
	s_nop 0
	v_fma_f32 v116, -v111, v114, 1.0
	v_fma_f32 v111, v116, v114, v114

; __device__ __forceinline__ float sigmoidf_(float x) { return 1.0f / (1.0f + __expf(-x)); }
;     __device__ __forceinline__ void operator()(const f32x4 (&acc)[2][2][4][2], const Unit& u, int wr, int wc, int fr, int fq) const {
;     ...
;                         for (int i = 0; i < 4; ++i) { float xv = acc[ai][bj][m][n][i] + bv[bj][n][i]; float r;
;                             if (type < 2) { const float sg = sigmoidf_(xv); r = -expm1f(-0.606531f * sg); }
;                             else if (type == 2) r = sigmoidf_(xv);
;                             else r = xv;
;                             v[4 * n + i] = (f16)r; }
.LBB0_683:
	v_mul_f32_e32 v111, 0xbfb8aa3b, v112
	v_exp_f32_e32 v111, v111
	s_nop 0
	v_min_f32_e32 v111, 0x7e800000, v111
	v_add_f32_e32 v111, 1.0, v111
	v_rcp_f32_e32 v113, v111
	s_nop 0
	v_fma_f32 v115, -v111, v113, 1.0
	v_fma_f32 v111, v115, v113, v113
	v_mul_f32_e32 v111, 0xbf1b459e, v111
	v_mul_f32_e32 v112, 0x3fb8aa3b, v111
	v_exp_f32_e32 v112, v112
	s_nop 0
	v_sub_f32_e32 v111, 1.0, v112
.LBB0_684:
	v_add_f32_e32 v104, v104, v28
	s_and_b64 vcc, exec, s[8:9]
	s_mov_b64 s[14:15], -1
	s_cbranch_vccnz .LBB0_688
	s_and_b64 vcc, exec, s[6:7]
	v_mov_b32_e32 v112, v104
	s_cbranch_vccnz .LBB0_687
	v_mul_f32_e32 v112, 0xbfb8aa3b, v104
	v_exp_f32_e32 v112, v112
	s_nop 0
	v_min_f32_e32 v112, 0x7e800000, v112
	v_add_f32_e32 v112, 1.0, v112
	v_rcp_f32_e32 v114, v112
	s_nop 0
	v_fma_f32 v116, -v112, v114, 1.0
	v_fma_f32 v112, v116, v114, v114

; __device__ __forceinline__ float sigmoidf_(float x) { return 1.0f / (1.0f + __expf(-x)); }
;     __device__ __forceinline__ void operator()(const f32x4 (&acc)[2][2][4][2], const Unit& u, int wr, int wc, int fr, int fq) const {
;     ...
;                         for (int i = 0; i < 4; ++i) { float xv = acc[ai][bj][m][n][i] + bv[bj][n][i]; float r;
;                             if (type < 2) { const float sg = sigmoidf_(xv); r = -expm1f(-0.606531f * sg); }
;                             else if (type == 2) r = sigmoidf_(xv);
;                             else r = xv;
;                             v[4 * n + i] = (f16)r; }
.LBB0_689:
	v_mul_f32_e32 v104, 0xbfb8aa3b, v104
	v_exp_f32_e32 v104, v104
	s_nop 0
	v_min_f32_e32 v104, 0x7e800000, v104
	v_add_f32_e32 v104, 1.0, v104
	v_rcp_f32_e32 v113, v104
	s_nop 0
	v_fma_f32 v115, -v104, v113, 1.0
	v_fma_f32 v104, v115, v113, v113
	v_mul_f32_e32 v104, 0xbf1b459e, v104
	v_mul_f32_e32 v112, 0x3fb8aa3b, v104
	v_exp_f32_e32 v112, v112
	s_nop 0
	v_sub_f32_e32 v112, 1.0, v112
.LBB0_690:
	v_add_f32_e32 v104, v105, v29
	s_and_b64 vcc, exec, s[8:9]
	s_mov_b64 s[14:15], -1
	s_cbranch_vccnz .LBB0_694
	s_and_b64 vcc, exec, s[6:7]
	v_mov_b32_e32 v113, v104
	s_cbranch_vccnz .LBB0_693
	v_mul_f32_e32 v105, 0xbfb8aa3b, v104
	v_exp_f32_e32 v105, v105
	s_nop 0
	v_min_f32_e32 v105, 0x7e800000, v105
	v_add_f32_e32 v105, 1.0, v105
	v_rcp_f32_e32 v114, v105
	s_nop 0
	v_fma_f32 v116, -v105, v114, 1.0
	v_fma_f32 v113, v116, v114, v114

; __device__ __forceinline__ float sigmoidf_(float x) { return 1.0f / (1.0f + __expf(-x)); }
;     __device__ __forceinline__ void operator()(const f32x4 (&acc)[2][2][4][2], const Unit& u, int wr, int wc, int fr, int fq) const {
;     ...
;                         for (int i = 0; i < 4; ++i) { float xv = acc[ai][bj][m][n][i] + bv[bj][n][i]; float r;
;                             if (type < 2) { const float sg = sigmoidf_(xv); r = -expm1f(-0.606531f * sg); }
;                             else if (type == 2) r = sigmoidf_(xv);
;                             else r = xv;
;                             v[4 * n + i] = (f16)r; }
.LBB0_695:
	v_mul_f32_e32 v104, 0xbfb8aa3b, v104
	v_exp_f32_e32 v104, v104
	s_nop 0
	v_min_f32_e32 v104, 0x7e800000, v104
	v_add_f32_e32 v104, 1.0, v104
	v_rcp_f32_e32 v113, v104
	s_nop 0
	v_fma_f32 v115, -v104, v113, 1.0
	v_fma_f32 v104, v115, v113, v113
	v_mul_f32_e32 v104, 0xbf1b459e, v104
	v_mul_f32_e32 v105, 0x3fb8aa3b, v104
	v_exp_f32_e32 v105, v105
	s_nop 0
	v_sub_f32_e32 v113, 1.0, v105
.LBB0_696:
	v_add_f32_e32 v104, v106, v30
	s_and_b64 vcc, exec, s[8:9]
	s_mov_b64 s[14:15], -1
	s_cbranch_vccnz .LBB0_700
	s_and_b64 vcc, exec, s[6:7]
	v_mov_b32_e32 v106, v104
	s_cbranch_vccnz .LBB0_699
	v_mul_f32_e32 v105, 0xbfb8aa3b, v104
	v_exp_f32_e32 v105, v105
	s_nop 0
	v_min_f32_e32 v105, 0x7e800000, v105
	v_add_f32_e32 v105, 1.0, v105
	v_rcp_f32_e32 v114, v105
	s_nop 0
	v_fma_f32 v116, -v105, v114, 1.0
	v_fma_f32 v106, v116, v114, v114

; __device__ __forceinline__ float sigmoidf_(float x) { return 1.0f / (1.0f + __expf(-x)); }
;     __device__ __forceinline__ void operator()(const f32x4 (&acc)[2][2][4][2], const Unit& u, int wr, int wc, int fr, int fq) const {
;     ...
;                         for (int i = 0; i < 4; ++i) { float xv = acc[ai][bj][m][n][i] + bv[bj][n][i]; float r;
;                             if (type < 2) { const float sg = sigmoidf_(xv); r = -expm1f(-0.606531f * sg); }
;                             else if (type == 2) r = sigmoidf_(xv);
;                             else r = xv;
;                             v[4 * n + i] = (f16)r; }
.LBB0_701:
	v_mul_f32_e32 v104, 0xbfb8aa3b, v104
	v_exp_f32_e32 v104, v104
	s_nop 0
	v_min_f32_e32 v104, 0x7e800000, v104
	v_add_f32_e32 v104, 1.0, v104
	v_rcp_f32_e32 v106, v104
	s_nop 0
	v_fma_f32 v115, -v104, v106, 1.0
	v_fma_f32 v104, v115, v106, v106
	v_mul_f32_e32 v104, 0xbf1b459e, v104
	v_mul_f32_e32 v105, 0x3fb8aa3b, v104
	v_exp_f32_e32 v105, v105
	s_nop 0
	v_sub_f32_e32 v106, 1.0, v105
.LBB0_702:
	v_add_f32_e32 v104, v107, v31
	s_and_b64 vcc, exec, s[8:9]
	s_mov_b64 s[14:15], -1
	s_cbranch_vccnz .LBB0_706
	s_and_b64 vcc, exec, s[6:7]
	v_mov_b32_e32 v107, v104
	s_cbranch_vccnz .LBB0_705
	v_mul_f32_e32 v105, 0xbfb8aa3b, v104
	v_exp_f32_e32 v105, v105
	s_nop 0
	v_min_f32_e32 v105, 0x7e800000, v105
	v_add_f32_e32 v105, 1.0, v105
	v_rcp_f32_e32 v114, v105
	s_nop 0
	v_fma_f32 v116, -v105, v114, 1.0
	v_fma_f32 v107, v116, v114, v114

; __device__ __forceinline__ float sigmoidf_(float x) { return 1.0f / (1.0f + __expf(-x)); }
;     __device__ __forceinline__ void operator()(const f32x4 (&acc)[2][2][4][2], const Unit& u, int wr, int wc, int fr, int fq) const {
;     ...
;                         for (int i = 0; i < 4; ++i) { float xv = acc[ai][bj][m][n][i] + bv[bj][n][i]; float r;
;                             if (type < 2) { const float sg = sigmoidf_(xv); r = -expm1f(-0.606531f * sg); }
;                             else if (type == 2) r = sigmoidf_(xv);
;                             else r = xv;
;                             v[4 * n + i] = (f16)r; }
;                     *(f16x8*)(rowp + bj * 128) = v; } }
.LBB0_707:
	v_mul_f32_e32 v104, 0xbfb8aa3b, v104
	v_exp_f32_e32 v104, v104
	s_nop 0
	v_min_f32_e32 v104, 0x7e800000, v104
	v_add_f32_e32 v104, 1.0, v104
	v_rcp_f32_e32 v107, v104
	s_nop 0
	v_fma_f32 v115, -v104, v107, 1.0
	v_fma_f32 v104, v115, v107, v107
	v_mul_f32_e32 v104, 0xbf1b459e, v104
	v_mul_f32_e32 v105, 0x3fb8aa3b, v104
	v_exp_f32_e32 v105, v105
	s_nop 0
	v_sub_f32_e32 v107, 1.0, v105
.LBB0_708:
	v_or_b32_e32 v104, 32, v138
	v_ashrrev_i32_e32 v105, 31, v104
	v_lshlrev_b64 v[104:105], 13, v[104:105]
	v_lshl_add_u64 v[104:105], s[28:29], 0, v[104:105]
	v_lshl_add_u64 v[104:105], v[136:137], 1, v[104:105]
	v_cvt_pk_f16_f32 v115, v106, v107
	v_cvt_pk_f16_f32 v114, v112, v113
	v_cvt_pk_f16_f32 v113, v110, v111
	v_cvt_pk_f16_f32 v112, v108, v109
	v_add_f32_e32 v106, v100, v20
	s_and_b64 vcc, exec, s[8:9]
	s_mov_b64 s[14:15], -1
	global_store_dwordx4 v[104:105], v[112:115], off
	s_cbranch_vccnz .LBB0_712
	s_and_b64 vcc, exec, s[6:7]
	v_mov_b32_e32 v100, v106
	s_cbranch_vccnz .LBB0_711
	v_mul_f32_e32 v100, 0xbfb8aa3b, v106
	v_exp_f32_e32 v100, v100
	s_nop 0
	v_min_f32_e32 v100, 0x7e800000, v100
	v_add_f32_e32 v100, 1.0, v100
	v_rcp_f32_e32 v108, v100
	s_nop 0
	v_fma_f32 v110, -v100, v108, 1.0
	v_fma_f32 v100, v110, v108, v108

; __device__ __forceinline__ float sigmoidf_(float x) { return 1.0f / (1.0f + __expf(-x)); }
;     __device__ __forceinline__ void operator()(const f32x4 (&acc)[2][2][4][2], const Unit& u, int wr, int wc, int fr, int fq) const {
;     ...
;                         for (int i = 0; i < 4; ++i) { float xv = acc[ai][bj][m][n][i] + bv[bj][n][i]; float r;
;                             if (type < 2) { const float sg = sigmoidf_(xv); r = -expm1f(-0.606531f * sg); }
;                             else if (type == 2) r = sigmoidf_(xv);
;                             else r = xv;
;                             v[4 * n + i] = (f16)r; }
.LBB0_713:
	v_mul_f32_e32 v100, 0xbfb8aa3b, v106
	v_exp_f32_e32 v100, v100
	s_nop 0
	v_min_f32_e32 v100, 0x7e800000, v100
	v_add_f32_e32 v100, 1.0, v100
	v_rcp_f32_e32 v107, v100
	s_nop 0
	v_fma_f32 v109, -v100, v107, 1.0
	v_fma_f32 v100, v109, v107, v107
	v_mul_f32_e32 v100, 0xbf1b459e, v100
	v_mul_f32_e32 v106, 0x3fb8aa3b, v100
	v_exp_f32_e32 v106, v106
	s_nop 0
	v_sub_f32_e32 v100, 1.0, v106
.LBB0_714:
	v_add_f32_e32 v106, v101, v21
	s_and_b64 vcc, exec, s[8:9]
	s_mov_b64 s[14:15], -1
	s_cbranch_vccnz .LBB0_718
	s_and_b64 vcc, exec, s[6:7]
	v_mov_b32_e32 v101, v106
	s_cbranch_vccnz .LBB0_717
	v_mul_f32_e32 v101, 0xbfb8aa3b, v106
	v_exp_f32_e32 v101, v101
	s_nop 0
	v_min_f32_e32 v101, 0x7e800000, v101
	v_add_f32_e32 v101, 1.0, v101
	v_rcp_f32_e32 v108, v101
	s_nop 0
	v_fma_f32 v110, -v101, v108, 1.0
	v_fma_f32 v101, v110, v108, v108

; __device__ __forceinline__ float sigmoidf_(float x) { return 1.0f / (1.0f + __expf(-x)); }
;     __device__ __forceinline__ void operator()(const f32x4 (&acc)[2][2][4][2], const Unit& u, int wr, int wc, int fr, int fq) const {
;     ...
;                         for (int i = 0; i < 4; ++i) { float xv = acc[ai][bj][m][n][i] + bv[bj][n][i]; float r;
;                             if (type < 2) { const float sg = sigmoidf_(xv); r = -expm1f(-0.606531f * sg); }
;                             else if (type == 2) r = sigmoidf_(xv);
;                             else r = xv;
;                             v[4 * n + i] = (f16)r; }
.LBB0_719:
	v_mul_f32_e32 v101, 0xbfb8aa3b, v106
	v_exp_f32_e32 v101, v101
	s_nop 0
	v_min_f32_e32 v101, 0x7e800000, v101
	v_add_f32_e32 v101, 1.0, v101
	v_rcp_f32_e32 v107, v101
	s_nop 0
	v_fma_f32 v109, -v101, v107, 1.0
	v_fma_f32 v101, v109, v107, v107
	v_mul_f32_e32 v101, 0xbf1b459e, v101
	v_mul_f32_e32 v106, 0x3fb8aa3b, v101
	v_exp_f32_e32 v106, v106
	s_nop 0
	v_sub_f32_e32 v101, 1.0, v106
.LBB0_720:
	v_add_f32_e32 v106, v102, v22
	s_and_b64 vcc, exec, s[8:9]
	s_mov_b64 s[14:15], -1
	s_cbranch_vccnz .LBB0_724
	s_and_b64 vcc, exec, s[6:7]
	v_mov_b32_e32 v102, v106
	s_cbranch_vccnz .LBB0_723
	v_mul_f32_e32 v102, 0xbfb8aa3b, v106
	v_exp_f32_e32 v102, v102
	s_nop 0
	v_min_f32_e32 v102, 0x7e800000, v102
	v_add_f32_e32 v102, 1.0, v102
	v_rcp_f32_e32 v108, v102
	s_nop 0
	v_fma_f32 v110, -v102, v108, 1.0
	v_fma_f32 v102, v110, v108, v108

; __device__ __forceinline__ float sigmoidf_(float x) { return 1.0f / (1.0f + __expf(-x)); }
;     __device__ __forceinline__ void operator()(const f32x4 (&acc)[2][2][4][2], const Unit& u, int wr, int wc, int fr, int fq) const {
;     ...
;                         for (int i = 0; i < 4; ++i) { float xv = acc[ai][bj][m][n][i] + bv[bj][n][i]; float r;
;                             if (type < 2) { const float sg = sigmoidf_(xv); r = -expm1f(-0.606531f * sg); }
;                             else if (type == 2) r = sigmoidf_(xv);
;                             else r = xv;
;                             v[4 * n + i] = (f16)r; }
.LBB0_725:
	v_mul_f32_e32 v102, 0xbfb8aa3b, v106
	v_exp_f32_e32 v102, v102
	s_nop 0
	v_min_f32_e32 v102, 0x7e800000, v102
	v_add_f32_e32 v102, 1.0, v102
	v_rcp_f32_e32 v107, v102
	s_nop 0
	v_fma_f32 v109, -v102, v107, 1.0
	v_fma_f32 v102, v109, v107, v107
	v_mul_f32_e32 v102, 0xbf1b459e, v102
	v_mul_f32_e32 v106, 0x3fb8aa3b, v102
	v_exp_f32_e32 v106, v106
	s_nop 0
	v_sub_f32_e32 v102, 1.0, v106
.LBB0_726:
	v_add_f32_e32 v106, v103, v23
	s_and_b64 vcc, exec, s[8:9]
	s_mov_b64 s[14:15], -1
	s_cbranch_vccnz .LBB0_730
	s_and_b64 vcc, exec, s[6:7]
	v_mov_b32_e32 v103, v106
	s_cbranch_vccnz .LBB0_729
	v_mul_f32_e32 v103, 0xbfb8aa3b, v106
	v_exp_f32_e32 v103, v103
	s_nop 0
	v_min_f32_e32 v103, 0x7e800000, v103
	v_add_f32_e32 v103, 1.0, v103
	v_rcp_f32_e32 v108, v103
	s_nop 0
	v_fma_f32 v110, -v103, v108, 1.0
	v_fma_f32 v103, v110, v108, v108

; __device__ __forceinline__ float sigmoidf_(float x) { return 1.0f / (1.0f + __expf(-x)); }
;     __device__ __forceinline__ void operator()(const f32x4 (&acc)[2][2][4][2], const Unit& u, int wr, int wc, int fr, int fq) const {
;     ...
;                         for (int i = 0; i < 4; ++i) { float xv = acc[ai][bj][m][n][i] + bv[bj][n][i]; float r;
;                             if (type < 2) { const float sg = sigmoidf_(xv); r = -expm1f(-0.606531f * sg); }
;                             else if (type == 2) r = sigmoidf_(xv);
;                             else r = xv;
;                             v[4 * n + i] = (f16)r; }
.LBB0_731:
	v_mul_f32_e32 v103, 0xbfb8aa3b, v106
	v_exp_f32_e32 v103, v103
	s_nop 0
	v_min_f32_e32 v103, 0x7e800000, v103
	v_add_f32_e32 v103, 1.0, v103
	v_rcp_f32_e32 v107, v103
	s_nop 0
	v_fma_f32 v109, -v103, v107, 1.0
	v_fma_f32 v103, v109, v107, v107
	v_mul_f32_e32 v103, 0xbf1b459e, v103
	v_mul_f32_e32 v106, 0x3fb8aa3b, v103
	v_exp_f32_e32 v106, v106
	s_nop 0
	v_sub_f32_e32 v103, 1.0, v106
.LBB0_732:
	v_add_f32_e32 v106, v96, v12
	s_and_b64 vcc, exec, s[8:9]
	s_mov_b64 s[14:15], -1
	s_cbranch_vccnz .LBB0_736
	s_and_b64 vcc, exec, s[6:7]
	v_mov_b32_e32 v96, v106
	s_cbranch_vccnz .LBB0_735
	v_mul_f32_e32 v96, 0xbfb8aa3b, v106
	v_exp_f32_e32 v96, v96
	s_nop 0
	v_min_f32_e32 v96, 0x7e800000, v96
	v_add_f32_e32 v96, 1.0, v96
	v_rcp_f32_e32 v108, v96
	s_nop 0
	v_fma_f32 v110, -v96, v108, 1.0
	v_fma_f32 v96, v110, v108, v108

; __device__ __forceinline__ float sigmoidf_(float x) { return 1.0f / (1.0f + __expf(-x)); }
;     __device__ __forceinline__ void operator()(const f32x4 (&acc)[2][2][4][2], const Unit& u, int wr, int wc, int fr, int fq) const {
;     ...
;                         for (int i = 0; i < 4; ++i) { float xv = acc[ai][bj][m][n][i] + bv[bj][n][i]; float r;
;                             if (type < 2) { const float sg = sigmoidf_(xv); r = -expm1f(-0.606531f * sg); }
;                             else if (type == 2) r = sigmoidf_(xv);
;                             else r = xv;
;                             v[4 * n + i] = (f16)r; }
.LBB0_737:
	v_mul_f32_e32 v96, 0xbfb8aa3b, v106
	v_exp_f32_e32 v96, v96
	s_nop 0
	v_min_f32_e32 v96, 0x7e800000, v96
	v_add_f32_e32 v96, 1.0, v96
	v_rcp_f32_e32 v107, v96
	s_nop 0
	v_fma_f32 v109, -v96, v107, 1.0
	v_fma_f32 v96, v109, v107, v107
	v_mul_f32_e32 v96, 0xbf1b459e, v96
	v_mul_f32_e32 v106, 0x3fb8aa3b, v96
	v_exp_f32_e32 v106, v106
	s_nop 0
	v_sub_f32_e32 v96, 1.0, v106
.LBB0_738:
	v_add_f32_e32 v106, v97, v13
	s_and_b64 vcc, exec, s[8:9]
	s_mov_b64 s[14:15], -1
	s_cbranch_vccnz .LBB0_742
	s_and_b64 vcc, exec, s[6:7]
	v_mov_b32_e32 v97, v106
	s_cbranch_vccnz .LBB0_741
	v_mul_f32_e32 v97, 0xbfb8aa3b, v106
	v_exp_f32_e32 v97, v97
	s_nop 0
	v_min_f32_e32 v97, 0x7e800000, v97
	v_add_f32_e32 v97, 1.0, v97
	v_rcp_f32_e32 v108, v97
	s_nop 0
	v_fma_f32 v110, -v97, v108, 1.0
	v_fma_f32 v97, v110, v108, v108

; __device__ __forceinline__ float sigmoidf_(float x) { return 1.0f / (1.0f + __expf(-x)); }
;     __device__ __forceinline__ void operator()(const f32x4 (&acc)[2][2][4][2], const Unit& u, int wr, int wc, int fr, int fq) const {
;     ...
;                         for (int i = 0; i < 4; ++i) { float xv = acc[ai][bj][m][n][i] + bv[bj][n][i]; float r;
;                             if (type < 2) { const float sg = sigmoidf_(xv); r = -expm1f(-0.606531f * sg); }
;                             else if (type == 2) r = sigmoidf_(xv);
;                             else r = xv;
;                             v[4 * n + i] = (f16)r; }
.LBB0_743:
	v_mul_f32_e32 v97, 0xbfb8aa3b, v106
	v_exp_f32_e32 v97, v97
	s_nop 0
	v_min_f32_e32 v97, 0x7e800000, v97
	v_add_f32_e32 v97, 1.0, v97
	v_rcp_f32_e32 v107, v97
	s_nop 0
	v_fma_f32 v109, -v97, v107, 1.0
	v_fma_f32 v97, v109, v107, v107
	v_mul_f32_e32 v97, 0xbf1b459e, v97
	v_mul_f32_e32 v106, 0x3fb8aa3b, v97
	v_exp_f32_e32 v106, v106
	s_nop 0
	v_sub_f32_e32 v97, 1.0, v106
.LBB0_744:
	v_add_f32_e32 v106, v98, v14
	s_and_b64 vcc, exec, s[8:9]
	s_mov_b64 s[14:15], -1
	s_cbranch_vccnz .LBB0_748
	s_and_b64 vcc, exec, s[6:7]
	v_mov_b32_e32 v98, v106
	s_cbranch_vccnz .LBB0_747
	v_mul_f32_e32 v98, 0xbfb8aa3b, v106
	v_exp_f32_e32 v98, v98
	s_nop 0
	v_min_f32_e32 v98, 0x7e800000, v98
	v_add_f32_e32 v98, 1.0, v98
	v_rcp_f32_e32 v108, v98
	s_nop 0
	v_fma_f32 v110, -v98, v108, 1.0
	v_fma_f32 v98, v110, v108, v108

; __device__ __forceinline__ float sigmoidf_(float x) { return 1.0f / (1.0f + __expf(-x)); }
;     __device__ __forceinline__ void operator()(const f32x4 (&acc)[2][2][4][2], const Unit& u, int wr, int wc, int fr, int fq) const {
;     ...
;                         for (int i = 0; i < 4; ++i) { float xv = acc[ai][bj][m][n][i] + bv[bj][n][i]; float r;
;                             if (type < 2) { const float sg = sigmoidf_(xv); r = -expm1f(-0.606531f * sg); }
;                             else if (type == 2) r = sigmoidf_(xv);
;                             else r = xv;
;                             v[4 * n + i] = (f16)r; }
.LBB0_749:
	v_mul_f32_e32 v98, 0xbfb8aa3b, v106
	v_exp_f32_e32 v98, v98
	s_nop 0
	v_min_f32_e32 v98, 0x7e800000, v98
	v_add_f32_e32 v98, 1.0, v98
	v_rcp_f32_e32 v107, v98
	s_nop 0
	v_fma_f32 v109, -v98, v107, 1.0
	v_fma_f32 v98, v109, v107, v107
	v_mul_f32_e32 v98, 0xbf1b459e, v98
	v_mul_f32_e32 v106, 0x3fb8aa3b, v98
	v_exp_f32_e32 v106, v106
	s_nop 0
	v_sub_f32_e32 v98, 1.0, v106
.LBB0_750:
	v_add_f32_e32 v99, v99, v15
	s_and_b64 vcc, exec, s[8:9]
	s_mov_b64 s[14:15], -1
	s_cbranch_vccnz .LBB0_754
	s_and_b64 vcc, exec, s[6:7]
	v_mov_b32_e32 v106, v99
	s_cbranch_vccnz .LBB0_753
	v_mul_f32_e32 v106, 0xbfb8aa3b, v99
	v_exp_f32_e32 v106, v106
	s_nop 0
	v_min_f32_e32 v106, 0x7e800000, v106
	v_add_f32_e32 v106, 1.0, v106
	v_rcp_f32_e32 v108, v106
	s_nop 0
	v_fma_f32 v110, -v106, v108, 1.0
	v_fma_f32 v106, v110, v108, v108

; __device__ __forceinline__ float sigmoidf_(float x) { return 1.0f / (1.0f + __expf(-x)); }
;     __device__ __forceinline__ void operator()(const f32x4 (&acc)[2][2][4][2], const Unit& u, int wr, int wc, int fr, int fq) const {
;     ...
;                         for (int i = 0; i < 4; ++i) { float xv = acc[ai][bj][m][n][i] + bv[bj][n][i]; float r;
;                             if (type < 2) { const float sg = sigmoidf_(xv); r = -expm1f(-0.606531f * sg); }
;                             else if (type == 2) r = sigmoidf_(xv);
;                             else r = xv;
;                             v[4 * n + i] = (f16)r; }
;                     *(f16x8*)(rowp + bj * 128) = v; } }
.LBB0_755:
	v_mul_f32_e32 v99, 0xbfb8aa3b, v99
	v_exp_f32_e32 v99, v99
	s_nop 0
	v_min_f32_e32 v99, 0x7e800000, v99
	v_add_f32_e32 v99, 1.0, v99
	v_rcp_f32_e32 v107, v99
	s_nop 0
	v_fma_f32 v109, -v99, v107, 1.0
	v_fma_f32 v99, v109, v107, v107
	v_mul_f32_e32 v99, 0xbf1b459e, v99
	v_mul_f32_e32 v106, 0x3fb8aa3b, v99
	v_exp_f32_e32 v106, v106
	s_nop 0
	v_sub_f32_e32 v106, 1.0, v106
.LBB0_756:
	v_cvt_pk_f16_f32 v99, v98, v106
	v_cvt_pk_f16_f32 v98, v96, v97
	v_cvt_pk_f16_f32 v97, v102, v103
	v_cvt_pk_f16_f32 v96, v100, v101
	global_store_dwordx4 v[104:105], v[96:99], off offset:256
	s_and_b64 vcc, exec, s[8:9]
	s_mov_b64 s[14:15], -1
	v_add_f32_e32 v96, v92, v32
	s_cbranch_vccnz .LBB0_760
	s_and_b64 vcc, exec, s[6:7]
	v_mov_b32_e32 v92, v96
	s_cbranch_vccnz .LBB0_759
	v_mul_f32_e32 v92, 0xbfb8aa3b, v96
	v_exp_f32_e32 v92, v92
	s_nop 0
	v_min_f32_e32 v92, 0x7e800000, v92
	v_add_f32_e32 v92, 1.0, v92
	v_rcp_f32_e32 v98, v92
	s_nop 0
	v_fma_f32 v100, -v92, v98, 1.0
	v_fma_f32 v92, v100, v98, v98

; __device__ __forceinline__ float sigmoidf_(float x) { return 1.0f / (1.0f + __expf(-x)); }
;     __device__ __forceinline__ void operator()(const f32x4 (&acc)[2][2][4][2], const Unit& u, int wr, int wc, int fr, int fq) const {
;     ...
;                         for (int i = 0; i < 4; ++i) { float xv = acc[ai][bj][m][n][i] + bv[bj][n][i]; float r;
;                             if (type < 2) { const float sg = sigmoidf_(xv); r = -expm1f(-0.606531f * sg); }
;                             else if (type == 2) r = sigmoidf_(xv);
;                             else r = xv;
;                             v[4 * n + i] = (f16)r; }
.LBB0_761:
	v_mul_f32_e32 v92, 0xbfb8aa3b, v96
	v_exp_f32_e32 v92, v92
	s_nop 0
	v_min_f32_e32 v92, 0x7e800000, v92
	v_add_f32_e32 v92, 1.0, v92
	v_rcp_f32_e32 v97, v92
	s_nop 0
	v_fma_f32 v99, -v92, v97, 1.0
	v_fma_f32 v92, v99, v97, v97
	v_mul_f32_e32 v92, 0xbf1b459e, v92
	v_mul_f32_e32 v96, 0x3fb8aa3b, v92
	v_exp_f32_e32 v96, v96
	s_nop 0
	v_sub_f32_e32 v92, 1.0, v96
.LBB0_762:
	v_add_f32_e32 v96, v93, v33
	s_and_b64 vcc, exec, s[8:9]
	s_mov_b64 s[14:15], -1
	s_cbranch_vccnz .LBB0_766
	s_and_b64 vcc, exec, s[6:7]
	v_mov_b32_e32 v93, v96
	s_cbranch_vccnz .LBB0_765
	v_mul_f32_e32 v93, 0xbfb8aa3b, v96
	v_exp_f32_e32 v93, v93
	s_nop 0
	v_min_f32_e32 v93, 0x7e800000, v93
	v_add_f32_e32 v93, 1.0, v93
	v_rcp_f32_e32 v98, v93
	s_nop 0
	v_fma_f32 v100, -v93, v98, 1.0
	v_fma_f32 v93, v100, v98, v98

; __device__ __forceinline__ float sigmoidf_(float x) { return 1.0f / (1.0f + __expf(-x)); }
;     __device__ __forceinline__ void operator()(const f32x4 (&acc)[2][2][4][2], const Unit& u, int wr, int wc, int fr, int fq) const {
;     ...
;                         for (int i = 0; i < 4; ++i) { float xv = acc[ai][bj][m][n][i] + bv[bj][n][i]; float r;
;                             if (type < 2) { const float sg = sigmoidf_(xv); r = -expm1f(-0.606531f * sg); }
;                             else if (type == 2) r = sigmoidf_(xv);
;                             else r = xv;
;                             v[4 * n + i] = (f16)r; }
.LBB0_767:
	v_mul_f32_e32 v93, 0xbfb8aa3b, v96
	v_exp_f32_e32 v93, v93
	s_nop 0
	v_min_f32_e32 v93, 0x7e800000, v93
	v_add_f32_e32 v93, 1.0, v93
	v_rcp_f32_e32 v97, v93
	s_nop 0
	v_fma_f32 v99, -v93, v97, 1.0
	v_fma_f32 v93, v99, v97, v97
	v_mul_f32_e32 v93, 0xbf1b459e, v93
	v_mul_f32_e32 v96, 0x3fb8aa3b, v93
	v_exp_f32_e32 v96, v96
	s_nop 0
	v_sub_f32_e32 v93, 1.0, v96
.LBB0_768:
	v_add_f32_e32 v96, v94, v34
	s_and_b64 vcc, exec, s[8:9]
	s_mov_b64 s[14:15], -1
	s_cbranch_vccnz .LBB0_772
	s_and_b64 vcc, exec, s[6:7]
	v_mov_b32_e32 v94, v96
	s_cbranch_vccnz .LBB0_771
	v_mul_f32_e32 v94, 0xbfb8aa3b, v96
	v_exp_f32_e32 v94, v94
	s_nop 0
	v_min_f32_e32 v94, 0x7e800000, v94
	v_add_f32_e32 v94, 1.0, v94
	v_rcp_f32_e32 v98, v94
	s_nop 0
	v_fma_f32 v100, -v94, v98, 1.0
	v_fma_f32 v94, v100, v98, v98

; __device__ __forceinline__ float sigmoidf_(float x) { return 1.0f / (1.0f + __expf(-x)); }
;     __device__ __forceinline__ void operator()(const f32x4 (&acc)[2][2][4][2], const Unit& u, int wr, int wc, int fr, int fq) const {
;     ...
;                         for (int i = 0; i < 4; ++i) { float xv = acc[ai][bj][m][n][i] + bv[bj][n][i]; float r;
;                             if (type < 2) { const float sg = sigmoidf_(xv); r = -expm1f(-0.606531f * sg); }
;                             else if (type == 2) r = sigmoidf_(xv);
;                             else r = xv;
;                             v[4 * n + i] = (f16)r; }
.LBB0_773:
	v_mul_f32_e32 v94, 0xbfb8aa3b, v96
	v_exp_f32_e32 v94, v94
	s_nop 0
	v_min_f32_e32 v94, 0x7e800000, v94
	v_add_f32_e32 v94, 1.0, v94
	v_rcp_f32_e32 v97, v94
	s_nop 0
	v_fma_f32 v99, -v94, v97, 1.0
	v_fma_f32 v94, v99, v97, v97
	v_mul_f32_e32 v94, 0xbf1b459e, v94
	v_mul_f32_e32 v96, 0x3fb8aa3b, v94
	v_exp_f32_e32 v96, v96
	s_nop 0
	v_sub_f32_e32 v94, 1.0, v96
.LBB0_774:
	v_add_f32_e32 v96, v95, v35
	s_and_b64 vcc, exec, s[8:9]
	s_mov_b64 s[14:15], -1
	s_cbranch_vccnz .LBB0_778
	s_and_b64 vcc, exec, s[6:7]
	v_mov_b32_e32 v95, v96
	s_cbranch_vccnz .LBB0_777
	v_mul_f32_e32 v95, 0xbfb8aa3b, v96
	v_exp_f32_e32 v95, v95
	s_nop 0
	v_min_f32_e32 v95, 0x7e800000, v95
	v_add_f32_e32 v95, 1.0, v95
	v_rcp_f32_e32 v98, v95
	s_nop 0
	v_fma_f32 v100, -v95, v98, 1.0
	v_fma_f32 v95, v100, v98, v98

; __device__ __forceinline__ float sigmoidf_(float x) { return 1.0f / (1.0f + __expf(-x)); }
;     __device__ __forceinline__ void operator()(const f32x4 (&acc)[2][2][4][2], const Unit& u, int wr, int wc, int fr, int fq) const {
;     ...
;                         for (int i = 0; i < 4; ++i) { float xv = acc[ai][bj][m][n][i] + bv[bj][n][i]; float r;
;                             if (type < 2) { const float sg = sigmoidf_(xv); r = -expm1f(-0.606531f * sg); }
;                             else if (type == 2) r = sigmoidf_(xv);
;                             else r = xv;
;                             v[4 * n + i] = (f16)r; }
.LBB0_779:
	v_mul_f32_e32 v95, 0xbfb8aa3b, v96
	v_exp_f32_e32 v95, v95
	s_nop 0
	v_min_f32_e32 v95, 0x7e800000, v95
	v_add_f32_e32 v95, 1.0, v95
	v_rcp_f32_e32 v97, v95
	s_nop 0
	v_fma_f32 v99, -v95, v97, 1.0
	v_fma_f32 v95, v99, v97, v97
	v_mul_f32_e32 v95, 0xbf1b459e, v95
	v_mul_f32_e32 v96, 0x3fb8aa3b, v95
	v_exp_f32_e32 v96, v96
	s_nop 0
	v_sub_f32_e32 v95, 1.0, v96
.LBB0_780:
	v_add_f32_e32 v88, v88, v28
	s_and_b64 vcc, exec, s[8:9]
	s_mov_b64 s[14:15], -1
	s_cbranch_vccnz .LBB0_784
	s_and_b64 vcc, exec, s[6:7]
	v_mov_b32_e32 v96, v88
	s_cbranch_vccnz .LBB0_783
	v_mul_f32_e32 v96, 0xbfb8aa3b, v88
	v_exp_f32_e32 v96, v96
	s_nop 0
	v_min_f32_e32 v96, 0x7e800000, v96
	v_add_f32_e32 v96, 1.0, v96
	v_rcp_f32_e32 v98, v96
	s_nop 0
	v_fma_f32 v100, -v96, v98, 1.0
	v_fma_f32 v96, v100, v98, v98

; __device__ __forceinline__ float sigmoidf_(float x) { return 1.0f / (1.0f + __expf(-x)); }
;     __device__ __forceinline__ void operator()(const f32x4 (&acc)[2][2][4][2], const Unit& u, int wr, int wc, int fr, int fq) const {
;     ...
;                         for (int i = 0; i < 4; ++i) { float xv = acc[ai][bj][m][n][i] + bv[bj][n][i]; float r;
;                             if (type < 2) { const float sg = sigmoidf_(xv); r = -expm1f(-0.606531f * sg); }
;                             else if (type == 2) r = sigmoidf_(xv);
;                             else r = xv;
;                             v[4 * n + i] = (f16)r; }
.LBB0_785:
	v_mul_f32_e32 v88, 0xbfb8aa3b, v88
	v_exp_f32_e32 v88, v88
	s_nop 0
	v_min_f32_e32 v88, 0x7e800000, v88
	v_add_f32_e32 v88, 1.0, v88
	v_rcp_f32_e32 v97, v88
	s_nop 0
	v_fma_f32 v99, -v88, v97, 1.0
	v_fma_f32 v88, v99, v97, v97
	v_mul_f32_e32 v88, 0xbf1b459e, v88
	v_mul_f32_e32 v96, 0x3fb8aa3b, v88
	v_exp_f32_e32 v96, v96
	s_nop 0
	v_sub_f32_e32 v96, 1.0, v96
.LBB0_786:
	v_add_f32_e32 v88, v89, v29
	s_and_b64 vcc, exec, s[8:9]
	s_mov_b64 s[14:15], -1
	s_cbranch_vccnz .LBB0_790
	s_and_b64 vcc, exec, s[6:7]
	v_mov_b32_e32 v97, v88
	s_cbranch_vccnz .LBB0_789
	v_mul_f32_e32 v89, 0xbfb8aa3b, v88
	v_exp_f32_e32 v89, v89
	s_nop 0
	v_min_f32_e32 v89, 0x7e800000, v89
	v_add_f32_e32 v89, 1.0, v89
	v_rcp_f32_e32 v98, v89
	s_nop 0
	v_fma_f32 v100, -v89, v98, 1.0
	v_fma_f32 v97, v100, v98, v98

; __device__ __forceinline__ float sigmoidf_(float x) { return 1.0f / (1.0f + __expf(-x)); }
;     __device__ __forceinline__ void operator()(const f32x4 (&acc)[2][2][4][2], const Unit& u, int wr, int wc, int fr, int fq) const {
;     ...
;                         for (int i = 0; i < 4; ++i) { float xv = acc[ai][bj][m][n][i] + bv[bj][n][i]; float r;
;                             if (type < 2) { const float sg = sigmoidf_(xv); r = -expm1f(-0.606531f * sg); }
;                             else if (type == 2) r = sigmoidf_(xv);
;                             else r = xv;
;                             v[4 * n + i] = (f16)r; }
.LBB0_791:
	v_mul_f32_e32 v88, 0xbfb8aa3b, v88
	v_exp_f32_e32 v88, v88
	s_nop 0
	v_min_f32_e32 v88, 0x7e800000, v88
	v_add_f32_e32 v88, 1.0, v88
	v_rcp_f32_e32 v97, v88
	s_nop 0
	v_fma_f32 v99, -v88, v97, 1.0
	v_fma_f32 v88, v99, v97, v97
	v_mul_f32_e32 v88, 0xbf1b459e, v88
	v_mul_f32_e32 v89, 0x3fb8aa3b, v88
	v_exp_f32_e32 v89, v89
	s_nop 0
	v_sub_f32_e32 v97, 1.0, v89
.LBB0_792:
	v_add_f32_e32 v88, v90, v30
	s_and_b64 vcc, exec, s[8:9]
	s_mov_b64 s[14:15], -1
	s_cbranch_vccnz .LBB0_796
	s_and_b64 vcc, exec, s[6:7]
	v_mov_b32_e32 v90, v88
	s_cbranch_vccnz .LBB0_795
	v_mul_f32_e32 v89, 0xbfb8aa3b, v88
	v_exp_f32_e32 v89, v89
	s_nop 0
	v_min_f32_e32 v89, 0x7e800000, v89
	v_add_f32_e32 v89, 1.0, v89
	v_rcp_f32_e32 v98, v89
	s_nop 0
	v_fma_f32 v100, -v89, v98, 1.0
	v_fma_f32 v90, v100, v98, v98

; __device__ __forceinline__ float sigmoidf_(float x) { return 1.0f / (1.0f + __expf(-x)); }
;     __device__ __forceinline__ void operator()(const f32x4 (&acc)[2][2][4][2], const Unit& u, int wr, int wc, int fr, int fq) const {
;     ...
;                         for (int i = 0; i < 4; ++i) { float xv = acc[ai][bj][m][n][i] + bv[bj][n][i]; float r;
;                             if (type < 2) { const float sg = sigmoidf_(xv); r = -expm1f(-0.606531f * sg); }
;                             else if (type == 2) r = sigmoidf_(xv);
;                             else r = xv;
;                             v[4 * n + i] = (f16)r; }
.LBB0_797:
	v_mul_f32_e32 v88, 0xbfb8aa3b, v88
	v_exp_f32_e32 v88, v88
	s_nop 0
	v_min_f32_e32 v88, 0x7e800000, v88
	v_add_f32_e32 v88, 1.0, v88
	v_rcp_f32_e32 v90, v88
	s_nop 0
	v_fma_f32 v99, -v88, v90, 1.0
	v_fma_f32 v88, v99, v90, v90
	v_mul_f32_e32 v88, 0xbf1b459e, v88
	v_mul_f32_e32 v89, 0x3fb8aa3b, v88
	v_exp_f32_e32 v89, v89
	s_nop 0
	v_sub_f32_e32 v90, 1.0, v89
.LBB0_798:
	v_add_f32_e32 v88, v91, v31
	s_and_b64 vcc, exec, s[8:9]
	s_mov_b64 s[14:15], -1
	s_cbranch_vccnz .LBB0_802
	s_and_b64 vcc, exec, s[6:7]
	v_mov_b32_e32 v91, v88
	s_cbranch_vccnz .LBB0_801
	v_mul_f32_e32 v89, 0xbfb8aa3b, v88
	v_exp_f32_e32 v89, v89
	s_nop 0
	v_min_f32_e32 v89, 0x7e800000, v89
	v_add_f32_e32 v89, 1.0, v89
	v_rcp_f32_e32 v98, v89
	s_nop 0
	v_fma_f32 v100, -v89, v98, 1.0
	v_fma_f32 v91, v100, v98, v98

; __device__ __forceinline__ float sigmoidf_(float x) { return 1.0f / (1.0f + __expf(-x)); }
;     __device__ __forceinline__ void operator()(const f32x4 (&acc)[2][2][4][2], const Unit& u, int wr, int wc, int fr, int fq) const {
;     ...
;                         for (int i = 0; i < 4; ++i) { float xv = acc[ai][bj][m][n][i] + bv[bj][n][i]; float r;
;                             if (type < 2) { const float sg = sigmoidf_(xv); r = -expm1f(-0.606531f * sg); }
;                             else if (type == 2) r = sigmoidf_(xv);
;                             else r = xv;
;                             v[4 * n + i] = (f16)r; }
;                     *(f16x8*)(rowp + bj * 128) = v; } }
.LBB0_803:
	v_mul_f32_e32 v88, 0xbfb8aa3b, v88
	v_exp_f32_e32 v88, v88
	s_nop 0
	v_min_f32_e32 v88, 0x7e800000, v88
	v_add_f32_e32 v88, 1.0, v88
	v_rcp_f32_e32 v91, v88
	s_nop 0
	v_fma_f32 v99, -v88, v91, 1.0
	v_fma_f32 v88, v99, v91, v91
	v_mul_f32_e32 v88, 0xbf1b459e, v88
	v_mul_f32_e32 v89, 0x3fb8aa3b, v88
	v_exp_f32_e32 v89, v89
	s_nop 0
	v_sub_f32_e32 v91, 1.0, v89
.LBB0_804:
	v_or_b32_e32 v88, 48, v138
	v_ashrrev_i32_e32 v89, 31, v88
	v_lshlrev_b64 v[88:89], 13, v[88:89]
	v_lshl_add_u64 v[88:89], s[28:29], 0, v[88:89]
	v_lshl_add_u64 v[88:89], v[136:137], 1, v[88:89]
	v_cvt_pk_f16_f32 v99, v90, v91
	v_cvt_pk_f16_f32 v98, v96, v97
	v_cvt_pk_f16_f32 v97, v94, v95
	v_cvt_pk_f16_f32 v96, v92, v93
	v_add_f32_e32 v90, v84, v20
	s_and_b64 vcc, exec, s[8:9]
	s_mov_b64 s[14:15], -1
	global_store_dwordx4 v[88:89], v[96:99], off
	s_cbranch_vccnz .LBB0_808
	s_and_b64 vcc, exec, s[6:7]
	v_mov_b32_e32 v84, v90
	s_cbranch_vccnz .LBB0_807
	v_mul_f32_e32 v84, 0xbfb8aa3b, v90
	v_exp_f32_e32 v84, v84
	s_nop 0
	v_min_f32_e32 v84, 0x7e800000, v84
	v_add_f32_e32 v84, 1.0, v84
	v_rcp_f32_e32 v92, v84
	s_nop 0
	v_fma_f32 v94, -v84, v92, 1.0
	v_fma_f32 v84, v94, v92, v92

; __device__ __forceinline__ float sigmoidf_(float x) { return 1.0f / (1.0f + __expf(-x)); }
;     __device__ __forceinline__ void operator()(const f32x4 (&acc)[2][2][4][2], const Unit& u, int wr, int wc, int fr, int fq) const {
;     ...
;                         for (int i = 0; i < 4; ++i) { float xv = acc[ai][bj][m][n][i] + bv[bj][n][i]; float r;
;                             if (type < 2) { const float sg = sigmoidf_(xv); r = -expm1f(-0.606531f * sg); }
;                             else if (type == 2) r = sigmoidf_(xv);
;                             else r = xv;
;                             v[4 * n + i] = (f16)r; }
.LBB0_809:
	v_mul_f32_e32 v84, 0xbfb8aa3b, v90
	v_exp_f32_e32 v84, v84
	s_nop 0
	v_min_f32_e32 v84, 0x7e800000, v84
	v_add_f32_e32 v84, 1.0, v84
	v_rcp_f32_e32 v91, v84
	s_nop 0
	v_fma_f32 v93, -v84, v91, 1.0
	v_fma_f32 v84, v93, v91, v91
	v_mul_f32_e32 v84, 0xbf1b459e, v84
	v_mul_f32_e32 v90, 0x3fb8aa3b, v84
	v_exp_f32_e32 v90, v90
	s_nop 0
	v_sub_f32_e32 v84, 1.0, v90
.LBB0_810:
	v_add_f32_e32 v90, v85, v21
	s_and_b64 vcc, exec, s[8:9]
	s_mov_b64 s[14:15], -1
	s_cbranch_vccnz .LBB0_814
	s_and_b64 vcc, exec, s[6:7]
	v_mov_b32_e32 v85, v90
	s_cbranch_vccnz .LBB0_813
	v_mul_f32_e32 v85, 0xbfb8aa3b, v90
	v_exp_f32_e32 v85, v85
	s_nop 0
	v_min_f32_e32 v85, 0x7e800000, v85
	v_add_f32_e32 v85, 1.0, v85
	v_rcp_f32_e32 v92, v85
	s_nop 0
	v_fma_f32 v94, -v85, v92, 1.0
	v_fma_f32 v85, v94, v92, v92

; __device__ __forceinline__ float sigmoidf_(float x) { return 1.0f / (1.0f + __expf(-x)); }
;     __device__ __forceinline__ void operator()(const f32x4 (&acc)[2][2][4][2], const Unit& u, int wr, int wc, int fr, int fq) const {
;     ...
;                         for (int i = 0; i < 4; ++i) { float xv = acc[ai][bj][m][n][i] + bv[bj][n][i]; float r;
;                             if (type < 2) { const float sg = sigmoidf_(xv); r = -expm1f(-0.606531f * sg); }
;                             else if (type == 2) r = sigmoidf_(xv);
;                             else r = xv;
;                             v[4 * n + i] = (f16)r; }
.LBB0_815:
	v_mul_f32_e32 v85, 0xbfb8aa3b, v90
	v_exp_f32_e32 v85, v85
	s_nop 0
	v_min_f32_e32 v85, 0x7e800000, v85
	v_add_f32_e32 v85, 1.0, v85
	v_rcp_f32_e32 v91, v85
	s_nop 0
	v_fma_f32 v93, -v85, v91, 1.0
	v_fma_f32 v85, v93, v91, v91
	v_mul_f32_e32 v85, 0xbf1b459e, v85
	v_mul_f32_e32 v90, 0x3fb8aa3b, v85
	v_exp_f32_e32 v90, v90
	s_nop 0
	v_sub_f32_e32 v85, 1.0, v90
.LBB0_816:
	v_add_f32_e32 v90, v86, v22
	s_and_b64 vcc, exec, s[8:9]
	s_mov_b64 s[14:15], -1
	s_cbranch_vccnz .LBB0_820
	s_and_b64 vcc, exec, s[6:7]
	v_mov_b32_e32 v86, v90
	s_cbranch_vccnz .LBB0_819
	v_mul_f32_e32 v86, 0xbfb8aa3b, v90
	v_exp_f32_e32 v86, v86
	s_nop 0
	v_min_f32_e32 v86, 0x7e800000, v86
	v_add_f32_e32 v86, 1.0, v86
	v_rcp_f32_e32 v92, v86
	s_nop 0
	v_fma_f32 v94, -v86, v92, 1.0
	v_fma_f32 v86, v94, v92, v92

; __device__ __forceinline__ float sigmoidf_(float x) { return 1.0f / (1.0f + __expf(-x)); }
;     __device__ __forceinline__ void operator()(const f32x4 (&acc)[2][2][4][2], const Unit& u, int wr, int wc, int fr, int fq) const {
;     ...
;                         for (int i = 0; i < 4; ++i) { float xv = acc[ai][bj][m][n][i] + bv[bj][n][i]; float r;
;                             if (type < 2) { const float sg = sigmoidf_(xv); r = -expm1f(-0.606531f * sg); }
;                             else if (type == 2) r = sigmoidf_(xv);
;                             else r = xv;
;                             v[4 * n + i] = (f16)r; }
.LBB0_821:
	v_mul_f32_e32 v86, 0xbfb8aa3b, v90
	v_exp_f32_e32 v86, v86
	s_nop 0
	v_min_f32_e32 v86, 0x7e800000, v86
	v_add_f32_e32 v86, 1.0, v86
	v_rcp_f32_e32 v91, v86
	s_nop 0
	v_fma_f32 v93, -v86, v91, 1.0
	v_fma_f32 v86, v93, v91, v91
	v_mul_f32_e32 v86, 0xbf1b459e, v86
	v_mul_f32_e32 v90, 0x3fb8aa3b, v86
	v_exp_f32_e32 v90, v90
	s_nop 0
	v_sub_f32_e32 v86, 1.0, v90
.LBB0_822:
	v_add_f32_e32 v90, v87, v23
	s_and_b64 vcc, exec, s[8:9]
	s_mov_b64 s[14:15], -1
	s_cbranch_vccnz .LBB0_826
	s_and_b64 vcc, exec, s[6:7]
	v_mov_b32_e32 v87, v90
	s_cbranch_vccnz .LBB0_825
	v_mul_f32_e32 v87, 0xbfb8aa3b, v90
	v_exp_f32_e32 v87, v87
	s_nop 0
	v_min_f32_e32 v87, 0x7e800000, v87
	v_add_f32_e32 v87, 1.0, v87
	v_rcp_f32_e32 v92, v87
	s_nop 0
	v_fma_f32 v94, -v87, v92, 1.0
	v_fma_f32 v87, v94, v92, v92

; __device__ __forceinline__ float sigmoidf_(float x) { return 1.0f / (1.0f + __expf(-x)); }
;     __device__ __forceinline__ void operator()(const f32x4 (&acc)[2][2][4][2], const Unit& u, int wr, int wc, int fr, int fq) const {
;     ...
;                         for (int i = 0; i < 4; ++i) { float xv = acc[ai][bj][m][n][i] + bv[bj][n][i]; float r;
;                             if (type < 2) { const float sg = sigmoidf_(xv); r = -expm1f(-0.606531f * sg); }
;                             else if (type == 2) r = sigmoidf_(xv);
;                             else r = xv;
;                             v[4 * n + i] = (f16)r; }
.LBB0_827:
	v_mul_f32_e32 v87, 0xbfb8aa3b, v90
	v_exp_f32_e32 v87, v87
	s_nop 0
	v_min_f32_e32 v87, 0x7e800000, v87
	v_add_f32_e32 v87, 1.0, v87
	v_rcp_f32_e32 v91, v87
	s_nop 0
	v_fma_f32 v93, -v87, v91, 1.0
	v_fma_f32 v87, v93, v91, v91
	v_mul_f32_e32 v87, 0xbf1b459e, v87
	v_mul_f32_e32 v90, 0x3fb8aa3b, v87
	v_exp_f32_e32 v90, v90
	s_nop 0
	v_sub_f32_e32 v87, 1.0, v90
.LBB0_828:
	v_add_f32_e32 v90, v80, v12
	s_and_b64 vcc, exec, s[8:9]
	s_mov_b64 s[14:15], -1
	s_cbranch_vccnz .LBB0_832
	s_and_b64 vcc, exec, s[6:7]
	v_mov_b32_e32 v80, v90
	s_cbranch_vccnz .LBB0_831
	v_mul_f32_e32 v80, 0xbfb8aa3b, v90
	v_exp_f32_e32 v80, v80
	s_nop 0
	v_min_f32_e32 v80, 0x7e800000, v80
	v_add_f32_e32 v80, 1.0, v80
	v_rcp_f32_e32 v92, v80
	s_nop 0
	v_fma_f32 v94, -v80, v92, 1.0
	v_fma_f32 v80, v94, v92, v92

; __device__ __forceinline__ float sigmoidf_(float x) { return 1.0f / (1.0f + __expf(-x)); }
;     __device__ __forceinline__ void operator()(const f32x4 (&acc)[2][2][4][2], const Unit& u, int wr, int wc, int fr, int fq) const {
;     ...
;                         for (int i = 0; i < 4; ++i) { float xv = acc[ai][bj][m][n][i] + bv[bj][n][i]; float r;
;                             if (type < 2) { const float sg = sigmoidf_(xv); r = -expm1f(-0.606531f * sg); }
;                             else if (type == 2) r = sigmoidf_(xv);
;                             else r = xv;
;                             v[4 * n + i] = (f16)r; }
.LBB0_833:
	v_mul_f32_e32 v80, 0xbfb8aa3b, v90
	v_exp_f32_e32 v80, v80
	s_nop 0
	v_min_f32_e32 v80, 0x7e800000, v80
	v_add_f32_e32 v80, 1.0, v80
	v_rcp_f32_e32 v91, v80
	s_nop 0
	v_fma_f32 v93, -v80, v91, 1.0
	v_fma_f32 v80, v93, v91, v91
	v_mul_f32_e32 v80, 0xbf1b459e, v80
	v_mul_f32_e32 v90, 0x3fb8aa3b, v80
	v_exp_f32_e32 v90, v90
	s_nop 0
	v_sub_f32_e32 v80, 1.0, v90
.LBB0_834:
	v_add_f32_e32 v90, v81, v13
	s_and_b64 vcc, exec, s[8:9]
	s_mov_b64 s[14:15], -1
	s_cbranch_vccnz .LBB0_838
	s_and_b64 vcc, exec, s[6:7]
	v_mov_b32_e32 v81, v90
	s_cbranch_vccnz .LBB0_837
	v_mul_f32_e32 v81, 0xbfb8aa3b, v90
	v_exp_f32_e32 v81, v81
	s_nop 0
	v_min_f32_e32 v81, 0x7e800000, v81
	v_add_f32_e32 v81, 1.0, v81
	v_rcp_f32_e32 v92, v81
	s_nop 0
	v_fma_f32 v94, -v81, v92, 1.0
	v_fma_f32 v81, v94, v92, v92

; __device__ __forceinline__ float sigmoidf_(float x) { return 1.0f / (1.0f + __expf(-x)); }
;     __device__ __forceinline__ void operator()(const f32x4 (&acc)[2][2][4][2], const Unit& u, int wr, int wc, int fr, int fq) const {
;     ...
;                         for (int i = 0; i < 4; ++i) { float xv = acc[ai][bj][m][n][i] + bv[bj][n][i]; float r;
;                             if (type < 2) { const float sg = sigmoidf_(xv); r = -expm1f(-0.606531f * sg); }
;                             else if (type == 2) r = sigmoidf_(xv);
;                             else r = xv;
;                             v[4 * n + i] = (f16)r; }
.LBB0_839:
	v_mul_f32_e32 v81, 0xbfb8aa3b, v90
	v_exp_f32_e32 v81, v81
	s_nop 0
	v_min_f32_e32 v81, 0x7e800000, v81
	v_add_f32_e32 v81, 1.0, v81
	v_rcp_f32_e32 v91, v81
	s_nop 0
	v_fma_f32 v93, -v81, v91, 1.0
	v_fma_f32 v81, v93, v91, v91
	v_mul_f32_e32 v81, 0xbf1b459e, v81
	v_mul_f32_e32 v90, 0x3fb8aa3b, v81
	v_exp_f32_e32 v90, v90
	s_nop 0
	v_sub_f32_e32 v81, 1.0, v90
.LBB0_840:
	v_add_f32_e32 v90, v82, v14
	s_and_b64 vcc, exec, s[8:9]
	s_mov_b64 s[14:15], -1
	s_cbranch_vccnz .LBB0_844
	s_and_b64 vcc, exec, s[6:7]
	v_mov_b32_e32 v82, v90
	s_cbranch_vccnz .LBB0_843
	v_mul_f32_e32 v82, 0xbfb8aa3b, v90
	v_exp_f32_e32 v82, v82
	s_nop 0
	v_min_f32_e32 v82, 0x7e800000, v82
	v_add_f32_e32 v82, 1.0, v82
	v_rcp_f32_e32 v92, v82
	s_nop 0
	v_fma_f32 v94, -v82, v92, 1.0
	v_fma_f32 v82, v94, v92, v92

; __device__ __forceinline__ float sigmoidf_(float x) { return 1.0f / (1.0f + __expf(-x)); }
;     __device__ __forceinline__ void operator()(const f32x4 (&acc)[2][2][4][2], const Unit& u, int wr, int wc, int fr, int fq) const {
;     ...
;                         for (int i = 0; i < 4; ++i) { float xv = acc[ai][bj][m][n][i] + bv[bj][n][i]; float r;
;                             if (type < 2) { const float sg = sigmoidf_(xv); r = -expm1f(-0.606531f * sg); }
;                             else if (type == 2) r = sigmoidf_(xv);
;                             else r = xv;
;                             v[4 * n + i] = (f16)r; }
.LBB0_845:
	v_mul_f32_e32 v82, 0xbfb8aa3b, v90
	v_exp_f32_e32 v82, v82
	s_nop 0
	v_min_f32_e32 v82, 0x7e800000, v82
	v_add_f32_e32 v82, 1.0, v82
	v_rcp_f32_e32 v91, v82
	s_nop 0
	v_fma_f32 v93, -v82, v91, 1.0
	v_fma_f32 v82, v93, v91, v91
	v_mul_f32_e32 v82, 0xbf1b459e, v82
	v_mul_f32_e32 v90, 0x3fb8aa3b, v82
	v_exp_f32_e32 v90, v90
	s_nop 0
	v_sub_f32_e32 v82, 1.0, v90
.LBB0_846:
	v_add_f32_e32 v83, v83, v15
	s_and_b64 vcc, exec, s[8:9]
	s_mov_b64 s[14:15], -1
	s_cbranch_vccnz .LBB0_850
	s_and_b64 vcc, exec, s[6:7]
	v_mov_b32_e32 v90, v83
	s_cbranch_vccnz .LBB0_849
	v_mul_f32_e32 v90, 0xbfb8aa3b, v83
	v_exp_f32_e32 v90, v90
	s_nop 0
	v_min_f32_e32 v90, 0x7e800000, v90
	v_add_f32_e32 v90, 1.0, v90
	v_rcp_f32_e32 v92, v90
	s_nop 0
	v_fma_f32 v94, -v90, v92, 1.0
	v_fma_f32 v90, v94, v92, v92

; __device__ __forceinline__ float sigmoidf_(float x) { return 1.0f / (1.0f + __expf(-x)); }
;     __device__ __forceinline__ void operator()(const f32x4 (&acc)[2][2][4][2], const Unit& u, int wr, int wc, int fr, int fq) const {
;     ...
;                         for (int i = 0; i < 4; ++i) { float xv = acc[ai][bj][m][n][i] + bv[bj][n][i]; float r;
;                             if (type < 2) { const float sg = sigmoidf_(xv); r = -expm1f(-0.606531f * sg); }
;                             else if (type == 2) r = sigmoidf_(xv);
;                             else r = xv;
;                             v[4 * n + i] = (f16)r; }
;                     *(f16x8*)(rowp + bj * 128) = v; } }
.LBB0_851:
	v_mul_f32_e32 v83, 0xbfb8aa3b, v83
	v_exp_f32_e32 v83, v83
	s_nop 0
	v_min_f32_e32 v83, 0x7e800000, v83
	v_add_f32_e32 v83, 1.0, v83
	v_rcp_f32_e32 v91, v83
	s_nop 0
	v_fma_f32 v93, -v83, v91, 1.0
	v_fma_f32 v83, v93, v91, v91
	v_mul_f32_e32 v83, 0xbf1b459e, v83
	v_mul_f32_e32 v90, 0x3fb8aa3b, v83
	v_exp_f32_e32 v90, v90
	s_nop 0
	v_sub_f32_e32 v90, 1.0, v90
.LBB0_852:
	v_cvt_pk_f16_f32 v83, v82, v90
	v_cvt_pk_f16_f32 v82, v80, v81
	v_cvt_pk_f16_f32 v81, v86, v87
	v_cvt_pk_f16_f32 v80, v84, v85
	global_store_dwordx4 v[88:89], v[80:83], off offset:256
	s_and_b64 vcc, exec, s[8:9]
	s_mov_b64 s[14:15], -1
	v_add_f32_e32 v80, v76, v32
	s_cbranch_vccnz .LBB0_856
	s_and_b64 vcc, exec, s[6:7]
	v_mov_b32_e32 v76, v80
	s_cbranch_vccnz .LBB0_855
	v_mul_f32_e32 v76, 0xbfb8aa3b, v80
	v_exp_f32_e32 v76, v76
	s_nop 0
	v_min_f32_e32 v76, 0x7e800000, v76
	v_add_f32_e32 v76, 1.0, v76
	v_rcp_f32_e32 v82, v76
	s_nop 0
	v_fma_f32 v84, -v76, v82, 1.0
	v_fma_f32 v76, v84, v82, v82

; __device__ __forceinline__ float sigmoidf_(float x) { return 1.0f / (1.0f + __expf(-x)); }
;     __device__ __forceinline__ void operator()(const f32x4 (&acc)[2][2][4][2], const Unit& u, int wr, int wc, int fr, int fq) const {
;     ...
;                         for (int i = 0; i < 4; ++i) { float xv = acc[ai][bj][m][n][i] + bv[bj][n][i]; float r;
;                             if (type < 2) { const float sg = sigmoidf_(xv); r = -expm1f(-0.606531f * sg); }
;                             else if (type == 2) r = sigmoidf_(xv);
;                             else r = xv;
;                             v[4 * n + i] = (f16)r; }
.LBB0_857:
	v_mul_f32_e32 v76, 0xbfb8aa3b, v80
	v_exp_f32_e32 v76, v76
	s_nop 0
	v_min_f32_e32 v76, 0x7e800000, v76
	v_add_f32_e32 v76, 1.0, v76
	v_rcp_f32_e32 v81, v76
	s_nop 0
	v_fma_f32 v83, -v76, v81, 1.0
	v_fma_f32 v76, v83, v81, v81
	v_mul_f32_e32 v76, 0xbf1b459e, v76
	v_mul_f32_e32 v80, 0x3fb8aa3b, v76
	v_exp_f32_e32 v80, v80
	s_nop 0
	v_sub_f32_e32 v76, 1.0, v80
.LBB0_858:
	v_add_f32_e32 v80, v77, v33
	s_and_b64 vcc, exec, s[8:9]
	s_mov_b64 s[14:15], -1
	s_cbranch_vccnz .LBB0_862
	s_and_b64 vcc, exec, s[6:7]
	v_mov_b32_e32 v77, v80
	s_cbranch_vccnz .LBB0_861
	v_mul_f32_e32 v77, 0xbfb8aa3b, v80
	v_exp_f32_e32 v77, v77
	s_nop 0
	v_min_f32_e32 v77, 0x7e800000, v77
	v_add_f32_e32 v77, 1.0, v77
	v_rcp_f32_e32 v82, v77
	s_nop 0
	v_fma_f32 v84, -v77, v82, 1.0
	v_fma_f32 v77, v84, v82, v82

; __device__ __forceinline__ float sigmoidf_(float x) { return 1.0f / (1.0f + __expf(-x)); }
;     __device__ __forceinline__ void operator()(const f32x4 (&acc)[2][2][4][2], const Unit& u, int wr, int wc, int fr, int fq) const {
;     ...
;                         for (int i = 0; i < 4; ++i) { float xv = acc[ai][bj][m][n][i] + bv[bj][n][i]; float r;
;                             if (type < 2) { const float sg = sigmoidf_(xv); r = -expm1f(-0.606531f * sg); }
;                             else if (type == 2) r = sigmoidf_(xv);
;                             else r = xv;
;                             v[4 * n + i] = (f16)r; }
.LBB0_863:
	v_mul_f32_e32 v77, 0xbfb8aa3b, v80
	v_exp_f32_e32 v77, v77
	s_nop 0
	v_min_f32_e32 v77, 0x7e800000, v77
	v_add_f32_e32 v77, 1.0, v77
	v_rcp_f32_e32 v81, v77
	s_nop 0
	v_fma_f32 v83, -v77, v81, 1.0
	v_fma_f32 v77, v83, v81, v81
	v_mul_f32_e32 v77, 0xbf1b459e, v77
	v_mul_f32_e32 v80, 0x3fb8aa3b, v77
	v_exp_f32_e32 v80, v80
	s_nop 0
	v_sub_f32_e32 v77, 1.0, v80
.LBB0_864:
	v_add_f32_e32 v80, v78, v34
	s_and_b64 vcc, exec, s[8:9]
	s_mov_b64 s[14:15], -1
	s_cbranch_vccnz .LBB0_868
	s_and_b64 vcc, exec, s[6:7]
	v_mov_b32_e32 v78, v80
	s_cbranch_vccnz .LBB0_867
	v_mul_f32_e32 v78, 0xbfb8aa3b, v80
	v_exp_f32_e32 v78, v78
	s_nop 0
	v_min_f32_e32 v78, 0x7e800000, v78
	v_add_f32_e32 v78, 1.0, v78
	v_rcp_f32_e32 v82, v78
	s_nop 0
	v_fma_f32 v84, -v78, v82, 1.0
	v_fma_f32 v78, v84, v82, v82

; __device__ __forceinline__ float sigmoidf_(float x) { return 1.0f / (1.0f + __expf(-x)); }
;     __device__ __forceinline__ void operator()(const f32x4 (&acc)[2][2][4][2], const Unit& u, int wr, int wc, int fr, int fq) const {
;     ...
;                         for (int i = 0; i < 4; ++i) { float xv = acc[ai][bj][m][n][i] + bv[bj][n][i]; float r;
;                             if (type < 2) { const float sg = sigmoidf_(xv); r = -expm1f(-0.606531f * sg); }
;                             else if (type == 2) r = sigmoidf_(xv);
;                             else r = xv;
;                             v[4 * n + i] = (f16)r; }
.LBB0_869:
	v_mul_f32_e32 v78, 0xbfb8aa3b, v80
	v_exp_f32_e32 v78, v78
	s_nop 0
	v_min_f32_e32 v78, 0x7e800000, v78
	v_add_f32_e32 v78, 1.0, v78
	v_rcp_f32_e32 v81, v78
	s_nop 0
	v_fma_f32 v83, -v78, v81, 1.0
	v_fma_f32 v78, v83, v81, v81
	v_mul_f32_e32 v78, 0xbf1b459e, v78
	v_mul_f32_e32 v80, 0x3fb8aa3b, v78
	v_exp_f32_e32 v80, v80
	s_nop 0
	v_sub_f32_e32 v78, 1.0, v80
.LBB0_870:
	v_add_f32_e32 v80, v79, v35
	s_and_b64 vcc, exec, s[8:9]
	s_mov_b64 s[14:15], -1
	s_cbranch_vccnz .LBB0_874
	s_and_b64 vcc, exec, s[6:7]
	v_mov_b32_e32 v79, v80
	s_cbranch_vccnz .LBB0_873
	v_mul_f32_e32 v79, 0xbfb8aa3b, v80
	v_exp_f32_e32 v79, v79
	s_nop 0
	v_min_f32_e32 v79, 0x7e800000, v79
	v_add_f32_e32 v79, 1.0, v79
	v_rcp_f32_e32 v82, v79
	s_nop 0
	v_fma_f32 v84, -v79, v82, 1.0
	v_fma_f32 v79, v84, v82, v82

; __device__ __forceinline__ float sigmoidf_(float x) { return 1.0f / (1.0f + __expf(-x)); }
;     __device__ __forceinline__ void operator()(const f32x4 (&acc)[2][2][4][2], const Unit& u, int wr, int wc, int fr, int fq) const {
;     ...
;                         for (int i = 0; i < 4; ++i) { float xv = acc[ai][bj][m][n][i] + bv[bj][n][i]; float r;
;                             if (type < 2) { const float sg = sigmoidf_(xv); r = -expm1f(-0.606531f * sg); }
;                             else if (type == 2) r = sigmoidf_(xv);
;                             else r = xv;
;                             v[4 * n + i] = (f16)r; }
.LBB0_875:
	v_mul_f32_e32 v79, 0xbfb8aa3b, v80
	v_exp_f32_e32 v79, v79
	s_nop 0
	v_min_f32_e32 v79, 0x7e800000, v79
	v_add_f32_e32 v79, 1.0, v79
	v_rcp_f32_e32 v81, v79
	s_nop 0
	v_fma_f32 v83, -v79, v81, 1.0
	v_fma_f32 v79, v83, v81, v81
	v_mul_f32_e32 v79, 0xbf1b459e, v79
	v_mul_f32_e32 v80, 0x3fb8aa3b, v79
	v_exp_f32_e32 v80, v80
	s_nop 0
	v_sub_f32_e32 v79, 1.0, v80
.LBB0_876:
	v_add_f32_e32 v72, v72, v28
	s_and_b64 vcc, exec, s[8:9]
	s_mov_b64 s[14:15], -1
	s_cbranch_vccnz .LBB0_880
	s_and_b64 vcc, exec, s[6:7]
	v_mov_b32_e32 v80, v72
	s_cbranch_vccnz .LBB0_879
	v_mul_f32_e32 v80, 0xbfb8aa3b, v72
	v_exp_f32_e32 v80, v80
	s_nop 0
	v_min_f32_e32 v80, 0x7e800000, v80
	v_add_f32_e32 v80, 1.0, v80
	v_rcp_f32_e32 v82, v80
	s_nop 0
	v_fma_f32 v84, -v80, v82, 1.0
	v_fma_f32 v80, v84, v82, v82

; __device__ __forceinline__ float sigmoidf_(float x) { return 1.0f / (1.0f + __expf(-x)); }
;     __device__ __forceinline__ void operator()(const f32x4 (&acc)[2][2][4][2], const Unit& u, int wr, int wc, int fr, int fq) const {
;     ...
;                         for (int i = 0; i < 4; ++i) { float xv = acc[ai][bj][m][n][i] + bv[bj][n][i]; float r;
;                             if (type < 2) { const float sg = sigmoidf_(xv); r = -expm1f(-0.606531f * sg); }
;                             else if (type == 2) r = sigmoidf_(xv);
;                             else r = xv;
;                             v[4 * n + i] = (f16)r; }
.LBB0_881:
	v_mul_f32_e32 v72, 0xbfb8aa3b, v72
	v_exp_f32_e32 v72, v72
	s_nop 0
	v_min_f32_e32 v72, 0x7e800000, v72
	v_add_f32_e32 v72, 1.0, v72
	v_rcp_f32_e32 v81, v72
	s_nop 0
	v_fma_f32 v83, -v72, v81, 1.0
	v_fma_f32 v72, v83, v81, v81
	v_mul_f32_e32 v72, 0xbf1b459e, v72
	v_mul_f32_e32 v80, 0x3fb8aa3b, v72
	v_exp_f32_e32 v80, v80
	s_nop 0
	v_sub_f32_e32 v80, 1.0, v80
.LBB0_882:
	v_add_f32_e32 v72, v73, v29
	s_and_b64 vcc, exec, s[8:9]
	s_mov_b64 s[14:15], -1
	s_cbranch_vccnz .LBB0_886
	s_and_b64 vcc, exec, s[6:7]
	v_mov_b32_e32 v81, v72
	s_cbranch_vccnz .LBB0_885
	v_mul_f32_e32 v73, 0xbfb8aa3b, v72
	v_exp_f32_e32 v73, v73
	s_nop 0
	v_min_f32_e32 v73, 0x7e800000, v73
	v_add_f32_e32 v73, 1.0, v73
	v_rcp_f32_e32 v82, v73
	s_nop 0
	v_fma_f32 v84, -v73, v82, 1.0
	v_fma_f32 v81, v84, v82, v82

; __device__ __forceinline__ float sigmoidf_(float x) { return 1.0f / (1.0f + __expf(-x)); }
;     __device__ __forceinline__ void operator()(const f32x4 (&acc)[2][2][4][2], const Unit& u, int wr, int wc, int fr, int fq) const {
;     ...
;                         for (int i = 0; i < 4; ++i) { float xv = acc[ai][bj][m][n][i] + bv[bj][n][i]; float r;
;                             if (type < 2) { const float sg = sigmoidf_(xv); r = -expm1f(-0.606531f * sg); }
;                             else if (type == 2) r = sigmoidf_(xv);
;                             else r = xv;
;                             v[4 * n + i] = (f16)r; }
.LBB0_887:
	v_mul_f32_e32 v72, 0xbfb8aa3b, v72
	v_exp_f32_e32 v72, v72
	s_nop 0
	v_min_f32_e32 v72, 0x7e800000, v72
	v_add_f32_e32 v72, 1.0, v72
	v_rcp_f32_e32 v81, v72
	s_nop 0
	v_fma_f32 v83, -v72, v81, 1.0
	v_fma_f32 v72, v83, v81, v81
	v_mul_f32_e32 v72, 0xbf1b459e, v72
	v_mul_f32_e32 v73, 0x3fb8aa3b, v72
	v_exp_f32_e32 v73, v73
	s_nop 0
	v_sub_f32_e32 v81, 1.0, v73
.LBB0_888:
	v_add_f32_e32 v72, v74, v30
	s_and_b64 vcc, exec, s[8:9]
	s_mov_b64 s[14:15], -1
	s_cbranch_vccnz .LBB0_892
	s_and_b64 vcc, exec, s[6:7]
	v_mov_b32_e32 v74, v72
	s_cbranch_vccnz .LBB0_891
	v_mul_f32_e32 v73, 0xbfb8aa3b, v72
	v_exp_f32_e32 v73, v73
	s_nop 0
	v_min_f32_e32 v73, 0x7e800000, v73
	v_add_f32_e32 v73, 1.0, v73
	v_rcp_f32_e32 v82, v73
	s_nop 0
	v_fma_f32 v84, -v73, v82, 1.0
	v_fma_f32 v74, v84, v82, v82

; __device__ __forceinline__ float sigmoidf_(float x) { return 1.0f / (1.0f + __expf(-x)); }
;     __device__ __forceinline__ void operator()(const f32x4 (&acc)[2][2][4][2], const Unit& u, int wr, int wc, int fr, int fq) const {
;     ...
;                         for (int i = 0; i < 4; ++i) { float xv = acc[ai][bj][m][n][i] + bv[bj][n][i]; float r;
;                             if (type < 2) { const float sg = sigmoidf_(xv); r = -expm1f(-0.606531f * sg); }
;                             else if (type == 2) r = sigmoidf_(xv);
;                             else r = xv;
;                             v[4 * n + i] = (f16)r; }
.LBB0_893:
	v_mul_f32_e32 v72, 0xbfb8aa3b, v72
	v_exp_f32_e32 v72, v72
	s_nop 0
	v_min_f32_e32 v72, 0x7e800000, v72
	v_add_f32_e32 v72, 1.0, v72
	v_rcp_f32_e32 v74, v72
	s_nop 0
	v_fma_f32 v83, -v72, v74, 1.0
	v_fma_f32 v72, v83, v74, v74
	v_mul_f32_e32 v72, 0xbf1b459e, v72
	v_mul_f32_e32 v73, 0x3fb8aa3b, v72
	v_exp_f32_e32 v73, v73
	s_nop 0
	v_sub_f32_e32 v74, 1.0, v73
.LBB0_894:
	v_add_f32_e32 v72, v75, v31
	s_and_b64 vcc, exec, s[8:9]
	s_mov_b64 s[14:15], -1
	s_cbranch_vccnz .LBB0_898
	s_and_b64 vcc, exec, s[6:7]
	v_mov_b32_e32 v75, v72
	s_cbranch_vccnz .LBB0_897
	v_mul_f32_e32 v73, 0xbfb8aa3b, v72
	v_exp_f32_e32 v73, v73
	s_nop 0
	v_min_f32_e32 v73, 0x7e800000, v73
	v_add_f32_e32 v73, 1.0, v73
	v_rcp_f32_e32 v82, v73
	s_nop 0
	v_fma_f32 v84, -v73, v82, 1.0
	v_fma_f32 v75, v84, v82, v82

; __device__ __forceinline__ float sigmoidf_(float x) { return 1.0f / (1.0f + __expf(-x)); }
;     __device__ __forceinline__ void operator()(const f32x4 (&acc)[2][2][4][2], const Unit& u, int wr, int wc, int fr, int fq) const {
;     ...
;                         for (int i = 0; i < 4; ++i) { float xv = acc[ai][bj][m][n][i] + bv[bj][n][i]; float r;
;                             if (type < 2) { const float sg = sigmoidf_(xv); r = -expm1f(-0.606531f * sg); }
;                             else if (type == 2) r = sigmoidf_(xv);
;                             else r = xv;
;                             v[4 * n + i] = (f16)r; }
;                     *(f16x8*)(rowp + bj * 128) = v; } }
.LBB0_899:
	v_mul_f32_e32 v72, 0xbfb8aa3b, v72
	v_exp_f32_e32 v72, v72
	s_nop 0
	v_min_f32_e32 v72, 0x7e800000, v72
	v_add_f32_e32 v72, 1.0, v72
	v_rcp_f32_e32 v75, v72
	s_nop 0
	v_fma_f32 v83, -v72, v75, 1.0
	v_fma_f32 v72, v83, v75, v75
	v_mul_f32_e32 v72, 0xbf1b459e, v72
	v_mul_f32_e32 v73, 0x3fb8aa3b, v72
	v_exp_f32_e32 v73, v73
	s_nop 0
	v_sub_f32_e32 v75, 1.0, v73
.LBB0_900:
	v_lshlrev_b64 v[72:73], 13, v[138:139]
	v_lshl_add_u64 v[72:73], s[28:29], 0, v[72:73]
	v_lshl_add_u64 v[72:73], v[136:137], 1, v[72:73]
	v_cvt_pk_f16_f32 v83, v74, v75
	v_add_co_u32_e32 v74, vcc, 0x100000, v72
	v_cvt_pk_f16_f32 v82, v80, v81
	v_cvt_pk_f16_f32 v81, v78, v79
	v_cvt_pk_f16_f32 v80, v76, v77
	v_addc_co_u32_e32 v75, vcc, 0, v73, vcc
	global_store_dwordx4 v[74:75], v[80:83], off
	v_add_f32_e32 v74, v68, v20
	s_and_b64 vcc, exec, s[8:9]
	s_mov_b64 s[14:15], -1
	s_cbranch_vccnz .LBB0_904
	s_and_b64 vcc, exec, s[6:7]
	v_mov_b32_e32 v68, v74
	s_cbranch_vccnz .LBB0_903
	v_mul_f32_e32 v68, 0xbfb8aa3b, v74
	v_exp_f32_e32 v68, v68
	s_nop 0
	v_min_f32_e32 v68, 0x7e800000, v68
	v_add_f32_e32 v68, 1.0, v68
	v_rcp_f32_e32 v76, v68
	s_nop 0
	v_fma_f32 v78, -v68, v76, 1.0
	v_fma_f32 v68, v78, v76, v76

; __device__ __forceinline__ float sigmoidf_(float x) { return 1.0f / (1.0f + __expf(-x)); }
;     __device__ __forceinline__ void operator()(const f32x4 (&acc)[2][2][4][2], const Unit& u, int wr, int wc, int fr, int fq) const {
;     ...
;                         for (int i = 0; i < 4; ++i) { float xv = acc[ai][bj][m][n][i] + bv[bj][n][i]; float r;
;                             if (type < 2) { const float sg = sigmoidf_(xv); r = -expm1f(-0.606531f * sg); }
;                             else if (type == 2) r = sigmoidf_(xv);
;                             else r = xv;
;                             v[4 * n + i] = (f16)r; }
.LBB0_905:
	v_mul_f32_e32 v68, 0xbfb8aa3b, v74
	v_exp_f32_e32 v68, v68
	s_nop 0
	v_min_f32_e32 v68, 0x7e800000, v68
	v_add_f32_e32 v68, 1.0, v68
	v_rcp_f32_e32 v75, v68
	s_nop 0
	v_fma_f32 v77, -v68, v75, 1.0
	v_fma_f32 v68, v77, v75, v75
	v_mul_f32_e32 v68, 0xbf1b459e, v68
	v_mul_f32_e32 v74, 0x3fb8aa3b, v68
	v_exp_f32_e32 v74, v74
	s_nop 0
	v_sub_f32_e32 v68, 1.0, v74
.LBB0_906:
	v_add_f32_e32 v74, v69, v21
	s_and_b64 vcc, exec, s[8:9]
	s_mov_b64 s[14:15], -1
	s_cbranch_vccnz .LBB0_910
	s_and_b64 vcc, exec, s[6:7]
	v_mov_b32_e32 v69, v74
	s_cbranch_vccnz .LBB0_909
	v_mul_f32_e32 v69, 0xbfb8aa3b, v74
	v_exp_f32_e32 v69, v69
	s_nop 0
	v_min_f32_e32 v69, 0x7e800000, v69
	v_add_f32_e32 v69, 1.0, v69
	v_rcp_f32_e32 v76, v69
	s_nop 0
	v_fma_f32 v78, -v69, v76, 1.0
	v_fma_f32 v69, v78, v76, v76

; __device__ __forceinline__ float sigmoidf_(float x) { return 1.0f / (1.0f + __expf(-x)); }
;     __device__ __forceinline__ void operator()(const f32x4 (&acc)[2][2][4][2], const Unit& u, int wr, int wc, int fr, int fq) const {
;     ...
;                         for (int i = 0; i < 4; ++i) { float xv = acc[ai][bj][m][n][i] + bv[bj][n][i]; float r;
;                             if (type < 2) { const float sg = sigmoidf_(xv); r = -expm1f(-0.606531f * sg); }
;                             else if (type == 2) r = sigmoidf_(xv);
;                             else r = xv;
;                             v[4 * n + i] = (f16)r; }
.LBB0_911:
	v_mul_f32_e32 v69, 0xbfb8aa3b, v74
	v_exp_f32_e32 v69, v69
	s_nop 0
	v_min_f32_e32 v69, 0x7e800000, v69
	v_add_f32_e32 v69, 1.0, v69
	v_rcp_f32_e32 v75, v69
	s_nop 0
	v_fma_f32 v77, -v69, v75, 1.0
	v_fma_f32 v69, v77, v75, v75
	v_mul_f32_e32 v69, 0xbf1b459e, v69
	v_mul_f32_e32 v74, 0x3fb8aa3b, v69
	v_exp_f32_e32 v74, v74
	s_nop 0
	v_sub_f32_e32 v69, 1.0, v74
.LBB0_912:
	v_add_f32_e32 v74, v70, v22
	s_and_b64 vcc, exec, s[8:9]
	s_mov_b64 s[14:15], -1
	s_cbranch_vccnz .LBB0_916
	s_and_b64 vcc, exec, s[6:7]
	v_mov_b32_e32 v70, v74
	s_cbranch_vccnz .LBB0_915
	v_mul_f32_e32 v70, 0xbfb8aa3b, v74
	v_exp_f32_e32 v70, v70
	s_nop 0
	v_min_f32_e32 v70, 0x7e800000, v70
	v_add_f32_e32 v70, 1.0, v70
	v_rcp_f32_e32 v76, v70
	s_nop 0
	v_fma_f32 v78, -v70, v76, 1.0
	v_fma_f32 v70, v78, v76, v76

; __device__ __forceinline__ float sigmoidf_(float x) { return 1.0f / (1.0f + __expf(-x)); }
;     __device__ __forceinline__ void operator()(const f32x4 (&acc)[2][2][4][2], const Unit& u, int wr, int wc, int fr, int fq) const {
;     ...
;                         for (int i = 0; i < 4; ++i) { float xv = acc[ai][bj][m][n][i] + bv[bj][n][i]; float r;
;                             if (type < 2) { const float sg = sigmoidf_(xv); r = -expm1f(-0.606531f * sg); }
;                             else if (type == 2) r = sigmoidf_(xv);
;                             else r = xv;
;                             v[4 * n + i] = (f16)r; }
.LBB0_917:
	v_mul_f32_e32 v70, 0xbfb8aa3b, v74
	v_exp_f32_e32 v70, v70
	s_nop 0
	v_min_f32_e32 v70, 0x7e800000, v70
	v_add_f32_e32 v70, 1.0, v70
	v_rcp_f32_e32 v75, v70
	s_nop 0
	v_fma_f32 v77, -v70, v75, 1.0
	v_fma_f32 v70, v77, v75, v75
	v_mul_f32_e32 v70, 0xbf1b459e, v70
	v_mul_f32_e32 v74, 0x3fb8aa3b, v70
	v_exp_f32_e32 v74, v74
	s_nop 0
	v_sub_f32_e32 v70, 1.0, v74
.LBB0_918:
	v_add_f32_e32 v74, v71, v23
	s_and_b64 vcc, exec, s[8:9]
	s_mov_b64 s[14:15], -1
	s_cbranch_vccnz .LBB0_922
	s_and_b64 vcc, exec, s[6:7]
	v_mov_b32_e32 v71, v74
	s_cbranch_vccnz .LBB0_921
	v_mul_f32_e32 v71, 0xbfb8aa3b, v74
	v_exp_f32_e32 v71, v71
	s_nop 0
	v_min_f32_e32 v71, 0x7e800000, v71
	v_add_f32_e32 v71, 1.0, v71
	v_rcp_f32_e32 v76, v71
	s_nop 0
	v_fma_f32 v78, -v71, v76, 1.0
	v_fma_f32 v71, v78, v76, v76

; __device__ __forceinline__ float sigmoidf_(float x) { return 1.0f / (1.0f + __expf(-x)); }
;     __device__ __forceinline__ void operator()(const f32x4 (&acc)[2][2][4][2], const Unit& u, int wr, int wc, int fr, int fq) const {
;     ...
;                         for (int i = 0; i < 4; ++i) { float xv = acc[ai][bj][m][n][i] + bv[bj][n][i]; float r;
;                             if (type < 2) { const float sg = sigmoidf_(xv); r = -expm1f(-0.606531f * sg); }
;                             else if (type == 2) r = sigmoidf_(xv);
;                             else r = xv;
;                             v[4 * n + i] = (f16)r; }
.LBB0_923:
	v_mul_f32_e32 v71, 0xbfb8aa3b, v74
	v_exp_f32_e32 v71, v71
	s_nop 0
	v_min_f32_e32 v71, 0x7e800000, v71
	v_add_f32_e32 v71, 1.0, v71
	v_rcp_f32_e32 v75, v71
	s_nop 0
	v_fma_f32 v77, -v71, v75, 1.0
	v_fma_f32 v71, v77, v75, v75
	v_mul_f32_e32 v71, 0xbf1b459e, v71
	v_mul_f32_e32 v74, 0x3fb8aa3b, v71
	v_exp_f32_e32 v74, v74
	s_nop 0
	v_sub_f32_e32 v71, 1.0, v74
.LBB0_924:
	v_add_f32_e32 v74, v64, v12
	s_and_b64 vcc, exec, s[8:9]
	s_mov_b64 s[14:15], -1
	s_cbranch_vccnz .LBB0_928
	s_and_b64 vcc, exec, s[6:7]
	v_mov_b32_e32 v64, v74
	s_cbranch_vccnz .LBB0_927
	v_mul_f32_e32 v64, 0xbfb8aa3b, v74
	v_exp_f32_e32 v64, v64
	s_nop 0
	v_min_f32_e32 v64, 0x7e800000, v64
	v_add_f32_e32 v64, 1.0, v64
	v_rcp_f32_e32 v76, v64
	s_nop 0
	v_fma_f32 v78, -v64, v76, 1.0
	v_fma_f32 v64, v78, v76, v76

; __device__ __forceinline__ float sigmoidf_(float x) { return 1.0f / (1.0f + __expf(-x)); }
;     __device__ __forceinline__ void operator()(const f32x4 (&acc)[2][2][4][2], const Unit& u, int wr, int wc, int fr, int fq) const {
;     ...
;                         for (int i = 0; i < 4; ++i) { float xv = acc[ai][bj][m][n][i] + bv[bj][n][i]; float r;
;                             if (type < 2) { const float sg = sigmoidf_(xv); r = -expm1f(-0.606531f * sg); }
;                             else if (type == 2) r = sigmoidf_(xv);
;                             else r = xv;
;                             v[4 * n + i] = (f16)r; }
.LBB0_929:
	v_mul_f32_e32 v64, 0xbfb8aa3b, v74
	v_exp_f32_e32 v64, v64
	s_nop 0
	v_min_f32_e32 v64, 0x7e800000, v64
	v_add_f32_e32 v64, 1.0, v64
	v_rcp_f32_e32 v75, v64
	s_nop 0
	v_fma_f32 v77, -v64, v75, 1.0
	v_fma_f32 v64, v77, v75, v75
	v_mul_f32_e32 v64, 0xbf1b459e, v64
	v_mul_f32_e32 v74, 0x3fb8aa3b, v64
	v_exp_f32_e32 v74, v74
	s_nop 0
	v_sub_f32_e32 v64, 1.0, v74
.LBB0_930:
	v_add_f32_e32 v74, v65, v13
	s_and_b64 vcc, exec, s[8:9]
	s_mov_b64 s[14:15], -1
	s_cbranch_vccnz .LBB0_934
	s_and_b64 vcc, exec, s[6:7]
	v_mov_b32_e32 v65, v74
	s_cbranch_vccnz .LBB0_933
	v_mul_f32_e32 v65, 0xbfb8aa3b, v74
	v_exp_f32_e32 v65, v65
	s_nop 0
	v_min_f32_e32 v65, 0x7e800000, v65
	v_add_f32_e32 v65, 1.0, v65
	v_rcp_f32_e32 v76, v65
	s_nop 0
	v_fma_f32 v78, -v65, v76, 1.0
	v_fma_f32 v65, v78, v76, v76

; __device__ __forceinline__ float sigmoidf_(float x) { return 1.0f / (1.0f + __expf(-x)); }
;     __device__ __forceinline__ void operator()(const f32x4 (&acc)[2][2][4][2], const Unit& u, int wr, int wc, int fr, int fq) const {
;     ...
;                         for (int i = 0; i < 4; ++i) { float xv = acc[ai][bj][m][n][i] + bv[bj][n][i]; float r;
;                             if (type < 2) { const float sg = sigmoidf_(xv); r = -expm1f(-0.606531f * sg); }
;                             else if (type == 2) r = sigmoidf_(xv);
;                             else r = xv;
;                             v[4 * n + i] = (f16)r; }
.LBB0_935:
	v_mul_f32_e32 v65, 0xbfb8aa3b, v74
	v_exp_f32_e32 v65, v65
	s_nop 0
	v_min_f32_e32 v65, 0x7e800000, v65
	v_add_f32_e32 v65, 1.0, v65
	v_rcp_f32_e32 v75, v65
	s_nop 0
	v_fma_f32 v77, -v65, v75, 1.0
	v_fma_f32 v65, v77, v75, v75
	v_mul_f32_e32 v65, 0xbf1b459e, v65
	v_mul_f32_e32 v74, 0x3fb8aa3b, v65
	v_exp_f32_e32 v74, v74
	s_nop 0
	v_sub_f32_e32 v65, 1.0, v74
.LBB0_936:
	v_add_f32_e32 v74, v66, v14
	s_and_b64 vcc, exec, s[8:9]
	s_mov_b64 s[14:15], -1
	s_cbranch_vccnz .LBB0_940
	s_and_b64 vcc, exec, s[6:7]
	v_mov_b32_e32 v66, v74
	s_cbranch_vccnz .LBB0_939
	v_mul_f32_e32 v66, 0xbfb8aa3b, v74
	v_exp_f32_e32 v66, v66
	s_nop 0
	v_min_f32_e32 v66, 0x7e800000, v66
	v_add_f32_e32 v66, 1.0, v66
	v_rcp_f32_e32 v76, v66
	s_nop 0
	v_fma_f32 v78, -v66, v76, 1.0
	v_fma_f32 v66, v78, v76, v76

; __device__ __forceinline__ float sigmoidf_(float x) { return 1.0f / (1.0f + __expf(-x)); }
;     __device__ __forceinline__ void operator()(const f32x4 (&acc)[2][2][4][2], const Unit& u, int wr, int wc, int fr, int fq) const {
;     ...
;                         for (int i = 0; i < 4; ++i) { float xv = acc[ai][bj][m][n][i] + bv[bj][n][i]; float r;
;                             if (type < 2) { const float sg = sigmoidf_(xv); r = -expm1f(-0.606531f * sg); }
;                             else if (type == 2) r = sigmoidf_(xv);
;                             else r = xv;
;                             v[4 * n + i] = (f16)r; }
.LBB0_941:
	v_mul_f32_e32 v66, 0xbfb8aa3b, v74
	v_exp_f32_e32 v66, v66
	s_nop 0
	v_min_f32_e32 v66, 0x7e800000, v66
	v_add_f32_e32 v66, 1.0, v66
	v_rcp_f32_e32 v75, v66
	s_nop 0
	v_fma_f32 v77, -v66, v75, 1.0
	v_fma_f32 v66, v77, v75, v75
	v_mul_f32_e32 v66, 0xbf1b459e, v66
	v_mul_f32_e32 v74, 0x3fb8aa3b, v66
	v_exp_f32_e32 v74, v74
	s_nop 0
	v_sub_f32_e32 v66, 1.0, v74
.LBB0_942:
	v_add_f32_e32 v67, v67, v15
	s_and_b64 vcc, exec, s[8:9]
	s_mov_b64 s[14:15], -1
	s_cbranch_vccnz .LBB0_946
	s_and_b64 vcc, exec, s[6:7]
	v_mov_b32_e32 v74, v67
	s_cbranch_vccnz .LBB0_945
	v_mul_f32_e32 v74, 0xbfb8aa3b, v67
	v_exp_f32_e32 v74, v74
	s_nop 0
	v_min_f32_e32 v74, 0x7e800000, v74
	v_add_f32_e32 v74, 1.0, v74
	v_rcp_f32_e32 v76, v74
	s_nop 0
	v_fma_f32 v78, -v74, v76, 1.0
	v_fma_f32 v74, v78, v76, v76

; __device__ __forceinline__ float sigmoidf_(float x) { return 1.0f / (1.0f + __expf(-x)); }
;     __device__ __forceinline__ void operator()(const f32x4 (&acc)[2][2][4][2], const Unit& u, int wr, int wc, int fr, int fq) const {
;     ...
;                         for (int i = 0; i < 4; ++i) { float xv = acc[ai][bj][m][n][i] + bv[bj][n][i]; float r;
;                             if (type < 2) { const float sg = sigmoidf_(xv); r = -expm1f(-0.606531f * sg); }
;                             else if (type == 2) r = sigmoidf_(xv);
;                             else r = xv;
;                             v[4 * n + i] = (f16)r; }
;                     *(f16x8*)(rowp + bj * 128) = v; } }
.LBB0_947:
	v_mul_f32_e32 v67, 0xbfb8aa3b, v67
	v_exp_f32_e32 v67, v67
	s_nop 0
	v_min_f32_e32 v67, 0x7e800000, v67
	v_add_f32_e32 v67, 1.0, v67
	v_rcp_f32_e32 v75, v67
	s_nop 0
	v_fma_f32 v77, -v67, v75, 1.0
	v_fma_f32 v67, v77, v75, v75
	v_mul_f32_e32 v67, 0xbf1b459e, v67
	v_mul_f32_e32 v74, 0x3fb8aa3b, v67
	v_exp_f32_e32 v74, v74
	s_nop 0
	v_sub_f32_e32 v74, 1.0, v74
.LBB0_948:
	s_mov_b64 s[2:3], 0x100000
	v_lshl_add_u64 v[72:73], v[72:73], 0, s[2:3]
	v_cvt_pk_f16_f32 v67, v66, v74
	v_cvt_pk_f16_f32 v66, v64, v65
	v_cvt_pk_f16_f32 v65, v70, v71
	v_cvt_pk_f16_f32 v64, v68, v69
	global_store_dwordx4 v[72:73], v[64:67], off offset:256
	s_and_b64 vcc, exec, s[8:9]
	s_mov_b64 s[14:15], -1
	v_add_f32_e32 v64, v60, v32
	s_cbranch_vccnz .LBB0_952
	s_and_b64 vcc, exec, s[6:7]
	v_mov_b32_e32 v60, v64
	s_cbranch_vccnz .LBB0_951
	v_mul_f32_e32 v60, 0xbfb8aa3b, v64
	v_exp_f32_e32 v60, v60
	s_nop 0
	v_min_f32_e32 v60, 0x7e800000, v60
	v_add_f32_e32 v60, 1.0, v60
	v_rcp_f32_e32 v66, v60
	s_nop 0
	v_fma_f32 v68, -v60, v66, 1.0
	v_fma_f32 v60, v68, v66, v66

; __device__ __forceinline__ float sigmoidf_(float x) { return 1.0f / (1.0f + __expf(-x)); }
;     __device__ __forceinline__ void operator()(const f32x4 (&acc)[2][2][4][2], const Unit& u, int wr, int wc, int fr, int fq) const {
;     ...
;                         for (int i = 0; i < 4; ++i) { float xv = acc[ai][bj][m][n][i] + bv[bj][n][i]; float r;
;                             if (type < 2) { const float sg = sigmoidf_(xv); r = -expm1f(-0.606531f * sg); }
;                             else if (type == 2) r = sigmoidf_(xv);
;                             else r = xv;
;                             v[4 * n + i] = (f16)r; }
.LBB0_953:
	v_mul_f32_e32 v60, 0xbfb8aa3b, v64
	v_exp_f32_e32 v60, v60
	s_nop 0
	v_min_f32_e32 v60, 0x7e800000, v60
	v_add_f32_e32 v60, 1.0, v60
	v_rcp_f32_e32 v65, v60
	s_nop 0
	v_fma_f32 v67, -v60, v65, 1.0
	v_fma_f32 v60, v67, v65, v65
	v_mul_f32_e32 v60, 0xbf1b459e, v60
	v_mul_f32_e32 v64, 0x3fb8aa3b, v60
	v_exp_f32_e32 v64, v64
	s_nop 0
	v_sub_f32_e32 v60, 1.0, v64
.LBB0_954:
	v_add_f32_e32 v64, v61, v33
	s_and_b64 vcc, exec, s[8:9]
	s_mov_b64 s[14:15], -1
	s_cbranch_vccnz .LBB0_958
	s_and_b64 vcc, exec, s[6:7]
	v_mov_b32_e32 v61, v64
	s_cbranch_vccnz .LBB0_957
	v_mul_f32_e32 v61, 0xbfb8aa3b, v64
	v_exp_f32_e32 v61, v61
	s_nop 0
	v_min_f32_e32 v61, 0x7e800000, v61
	v_add_f32_e32 v61, 1.0, v61
	v_rcp_f32_e32 v66, v61
	s_nop 0
	v_fma_f32 v68, -v61, v66, 1.0
	v_fma_f32 v61, v68, v66, v66

; __device__ __forceinline__ float sigmoidf_(float x) { return 1.0f / (1.0f + __expf(-x)); }
;     __device__ __forceinline__ void operator()(const f32x4 (&acc)[2][2][4][2], const Unit& u, int wr, int wc, int fr, int fq) const {
;     ...
;                         for (int i = 0; i < 4; ++i) { float xv = acc[ai][bj][m][n][i] + bv[bj][n][i]; float r;
;                             if (type < 2) { const float sg = sigmoidf_(xv); r = -expm1f(-0.606531f * sg); }
;                             else if (type == 2) r = sigmoidf_(xv);
;                             else r = xv;
;                             v[4 * n + i] = (f16)r; }
.LBB0_959:
	v_mul_f32_e32 v61, 0xbfb8aa3b, v64
	v_exp_f32_e32 v61, v61
	s_nop 0
	v_min_f32_e32 v61, 0x7e800000, v61
	v_add_f32_e32 v61, 1.0, v61
	v_rcp_f32_e32 v65, v61
	s_nop 0
	v_fma_f32 v67, -v61, v65, 1.0
	v_fma_f32 v61, v67, v65, v65
	v_mul_f32_e32 v61, 0xbf1b459e, v61
	v_mul_f32_e32 v64, 0x3fb8aa3b, v61
	v_exp_f32_e32 v64, v64
	s_nop 0
	v_sub_f32_e32 v61, 1.0, v64
.LBB0_960:
	v_add_f32_e32 v64, v62, v34
	s_and_b64 vcc, exec, s[8:9]
	s_mov_b64 s[14:15], -1
	s_cbranch_vccnz .LBB0_964
	s_and_b64 vcc, exec, s[6:7]
	v_mov_b32_e32 v62, v64
	s_cbranch_vccnz .LBB0_963
	v_mul_f32_e32 v62, 0xbfb8aa3b, v64
	v_exp_f32_e32 v62, v62
	s_nop 0
	v_min_f32_e32 v62, 0x7e800000, v62
	v_add_f32_e32 v62, 1.0, v62
	v_rcp_f32_e32 v66, v62
	s_nop 0
	v_fma_f32 v68, -v62, v66, 1.0
	v_fma_f32 v62, v68, v66, v66

; __device__ __forceinline__ float sigmoidf_(float x) { return 1.0f / (1.0f + __expf(-x)); }
;     __device__ __forceinline__ void operator()(const f32x4 (&acc)[2][2][4][2], const Unit& u, int wr, int wc, int fr, int fq) const {
;     ...
;                         for (int i = 0; i < 4; ++i) { float xv = acc[ai][bj][m][n][i] + bv[bj][n][i]; float r;
;                             if (type < 2) { const float sg = sigmoidf_(xv); r = -expm1f(-0.606531f * sg); }
;                             else if (type == 2) r = sigmoidf_(xv);
;                             else r = xv;
;                             v[4 * n + i] = (f16)r; }
.LBB0_965:
	v_mul_f32_e32 v62, 0xbfb8aa3b, v64
	v_exp_f32_e32 v62, v62
	s_nop 0
	v_min_f32_e32 v62, 0x7e800000, v62
	v_add_f32_e32 v62, 1.0, v62
	v_rcp_f32_e32 v65, v62
	s_nop 0
	v_fma_f32 v67, -v62, v65, 1.0
	v_fma_f32 v62, v67, v65, v65
	v_mul_f32_e32 v62, 0xbf1b459e, v62
	v_mul_f32_e32 v64, 0x3fb8aa3b, v62
	v_exp_f32_e32 v64, v64
	s_nop 0
	v_sub_f32_e32 v62, 1.0, v64
.LBB0_966:
	v_add_f32_e32 v64, v63, v35
	s_and_b64 vcc, exec, s[8:9]
	s_mov_b64 s[14:15], -1
	s_cbranch_vccnz .LBB0_970
	s_and_b64 vcc, exec, s[6:7]
	v_mov_b32_e32 v63, v64
	s_cbranch_vccnz .LBB0_969
	v_mul_f32_e32 v63, 0xbfb8aa3b, v64
	v_exp_f32_e32 v63, v63
	s_nop 0
	v_min_f32_e32 v63, 0x7e800000, v63
	v_add_f32_e32 v63, 1.0, v63
	v_rcp_f32_e32 v66, v63
	s_nop 0
	v_fma_f32 v68, -v63, v66, 1.0
	v_fma_f32 v63, v68, v66, v66

; __device__ __forceinline__ float sigmoidf_(float x) { return 1.0f / (1.0f + __expf(-x)); }
;     __device__ __forceinline__ void operator()(const f32x4 (&acc)[2][2][4][2], const Unit& u, int wr, int wc, int fr, int fq) const {
;     ...
;                         for (int i = 0; i < 4; ++i) { float xv = acc[ai][bj][m][n][i] + bv[bj][n][i]; float r;
;                             if (type < 2) { const float sg = sigmoidf_(xv); r = -expm1f(-0.606531f * sg); }
;                             else if (type == 2) r = sigmoidf_(xv);
;                             else r = xv;
;                             v[4 * n + i] = (f16)r; }
.LBB0_971:
	v_mul_f32_e32 v63, 0xbfb8aa3b, v64
	v_exp_f32_e32 v63, v63
	s_nop 0
	v_min_f32_e32 v63, 0x7e800000, v63
	v_add_f32_e32 v63, 1.0, v63
	v_rcp_f32_e32 v65, v63
	s_nop 0
	v_fma_f32 v67, -v63, v65, 1.0
	v_fma_f32 v63, v67, v65, v65
	v_mul_f32_e32 v63, 0xbf1b459e, v63
	v_mul_f32_e32 v64, 0x3fb8aa3b, v63
	v_exp_f32_e32 v64, v64
	s_nop 0
	v_sub_f32_e32 v63, 1.0, v64
.LBB0_972:
	v_add_f32_e32 v56, v56, v28
	s_and_b64 vcc, exec, s[8:9]
	s_mov_b64 s[14:15], -1
	s_cbranch_vccnz .LBB0_976
	s_and_b64 vcc, exec, s[6:7]
	v_mov_b32_e32 v64, v56
	s_cbranch_vccnz .LBB0_975
	v_mul_f32_e32 v64, 0xbfb8aa3b, v56
	v_exp_f32_e32 v64, v64
	s_nop 0
	v_min_f32_e32 v64, 0x7e800000, v64
	v_add_f32_e32 v64, 1.0, v64
	v_rcp_f32_e32 v66, v64
	s_nop 0
	v_fma_f32 v68, -v64, v66, 1.0
	v_fma_f32 v64, v68, v66, v66

; __device__ __forceinline__ float sigmoidf_(float x) { return 1.0f / (1.0f + __expf(-x)); }
;     __device__ __forceinline__ void operator()(const f32x4 (&acc)[2][2][4][2], const Unit& u, int wr, int wc, int fr, int fq) const {
;     ...
;                         for (int i = 0; i < 4; ++i) { float xv = acc[ai][bj][m][n][i] + bv[bj][n][i]; float r;
;                             if (type < 2) { const float sg = sigmoidf_(xv); r = -expm1f(-0.606531f * sg); }
;                             else if (type == 2) r = sigmoidf_(xv);
;                             else r = xv;
;                             v[4 * n + i] = (f16)r; }
.LBB0_977:
	v_mul_f32_e32 v56, 0xbfb8aa3b, v56
	v_exp_f32_e32 v56, v56
	s_nop 0
	v_min_f32_e32 v56, 0x7e800000, v56
	v_add_f32_e32 v56, 1.0, v56
	v_rcp_f32_e32 v65, v56
	s_nop 0
	v_fma_f32 v67, -v56, v65, 1.0
	v_fma_f32 v56, v67, v65, v65
	v_mul_f32_e32 v56, 0xbf1b459e, v56
	v_mul_f32_e32 v64, 0x3fb8aa3b, v56
	v_exp_f32_e32 v64, v64
	s_nop 0
	v_sub_f32_e32 v64, 1.0, v64
.LBB0_978:
	v_add_f32_e32 v56, v57, v29
	s_and_b64 vcc, exec, s[8:9]
	s_mov_b64 s[14:15], -1
	s_cbranch_vccnz .LBB0_982
	s_and_b64 vcc, exec, s[6:7]
	v_mov_b32_e32 v65, v56
	s_cbranch_vccnz .LBB0_981
	v_mul_f32_e32 v57, 0xbfb8aa3b, v56
	v_exp_f32_e32 v57, v57
	s_nop 0
	v_min_f32_e32 v57, 0x7e800000, v57
	v_add_f32_e32 v57, 1.0, v57
	v_rcp_f32_e32 v66, v57
	s_nop 0
	v_fma_f32 v68, -v57, v66, 1.0
	v_fma_f32 v65, v68, v66, v66

; __device__ __forceinline__ float sigmoidf_(float x) { return 1.0f / (1.0f + __expf(-x)); }
;     __device__ __forceinline__ void operator()(const f32x4 (&acc)[2][2][4][2], const Unit& u, int wr, int wc, int fr, int fq) const {
;     ...
;                         for (int i = 0; i < 4; ++i) { float xv = acc[ai][bj][m][n][i] + bv[bj][n][i]; float r;
;                             if (type < 2) { const float sg = sigmoidf_(xv); r = -expm1f(-0.606531f * sg); }
;                             else if (type == 2) r = sigmoidf_(xv);
;                             else r = xv;
;                             v[4 * n + i] = (f16)r; }
.LBB0_983:
	v_mul_f32_e32 v56, 0xbfb8aa3b, v56
	v_exp_f32_e32 v56, v56
	s_nop 0
	v_min_f32_e32 v56, 0x7e800000, v56
	v_add_f32_e32 v56, 1.0, v56
	v_rcp_f32_e32 v65, v56
	s_nop 0
	v_fma_f32 v67, -v56, v65, 1.0
	v_fma_f32 v56, v67, v65, v65
	v_mul_f32_e32 v56, 0xbf1b459e, v56
	v_mul_f32_e32 v57, 0x3fb8aa3b, v56
	v_exp_f32_e32 v57, v57
	s_nop 0
	v_sub_f32_e32 v65, 1.0, v57
.LBB0_984:
	v_add_f32_e32 v56, v58, v30
	s_and_b64 vcc, exec, s[8:9]
	s_mov_b64 s[14:15], -1
	s_cbranch_vccnz .LBB0_988
	s_and_b64 vcc, exec, s[6:7]
	v_mov_b32_e32 v58, v56
	s_cbranch_vccnz .LBB0_987
	v_mul_f32_e32 v57, 0xbfb8aa3b, v56
	v_exp_f32_e32 v57, v57
	s_nop 0
	v_min_f32_e32 v57, 0x7e800000, v57
	v_add_f32_e32 v57, 1.0, v57
	v_rcp_f32_e32 v66, v57
	s_nop 0
	v_fma_f32 v68, -v57, v66, 1.0
	v_fma_f32 v58, v68, v66, v66

; __device__ __forceinline__ float sigmoidf_(float x) { return 1.0f / (1.0f + __expf(-x)); }
;     __device__ __forceinline__ void operator()(const f32x4 (&acc)[2][2][4][2], const Unit& u, int wr, int wc, int fr, int fq) const {
;     ...
;                         for (int i = 0; i < 4; ++i) { float xv = acc[ai][bj][m][n][i] + bv[bj][n][i]; float r;
;                             if (type < 2) { const float sg = sigmoidf_(xv); r = -expm1f(-0.606531f * sg); }
;                             else if (type == 2) r = sigmoidf_(xv);
;                             else r = xv;
;                             v[4 * n + i] = (f16)r; }
.LBB0_989:
	v_mul_f32_e32 v56, 0xbfb8aa3b, v56
	v_exp_f32_e32 v56, v56
	s_nop 0
	v_min_f32_e32 v56, 0x7e800000, v56
	v_add_f32_e32 v56, 1.0, v56
	v_rcp_f32_e32 v58, v56
	s_nop 0
	v_fma_f32 v67, -v56, v58, 1.0
	v_fma_f32 v56, v67, v58, v58
	v_mul_f32_e32 v56, 0xbf1b459e, v56
	v_mul_f32_e32 v57, 0x3fb8aa3b, v56
	v_exp_f32_e32 v57, v57
	s_nop 0
	v_sub_f32_e32 v58, 1.0, v57
.LBB0_990:
	v_add_f32_e32 v56, v59, v31
	s_and_b64 vcc, exec, s[8:9]
	s_mov_b64 s[14:15], -1
	s_cbranch_vccnz .LBB0_994
	s_and_b64 vcc, exec, s[6:7]
	v_mov_b32_e32 v59, v56
	s_cbranch_vccnz .LBB0_993
	v_mul_f32_e32 v57, 0xbfb8aa3b, v56
	v_exp_f32_e32 v57, v57
	s_nop 0
	v_min_f32_e32 v57, 0x7e800000, v57
	v_add_f32_e32 v57, 1.0, v57
	v_rcp_f32_e32 v66, v57
	s_nop 0
	v_fma_f32 v68, -v57, v66, 1.0
	v_fma_f32 v59, v68, v66, v66

; __device__ __forceinline__ float sigmoidf_(float x) { return 1.0f / (1.0f + __expf(-x)); }
;     __device__ __forceinline__ void operator()(const f32x4 (&acc)[2][2][4][2], const Unit& u, int wr, int wc, int fr, int fq) const {
;     ...
;                         for (int i = 0; i < 4; ++i) { float xv = acc[ai][bj][m][n][i] + bv[bj][n][i]; float r;
;                             if (type < 2) { const float sg = sigmoidf_(xv); r = -expm1f(-0.606531f * sg); }
;                             else if (type == 2) r = sigmoidf_(xv);
;                             else r = xv;
;                             v[4 * n + i] = (f16)r; }
;                     *(f16x8*)(rowp + bj * 128) = v; } }
.LBB0_995:
	v_mul_f32_e32 v56, 0xbfb8aa3b, v56
	v_exp_f32_e32 v56, v56
	s_nop 0
	v_min_f32_e32 v56, 0x7e800000, v56
	v_add_f32_e32 v56, 1.0, v56
	v_rcp_f32_e32 v59, v56
	s_nop 0
	v_fma_f32 v67, -v56, v59, 1.0
	v_fma_f32 v56, v67, v59, v59
	v_mul_f32_e32 v56, 0xbf1b459e, v56
	v_mul_f32_e32 v57, 0x3fb8aa3b, v56
	v_exp_f32_e32 v57, v57
	s_nop 0
	v_sub_f32_e32 v59, 1.0, v57
.LBB0_996:
	v_lshlrev_b64 v[56:57], 13, v[138:139]
	v_lshl_add_u64 v[56:57], s[28:29], 0, v[56:57]
	v_lshl_add_u64 v[56:57], v[136:137], 1, v[56:57]
	v_cvt_pk_f16_f32 v67, v58, v59
	v_add_co_u32_e32 v58, vcc, 0x120000, v56
	v_cvt_pk_f16_f32 v66, v64, v65
	v_cvt_pk_f16_f32 v65, v62, v63
	v_cvt_pk_f16_f32 v64, v60, v61
	v_addc_co_u32_e32 v59, vcc, 0, v57, vcc
	global_store_dwordx4 v[58:59], v[64:67], off
	v_add_f32_e32 v58, v52, v20
	s_and_b64 vcc, exec, s[8:9]
	s_mov_b64 s[14:15], -1
	s_cbranch_vccnz .LBB0_1000
	s_and_b64 vcc, exec, s[6:7]
	v_mov_b32_e32 v52, v58
	s_cbranch_vccnz .LBB0_999
	v_mul_f32_e32 v52, 0xbfb8aa3b, v58
	v_exp_f32_e32 v52, v52
	s_nop 0
	v_min_f32_e32 v52, 0x7e800000, v52
	v_add_f32_e32 v52, 1.0, v52
	v_rcp_f32_e32 v60, v52
	s_nop 0
	v_fma_f32 v62, -v52, v60, 1.0
	v_fma_f32 v52, v62, v60, v60

; __device__ __forceinline__ float sigmoidf_(float x) { return 1.0f / (1.0f + __expf(-x)); }
;     __device__ __forceinline__ void operator()(const f32x4 (&acc)[2][2][4][2], const Unit& u, int wr, int wc, int fr, int fq) const {
;     ...
;                         for (int i = 0; i < 4; ++i) { float xv = acc[ai][bj][m][n][i] + bv[bj][n][i]; float r;
;                             if (type < 2) { const float sg = sigmoidf_(xv); r = -expm1f(-0.606531f * sg); }
;                             else if (type == 2) r = sigmoidf_(xv);
;                             else r = xv;
;                             v[4 * n + i] = (f16)r; }
.LBB0_1001:
	v_mul_f32_e32 v52, 0xbfb8aa3b, v58
	v_exp_f32_e32 v52, v52
	s_nop 0
	v_min_f32_e32 v52, 0x7e800000, v52
	v_add_f32_e32 v52, 1.0, v52
	v_rcp_f32_e32 v59, v52
	s_nop 0
	v_fma_f32 v61, -v52, v59, 1.0
	v_fma_f32 v52, v61, v59, v59
	v_mul_f32_e32 v52, 0xbf1b459e, v52
	v_mul_f32_e32 v58, 0x3fb8aa3b, v52
	v_exp_f32_e32 v58, v58
	s_nop 0
	v_sub_f32_e32 v52, 1.0, v58
.LBB0_1002:
	v_add_f32_e32 v58, v53, v21
	s_and_b64 vcc, exec, s[8:9]
	s_mov_b64 s[14:15], -1
	s_cbranch_vccnz .LBB0_1006
	s_and_b64 vcc, exec, s[6:7]
	v_mov_b32_e32 v53, v58
	s_cbranch_vccnz .LBB0_1005
	v_mul_f32_e32 v53, 0xbfb8aa3b, v58
	v_exp_f32_e32 v53, v53
	s_nop 0
	v_min_f32_e32 v53, 0x7e800000, v53
	v_add_f32_e32 v53, 1.0, v53
	v_rcp_f32_e32 v60, v53
	s_nop 0
	v_fma_f32 v62, -v53, v60, 1.0
	v_fma_f32 v53, v62, v60, v60

; __device__ __forceinline__ float sigmoidf_(float x) { return 1.0f / (1.0f + __expf(-x)); }
;     __device__ __forceinline__ void operator()(const f32x4 (&acc)[2][2][4][2], const Unit& u, int wr, int wc, int fr, int fq) const {
;     ...
;                         for (int i = 0; i < 4; ++i) { float xv = acc[ai][bj][m][n][i] + bv[bj][n][i]; float r;
;                             if (type < 2) { const float sg = sigmoidf_(xv); r = -expm1f(-0.606531f * sg); }
;                             else if (type == 2) r = sigmoidf_(xv);
;                             else r = xv;
;                             v[4 * n + i] = (f16)r; }
.LBB0_1007:
	v_mul_f32_e32 v53, 0xbfb8aa3b, v58
	v_exp_f32_e32 v53, v53
	s_nop 0
	v_min_f32_e32 v53, 0x7e800000, v53
	v_add_f32_e32 v53, 1.0, v53
	v_rcp_f32_e32 v59, v53
	s_nop 0
	v_fma_f32 v61, -v53, v59, 1.0
	v_fma_f32 v53, v61, v59, v59
	v_mul_f32_e32 v53, 0xbf1b459e, v53
	v_mul_f32_e32 v58, 0x3fb8aa3b, v53
	v_exp_f32_e32 v58, v58
	s_nop 0
	v_sub_f32_e32 v53, 1.0, v58
.LBB0_1008:
	v_add_f32_e32 v58, v54, v22
	s_and_b64 vcc, exec, s[8:9]
	s_mov_b64 s[14:15], -1
	s_cbranch_vccnz .LBB0_1012
	s_and_b64 vcc, exec, s[6:7]
	v_mov_b32_e32 v54, v58
	s_cbranch_vccnz .LBB0_1011
	v_mul_f32_e32 v54, 0xbfb8aa3b, v58
	v_exp_f32_e32 v54, v54
	s_nop 0
	v_min_f32_e32 v54, 0x7e800000, v54
	v_add_f32_e32 v54, 1.0, v54
	v_rcp_f32_e32 v60, v54
	s_nop 0
	v_fma_f32 v62, -v54, v60, 1.0
	v_fma_f32 v54, v62, v60, v60

; __device__ __forceinline__ float sigmoidf_(float x) { return 1.0f / (1.0f + __expf(-x)); }
;     __device__ __forceinline__ void operator()(const f32x4 (&acc)[2][2][4][2], const Unit& u, int wr, int wc, int fr, int fq) const {
;     ...
;                         for (int i = 0; i < 4; ++i) { float xv = acc[ai][bj][m][n][i] + bv[bj][n][i]; float r;
;                             if (type < 2) { const float sg = sigmoidf_(xv); r = -expm1f(-0.606531f * sg); }
;                             else if (type == 2) r = sigmoidf_(xv);
;                             else r = xv;
;                             v[4 * n + i] = (f16)r; }
.LBB0_1013:
	v_mul_f32_e32 v54, 0xbfb8aa3b, v58
	v_exp_f32_e32 v54, v54
	s_nop 0
	v_min_f32_e32 v54, 0x7e800000, v54
	v_add_f32_e32 v54, 1.0, v54
	v_rcp_f32_e32 v59, v54
	s_nop 0
	v_fma_f32 v61, -v54, v59, 1.0
	v_fma_f32 v54, v61, v59, v59
	v_mul_f32_e32 v54, 0xbf1b459e, v54
	v_mul_f32_e32 v58, 0x3fb8aa3b, v54
	v_exp_f32_e32 v58, v58
	s_nop 0
	v_sub_f32_e32 v54, 1.0, v58
.LBB0_1014:
	v_add_f32_e32 v58, v55, v23
	s_and_b64 vcc, exec, s[8:9]
	s_mov_b64 s[14:15], -1
	s_cbranch_vccnz .LBB0_1018
	s_and_b64 vcc, exec, s[6:7]
	v_mov_b32_e32 v55, v58
	s_cbranch_vccnz .LBB0_1017
	v_mul_f32_e32 v55, 0xbfb8aa3b, v58
	v_exp_f32_e32 v55, v55
	s_nop 0
	v_min_f32_e32 v55, 0x7e800000, v55
	v_add_f32_e32 v55, 1.0, v55
	v_rcp_f32_e32 v60, v55
	s_nop 0
	v_fma_f32 v62, -v55, v60, 1.0
	v_fma_f32 v55, v62, v60, v60

; __device__ __forceinline__ float sigmoidf_(float x) { return 1.0f / (1.0f + __expf(-x)); }
;     __device__ __forceinline__ void operator()(const f32x4 (&acc)[2][2][4][2], const Unit& u, int wr, int wc, int fr, int fq) const {
;     ...
;                         for (int i = 0; i < 4; ++i) { float xv = acc[ai][bj][m][n][i] + bv[bj][n][i]; float r;
;                             if (type < 2) { const float sg = sigmoidf_(xv); r = -expm1f(-0.606531f * sg); }
;                             else if (type == 2) r = sigmoidf_(xv);
;                             else r = xv;
;                             v[4 * n + i] = (f16)r; }
.LBB0_1019:
	v_mul_f32_e32 v55, 0xbfb8aa3b, v58
	v_exp_f32_e32 v55, v55
	s_nop 0
	v_min_f32_e32 v55, 0x7e800000, v55
	v_add_f32_e32 v55, 1.0, v55
	v_rcp_f32_e32 v59, v55
	s_nop 0
	v_fma_f32 v61, -v55, v59, 1.0
	v_fma_f32 v55, v61, v59, v59
	v_mul_f32_e32 v55, 0xbf1b459e, v55
	v_mul_f32_e32 v58, 0x3fb8aa3b, v55
	v_exp_f32_e32 v58, v58
	s_nop 0
	v_sub_f32_e32 v55, 1.0, v58
.LBB0_1020:
	v_add_f32_e32 v58, v48, v12
	s_and_b64 vcc, exec, s[8:9]
	s_mov_b64 s[14:15], -1
	s_cbranch_vccnz .LBB0_1024
	s_and_b64 vcc, exec, s[6:7]
	v_mov_b32_e32 v48, v58
	s_cbranch_vccnz .LBB0_1023
	v_mul_f32_e32 v48, 0xbfb8aa3b, v58
	v_exp_f32_e32 v48, v48
	s_nop 0
	v_min_f32_e32 v48, 0x7e800000, v48
	v_add_f32_e32 v48, 1.0, v48
	v_rcp_f32_e32 v60, v48
	s_nop 0
	v_fma_f32 v62, -v48, v60, 1.0
	v_fma_f32 v48, v62, v60, v60

; __device__ __forceinline__ float sigmoidf_(float x) { return 1.0f / (1.0f + __expf(-x)); }
;     __device__ __forceinline__ void operator()(const f32x4 (&acc)[2][2][4][2], const Unit& u, int wr, int wc, int fr, int fq) const {
;     ...
;                         for (int i = 0; i < 4; ++i) { float xv = acc[ai][bj][m][n][i] + bv[bj][n][i]; float r;
;                             if (type < 2) { const float sg = sigmoidf_(xv); r = -expm1f(-0.606531f * sg); }
;                             else if (type == 2) r = sigmoidf_(xv);
;                             else r = xv;
;                             v[4 * n + i] = (f16)r; }
.LBB0_1025:
	v_mul_f32_e32 v48, 0xbfb8aa3b, v58
	v_exp_f32_e32 v48, v48
	s_nop 0
	v_min_f32_e32 v48, 0x7e800000, v48
	v_add_f32_e32 v48, 1.0, v48
	v_rcp_f32_e32 v59, v48
	s_nop 0
	v_fma_f32 v61, -v48, v59, 1.0
	v_fma_f32 v48, v61, v59, v59
	v_mul_f32_e32 v48, 0xbf1b459e, v48
	v_mul_f32_e32 v58, 0x3fb8aa3b, v48
	v_exp_f32_e32 v58, v58
	s_nop 0
	v_sub_f32_e32 v48, 1.0, v58
.LBB0_1026:
	v_add_f32_e32 v58, v49, v13
	s_and_b64 vcc, exec, s[8:9]
	s_mov_b64 s[14:15], -1
	s_cbranch_vccnz .LBB0_1030
	s_and_b64 vcc, exec, s[6:7]
	v_mov_b32_e32 v49, v58
	s_cbranch_vccnz .LBB0_1029
	v_mul_f32_e32 v49, 0xbfb8aa3b, v58
	v_exp_f32_e32 v49, v49
	s_nop 0
	v_min_f32_e32 v49, 0x7e800000, v49
	v_add_f32_e32 v49, 1.0, v49
	v_rcp_f32_e32 v60, v49
	s_nop 0
	v_fma_f32 v62, -v49, v60, 1.0
	v_fma_f32 v49, v62, v60, v60

; __device__ __forceinline__ float sigmoidf_(float x) { return 1.0f / (1.0f + __expf(-x)); }
;     __device__ __forceinline__ void operator()(const f32x4 (&acc)[2][2][4][2], const Unit& u, int wr, int wc, int fr, int fq) const {
;     ...
;                         for (int i = 0; i < 4; ++i) { float xv = acc[ai][bj][m][n][i] + bv[bj][n][i]; float r;
;                             if (type < 2) { const float sg = sigmoidf_(xv); r = -expm1f(-0.606531f * sg); }
;                             else if (type == 2) r = sigmoidf_(xv);
;                             else r = xv;
;                             v[4 * n + i] = (f16)r; }
.LBB0_1031:
	v_mul_f32_e32 v49, 0xbfb8aa3b, v58
	v_exp_f32_e32 v49, v49
	s_nop 0
	v_min_f32_e32 v49, 0x7e800000, v49
	v_add_f32_e32 v49, 1.0, v49
	v_rcp_f32_e32 v59, v49
	s_nop 0
	v_fma_f32 v61, -v49, v59, 1.0
	v_fma_f32 v49, v61, v59, v59
	v_mul_f32_e32 v49, 0xbf1b459e, v49
	v_mul_f32_e32 v58, 0x3fb8aa3b, v49
	v_exp_f32_e32 v58, v58
	s_nop 0
	v_sub_f32_e32 v49, 1.0, v58
.LBB0_1032:
	v_add_f32_e32 v58, v50, v14
	s_and_b64 vcc, exec, s[8:9]
	s_mov_b64 s[14:15], -1
	s_cbranch_vccnz .LBB0_1036
	s_and_b64 vcc, exec, s[6:7]
	v_mov_b32_e32 v50, v58
	s_cbranch_vccnz .LBB0_1035
	v_mul_f32_e32 v50, 0xbfb8aa3b, v58
	v_exp_f32_e32 v50, v50
	s_nop 0
	v_min_f32_e32 v50, 0x7e800000, v50
	v_add_f32_e32 v50, 1.0, v50
	v_rcp_f32_e32 v60, v50
	s_nop 0
	v_fma_f32 v62, -v50, v60, 1.0
	v_fma_f32 v50, v62, v60, v60

; __device__ __forceinline__ float sigmoidf_(float x) { return 1.0f / (1.0f + __expf(-x)); }
;     __device__ __forceinline__ void operator()(const f32x4 (&acc)[2][2][4][2], const Unit& u, int wr, int wc, int fr, int fq) const {
;     ...
;                         for (int i = 0; i < 4; ++i) { float xv = acc[ai][bj][m][n][i] + bv[bj][n][i]; float r;
;                             if (type < 2) { const float sg = sigmoidf_(xv); r = -expm1f(-0.606531f * sg); }
;                             else if (type == 2) r = sigmoidf_(xv);
;                             else r = xv;
;                             v[4 * n + i] = (f16)r; }
.LBB0_1037:
	v_mul_f32_e32 v50, 0xbfb8aa3b, v58
	v_exp_f32_e32 v50, v50
	s_nop 0
	v_min_f32_e32 v50, 0x7e800000, v50
	v_add_f32_e32 v50, 1.0, v50
	v_rcp_f32_e32 v59, v50
	s_nop 0
	v_fma_f32 v61, -v50, v59, 1.0
	v_fma_f32 v50, v61, v59, v59
	v_mul_f32_e32 v50, 0xbf1b459e, v50
	v_mul_f32_e32 v58, 0x3fb8aa3b, v50
	v_exp_f32_e32 v58, v58
	s_nop 0
	v_sub_f32_e32 v50, 1.0, v58
.LBB0_1038:
	v_add_f32_e32 v51, v51, v15
	s_and_b64 vcc, exec, s[8:9]
	s_mov_b64 s[14:15], -1
	s_cbranch_vccnz .LBB0_1042
	s_and_b64 vcc, exec, s[6:7]
	v_mov_b32_e32 v58, v51
	s_cbranch_vccnz .LBB0_1041
	v_mul_f32_e32 v58, 0xbfb8aa3b, v51
	v_exp_f32_e32 v58, v58
	s_nop 0
	v_min_f32_e32 v58, 0x7e800000, v58
	v_add_f32_e32 v58, 1.0, v58
	v_rcp_f32_e32 v60, v58
	s_nop 0
	v_fma_f32 v62, -v58, v60, 1.0
	v_fma_f32 v58, v62, v60, v60

; __device__ __forceinline__ float sigmoidf_(float x) { return 1.0f / (1.0f + __expf(-x)); }
;     __device__ __forceinline__ void operator()(const f32x4 (&acc)[2][2][4][2], const Unit& u, int wr, int wc, int fr, int fq) const {
;     ...
;                         for (int i = 0; i < 4; ++i) { float xv = acc[ai][bj][m][n][i] + bv[bj][n][i]; float r;
;                             if (type < 2) { const float sg = sigmoidf_(xv); r = -expm1f(-0.606531f * sg); }
;                             else if (type == 2) r = sigmoidf_(xv);
;                             else r = xv;
;                             v[4 * n + i] = (f16)r; }
;                     *(f16x8*)(rowp + bj * 128) = v; } }
.LBB0_1043:
	v_mul_f32_e32 v51, 0xbfb8aa3b, v51
	v_exp_f32_e32 v51, v51
	s_nop 0
	v_min_f32_e32 v51, 0x7e800000, v51
	v_add_f32_e32 v51, 1.0, v51
	v_rcp_f32_e32 v59, v51
	s_nop 0
	v_fma_f32 v61, -v51, v59, 1.0
	v_fma_f32 v51, v61, v59, v59
	v_mul_f32_e32 v51, 0xbf1b459e, v51
	v_mul_f32_e32 v58, 0x3fb8aa3b, v51
	v_exp_f32_e32 v58, v58
	s_nop 0
	v_sub_f32_e32 v58, 1.0, v58
.LBB0_1044:
	s_mov_b64 s[2:3], 0x120000
	v_lshl_add_u64 v[56:57], v[56:57], 0, s[2:3]
	v_cvt_pk_f16_f32 v51, v50, v58
	v_cvt_pk_f16_f32 v50, v48, v49
	v_cvt_pk_f16_f32 v49, v54, v55
	v_cvt_pk_f16_f32 v48, v52, v53
	global_store_dwordx4 v[56:57], v[48:51], off offset:256
	s_and_b64 vcc, exec, s[8:9]
	s_mov_b64 s[14:15], -1
	v_add_f32_e32 v48, v44, v32
	s_cbranch_vccnz .LBB0_1048
	s_and_b64 vcc, exec, s[6:7]
	v_mov_b32_e32 v44, v48
	s_cbranch_vccnz .LBB0_1047
	v_mul_f32_e32 v44, 0xbfb8aa3b, v48
	v_exp_f32_e32 v44, v44
	s_nop 0
	v_min_f32_e32 v44, 0x7e800000, v44
	v_add_f32_e32 v44, 1.0, v44
	v_rcp_f32_e32 v50, v44
	s_nop 0
	v_fma_f32 v52, -v44, v50, 1.0
	v_fma_f32 v44, v52, v50, v50

; __device__ __forceinline__ float sigmoidf_(float x) { return 1.0f / (1.0f + __expf(-x)); }
;     __device__ __forceinline__ void operator()(const f32x4 (&acc)[2][2][4][2], const Unit& u, int wr, int wc, int fr, int fq) const {
;     ...
;                         for (int i = 0; i < 4; ++i) { float xv = acc[ai][bj][m][n][i] + bv[bj][n][i]; float r;
;                             if (type < 2) { const float sg = sigmoidf_(xv); r = -expm1f(-0.606531f * sg); }
;                             else if (type == 2) r = sigmoidf_(xv);
;                             else r = xv;
;                             v[4 * n + i] = (f16)r; }
.LBB0_1049:
	v_mul_f32_e32 v44, 0xbfb8aa3b, v48
	v_exp_f32_e32 v44, v44
	s_nop 0
	v_min_f32_e32 v44, 0x7e800000, v44
	v_add_f32_e32 v44, 1.0, v44
	v_rcp_f32_e32 v49, v44
	s_nop 0
	v_fma_f32 v51, -v44, v49, 1.0
	v_fma_f32 v44, v51, v49, v49
	v_mul_f32_e32 v44, 0xbf1b459e, v44
	v_mul_f32_e32 v48, 0x3fb8aa3b, v44
	v_exp_f32_e32 v48, v48
	s_nop 0
	v_sub_f32_e32 v44, 1.0, v48
.LBB0_1050:
	v_add_f32_e32 v48, v45, v33
	s_and_b64 vcc, exec, s[8:9]
	s_mov_b64 s[14:15], -1
	s_cbranch_vccnz .LBB0_1054
	s_and_b64 vcc, exec, s[6:7]
	v_mov_b32_e32 v45, v48
	s_cbranch_vccnz .LBB0_1053
	v_mul_f32_e32 v45, 0xbfb8aa3b, v48
	v_exp_f32_e32 v45, v45
	s_nop 0
	v_min_f32_e32 v45, 0x7e800000, v45
	v_add_f32_e32 v45, 1.0, v45
	v_rcp_f32_e32 v50, v45
	s_nop 0
	v_fma_f32 v52, -v45, v50, 1.0
	v_fma_f32 v45, v52, v50, v50

; __device__ __forceinline__ float sigmoidf_(float x) { return 1.0f / (1.0f + __expf(-x)); }
;     __device__ __forceinline__ void operator()(const f32x4 (&acc)[2][2][4][2], const Unit& u, int wr, int wc, int fr, int fq) const {
;     ...
;         for (int ai = 0; ai < 2; ++ai)
; #pragma unroll
;             for (int m = 0; m < 4; ++m) { f16* rowp = O + (size_t)(row0 + ai * 128 + m * 16) * 4096 + col0;
; #pragma unroll
;                 for (int bj = 0; bj < 2; ++bj) { f16x8 v;
; #pragma unroll
;                     for (int n = 0; n < 2; ++n)
; #pragma unroll
;                         for (int i = 0; i < 4; ++i) { float xv = acc[ai][bj][m][n][i] + bv[bj][n][i]; float r;
;                             if (type < 2) { const float sg = sigmoidf_(xv); r = -expm1f(-0.606531f * sg); }
;                             else if (type == 2) r = sigmoidf_(xv);
;                             else r = xv;
;                             v[4 * n + i] = (f16)r; }
;                     *(f16x8*)(rowp + bj * 128) = v; } }
.LBB0_1055:
	v_mul_f32_e32 v45, 0xbfb8aa3b, v48
	v_exp_f32_e32 v45, v45
	s_nop 0
	v_min_f32_e32 v45, 0x7e800000, v45
	v_add_f32_e32 v45, 1.0, v45
	v_rcp_f32_e32 v49, v45
	s_nop 0
	v_fma_f32 v51, -v45, v49, 1.0
	v_fma_f32 v45, v51, v49, v49
	v_mul_f32_e32 v45, 0xbf1b459e, v45
	v_mul_f32_e32 v48, 0x3fb8aa3b, v45
	v_exp_f32_e32 v48, v48
	s_nop 0
	v_sub_f32_e32 v45, 1.0, v48
.LBB0_1056:
	v_add_f32_e32 v48, v46, v34
	s_and_b64 vcc, exec, s[8:9]
	s_mov_b64 s[14:15], -1
	s_cbranch_vccnz .LBB0_1060
	s_and_b64 vcc, exec, s[6:7]
	v_mov_b32_e32 v46, v48
	s_cbranch_vccnz .LBB0_1059
	v_mul_f32_e32 v46, 0xbfb8aa3b, v48
	v_exp_f32_e32 v46, v46
	s_nop 0
	v_min_f32_e32 v46, 0x7e800000, v46
	v_add_f32_e32 v46, 1.0, v46
	v_rcp_f32_e32 v50, v46
	s_nop 0
	v_fma_f32 v52, -v46, v50, 1.0
	v_fma_f32 v46, v52, v50, v50

; __device__ __forceinline__ float sigmoidf_(float x) { return 1.0f / (1.0f + __expf(-x)); }
;     __device__ __forceinline__ void operator()(const f32x4 (&acc)[2][2][4][2], const Unit& u, int wr, int wc, int fr, int fq) const {
;     ...
;         for (int ai = 0; ai < 2; ++ai)
; #pragma unroll
;             for (int m = 0; m < 4; ++m) { f16* rowp = O + (size_t)(row0 + ai * 128 + m * 16) * 4096 + col0;
; #pragma unroll
;                 for (int bj = 0; bj < 2; ++bj) { f16x8 v;
; #pragma unroll
;                     for (int n = 0; n < 2; ++n)
; #pragma unroll
;                         for (int i = 0; i < 4; ++i) { float xv = acc[ai][bj][m][n][i] + bv[bj][n][i]; float r;
;                             if (type < 2) { const float sg = sigmoidf_(xv); r = -expm1f(-0.606531f * sg); }
;                             else if (type == 2) r = sigmoidf_(xv);
;                             else r = xv;
;                             v[4 * n + i] = (f16)r; }
;                     *(f16x8*)(rowp + bj * 128) = v; } }
.LBB0_1061:
	v_mul_f32_e32 v46, 0xbfb8aa3b, v48
	v_exp_f32_e32 v46, v46
	s_nop 0
	v_min_f32_e32 v46, 0x7e800000, v46
	v_add_f32_e32 v46, 1.0, v46
	v_rcp_f32_e32 v49, v46
	s_nop 0
	v_fma_f32 v51, -v46, v49, 1.0
	v_fma_f32 v46, v51, v49, v49
	v_mul_f32_e32 v46, 0xbf1b459e, v46
	v_mul_f32_e32 v48, 0x3fb8aa3b, v46
	v_exp_f32_e32 v48, v48
	s_nop 0
	v_sub_f32_e32 v46, 1.0, v48
.LBB0_1062:
	v_add_f32_e32 v48, v47, v35
	s_and_b64 vcc, exec, s[8:9]
	s_mov_b64 s[14:15], -1
	s_cbranch_vccnz .LBB0_1066
	s_and_b64 vcc, exec, s[6:7]
	v_mov_b32_e32 v47, v48
	s_cbranch_vccnz .LBB0_1065
	v_mul_f32_e32 v47, 0xbfb8aa3b, v48
	v_exp_f32_e32 v47, v47
	s_nop 0
	v_min_f32_e32 v47, 0x7e800000, v47
	v_add_f32_e32 v47, 1.0, v47
	v_rcp_f32_e32 v50, v47
	s_nop 0
	v_fma_f32 v52, -v47, v50, 1.0
	v_fma_f32 v47, v52, v50, v50

; __device__ __forceinline__ float sigmoidf_(float x) { return 1.0f / (1.0f + __expf(-x)); }
;     __device__ __forceinline__ void operator()(const f32x4 (&acc)[2][2][4][2], const Unit& u, int wr, int wc, int fr, int fq) const {
;     ...
;         for (int ai = 0; ai < 2; ++ai)
; #pragma unroll
;             for (int m = 0; m < 4; ++m) { f16* rowp = O + (size_t)(row0 + ai * 128 + m * 16) * 4096 + col0;
; #pragma unroll
;                 for (int bj = 0; bj < 2; ++bj) { f16x8 v;
; #pragma unroll
;                     for (int n = 0; n < 2; ++n)
; #pragma unroll
;                         for (int i = 0; i < 4; ++i) { float xv = acc[ai][bj][m][n][i] + bv[bj][n][i]; float r;
;                             if (type < 2) { const float sg = sigmoidf_(xv); r = -expm1f(-0.606531f * sg); }
;                             else if (type == 2) r = sigmoidf_(xv);
;                             else r = xv;
;                             v[4 * n + i] = (f16)r; }
;                     *(f16x8*)(rowp + bj * 128) = v; } }
.LBB0_1067:
	v_mul_f32_e32 v47, 0xbfb8aa3b, v48
	v_exp_f32_e32 v47, v47
	s_nop 0
	v_min_f32_e32 v47, 0x7e800000, v47
	v_add_f32_e32 v47, 1.0, v47
	v_rcp_f32_e32 v49, v47
	s_nop 0
	v_fma_f32 v51, -v47, v49, 1.0
	v_fma_f32 v47, v51, v49, v49
	v_mul_f32_e32 v47, 0xbf1b459e, v47
	v_mul_f32_e32 v48, 0x3fb8aa3b, v47
	v_exp_f32_e32 v48, v48
	s_nop 0
	v_sub_f32_e32 v47, 1.0, v48
.LBB0_1068:
	v_add_f32_e32 v40, v40, v28
	s_and_b64 vcc, exec, s[8:9]
	s_mov_b64 s[14:15], -1
	s_cbranch_vccnz .LBB0_1072
	s_and_b64 vcc, exec, s[6:7]
	v_mov_b32_e32 v48, v40
	s_cbranch_vccnz .LBB0_1071
	v_mul_f32_e32 v48, 0xbfb8aa3b, v40
	v_exp_f32_e32 v48, v48
	s_nop 0
	v_min_f32_e32 v48, 0x7e800000, v48
	v_add_f32_e32 v48, 1.0, v48
	v_rcp_f32_e32 v50, v48
	s_nop 0
	v_fma_f32 v52, -v48, v50, 1.0
	v_fma_f32 v48, v52, v50, v50

; __device__ __forceinline__ float sigmoidf_(float x) { return 1.0f / (1.0f + __expf(-x)); }
;     __device__ __forceinline__ void operator()(const f32x4 (&acc)[2][2][4][2], const Unit& u, int wr, int wc, int fr, int fq) const {
;     ...
;         for (int ai = 0; ai < 2; ++ai)
; #pragma unroll
;             for (int m = 0; m < 4; ++m) { f16* rowp = O + (size_t)(row0 + ai * 128 + m * 16) * 4096 + col0;
; #pragma unroll
;                 for (int bj = 0; bj < 2; ++bj) { f16x8 v;
; #pragma unroll
;                     for (int n = 0; n < 2; ++n)
; #pragma unroll
;                         for (int i = 0; i < 4; ++i) { float xv = acc[ai][bj][m][n][i] + bv[bj][n][i]; float r;
;                             if (type < 2) { const float sg = sigmoidf_(xv); r = -expm1f(-0.606531f * sg); }
;                             else if (type == 2) r = sigmoidf_(xv);
;                             else r = xv;
;                             v[4 * n + i] = (f16)r; }
;                     *(f16x8*)(rowp + bj * 128) = v; } }
.LBB0_1073:
	v_mul_f32_e32 v40, 0xbfb8aa3b, v40
	v_exp_f32_e32 v40, v40
	s_nop 0
	v_min_f32_e32 v40, 0x7e800000, v40
	v_add_f32_e32 v40, 1.0, v40
	v_rcp_f32_e32 v49, v40
	s_nop 0
	v_fma_f32 v51, -v40, v49, 1.0
	v_fma_f32 v40, v51, v49, v49
	v_mul_f32_e32 v40, 0xbf1b459e, v40
	v_mul_f32_e32 v48, 0x3fb8aa3b, v40
	v_exp_f32_e32 v48, v48
	s_nop 0
	v_sub_f32_e32 v48, 1.0, v48
.LBB0_1074:
	v_add_f32_e32 v40, v41, v29
	s_and_b64 vcc, exec, s[8:9]
	s_mov_b64 s[14:15], -1
	s_cbranch_vccnz .LBB0_1078
	s_and_b64 vcc, exec, s[6:7]
	v_mov_b32_e32 v49, v40
	s_cbranch_vccnz .LBB0_1077
	v_mul_f32_e32 v41, 0xbfb8aa3b, v40
	v_exp_f32_e32 v41, v41
	s_nop 0
	v_min_f32_e32 v41, 0x7e800000, v41
	v_add_f32_e32 v41, 1.0, v41
	v_rcp_f32_e32 v50, v41
	s_nop 0
	v_fma_f32 v52, -v41, v50, 1.0
	v_fma_f32 v49, v52, v50, v50

; __device__ __forceinline__ float sigmoidf_(float x) { return 1.0f / (1.0f + __expf(-x)); }
;     __device__ __forceinline__ void operator()(const f32x4 (&acc)[2][2][4][2], const Unit& u, int wr, int wc, int fr, int fq) const {
;     ...
;         for (int ai = 0; ai < 2; ++ai)
; #pragma unroll
;             for (int m = 0; m < 4; ++m) { f16* rowp = O + (size_t)(row0 + ai * 128 + m * 16) * 4096 + col0;
; #pragma unroll
;                 for (int bj = 0; bj < 2; ++bj) { f16x8 v;
; #pragma unroll
;                     for (int n = 0; n < 2; ++n)
; #pragma unroll
;                         for (int i = 0; i < 4; ++i) { float xv = acc[ai][bj][m][n][i] + bv[bj][n][i]; float r;
;                             if (type < 2) { const float sg = sigmoidf_(xv); r = -expm1f(-0.606531f * sg); }
;                             else if (type == 2) r = sigmoidf_(xv);
;                             else r = xv;
;                             v[4 * n + i] = (f16)r; }
;                     *(f16x8*)(rowp + bj * 128) = v; } }
.LBB0_1079:
	v_mul_f32_e32 v40, 0xbfb8aa3b, v40
	v_exp_f32_e32 v40, v40
	s_nop 0
	v_min_f32_e32 v40, 0x7e800000, v40
	v_add_f32_e32 v40, 1.0, v40
	v_rcp_f32_e32 v49, v40
	s_nop 0
	v_fma_f32 v51, -v40, v49, 1.0
	v_fma_f32 v40, v51, v49, v49
	v_mul_f32_e32 v40, 0xbf1b459e, v40
	v_mul_f32_e32 v41, 0x3fb8aa3b, v40
	v_exp_f32_e32 v41, v41
	s_nop 0
	v_sub_f32_e32 v49, 1.0, v41
.LBB0_1080:
	v_add_f32_e32 v40, v42, v30
	s_and_b64 vcc, exec, s[8:9]
	s_mov_b64 s[14:15], -1
	s_cbranch_vccnz .LBB0_1084
	s_and_b64 vcc, exec, s[6:7]
	v_mov_b32_e32 v42, v40
	s_cbranch_vccnz .LBB0_1083
	v_mul_f32_e32 v41, 0xbfb8aa3b, v40
	v_exp_f32_e32 v41, v41
	s_nop 0
	v_min_f32_e32 v41, 0x7e800000, v41
	v_add_f32_e32 v41, 1.0, v41
	v_rcp_f32_e32 v50, v41
	s_nop 0
	v_fma_f32 v52, -v41, v50, 1.0
	v_fma_f32 v42, v52, v50, v50

; __device__ __forceinline__ float sigmoidf_(float x) { return 1.0f / (1.0f + __expf(-x)); }
;     __device__ __forceinline__ void operator()(const f32x4 (&acc)[2][2][4][2], const Unit& u, int wr, int wc, int fr, int fq) const {
;     ...
;         for (int ai = 0; ai < 2; ++ai)
; #pragma unroll
;             for (int m = 0; m < 4; ++m) { f16* rowp = O + (size_t)(row0 + ai * 128 + m * 16) * 4096 + col0;
; #pragma unroll
;                 for (int bj = 0; bj < 2; ++bj) { f16x8 v;
; #pragma unroll
;                     for (int n = 0; n < 2; ++n)
; #pragma unroll
;                         for (int i = 0; i < 4; ++i) { float xv = acc[ai][bj][m][n][i] + bv[bj][n][i]; float r;
;                             if (type < 2) { const float sg = sigmoidf_(xv); r = -expm1f(-0.606531f * sg); }
;                             else if (type == 2) r = sigmoidf_(xv);
;                             else r = xv;
;                             v[4 * n + i] = (f16)r; }
;                     *(f16x8*)(rowp + bj * 128) = v; } }
.LBB0_1085:
	v_mul_f32_e32 v40, 0xbfb8aa3b, v40
	v_exp_f32_e32 v40, v40
	s_nop 0
	v_min_f32_e32 v40, 0x7e800000, v40
	v_add_f32_e32 v40, 1.0, v40
	v_rcp_f32_e32 v42, v40
	s_nop 0
	v_fma_f32 v51, -v40, v42, 1.0
	v_fma_f32 v40, v51, v42, v42
	v_mul_f32_e32 v40, 0xbf1b459e, v40
	v_mul_f32_e32 v41, 0x3fb8aa3b, v40
	v_exp_f32_e32 v41, v41
	s_nop 0
	v_sub_f32_e32 v42, 1.0, v41
.LBB0_1086:
	v_add_f32_e32 v40, v43, v31
	s_and_b64 vcc, exec, s[8:9]
	s_mov_b64 s[14:15], -1
	s_cbranch_vccnz .LBB0_1090
	s_and_b64 vcc, exec, s[6:7]
	v_mov_b32_e32 v43, v40
	s_cbranch_vccnz .LBB0_1089
	v_mul_f32_e32 v41, 0xbfb8aa3b, v40
	v_exp_f32_e32 v41, v41
	s_nop 0
	v_min_f32_e32 v41, 0x7e800000, v41
	v_add_f32_e32 v41, 1.0, v41
	v_rcp_f32_e32 v50, v41
	s_nop 0
	v_fma_f32 v52, -v41, v50, 1.0
	v_fma_f32 v43, v52, v50, v50

; __device__ __forceinline__ float sigmoidf_(float x) { return 1.0f / (1.0f + __expf(-x)); }
;     __device__ __forceinline__ void operator()(const f32x4 (&acc)[2][2][4][2], const Unit& u, int wr, int wc, int fr, int fq) const {
;     ...
;         for (int ai = 0; ai < 2; ++ai)
; #pragma unroll
;             for (int m = 0; m < 4; ++m) { f16* rowp = O + (size_t)(row0 + ai * 128 + m * 16) * 4096 + col0;
; #pragma unroll
;                 for (int bj = 0; bj < 2; ++bj) { f16x8 v;
; #pragma unroll
;                     for (int n = 0; n < 2; ++n)
; #pragma unroll
;                         for (int i = 0; i < 4; ++i) { float xv = acc[ai][bj][m][n][i] + bv[bj][n][i]; float r;
;                             if (type < 2) { const float sg = sigmoidf_(xv); r = -expm1f(-0.606531f * sg); }
;                             else if (type == 2) r = sigmoidf_(xv);
;                             else r = xv;
;                             v[4 * n + i] = (f16)r; }
;                     *(f16x8*)(rowp + bj * 128) = v; } }
.LBB0_1091:
	v_mul_f32_e32 v40, 0xbfb8aa3b, v40
	v_exp_f32_e32 v40, v40
	s_nop 0
	v_min_f32_e32 v40, 0x7e800000, v40
	v_add_f32_e32 v40, 1.0, v40
	v_rcp_f32_e32 v43, v40
	s_nop 0
	v_fma_f32 v51, -v40, v43, 1.0
	v_fma_f32 v40, v51, v43, v43
	v_mul_f32_e32 v40, 0xbf1b459e, v40
	v_mul_f32_e32 v41, 0x3fb8aa3b, v40
	v_exp_f32_e32 v41, v41
	s_nop 0
	v_sub_f32_e32 v43, 1.0, v41
.LBB0_1092:
	v_lshlrev_b64 v[40:41], 13, v[138:139]
	v_lshl_add_u64 v[40:41], s[28:29], 0, v[40:41]
	v_lshl_add_u64 v[40:41], v[136:137], 1, v[40:41]
	v_cvt_pk_f16_f32 v51, v42, v43
	v_add_co_u32_e32 v42, vcc, 0x140000, v40
	v_cvt_pk_f16_f32 v50, v48, v49
	v_cvt_pk_f16_f32 v49, v46, v47
	v_cvt_pk_f16_f32 v48, v44, v45
	v_addc_co_u32_e32 v43, vcc, 0, v41, vcc
	global_store_dwordx4 v[42:43], v[48:51], off
	v_add_f32_e32 v42, v36, v20
	s_and_b64 vcc, exec, s[8:9]
	s_mov_b64 s[14:15], -1
	s_cbranch_vccnz .LBB0_1096
	s_and_b64 vcc, exec, s[6:7]
	v_mov_b32_e32 v36, v42
	s_cbranch_vccnz .LBB0_1095
	v_mul_f32_e32 v36, 0xbfb8aa3b, v42
	v_exp_f32_e32 v36, v36
	s_nop 0
	v_min_f32_e32 v36, 0x7e800000, v36
	v_add_f32_e32 v36, 1.0, v36
	v_rcp_f32_e32 v44, v36
	s_nop 0
	v_fma_f32 v46, -v36, v44, 1.0
	v_fma_f32 v36, v46, v44, v44

; __device__ __forceinline__ float sigmoidf_(float x) { return 1.0f / (1.0f + __expf(-x)); }
;     __device__ __forceinline__ void operator()(const f32x4 (&acc)[2][2][4][2], const Unit& u, int wr, int wc, int fr, int fq) const {
;     ...
;         for (int ai = 0; ai < 2; ++ai)
; #pragma unroll
;             for (int m = 0; m < 4; ++m) { f16* rowp = O + (size_t)(row0 + ai * 128 + m * 16) * 4096 + col0;
; #pragma unroll
;                 for (int bj = 0; bj < 2; ++bj) { f16x8 v;
; #pragma unroll
;                     for (int n = 0; n < 2; ++n)
; #pragma unroll
;                         for (int i = 0; i < 4; ++i) { float xv = acc[ai][bj][m][n][i] + bv[bj][n][i]; float r;
;                             if (type < 2) { const float sg = sigmoidf_(xv); r = -expm1f(-0.606531f * sg); }
;                             else if (type == 2) r = sigmoidf_(xv);
;                             else r = xv;
;                             v[4 * n + i] = (f16)r; }
;                     *(f16x8*)(rowp + bj * 128) = v; } }
.LBB0_1097:
	v_mul_f32_e32 v36, 0xbfb8aa3b, v42
	v_exp_f32_e32 v36, v36
	s_nop 0
	v_min_f32_e32 v36, 0x7e800000, v36
	v_add_f32_e32 v36, 1.0, v36
	v_rcp_f32_e32 v43, v36
	s_nop 0
	v_fma_f32 v45, -v36, v43, 1.0
	v_fma_f32 v36, v45, v43, v43
	v_mul_f32_e32 v36, 0xbf1b459e, v36
	v_mul_f32_e32 v42, 0x3fb8aa3b, v36
	v_exp_f32_e32 v42, v42
	s_nop 0
	v_sub_f32_e32 v36, 1.0, v42
.LBB0_1098:
	v_add_f32_e32 v42, v37, v21
	s_and_b64 vcc, exec, s[8:9]
	s_mov_b64 s[14:15], -1
	s_cbranch_vccnz .LBB0_1102
	s_and_b64 vcc, exec, s[6:7]
	v_mov_b32_e32 v37, v42
	s_cbranch_vccnz .LBB0_1101
	v_mul_f32_e32 v37, 0xbfb8aa3b, v42
	v_exp_f32_e32 v37, v37
	s_nop 0
	v_min_f32_e32 v37, 0x7e800000, v37
	v_add_f32_e32 v37, 1.0, v37
	v_rcp_f32_e32 v44, v37
	s_nop 0
	v_fma_f32 v46, -v37, v44, 1.0
	v_fma_f32 v37, v46, v44, v44

; __device__ __forceinline__ float sigmoidf_(float x) { return 1.0f / (1.0f + __expf(-x)); }
;     __device__ __forceinline__ void operator()(const f32x4 (&acc)[2][2][4][2], const Unit& u, int wr, int wc, int fr, int fq) const {
;     ...
;         for (int ai = 0; ai < 2; ++ai)
; #pragma unroll
;             for (int m = 0; m < 4; ++m) { f16* rowp = O + (size_t)(row0 + ai * 128 + m * 16) * 4096 + col0;
; #pragma unroll
;                 for (int bj = 0; bj < 2; ++bj) { f16x8 v;
; #pragma unroll
;                     for (int n = 0; n < 2; ++n)
; #pragma unroll
;                         for (int i = 0; i < 4; ++i) { float xv = acc[ai][bj][m][n][i] + bv[bj][n][i]; float r;
;                             if (type < 2) { const float sg = sigmoidf_(xv); r = -expm1f(-0.606531f * sg); }
;                             else if (type == 2) r = sigmoidf_(xv);
;                             else r = xv;
;                             v[4 * n + i] = (f16)r; }
;                     *(f16x8*)(rowp + bj * 128) = v; } }
.LBB0_1103:
	v_mul_f32_e32 v37, 0xbfb8aa3b, v42
	v_exp_f32_e32 v37, v37
	s_nop 0
	v_min_f32_e32 v37, 0x7e800000, v37
	v_add_f32_e32 v37, 1.0, v37
	v_rcp_f32_e32 v43, v37
	s_nop 0
	v_fma_f32 v45, -v37, v43, 1.0
	v_fma_f32 v37, v45, v43, v43
	v_mul_f32_e32 v37, 0xbf1b459e, v37
	v_mul_f32_e32 v42, 0x3fb8aa3b, v37
	v_exp_f32_e32 v42, v42
	s_nop 0
	v_sub_f32_e32 v37, 1.0, v42
.LBB0_1104:
	v_add_f32_e32 v42, v38, v22
	s_and_b64 vcc, exec, s[8:9]
	s_mov_b64 s[14:15], -1
	s_cbranch_vccnz .LBB0_1108
	s_and_b64 vcc, exec, s[6:7]
	v_mov_b32_e32 v38, v42
	s_cbranch_vccnz .LBB0_1107
	v_mul_f32_e32 v38, 0xbfb8aa3b, v42
	v_exp_f32_e32 v38, v38
	s_nop 0
	v_min_f32_e32 v38, 0x7e800000, v38
	v_add_f32_e32 v38, 1.0, v38
	v_rcp_f32_e32 v44, v38
	s_nop 0
	v_fma_f32 v46, -v38, v44, 1.0
	v_fma_f32 v38, v46, v44, v44

; __device__ __forceinline__ float sigmoidf_(float x) { return 1.0f / (1.0f + __expf(-x)); }
;     __device__ __forceinline__ void operator()(const f32x4 (&acc)[2][2][4][2], const Unit& u, int wr, int wc, int fr, int fq) const {
;     ...
;         for (int ai = 0; ai < 2; ++ai)
; #pragma unroll
;             for (int m = 0; m < 4; ++m) { f16* rowp = O + (size_t)(row0 + ai * 128 + m * 16) * 4096 + col0;
; #pragma unroll
;                 for (int bj = 0; bj < 2; ++bj) { f16x8 v;
; #pragma unroll
;                     for (int n = 0; n < 2; ++n)
; #pragma unroll
;                         for (int i = 0; i < 4; ++i) { float xv = acc[ai][bj][m][n][i] + bv[bj][n][i]; float r;
;                             if (type < 2) { const float sg = sigmoidf_(xv); r = -expm1f(-0.606531f * sg); }
;                             else if (type == 2) r = sigmoidf_(xv);
;                             else r = xv;
;                             v[4 * n + i] = (f16)r; }
;                     *(f16x8*)(rowp + bj * 128) = v; } }
.LBB0_1109:
	v_mul_f32_e32 v38, 0xbfb8aa3b, v42
	v_exp_f32_e32 v38, v38
	s_nop 0
	v_min_f32_e32 v38, 0x7e800000, v38
	v_add_f32_e32 v38, 1.0, v38
	v_rcp_f32_e32 v43, v38
	s_nop 0
	v_fma_f32 v45, -v38, v43, 1.0
	v_fma_f32 v38, v45, v43, v43
	v_mul_f32_e32 v38, 0xbf1b459e, v38
	v_mul_f32_e32 v42, 0x3fb8aa3b, v38
	v_exp_f32_e32 v42, v42
	s_nop 0
	v_sub_f32_e32 v38, 1.0, v42
.LBB0_1110:
	v_add_f32_e32 v42, v39, v23
	s_and_b64 vcc, exec, s[8:9]
	s_mov_b64 s[14:15], -1
	s_cbranch_vccnz .LBB0_1114
	s_and_b64 vcc, exec, s[6:7]
	v_mov_b32_e32 v39, v42
	s_cbranch_vccnz .LBB0_1113
	v_mul_f32_e32 v39, 0xbfb8aa3b, v42
	v_exp_f32_e32 v39, v39
	s_nop 0
	v_min_f32_e32 v39, 0x7e800000, v39
	v_add_f32_e32 v39, 1.0, v39
	v_rcp_f32_e32 v44, v39
	s_nop 0
	v_fma_f32 v46, -v39, v44, 1.0
	v_fma_f32 v39, v46, v44, v44

; __device__ __forceinline__ float sigmoidf_(float x) { return 1.0f / (1.0f + __expf(-x)); }
;     __device__ __forceinline__ void operator()(const f32x4 (&acc)[2][2][4][2], const Unit& u, int wr, int wc, int fr, int fq) const {
;     ...
;         for (int ai = 0; ai < 2; ++ai)
; #pragma unroll
;             for (int m = 0; m < 4; ++m) { f16* rowp = O + (size_t)(row0 + ai * 128 + m * 16) * 4096 + col0;
; #pragma unroll
;                 for (int bj = 0; bj < 2; ++bj) { f16x8 v;
; #pragma unroll
;                     for (int n = 0; n < 2; ++n)
; #pragma unroll
;                         for (int i = 0; i < 4; ++i) { float xv = acc[ai][bj][m][n][i] + bv[bj][n][i]; float r;
;                             if (type < 2) { const float sg = sigmoidf_(xv); r = -expm1f(-0.606531f * sg); }
;                             else if (type == 2) r = sigmoidf_(xv);
;                             else r = xv;
;                             v[4 * n + i] = (f16)r; }
;                     *(f16x8*)(rowp + bj * 128) = v; } }
.LBB0_1115:
	v_mul_f32_e32 v39, 0xbfb8aa3b, v42
	v_exp_f32_e32 v39, v39
	s_nop 0
	v_min_f32_e32 v39, 0x7e800000, v39
	v_add_f32_e32 v39, 1.0, v39
	v_rcp_f32_e32 v43, v39
	s_nop 0
	v_fma_f32 v45, -v39, v43, 1.0
	v_fma_f32 v39, v45, v43, v43
	v_mul_f32_e32 v39, 0xbf1b459e, v39
	v_mul_f32_e32 v42, 0x3fb8aa3b, v39
	v_exp_f32_e32 v42, v42
	s_nop 0
	v_sub_f32_e32 v39, 1.0, v42
.LBB0_1116:
	v_add_f32_e32 v42, v24, v12
	s_and_b64 vcc, exec, s[8:9]
	s_mov_b64 s[14:15], -1
	s_cbranch_vccnz .LBB0_1120
	s_and_b64 vcc, exec, s[6:7]
	v_mov_b32_e32 v24, v42
	s_cbranch_vccnz .LBB0_1119
	v_mul_f32_e32 v24, 0xbfb8aa3b, v42
	v_exp_f32_e32 v24, v24
	s_nop 0
	v_min_f32_e32 v24, 0x7e800000, v24
	v_add_f32_e32 v24, 1.0, v24
	v_rcp_f32_e32 v44, v24
	s_nop 0
	v_fma_f32 v46, -v24, v44, 1.0
	v_fma_f32 v24, v46, v44, v44

; __device__ __forceinline__ float sigmoidf_(float x) { return 1.0f / (1.0f + __expf(-x)); }
;     __device__ __forceinline__ void operator()(const f32x4 (&acc)[2][2][4][2], const Unit& u, int wr, int wc, int fr, int fq) const {
;     ...
;         for (int ai = 0; ai < 2; ++ai)
; #pragma unroll
;             for (int m = 0; m < 4; ++m) { f16* rowp = O + (size_t)(row0 + ai * 128 + m * 16) * 4096 + col0;
; #pragma unroll
;                 for (int bj = 0; bj < 2; ++bj) { f16x8 v;
; #pragma unroll
;                     for (int n = 0; n < 2; ++n)
; #pragma unroll
;                         for (int i = 0; i < 4; ++i) { float xv = acc[ai][bj][m][n][i] + bv[bj][n][i]; float r;
;                             if (type < 2) { const float sg = sigmoidf_(xv); r = -expm1f(-0.606531f * sg); }
;                             else if (type == 2) r = sigmoidf_(xv);
;                             else r = xv;
;                             v[4 * n + i] = (f16)r; }
;                     *(f16x8*)(rowp + bj * 128) = v; } }
.LBB0_1121:
	v_mul_f32_e32 v24, 0xbfb8aa3b, v42
	v_exp_f32_e32 v24, v24
	s_nop 0
	v_min_f32_e32 v24, 0x7e800000, v24
	v_add_f32_e32 v24, 1.0, v24
	v_rcp_f32_e32 v43, v24
	s_nop 0
	v_fma_f32 v45, -v24, v43, 1.0
	v_fma_f32 v24, v45, v43, v43
	v_mul_f32_e32 v24, 0xbf1b459e, v24
	v_mul_f32_e32 v42, 0x3fb8aa3b, v24
	v_exp_f32_e32 v42, v42
	s_nop 0
	v_sub_f32_e32 v24, 1.0, v42
.LBB0_1122:
	v_add_f32_e32 v42, v25, v13
	s_and_b64 vcc, exec, s[8:9]
	s_mov_b64 s[14:15], -1
	s_cbranch_vccnz .LBB0_1126
	s_and_b64 vcc, exec, s[6:7]
	v_mov_b32_e32 v25, v42
	s_cbranch_vccnz .LBB0_1125
	v_mul_f32_e32 v25, 0xbfb8aa3b, v42
	v_exp_f32_e32 v25, v25
	s_nop 0
	v_min_f32_e32 v25, 0x7e800000, v25
	v_add_f32_e32 v25, 1.0, v25
	v_rcp_f32_e32 v44, v25
	s_nop 0
	v_fma_f32 v46, -v25, v44, 1.0
	v_fma_f32 v25, v46, v44, v44

; __device__ __forceinline__ float sigmoidf_(float x) { return 1.0f / (1.0f + __expf(-x)); }
;     __device__ __forceinline__ void operator()(const f32x4 (&acc)[2][2][4][2], const Unit& u, int wr, int wc, int fr, int fq) const {
;     ...
;         for (int ai = 0; ai < 2; ++ai)
; #pragma unroll
;             for (int m = 0; m < 4; ++m) { f16* rowp = O + (size_t)(row0 + ai * 128 + m * 16) * 4096 + col0;
; #pragma unroll
;                 for (int bj = 0; bj < 2; ++bj) { f16x8 v;
; #pragma unroll
;                     for (int n = 0; n < 2; ++n)
; #pragma unroll
;                         for (int i = 0; i < 4; ++i) { float xv = acc[ai][bj][m][n][i] + bv[bj][n][i]; float r;
;                             if (type < 2) { const float sg = sigmoidf_(xv); r = -expm1f(-0.606531f * sg); }
;                             else if (type == 2) r = sigmoidf_(xv);
;                             else r = xv;
;                             v[4 * n + i] = (f16)r; }
;                     *(f16x8*)(rowp + bj * 128) = v; } }
.LBB0_1127:
	v_mul_f32_e32 v25, 0xbfb8aa3b, v42
	v_exp_f32_e32 v25, v25
	s_nop 0
	v_min_f32_e32 v25, 0x7e800000, v25
	v_add_f32_e32 v25, 1.0, v25
	v_rcp_f32_e32 v43, v25
	s_nop 0
	v_fma_f32 v45, -v25, v43, 1.0
	v_fma_f32 v25, v45, v43, v43
	v_mul_f32_e32 v25, 0xbf1b459e, v25
	v_mul_f32_e32 v42, 0x3fb8aa3b, v25
	v_exp_f32_e32 v42, v42
	s_nop 0
	v_sub_f32_e32 v25, 1.0, v42
.LBB0_1128:
	v_add_f32_e32 v42, v26, v14
	s_and_b64 vcc, exec, s[8:9]
	s_mov_b64 s[14:15], -1
	s_cbranch_vccnz .LBB0_1132
	s_and_b64 vcc, exec, s[6:7]
	v_mov_b32_e32 v26, v42
	s_cbranch_vccnz .LBB0_1131
	v_mul_f32_e32 v26, 0xbfb8aa3b, v42
	v_exp_f32_e32 v26, v26
	s_nop 0
	v_min_f32_e32 v26, 0x7e800000, v26
	v_add_f32_e32 v26, 1.0, v26
	v_rcp_f32_e32 v44, v26
	s_nop 0
	v_fma_f32 v46, -v26, v44, 1.0
	v_fma_f32 v26, v46, v44, v44

; __device__ __forceinline__ float sigmoidf_(float x) { return 1.0f / (1.0f + __expf(-x)); }
;     __device__ __forceinline__ void operator()(const f32x4 (&acc)[2][2][4][2], const Unit& u, int wr, int wc, int fr, int fq) const {
;     ...
;         for (int ai = 0; ai < 2; ++ai)
; #pragma unroll
;             for (int m = 0; m < 4; ++m) { f16* rowp = O + (size_t)(row0 + ai * 128 + m * 16) * 4096 + col0;
; #pragma unroll
;                 for (int bj = 0; bj < 2; ++bj) { f16x8 v;
; #pragma unroll
;                     for (int n = 0; n < 2; ++n)
; #pragma unroll
;                         for (int i = 0; i < 4; ++i) { float xv = acc[ai][bj][m][n][i] + bv[bj][n][i]; float r;
;                             if (type < 2) { const float sg = sigmoidf_(xv); r = -expm1f(-0.606531f * sg); }
;                             else if (type == 2) r = sigmoidf_(xv);
;                             else r = xv;
;                             v[4 * n + i] = (f16)r; }
;                     *(f16x8*)(rowp + bj * 128) = v; } }
.LBB0_1133:
	v_mul_f32_e32 v26, 0xbfb8aa3b, v42
	v_exp_f32_e32 v26, v26
	s_nop 0
	v_min_f32_e32 v26, 0x7e800000, v26
	v_add_f32_e32 v26, 1.0, v26
	v_rcp_f32_e32 v43, v26
	s_nop 0
	v_fma_f32 v45, -v26, v43, 1.0
	v_fma_f32 v26, v45, v43, v43
	v_mul_f32_e32 v26, 0xbf1b459e, v26
	v_mul_f32_e32 v42, 0x3fb8aa3b, v26
	v_exp_f32_e32 v42, v42
	s_nop 0
	v_sub_f32_e32 v26, 1.0, v42
.LBB0_1134:
	v_add_f32_e32 v27, v27, v15
	s_and_b64 vcc, exec, s[8:9]
	s_mov_b64 s[14:15], -1
	s_cbranch_vccnz .LBB0_1138
	s_and_b64 vcc, exec, s[6:7]
	v_mov_b32_e32 v42, v27
	s_cbranch_vccnz .LBB0_1137
	v_mul_f32_e32 v42, 0xbfb8aa3b, v27
	v_exp_f32_e32 v42, v42
	s_nop 0
	v_min_f32_e32 v42, 0x7e800000, v42
	v_add_f32_e32 v42, 1.0, v42
	v_rcp_f32_e32 v44, v42
	s_nop 0
	v_fma_f32 v46, -v42, v44, 1.0
	v_fma_f32 v42, v46, v44, v44

; __device__ __forceinline__ float sigmoidf_(float x) { return 1.0f / (1.0f + __expf(-x)); }
;     __device__ __forceinline__ void operator()(const f32x4 (&acc)[2][2][4][2], const Unit& u, int wr, int wc, int fr, int fq) const {
;     ...
;         for (int ai = 0; ai < 2; ++ai)
; #pragma unroll
;             for (int m = 0; m < 4; ++m) { f16* rowp = O + (size_t)(row0 + ai * 128 + m * 16) * 4096 + col0;
; #pragma unroll
;                 for (int bj = 0; bj < 2; ++bj) { f16x8 v;
; #pragma unroll
;                     for (int n = 0; n < 2; ++n)
; #pragma unroll
;                         for (int i = 0; i < 4; ++i) { float xv = acc[ai][bj][m][n][i] + bv[bj][n][i]; float r;
;                             if (type < 2) { const float sg = sigmoidf_(xv); r = -expm1f(-0.606531f * sg); }
;                             else if (type == 2) r = sigmoidf_(xv);
;                             else r = xv;
;                             v[4 * n + i] = (f16)r; }
;                     *(f16x8*)(rowp + bj * 128) = v; } }
.LBB0_1139:
	v_mul_f32_e32 v27, 0xbfb8aa3b, v27
	v_exp_f32_e32 v27, v27
	s_nop 0
	v_min_f32_e32 v27, 0x7e800000, v27
	v_add_f32_e32 v27, 1.0, v27
	v_rcp_f32_e32 v43, v27
	s_nop 0
	v_fma_f32 v45, -v27, v43, 1.0
	v_fma_f32 v27, v45, v43, v43
	v_mul_f32_e32 v27, 0xbf1b459e, v27
	v_mul_f32_e32 v42, 0x3fb8aa3b, v27
	v_exp_f32_e32 v42, v42
	s_nop 0
	v_sub_f32_e32 v42, 1.0, v42
.LBB0_1140:
	s_mov_b64 s[2:3], 0x140000
	v_lshl_add_u64 v[40:41], v[40:41], 0, s[2:3]
	v_cvt_pk_f16_f32 v27, v26, v42
	v_cvt_pk_f16_f32 v26, v24, v25
	v_cvt_pk_f16_f32 v25, v38, v39
	v_cvt_pk_f16_f32 v24, v36, v37
	global_store_dwordx4 v[40:41], v[24:27], off offset:256
	s_and_b64 vcc, exec, s[8:9]
	s_mov_b64 s[14:15], -1
	v_add_f32_e32 v24, v16, v32
	s_cbranch_vccnz .LBB0_1144
	s_and_b64 vcc, exec, s[6:7]
	v_mov_b32_e32 v16, v24
	s_cbranch_vccnz .LBB0_1143
	v_mul_f32_e32 v16, 0xbfb8aa3b, v24
	v_exp_f32_e32 v16, v16
	s_nop 0
	v_min_f32_e32 v16, 0x7e800000, v16
	v_add_f32_e32 v16, 1.0, v16
	v_rcp_f32_e32 v26, v16
	s_nop 0
	v_fma_f32 v32, -v16, v26, 1.0
	v_fma_f32 v16, v32, v26, v26

; __device__ __forceinline__ float sigmoidf_(float x) { return 1.0f / (1.0f + __expf(-x)); }
;     __device__ __forceinline__ void operator()(const f32x4 (&acc)[2][2][4][2], const Unit& u, int wr, int wc, int fr, int fq) const {
;     ...
;         for (int ai = 0; ai < 2; ++ai)
; #pragma unroll
;             for (int m = 0; m < 4; ++m) { f16* rowp = O + (size_t)(row0 + ai * 128 + m * 16) * 4096 + col0;
; #pragma unroll
;                 for (int bj = 0; bj < 2; ++bj) { f16x8 v;
; #pragma unroll
;                     for (int n = 0; n < 2; ++n)
; #pragma unroll
;                         for (int i = 0; i < 4; ++i) { float xv = acc[ai][bj][m][n][i] + bv[bj][n][i]; float r;
;                             if (type < 2) { const float sg = sigmoidf_(xv); r = -expm1f(-0.606531f * sg); }
;                             else if (type == 2) r = sigmoidf_(xv);
;                             else r = xv;
;                             v[4 * n + i] = (f16)r; }
;                     *(f16x8*)(rowp + bj * 128) = v; } }
.LBB0_1145:
	v_mul_f32_e32 v16, 0xbfb8aa3b, v24
	v_exp_f32_e32 v16, v16
	s_nop 0
	v_min_f32_e32 v16, 0x7e800000, v16
	v_add_f32_e32 v16, 1.0, v16
	v_rcp_f32_e32 v25, v16
	s_nop 0
	v_fma_f32 v27, -v16, v25, 1.0
	v_fma_f32 v16, v27, v25, v25
	v_mul_f32_e32 v16, 0xbf1b459e, v16
	v_mul_f32_e32 v24, 0x3fb8aa3b, v16
	v_exp_f32_e32 v24, v24
	s_nop 0
	v_sub_f32_e32 v16, 1.0, v24
.LBB0_1146:
	v_add_f32_e32 v24, v17, v33
	s_and_b64 vcc, exec, s[8:9]
	s_mov_b64 s[14:15], -1
	s_cbranch_vccnz .LBB0_1150
	s_and_b64 vcc, exec, s[6:7]
	v_mov_b32_e32 v17, v24
	s_cbranch_vccnz .LBB0_1149
	v_mul_f32_e32 v17, 0xbfb8aa3b, v24
	v_exp_f32_e32 v17, v17
	s_nop 0
	v_min_f32_e32 v17, 0x7e800000, v17
	v_add_f32_e32 v17, 1.0, v17
	v_rcp_f32_e32 v26, v17
	s_nop 0
	v_fma_f32 v32, -v17, v26, 1.0
	v_fma_f32 v17, v32, v26, v26

; __device__ __forceinline__ float sigmoidf_(float x) { return 1.0f / (1.0f + __expf(-x)); }
;     __device__ __forceinline__ void operator()(const f32x4 (&acc)[2][2][4][2], const Unit& u, int wr, int wc, int fr, int fq) const {
;     ...
;         for (int ai = 0; ai < 2; ++ai)
; #pragma unroll
;             for (int m = 0; m < 4; ++m) { f16* rowp = O + (size_t)(row0 + ai * 128 + m * 16) * 4096 + col0;
; #pragma unroll
;                 for (int bj = 0; bj < 2; ++bj) { f16x8 v;
; #pragma unroll
;                     for (int n = 0; n < 2; ++n)
; #pragma unroll
;                         for (int i = 0; i < 4; ++i) { float xv = acc[ai][bj][m][n][i] + bv[bj][n][i]; float r;
;                             if (type < 2) { const float sg = sigmoidf_(xv); r = -expm1f(-0.606531f * sg); }
;                             else if (type == 2) r = sigmoidf_(xv);
;                             else r = xv;
;                             v[4 * n + i] = (f16)r; }
;                     *(f16x8*)(rowp + bj * 128) = v; } }
.LBB0_1151:
	v_mul_f32_e32 v17, 0xbfb8aa3b, v24
	v_exp_f32_e32 v17, v17
	s_nop 0
	v_min_f32_e32 v17, 0x7e800000, v17
	v_add_f32_e32 v17, 1.0, v17
	v_rcp_f32_e32 v25, v17
	s_nop 0
	v_fma_f32 v27, -v17, v25, 1.0
	v_fma_f32 v17, v27, v25, v25
	v_mul_f32_e32 v17, 0xbf1b459e, v17
	v_mul_f32_e32 v24, 0x3fb8aa3b, v17
	v_exp_f32_e32 v24, v24
	s_nop 0
	v_sub_f32_e32 v17, 1.0, v24
.LBB0_1152:
	v_add_f32_e32 v24, v18, v34
	s_and_b64 vcc, exec, s[8:9]
	s_mov_b64 s[14:15], -1
	s_cbranch_vccnz .LBB0_1156
	s_and_b64 vcc, exec, s[6:7]
	v_mov_b32_e32 v18, v24
	s_cbranch_vccnz .LBB0_1155
	v_mul_f32_e32 v18, 0xbfb8aa3b, v24
	v_exp_f32_e32 v18, v18
	s_nop 0
	v_min_f32_e32 v18, 0x7e800000, v18
	v_add_f32_e32 v18, 1.0, v18
	v_rcp_f32_e32 v26, v18
	s_nop 0
	v_fma_f32 v32, -v18, v26, 1.0
	v_fma_f32 v18, v32, v26, v26

; __device__ __forceinline__ float sigmoidf_(float x) { return 1.0f / (1.0f + __expf(-x)); }
;     __device__ __forceinline__ void operator()(const f32x4 (&acc)[2][2][4][2], const Unit& u, int wr, int wc, int fr, int fq) const {
;     ...
;         for (int ai = 0; ai < 2; ++ai)
; #pragma unroll
;             for (int m = 0; m < 4; ++m) { f16* rowp = O + (size_t)(row0 + ai * 128 + m * 16) * 4096 + col0;
; #pragma unroll
;                 for (int bj = 0; bj < 2; ++bj) { f16x8 v;
; #pragma unroll
;                     for (int n = 0; n < 2; ++n)
; #pragma unroll
;                         for (int i = 0; i < 4; ++i) { float xv = acc[ai][bj][m][n][i] + bv[bj][n][i]; float r;
;                             if (type < 2) { const float sg = sigmoidf_(xv); r = -expm1f(-0.606531f * sg); }
;                             else if (type == 2) r = sigmoidf_(xv);
;                             else r = xv;
;                             v[4 * n + i] = (f16)r; }
;                     *(f16x8*)(rowp + bj * 128) = v; } }
.LBB0_1157:
	v_mul_f32_e32 v18, 0xbfb8aa3b, v24
	v_exp_f32_e32 v18, v18
	s_nop 0
	v_min_f32_e32 v18, 0x7e800000, v18
	v_add_f32_e32 v18, 1.0, v18
	v_rcp_f32_e32 v25, v18
	s_nop 0
	v_fma_f32 v27, -v18, v25, 1.0
	v_fma_f32 v18, v27, v25, v25
	v_mul_f32_e32 v18, 0xbf1b459e, v18
	v_mul_f32_e32 v24, 0x3fb8aa3b, v18
	v_exp_f32_e32 v24, v24
	s_nop 0
	v_sub_f32_e32 v18, 1.0, v24
.LBB0_1158:
	v_add_f32_e32 v24, v19, v35
	s_and_b64 vcc, exec, s[8:9]
	s_mov_b64 s[14:15], -1
	s_cbranch_vccnz .LBB0_1162
	s_and_b64 vcc, exec, s[6:7]
	v_mov_b32_e32 v19, v24
	s_cbranch_vccnz .LBB0_1161
	v_mul_f32_e32 v19, 0xbfb8aa3b, v24
	v_exp_f32_e32 v19, v19
	s_nop 0
	v_min_f32_e32 v19, 0x7e800000, v19
	v_add_f32_e32 v19, 1.0, v19
	v_rcp_f32_e32 v26, v19
	s_nop 0
	v_fma_f32 v32, -v19, v26, 1.0
	v_fma_f32 v19, v32, v26, v26

; __device__ __forceinline__ float sigmoidf_(float x) { return 1.0f / (1.0f + __expf(-x)); }
;     __device__ __forceinline__ void operator()(const f32x4 (&acc)[2][2][4][2], const Unit& u, int wr, int wc, int fr, int fq) const {
;     ...
;         for (int ai = 0; ai < 2; ++ai)
; #pragma unroll
;             for (int m = 0; m < 4; ++m) { f16* rowp = O + (size_t)(row0 + ai * 128 + m * 16) * 4096 + col0;
; #pragma unroll
;                 for (int bj = 0; bj < 2; ++bj) { f16x8 v;
; #pragma unroll
;                     for (int n = 0; n < 2; ++n)
; #pragma unroll
;                         for (int i = 0; i < 4; ++i) { float xv = acc[ai][bj][m][n][i] + bv[bj][n][i]; float r;
;                             if (type < 2) { const float sg = sigmoidf_(xv); r = -expm1f(-0.606531f * sg); }
;                             else if (type == 2) r = sigmoidf_(xv);
;                             else r = xv;
;                             v[4 * n + i] = (f16)r; }
;                     *(f16x8*)(rowp + bj * 128) = v; } }
.LBB0_1163:
	v_mul_f32_e32 v19, 0xbfb8aa3b, v24
	v_exp_f32_e32 v19, v19
	s_nop 0
	v_min_f32_e32 v19, 0x7e800000, v19
	v_add_f32_e32 v19, 1.0, v19
	v_rcp_f32_e32 v25, v19
	s_nop 0
	v_fma_f32 v27, -v19, v25, 1.0
	v_fma_f32 v19, v27, v25, v25
	v_mul_f32_e32 v19, 0xbf1b459e, v19
	v_mul_f32_e32 v24, 0x3fb8aa3b, v19
	v_exp_f32_e32 v24, v24
	s_nop 0
	v_sub_f32_e32 v19, 1.0, v24
.LBB0_1164:
	v_add_f32_e32 v8, v8, v28
	s_and_b64 vcc, exec, s[8:9]
	s_mov_b64 s[14:15], -1
	s_cbranch_vccnz .LBB0_1168
	s_and_b64 vcc, exec, s[6:7]
	v_mov_b32_e32 v24, v8
	s_cbranch_vccnz .LBB0_1167
	v_mul_f32_e32 v24, 0xbfb8aa3b, v8
	v_exp_f32_e32 v24, v24
	s_nop 0
	v_min_f32_e32 v24, 0x7e800000, v24
	v_add_f32_e32 v24, 1.0, v24
	v_rcp_f32_e32 v26, v24
	s_nop 0
	v_fma_f32 v28, -v24, v26, 1.0
	v_fma_f32 v24, v28, v26, v26

; __device__ __forceinline__ float sigmoidf_(float x) { return 1.0f / (1.0f + __expf(-x)); }
;     __device__ __forceinline__ void operator()(const f32x4 (&acc)[2][2][4][2], const Unit& u, int wr, int wc, int fr, int fq) const {
;     ...
;         for (int ai = 0; ai < 2; ++ai)
; #pragma unroll
;             for (int m = 0; m < 4; ++m) { f16* rowp = O + (size_t)(row0 + ai * 128 + m * 16) * 4096 + col0;
; #pragma unroll
;                 for (int bj = 0; bj < 2; ++bj) { f16x8 v;
; #pragma unroll
;                     for (int n = 0; n < 2; ++n)
; #pragma unroll
;                         for (int i = 0; i < 4; ++i) { float xv = acc[ai][bj][m][n][i] + bv[bj][n][i]; float r;
;                             if (type < 2) { const float sg = sigmoidf_(xv); r = -expm1f(-0.606531f * sg); }
;                             else if (type == 2) r = sigmoidf_(xv);
;                             else r = xv;
;                             v[4 * n + i] = (f16)r; }
;                     *(f16x8*)(rowp + bj * 128) = v; } }
.LBB0_1169:
	v_mul_f32_e32 v8, 0xbfb8aa3b, v8
	v_exp_f32_e32 v8, v8
	s_nop 0
	v_min_f32_e32 v8, 0x7e800000, v8
	v_add_f32_e32 v8, 1.0, v8
	v_rcp_f32_e32 v25, v8
	s_nop 0
	v_fma_f32 v27, -v8, v25, 1.0
	v_fma_f32 v8, v27, v25, v25
	v_mul_f32_e32 v8, 0xbf1b459e, v8
	v_mul_f32_e32 v24, 0x3fb8aa3b, v8
	v_exp_f32_e32 v24, v24
	s_nop 0
	v_sub_f32_e32 v24, 1.0, v24
.LBB0_1170:
	v_add_f32_e32 v8, v9, v29
	s_and_b64 vcc, exec, s[8:9]
	s_mov_b64 s[14:15], -1
	s_cbranch_vccnz .LBB0_1174
	s_and_b64 vcc, exec, s[6:7]
	v_mov_b32_e32 v25, v8
	s_cbranch_vccnz .LBB0_1173
	v_mul_f32_e32 v9, 0xbfb8aa3b, v8
	v_exp_f32_e32 v9, v9
	s_nop 0
	v_min_f32_e32 v9, 0x7e800000, v9
	v_add_f32_e32 v9, 1.0, v9
	v_rcp_f32_e32 v26, v9
	s_nop 0
	v_fma_f32 v28, -v9, v26, 1.0
	v_fma_f32 v25, v28, v26, v26

; __device__ __forceinline__ float sigmoidf_(float x) { return 1.0f / (1.0f + __expf(-x)); }
;     __device__ __forceinline__ void operator()(const f32x4 (&acc)[2][2][4][2], const Unit& u, int wr, int wc, int fr, int fq) const {
;     ...
;         for (int ai = 0; ai < 2; ++ai)
; #pragma unroll
;             for (int m = 0; m < 4; ++m) { f16* rowp = O + (size_t)(row0 + ai * 128 + m * 16) * 4096 + col0;
; #pragma unroll
;                 for (int bj = 0; bj < 2; ++bj) { f16x8 v;
; #pragma unroll
;                     for (int n = 0; n < 2; ++n)
; #pragma unroll
;                         for (int i = 0; i < 4; ++i) { float xv = acc[ai][bj][m][n][i] + bv[bj][n][i]; float r;
;                             if (type < 2) { const float sg = sigmoidf_(xv); r = -expm1f(-0.606531f * sg); }
;                             else if (type == 2) r = sigmoidf_(xv);
;                             else r = xv;
;                             v[4 * n + i] = (f16)r; }
;                     *(f16x8*)(rowp + bj * 128) = v; } }
.LBB0_1175:
	v_mul_f32_e32 v8, 0xbfb8aa3b, v8
	v_exp_f32_e32 v8, v8
	s_nop 0
	v_min_f32_e32 v8, 0x7e800000, v8
	v_add_f32_e32 v8, 1.0, v8
	v_rcp_f32_e32 v25, v8
	s_nop 0
	v_fma_f32 v27, -v8, v25, 1.0
	v_fma_f32 v8, v27, v25, v25
	v_mul_f32_e32 v8, 0xbf1b459e, v8
	v_mul_f32_e32 v9, 0x3fb8aa3b, v8
	v_exp_f32_e32 v9, v9
	s_nop 0
	v_sub_f32_e32 v25, 1.0, v9
.LBB0_1176:
	v_add_f32_e32 v8, v10, v30
	s_and_b64 vcc, exec, s[8:9]
	s_mov_b64 s[14:15], -1
	s_cbranch_vccnz .LBB0_1180
	s_and_b64 vcc, exec, s[6:7]
	v_mov_b32_e32 v10, v8
	s_cbranch_vccnz .LBB0_1179
	v_mul_f32_e32 v9, 0xbfb8aa3b, v8
	v_exp_f32_e32 v9, v9
	s_nop 0
	v_min_f32_e32 v9, 0x7e800000, v9
	v_add_f32_e32 v9, 1.0, v9
	v_rcp_f32_e32 v26, v9
	s_nop 0
	v_fma_f32 v28, -v9, v26, 1.0
	v_fma_f32 v10, v28, v26, v26

; __device__ __forceinline__ float sigmoidf_(float x) { return 1.0f / (1.0f + __expf(-x)); }
;     __device__ __forceinline__ void operator()(const f32x4 (&acc)[2][2][4][2], const Unit& u, int wr, int wc, int fr, int fq) const {
;     ...
;         for (int ai = 0; ai < 2; ++ai)
; #pragma unroll
;             for (int m = 0; m < 4; ++m) { f16* rowp = O + (size_t)(row0 + ai * 128 + m * 16) * 4096 + col0;
; #pragma unroll
;                 for (int bj = 0; bj < 2; ++bj) { f16x8 v;
; #pragma unroll
;                     for (int n = 0; n < 2; ++n)
; #pragma unroll
;                         for (int i = 0; i < 4; ++i) { float xv = acc[ai][bj][m][n][i] + bv[bj][n][i]; float r;
;                             if (type < 2) { const float sg = sigmoidf_(xv); r = -expm1f(-0.606531f * sg); }
;                             else if (type == 2) r = sigmoidf_(xv);
;                             else r = xv;
;                             v[4 * n + i] = (f16)r; }
;                     *(f16x8*)(rowp + bj * 128) = v; } }
.LBB0_1181:
	v_mul_f32_e32 v8, 0xbfb8aa3b, v8
	v_exp_f32_e32 v8, v8
	s_nop 0
	v_min_f32_e32 v8, 0x7e800000, v8
	v_add_f32_e32 v8, 1.0, v8
	v_rcp_f32_e32 v10, v8
	s_nop 0
	v_fma_f32 v27, -v8, v10, 1.0
	v_fma_f32 v8, v27, v10, v10
	v_mul_f32_e32 v8, 0xbf1b459e, v8
	v_mul_f32_e32 v9, 0x3fb8aa3b, v8
	v_exp_f32_e32 v9, v9
	s_nop 0
	v_sub_f32_e32 v10, 1.0, v9
.LBB0_1182:
	v_add_f32_e32 v8, v11, v31
	s_and_b64 vcc, exec, s[8:9]
	s_mov_b64 s[14:15], -1
	s_cbranch_vccnz .LBB0_1186
	s_and_b64 vcc, exec, s[6:7]
	v_mov_b32_e32 v11, v8
	s_cbranch_vccnz .LBB0_1185
	v_mul_f32_e32 v9, 0xbfb8aa3b, v8
	v_exp_f32_e32 v9, v9
	s_nop 0
	v_min_f32_e32 v9, 0x7e800000, v9
	v_add_f32_e32 v9, 1.0, v9
	v_rcp_f32_e32 v26, v9
	s_nop 0
	v_fma_f32 v28, -v9, v26, 1.0
	v_fma_f32 v11, v28, v26, v26

; __device__ __forceinline__ float sigmoidf_(float x) { return 1.0f / (1.0f + __expf(-x)); }
;     __device__ __forceinline__ void operator()(const f32x4 (&acc)[2][2][4][2], const Unit& u, int wr, int wc, int fr, int fq) const {
;     ...
;         for (int ai = 0; ai < 2; ++ai)
; #pragma unroll
;             for (int m = 0; m < 4; ++m) { f16* rowp = O + (size_t)(row0 + ai * 128 + m * 16) * 4096 + col0;
; #pragma unroll
;                 for (int bj = 0; bj < 2; ++bj) { f16x8 v;
; #pragma unroll
;                     for (int n = 0; n < 2; ++n)
; #pragma unroll
;                         for (int i = 0; i < 4; ++i) { float xv = acc[ai][bj][m][n][i] + bv[bj][n][i]; float r;
;                             if (type < 2) { const float sg = sigmoidf_(xv); r = -expm1f(-0.606531f * sg); }
;                             else if (type == 2) r = sigmoidf_(xv);
;                             else r = xv;
;                             v[4 * n + i] = (f16)r; }
;                     *(f16x8*)(rowp + bj * 128) = v; } }
.LBB0_1187:
	v_mul_f32_e32 v8, 0xbfb8aa3b, v8
	v_exp_f32_e32 v8, v8
	s_nop 0
	v_min_f32_e32 v8, 0x7e800000, v8
	v_add_f32_e32 v8, 1.0, v8
	v_rcp_f32_e32 v11, v8
	s_nop 0
	v_fma_f32 v27, -v8, v11, 1.0
	v_fma_f32 v8, v27, v11, v11
	v_mul_f32_e32 v8, 0xbf1b459e, v8
	v_mul_f32_e32 v9, 0x3fb8aa3b, v8
	v_exp_f32_e32 v9, v9
	s_nop 0
	v_sub_f32_e32 v11, 1.0, v9
.LBB0_1188:
	v_lshlrev_b64 v[8:9], 13, v[138:139]
	v_lshl_add_u64 v[8:9], s[28:29], 0, v[8:9]
	v_lshl_add_u64 v[8:9], v[136:137], 1, v[8:9]
	v_cvt_pk_f16_f32 v27, v10, v11
	v_add_co_u32_e32 v10, vcc, 0x160000, v8
	v_cvt_pk_f16_f32 v26, v24, v25
	v_cvt_pk_f16_f32 v25, v18, v19
	v_cvt_pk_f16_f32 v24, v16, v17
	v_addc_co_u32_e32 v11, vcc, 0, v9, vcc
	global_store_dwordx4 v[10:11], v[24:27], off
	v_add_f32_e32 v10, v4, v20
	s_and_b64 vcc, exec, s[8:9]
	s_mov_b64 s[14:15], -1
	s_cbranch_vccnz .LBB0_1192
	s_and_b64 vcc, exec, s[6:7]
	v_mov_b32_e32 v4, v10
	s_cbranch_vccnz .LBB0_1191
	v_mul_f32_e32 v4, 0xbfb8aa3b, v10
	v_exp_f32_e32 v4, v4
	s_nop 0
	v_min_f32_e32 v4, 0x7e800000, v4
	v_add_f32_e32 v4, 1.0, v4
	v_rcp_f32_e32 v16, v4
	s_nop 0
	v_fma_f32 v18, -v4, v16, 1.0
	v_fma_f32 v4, v18, v16, v16

; __device__ __forceinline__ float sigmoidf_(float x) { return 1.0f / (1.0f + __expf(-x)); }
;     __device__ __forceinline__ void operator()(const f32x4 (&acc)[2][2][4][2], const Unit& u, int wr, int wc, int fr, int fq) const {
;     ...
;         for (int ai = 0; ai < 2; ++ai)
; #pragma unroll
;             for (int m = 0; m < 4; ++m) { f16* rowp = O + (size_t)(row0 + ai * 128 + m * 16) * 4096 + col0;
; #pragma unroll
;                 for (int bj = 0; bj < 2; ++bj) { f16x8 v;
; #pragma unroll
;                     for (int n = 0; n < 2; ++n)
; #pragma unroll
;                         for (int i = 0; i < 4; ++i) { float xv = acc[ai][bj][m][n][i] + bv[bj][n][i]; float r;
;                             if (type < 2) { const float sg = sigmoidf_(xv); r = -expm1f(-0.606531f * sg); }
;                             else if (type == 2) r = sigmoidf_(xv);
;                             else r = xv;
;                             v[4 * n + i] = (f16)r; }
;                     *(f16x8*)(rowp + bj * 128) = v; } }
.LBB0_1193:
	v_mul_f32_e32 v4, 0xbfb8aa3b, v10
	v_exp_f32_e32 v4, v4
	s_nop 0
	v_min_f32_e32 v4, 0x7e800000, v4
	v_add_f32_e32 v4, 1.0, v4
	v_rcp_f32_e32 v11, v4
	s_nop 0
	v_fma_f32 v17, -v4, v11, 1.0
	v_fma_f32 v4, v17, v11, v11
	v_mul_f32_e32 v4, 0xbf1b459e, v4
	v_mul_f32_e32 v10, 0x3fb8aa3b, v4
	v_exp_f32_e32 v10, v10
	s_nop 0
	v_sub_f32_e32 v4, 1.0, v10
.LBB0_1194:
	v_add_f32_e32 v10, v5, v21
	s_and_b64 vcc, exec, s[8:9]
	s_mov_b64 s[14:15], -1
	s_cbranch_vccnz .LBB0_1198
	s_and_b64 vcc, exec, s[6:7]
	v_mov_b32_e32 v5, v10
	s_cbranch_vccnz .LBB0_1197
	v_mul_f32_e32 v5, 0xbfb8aa3b, v10
	v_exp_f32_e32 v5, v5
	s_nop 0
	v_min_f32_e32 v5, 0x7e800000, v5
	v_add_f32_e32 v5, 1.0, v5
	v_rcp_f32_e32 v16, v5
	s_nop 0
	v_fma_f32 v18, -v5, v16, 1.0
	v_fma_f32 v5, v18, v16, v16

; __device__ __forceinline__ float sigmoidf_(float x) { return 1.0f / (1.0f + __expf(-x)); }
;     __device__ __forceinline__ void operator()(const f32x4 (&acc)[2][2][4][2], const Unit& u, int wr, int wc, int fr, int fq) const {
;     ...
;         for (int ai = 0; ai < 2; ++ai)
; #pragma unroll
;             for (int m = 0; m < 4; ++m) { f16* rowp = O + (size_t)(row0 + ai * 128 + m * 16) * 4096 + col0;
; #pragma unroll
;                 for (int bj = 0; bj < 2; ++bj) { f16x8 v;
; #pragma unroll
;                     for (int n = 0; n < 2; ++n)
; #pragma unroll
;                         for (int i = 0; i < 4; ++i) { float xv = acc[ai][bj][m][n][i] + bv[bj][n][i]; float r;
;                             if (type < 2) { const float sg = sigmoidf_(xv); r = -expm1f(-0.606531f * sg); }
;                             else if (type == 2) r = sigmoidf_(xv);
;                             else r = xv;
;                             v[4 * n + i] = (f16)r; }
;                     *(f16x8*)(rowp + bj * 128) = v; } }
.LBB0_1199:
	v_mul_f32_e32 v5, 0xbfb8aa3b, v10
	v_exp_f32_e32 v5, v5
	s_nop 0
	v_min_f32_e32 v5, 0x7e800000, v5
	v_add_f32_e32 v5, 1.0, v5
	v_rcp_f32_e32 v11, v5
	s_nop 0
	v_fma_f32 v17, -v5, v11, 1.0
	v_fma_f32 v5, v17, v11, v11
	v_mul_f32_e32 v5, 0xbf1b459e, v5
	v_mul_f32_e32 v10, 0x3fb8aa3b, v5
	v_exp_f32_e32 v10, v10
	s_nop 0
	v_sub_f32_e32 v5, 1.0, v10
.LBB0_1200:
	v_add_f32_e32 v10, v6, v22
	s_and_b64 vcc, exec, s[8:9]
	s_mov_b64 s[14:15], -1
	s_cbranch_vccnz .LBB0_1204
	s_and_b64 vcc, exec, s[6:7]
	v_mov_b32_e32 v6, v10
	s_cbranch_vccnz .LBB0_1203
	v_mul_f32_e32 v6, 0xbfb8aa3b, v10
	v_exp_f32_e32 v6, v6
	s_nop 0
	v_min_f32_e32 v6, 0x7e800000, v6
	v_add_f32_e32 v6, 1.0, v6
	v_rcp_f32_e32 v16, v6
	s_nop 0
	v_fma_f32 v18, -v6, v16, 1.0
	v_fma_f32 v6, v18, v16, v16

; __device__ __forceinline__ float sigmoidf_(float x) { return 1.0f / (1.0f + __expf(-x)); }
;     __device__ __forceinline__ void operator()(const f32x4 (&acc)[2][2][4][2], const Unit& u, int wr, int wc, int fr, int fq) const {
;     ...
;         for (int ai = 0; ai < 2; ++ai)
; #pragma unroll
;             for (int m = 0; m < 4; ++m) { f16* rowp = O + (size_t)(row0 + ai * 128 + m * 16) * 4096 + col0;
; #pragma unroll
;                 for (int bj = 0; bj < 2; ++bj) { f16x8 v;
; #pragma unroll
;                     for (int n = 0; n < 2; ++n)
; #pragma unroll
;                         for (int i = 0; i < 4; ++i) { float xv = acc[ai][bj][m][n][i] + bv[bj][n][i]; float r;
;                             if (type < 2) { const float sg = sigmoidf_(xv); r = -expm1f(-0.606531f * sg); }
;                             else if (type == 2) r = sigmoidf_(xv);
;                             else r = xv;
;                             v[4 * n + i] = (f16)r; }
;                     *(f16x8*)(rowp + bj * 128) = v; } }
.LBB0_1205:
	v_mul_f32_e32 v6, 0xbfb8aa3b, v10
	v_exp_f32_e32 v6, v6
	s_nop 0
	v_min_f32_e32 v6, 0x7e800000, v6
	v_add_f32_e32 v6, 1.0, v6
	v_rcp_f32_e32 v11, v6
	s_nop 0
	v_fma_f32 v17, -v6, v11, 1.0
	v_fma_f32 v6, v17, v11, v11
	v_mul_f32_e32 v6, 0xbf1b459e, v6
	v_mul_f32_e32 v10, 0x3fb8aa3b, v6
	v_exp_f32_e32 v10, v10
	s_nop 0
	v_sub_f32_e32 v6, 1.0, v10
.LBB0_1206:
	v_add_f32_e32 v10, v7, v23
	s_and_b64 vcc, exec, s[8:9]
	s_mov_b64 s[14:15], -1
	s_cbranch_vccnz .LBB0_1210
	s_and_b64 vcc, exec, s[6:7]
	v_mov_b32_e32 v7, v10
	s_cbranch_vccnz .LBB0_1209
	v_mul_f32_e32 v7, 0xbfb8aa3b, v10
	v_exp_f32_e32 v7, v7
	s_nop 0
	v_min_f32_e32 v7, 0x7e800000, v7
	v_add_f32_e32 v7, 1.0, v7
	v_rcp_f32_e32 v16, v7
	s_nop 0
	v_fma_f32 v18, -v7, v16, 1.0
	v_fma_f32 v7, v18, v16, v16

; __device__ __forceinline__ float sigmoidf_(float x) { return 1.0f / (1.0f + __expf(-x)); }
;     __device__ __forceinline__ void operator()(const f32x4 (&acc)[2][2][4][2], const Unit& u, int wr, int wc, int fr, int fq) const {
;     ...
;         for (int ai = 0; ai < 2; ++ai)
; #pragma unroll
;             for (int m = 0; m < 4; ++m) { f16* rowp = O + (size_t)(row0 + ai * 128 + m * 16) * 4096 + col0;
; #pragma unroll
;                 for (int bj = 0; bj < 2; ++bj) { f16x8 v;
; #pragma unroll
;                     for (int n = 0; n < 2; ++n)
; #pragma unroll
;                         for (int i = 0; i < 4; ++i) { float xv = acc[ai][bj][m][n][i] + bv[bj][n][i]; float r;
;                             if (type < 2) { const float sg = sigmoidf_(xv); r = -expm1f(-0.606531f * sg); }
;                             else if (type == 2) r = sigmoidf_(xv);
;                             else r = xv;
;                             v[4 * n + i] = (f16)r; }
;                     *(f16x8*)(rowp + bj * 128) = v; } }
.LBB0_1211:
	v_mul_f32_e32 v7, 0xbfb8aa3b, v10
	v_exp_f32_e32 v7, v7
	s_nop 0
	v_min_f32_e32 v7, 0x7e800000, v7
	v_add_f32_e32 v7, 1.0, v7
	v_rcp_f32_e32 v11, v7
	s_nop 0
	v_fma_f32 v17, -v7, v11, 1.0
	v_fma_f32 v7, v17, v11, v11
	v_mul_f32_e32 v7, 0xbf1b459e, v7
	v_mul_f32_e32 v10, 0x3fb8aa3b, v7
	v_exp_f32_e32 v10, v10
	s_nop 0
	v_sub_f32_e32 v7, 1.0, v10
.LBB0_1212:
	v_add_f32_e32 v10, v0, v12
	s_and_b64 vcc, exec, s[8:9]
	s_mov_b64 s[14:15], -1
	s_cbranch_vccnz .LBB0_1216
	s_and_b64 vcc, exec, s[6:7]
	v_mov_b32_e32 v0, v10
	s_cbranch_vccnz .LBB0_1215
	v_mul_f32_e32 v0, 0xbfb8aa3b, v10
	v_exp_f32_e32 v0, v0
	s_nop 0
	v_min_f32_e32 v0, 0x7e800000, v0
	v_add_f32_e32 v0, 1.0, v0
	v_rcp_f32_e32 v12, v0
	s_nop 0
	v_fma_f32 v17, -v0, v12, 1.0
	v_fma_f32 v0, v17, v12, v12

; __device__ __forceinline__ float sigmoidf_(float x) { return 1.0f / (1.0f + __expf(-x)); }
;     __device__ __forceinline__ void operator()(const f32x4 (&acc)[2][2][4][2], const Unit& u, int wr, int wc, int fr, int fq) const {
;     ...
;         for (int ai = 0; ai < 2; ++ai)
; #pragma unroll
;             for (int m = 0; m < 4; ++m) { f16* rowp = O + (size_t)(row0 + ai * 128 + m * 16) * 4096 + col0;
; #pragma unroll
;                 for (int bj = 0; bj < 2; ++bj) { f16x8 v;
; #pragma unroll
;                     for (int n = 0; n < 2; ++n)
; #pragma unroll
;                         for (int i = 0; i < 4; ++i) { float xv = acc[ai][bj][m][n][i] + bv[bj][n][i]; float r;
;                             if (type < 2) { const float sg = sigmoidf_(xv); r = -expm1f(-0.606531f * sg); }
;                             else if (type == 2) r = sigmoidf_(xv);
;                             else r = xv;
;                             v[4 * n + i] = (f16)r; }
;                     *(f16x8*)(rowp + bj * 128) = v; } }
.LBB0_1217:
	v_mul_f32_e32 v0, 0xbfb8aa3b, v10
	v_exp_f32_e32 v0, v0
	s_nop 0
	v_min_f32_e32 v0, 0x7e800000, v0
	v_add_f32_e32 v0, 1.0, v0
	v_rcp_f32_e32 v11, v0
	s_nop 0
	v_fma_f32 v16, -v0, v11, 1.0
	v_fma_f32 v0, v16, v11, v11
	v_mul_f32_e32 v0, 0xbf1b459e, v0
	v_mul_f32_e32 v10, 0x3fb8aa3b, v0
	v_exp_f32_e32 v10, v10
	s_nop 0
	v_sub_f32_e32 v0, 1.0, v10
.LBB0_1218:
	v_add_f32_e32 v10, v1, v13
	s_and_b64 vcc, exec, s[8:9]
	s_mov_b64 s[14:15], -1
	s_cbranch_vccnz .LBB0_1222
	s_and_b64 vcc, exec, s[6:7]
	v_mov_b32_e32 v1, v10
	s_cbranch_vccnz .LBB0_1221
	v_mul_f32_e32 v1, 0xbfb8aa3b, v10
	v_exp_f32_e32 v1, v1
	s_nop 0
	v_min_f32_e32 v1, 0x7e800000, v1
	v_add_f32_e32 v1, 1.0, v1
	v_rcp_f32_e32 v12, v1
	s_nop 0
	v_fma_f32 v16, -v1, v12, 1.0
	v_fma_f32 v1, v16, v12, v12

; __device__ __forceinline__ float sigmoidf_(float x) { return 1.0f / (1.0f + __expf(-x)); }
;     __device__ __forceinline__ void operator()(const f32x4 (&acc)[2][2][4][2], const Unit& u, int wr, int wc, int fr, int fq) const {
;     ...
;         for (int ai = 0; ai < 2; ++ai)
; #pragma unroll
;             for (int m = 0; m < 4; ++m) { f16* rowp = O + (size_t)(row0 + ai * 128 + m * 16) * 4096 + col0;
; #pragma unroll
;                 for (int bj = 0; bj < 2; ++bj) { f16x8 v;
; #pragma unroll
;                     for (int n = 0; n < 2; ++n)
; #pragma unroll
;                         for (int i = 0; i < 4; ++i) { float xv = acc[ai][bj][m][n][i] + bv[bj][n][i]; float r;
;                             if (type < 2) { const float sg = sigmoidf_(xv); r = -expm1f(-0.606531f * sg); }
;                             else if (type == 2) r = sigmoidf_(xv);
;                             else r = xv;
;                             v[4 * n + i] = (f16)r; }
;                     *(f16x8*)(rowp + bj * 128) = v; } }
.LBB0_1223:
	v_mul_f32_e32 v1, 0xbfb8aa3b, v10
	v_exp_f32_e32 v1, v1
	s_nop 0
	v_min_f32_e32 v1, 0x7e800000, v1
	v_add_f32_e32 v1, 1.0, v1
	v_rcp_f32_e32 v11, v1
	s_nop 0
	v_fma_f32 v13, -v1, v11, 1.0
	v_fma_f32 v1, v13, v11, v11
	v_mul_f32_e32 v1, 0xbf1b459e, v1
	v_mul_f32_e32 v10, 0x3fb8aa3b, v1
	v_exp_f32_e32 v10, v10
	s_nop 0
	v_sub_f32_e32 v1, 1.0, v10
.LBB0_1224:
	v_add_f32_e32 v10, v2, v14
	s_and_b64 vcc, exec, s[8:9]
	s_mov_b64 s[14:15], -1
	s_cbranch_vccnz .LBB0_1228
	s_and_b64 vcc, exec, s[6:7]
	v_mov_b32_e32 v2, v10
	s_cbranch_vccnz .LBB0_1227
	v_mul_f32_e32 v2, 0xbfb8aa3b, v10
	v_exp_f32_e32 v2, v2
	s_nop 0
	v_min_f32_e32 v2, 0x7e800000, v2
	v_add_f32_e32 v2, 1.0, v2
	v_rcp_f32_e32 v12, v2
	s_nop 0
	v_fma_f32 v14, -v2, v12, 1.0
	v_fma_f32 v2, v14, v12, v12

; __device__ __forceinline__ float sigmoidf_(float x) { return 1.0f / (1.0f + __expf(-x)); }
;     __device__ __forceinline__ void operator()(const f32x4 (&acc)[2][2][4][2], const Unit& u, int wr, int wc, int fr, int fq) const {
;     ...
;         for (int ai = 0; ai < 2; ++ai)
; #pragma unroll
;             for (int m = 0; m < 4; ++m) { f16* rowp = O + (size_t)(row0 + ai * 128 + m * 16) * 4096 + col0;
; #pragma unroll
;                 for (int bj = 0; bj < 2; ++bj) { f16x8 v;
; #pragma unroll
;                     for (int n = 0; n < 2; ++n)
; #pragma unroll
;                         for (int i = 0; i < 4; ++i) { float xv = acc[ai][bj][m][n][i] + bv[bj][n][i]; float r;
;                             if (type < 2) { const float sg = sigmoidf_(xv); r = -expm1f(-0.606531f * sg); }
;                             else if (type == 2) r = sigmoidf_(xv);
;                             else r = xv;
;                             v[4 * n + i] = (f16)r; }
;                     *(f16x8*)(rowp + bj * 128) = v; } }
.LBB0_1229:
	v_mul_f32_e32 v2, 0xbfb8aa3b, v10
	v_exp_f32_e32 v2, v2
	s_nop 0
	v_min_f32_e32 v2, 0x7e800000, v2
	v_add_f32_e32 v2, 1.0, v2
	v_rcp_f32_e32 v11, v2
	s_nop 0
	v_fma_f32 v13, -v2, v11, 1.0
	v_fma_f32 v2, v13, v11, v11
	v_mul_f32_e32 v2, 0xbf1b459e, v2
	v_mul_f32_e32 v10, 0x3fb8aa3b, v2
	v_exp_f32_e32 v10, v10
	s_nop 0
	v_sub_f32_e32 v2, 1.0, v10
.LBB0_1230:
	v_add_f32_e32 v3, v3, v15
	s_and_b64 vcc, exec, s[8:9]
	s_mov_b64 s[8:9], -1
	s_cbranch_vccnz .LBB0_1234
	s_and_b64 vcc, exec, s[6:7]
	v_mov_b32_e32 v10, v3
	s_cbranch_vccnz .LBB0_1233
	v_mul_f32_e32 v10, 0xbfb8aa3b, v3
	v_exp_f32_e32 v10, v10
	s_nop 0
	v_min_f32_e32 v10, 0x7e800000, v10
	v_add_f32_e32 v10, 1.0, v10
	v_rcp_f32_e32 v12, v10
	s_nop 0
	v_fma_f32 v14, -v10, v12, 1.0
	v_fma_f32 v10, v14, v12, v12

; __device__ __forceinline__ float sigmoidf_(float x) { return 1.0f / (1.0f + __expf(-x)); }
;     __device__ __forceinline__ void operator()(const f32x4 (&acc)[2][2][4][2], const Unit& u, int wr, int wc, int fr, int fq) const {
;     ...
;         for (int ai = 0; ai < 2; ++ai)
; #pragma unroll
;             for (int m = 0; m < 4; ++m) { f16* rowp = O + (size_t)(row0 + ai * 128 + m * 16) * 4096 + col0;
; #pragma unroll
;                 for (int bj = 0; bj < 2; ++bj) { f16x8 v;
; #pragma unroll
;                     for (int n = 0; n < 2; ++n)
; #pragma unroll
;                         for (int i = 0; i < 4; ++i) { float xv = acc[ai][bj][m][n][i] + bv[bj][n][i]; float r;
;                             if (type < 2) { const float sg = sigmoidf_(xv); r = -expm1f(-0.606531f * sg); }
;                             else if (type == 2) r = sigmoidf_(xv);
;                             else r = xv;
;                             v[4 * n + i] = (f16)r; }
;                     *(f16x8*)(rowp + bj * 128) = v; } }
.LBB0_1235:
	v_mul_f32_e32 v3, 0xbfb8aa3b, v3
	v_exp_f32_e32 v3, v3
	s_nop 0
	v_min_f32_e32 v3, 0x7e800000, v3
	v_add_f32_e32 v3, 1.0, v3
	v_rcp_f32_e32 v11, v3
	s_nop 0
	v_fma_f32 v13, -v3, v11, 1.0
	v_fma_f32 v3, v13, v11, v11
	v_mul_f32_e32 v3, 0xbf1b459e, v3
	v_mul_f32_e32 v10, 0x3fb8aa3b, v3
	v_exp_f32_e32 v10, v10
	s_nop 0
	v_sub_f32_e32 v10, 1.0, v10
	s_branch .LBB0_443

; #define PG8_STAGE(bufoff, gbase, voff) do { _Pragma("unroll") for (int _i = 0; _i < 2; ++_i) \
;         __builtin_amdgcn_global_load_lds((const unsigned*)((const char*)(gbase) + (voff)[_i]), (LAS unsigned*)(lds + (bufoff) + ldsw + _i * 8192), 16, 0, 0); } while (0)
; #define PG8_LDA(dst, b, h) do { _Pragma("unroll") for (int m = 0; m < 4; ++m) _Pragma("unroll") for (int k = 0; k < 2; ++k) dst[m][k] = *(const LAS bf16x8*)(lds + PG8_SA(b, h) + aoff + m * 2048 + k * 1024); } while (0)
; #define PG8_LDB(dst, b, h) do { _Pragma("unroll") for (int n = 0; n < 2; ++n) _Pragma("unroll") for (int k = 0; k < 2; ++k) dst[n][k] = *(const LAS bf16x8*)(lds + PG8_SB(b, h) + boff + n * 2048 + k * 1024); } while (0)
; #define PG8_MMA(ai, bj, At, Bt) do { __builtin_amdgcn_s_setprio(1); _Pragma("unroll") for (int m = 0; m < 4; ++m) _Pragma("unroll") for (int n = 0; n < 2; ++n) _Pragma("unroll") for (int k = 0; k < 2; ++k) \
;         acc[ai][bj][m][n] = __builtin_amdgcn_mfma_f32_16x16x32_bf16(Bt[n][k], At[m][k], acc[ai][bj][m][n], 0, 0, 0); __builtin_amdgcn_s_setprio(0); } while (0)
; #define PG8_WAIT_V(n) asm volatile("s_waitcnt vmcnt(" #n ")" ::: "memory")
; #define PG8_WAIT_L(n) asm volatile("s_waitcnt lgkmcnt(" #n ")" ::: "memory")
; template <class Epi>
; __device__ __forceinline__ void gemm_phase(LAS unsigned char* lds, const Gemm g, const StaticOrder& S, const Epi& E) {
;     ...
;         for (int t = 0; t < nt; t += 2) {
;             const bool last = (t == nt - 2);
;             const char* a1 = cA + (size_t)(t + 1) * kstep;
;             const char* a2 = last ? nA : cA + (size_t)(t + 2) * kstep; const char* b2 = last ? nB : cB + (size_t)(t + 2) * kstep;
;             const char* a3 = a2 + kstep; const char* b3 = b2 + kstep;
;             PG8_LDB(B0, 0, 0); PG8_SCHED; PG8_LDA(At, 0, 0); PG8_STAGE(PG8_SA(1, 1), a1 + hstep, voffA);
;             PG8_WAIT_L(8); PG8_BAR; PG8_WAIT_L(0); PG8_MMA(0, 0, At, B0); PG8_BAR; PG8_SCHED;
;             PG8_LDB(B1, 0, 1); PG8_STAGE(PG8_SB(0, 0), b2, voffB);
;             PG8_BAR; PG8_WAIT_L(0); PG8_MMA(0, 1, At, B1); PG8_BAR;
;             PG8_LDA(At, 0, 1); PG8_STAGE(PG8_SA(0, 0), a2, voffA);
;             PG8_BAR; PG8_WAIT_L(0); PG8_MMA(1, 0, At, B0); PG8_BAR; PG8_SCHED;
;             PG8_STAGE(PG8_SB(0, 1), b2 + hstep, voffB);
;             PG8_WAIT_V(6); PG8_BAR; PG8_MMA(1, 1, At, B1); PG8_BAR;
.LBB0_1769:
	ds_read_b128 v[154:157], v147
	ds_read_b128 v[158:161], v147 offset:1024
	ds_read_b128 v[162:165], v147 offset:2048
	ds_read_b128 v[166:169], v147 offset:3072
	s_add_u32 s30, s26, 0xfff80080
	s_addc_u32 s31, s27, -1
	s_cmp_eq_u32 s59, 28
	s_cselect_b32 s35, s13, s31
	s_cselect_b32 s34, s55, s30
	s_cselect_b32 s31, s7, s58
	s_cselect_b32 s30, s56, s57
	v_lshl_add_u64 v[150:151], s[26:27], 0, v[136:137]
	s_add_i32 m0, s21, 0xc000
	ds_read_b128 v[172:175], v148
	ds_read_b128 v[176:179], v148 offset:1024
	ds_read_b128 v[180:183], v148 offset:2048
	ds_read_b128 v[184:187], v148 offset:3072
	ds_read_b128 v[188:191], v148 offset:4096
	ds_read_b128 v[192:195], v148 offset:5120
	ds_read_b128 v[196:199], v148 offset:6144
	ds_read_b128 v[200:203], v148 offset:7168
	global_load_lds_dwordx4 v[150:151], off
	v_lshl_add_u64 v[150:151], s[26:27], 0, v[138:139]
	s_add_i32 m0, s21, 0xe000
	s_nop 0
	global_load_lds_dwordx4 v[150:151], off
	s_waitcnt lgkmcnt(8)
	s_barrier
	s_waitcnt lgkmcnt(0)
	s_setprio 1
	s_waitcnt lgkmcnt(0)
	v_mfma_f32_16x16x32_bf16 v[124:127], v[154:157], v[172:175], v[124:127]
	v_mfma_f32_16x16x32_bf16 v[116:119], v[162:165], v[172:175], v[116:119]
	v_mfma_f32_16x16x32_bf16 v[108:111], v[154:157], v[180:183], v[108:111]
	v_mfma_f32_16x16x32_bf16 v[100:103], v[162:165], v[180:183], v[100:103]
	v_mfma_f32_16x16x32_bf16 v[92:95], v[154:157], v[188:191], v[92:95]
	v_mfma_f32_16x16x32_bf16 v[84:87], v[162:165], v[188:191], v[84:87]
	v_mfma_f32_16x16x32_bf16 v[76:79], v[154:157], v[196:199], v[76:79]
	v_mfma_f32_16x16x32_bf16 v[68:71], v[162:165], v[196:199], v[68:71]
	v_mfma_f32_16x16x32_bf16 v[124:127], v[158:161], v[176:179], v[124:127]
	v_mfma_f32_16x16x32_bf16 v[116:119], v[166:169], v[176:179], v[116:119]
	v_mfma_f32_16x16x32_bf16 v[108:111], v[158:161], v[184:187], v[108:111]
	v_mfma_f32_16x16x32_bf16 v[100:103], v[166:169], v[184:187], v[100:103]
	v_mfma_f32_16x16x32_bf16 v[92:95], v[158:161], v[192:195], v[92:95]
	v_mfma_f32_16x16x32_bf16 v[84:87], v[166:169], v[192:195], v[84:87]
	v_mfma_f32_16x16x32_bf16 v[76:79], v[158:161], v[200:203], v[76:79]
	v_mfma_f32_16x16x32_bf16 v[68:71], v[166:169], v[200:203], v[68:71]
	s_setprio 0
	s_barrier
	s_add_i32 s60, s51, s37
	v_lshl_add_u64 v[150:151], s[30:31], 0, v[132:133]
	s_mov_b32 m0, s60
	ds_read_b128 v[204:207], v149
	ds_read_b128 v[208:211], v149 offset:1024
	ds_read_b128 v[212:215], v149 offset:2048
	ds_read_b128 v[216:219], v149 offset:3072
	global_load_lds_dwordx4 v[150:151], off
	v_lshl_add_u64 v[220:221], s[30:31], 0, v[128:129]
	s_add_i32 m0, s60, 0x2000
	s_nop 0
	global_load_lds_dwordx4 v[220:221], off
	s_barrier
	s_waitcnt lgkmcnt(0)
	s_setprio 1
	s_waitcnt lgkmcnt(0)
	v_mfma_f32_16x16x32_bf16 v[120:123], v[204:207], v[172:175], v[120:123]
	v_mfma_f32_16x16x32_bf16 v[112:115], v[212:215], v[172:175], v[112:115]
	v_mfma_f32_16x16x32_bf16 v[104:107], v[204:207], v[180:183], v[104:107]
	v_mfma_f32_16x16x32_bf16 v[96:99], v[212:215], v[180:183], v[96:99]
	v_mfma_f32_16x16x32_bf16 v[88:91], v[204:207], v[188:191], v[88:91]
	v_mfma_f32_16x16x32_bf16 v[80:83], v[212:215], v[188:191], v[80:83]
	v_mfma_f32_16x16x32_bf16 v[72:75], v[204:207], v[196:199], v[72:75]
	v_mfma_f32_16x16x32_bf16 v[64:67], v[212:215], v[196:199], v[64:67]
	v_mfma_f32_16x16x32_bf16 v[120:123], v[208:211], v[176:179], v[120:123]
	v_mfma_f32_16x16x32_bf16 v[112:115], v[216:219], v[176:179], v[112:115]
	v_mfma_f32_16x16x32_bf16 v[104:107], v[208:211], v[184:187], v[104:107]
	v_mfma_f32_16x16x32_bf16 v[96:99], v[216:219], v[184:187], v[96:99]
	v_mfma_f32_16x16x32_bf16 v[88:91], v[208:211], v[192:195], v[88:91]
	v_mfma_f32_16x16x32_bf16 v[80:83], v[216:219], v[192:195], v[80:83]
	v_mfma_f32_16x16x32_bf16 v[72:75], v[208:211], v[200:203], v[72:75]
	v_mfma_f32_16x16x32_bf16 v[64:67], v[216:219], v[200:203], v[64:67]
	s_setprio 0
	s_mov_b32 m0, s21
	v_lshl_add_u64 v[222:223], s[34:35], 0, v[134:135]
	s_barrier
	ds_read_b128 v[172:175], v148 offset:16384
	ds_read_b128 v[176:179], v148 offset:17408
	ds_read_b128 v[180:183], v148 offset:18432
	ds_read_b128 v[184:187], v148 offset:19456
	ds_read_b128 v[188:191], v148 offset:20480
	ds_read_b128 v[192:195], v148 offset:21504
	ds_read_b128 v[196:199], v148 offset:22528
	ds_read_b128 v[200:203], v148 offset:23552
	global_load_lds_dwordx4 v[222:223], off
	v_lshl_add_u64 v[224:225], s[34:35], 0, v[130:131]
	s_mov_b32 m0, s40
	s_nop 0
	global_load_lds_dwordx4 v[224:225], off
	s_barrier
	s_waitcnt lgkmcnt(0)
	s_setprio 1
	s_waitcnt lgkmcnt(0)
	v_mfma_f32_16x16x32_bf16 v[60:63], v[154:157], v[172:175], v[60:63]
	v_mfma_f32_16x16x32_bf16 v[52:55], v[162:165], v[172:175], v[52:55]
	v_mfma_f32_16x16x32_bf16 v[44:47], v[154:157], v[180:183], v[44:47]
	v_mfma_f32_16x16x32_bf16 v[36:39], v[162:165], v[180:183], v[36:39]
	v_mfma_f32_16x16x32_bf16 v[28:31], v[154:157], v[188:191], v[28:31]
	v_mfma_f32_16x16x32_bf16 v[20:23], v[162:165], v[188:191], v[20:23]
	v_mfma_f32_16x16x32_bf16 v[12:15], v[154:157], v[196:199], v[12:15]
	v_mfma_f32_16x16x32_bf16 v[4:7], v[162:165], v[196:199], v[4:7]
	v_mfma_f32_16x16x32_bf16 v[60:63], v[158:161], v[176:179], v[60:63]
	v_mfma_f32_16x16x32_bf16 v[52:55], v[166:169], v[176:179], v[52:55]
	v_mfma_f32_16x16x32_bf16 v[44:47], v[158:161], v[184:187], v[44:47]
	v_mfma_f32_16x16x32_bf16 v[36:39], v[166:169], v[184:187], v[36:39]
	v_mfma_f32_16x16x32_bf16 v[28:31], v[158:161], v[192:195], v[28:31]
	v_mfma_f32_16x16x32_bf16 v[20:23], v[166:169], v[192:195], v[20:23]
	v_mfma_f32_16x16x32_bf16 v[12:15], v[158:161], v[200:203], v[12:15]
	v_mfma_f32_16x16x32_bf16 v[4:7], v[166:169], v[200:203], v[4:7]
	s_setprio 0
	s_barrier
; #define PG8_STAGE(bufoff, gbase, voff) do { _Pragma("unroll") for (int _i = 0; _i < 2; ++_i) \
;         __builtin_amdgcn_global_load_lds((const unsigned*)((const char*)(gbase) + (voff)[_i]), (LAS unsigned*)(lds + (bufoff) + ldsw + _i * 8192), 16, 0, 0); } while (0)
; #define PG8_LDA(dst, b, h) do { _Pragma("unroll") for (int m = 0; m < 4; ++m) _Pragma("unroll") for (int k = 0; k < 2; ++k) dst[m][k] = *(const LAS bf16x8*)(lds + PG8_SA(b, h) + aoff + m * 2048 + k * 1024); } while (0)
; #define PG8_LDB(dst, b, h) do { _Pragma("unroll") for (int n = 0; n < 2; ++n) _Pragma("unroll") for (int k = 0; k < 2; ++k) dst[n][k] = *(const LAS bf16x8*)(lds + PG8_SB(b, h) + boff + n * 2048 + k * 1024); } while (0)
; #define PG8_MMA(ai, bj, At, Bt) do { __builtin_amdgcn_s_setprio(1); _Pragma("unroll") for (int m = 0; m < 4; ++m) _Pragma("unroll") for (int n = 0; n < 2; ++n) _Pragma("unroll") for (int k = 0; k < 2; ++k) \
;         acc[ai][bj][m][n] = __builtin_amdgcn_mfma_f32_16x16x32_bf16(Bt[n][k], At[m][k], acc[ai][bj][m][n], 0, 0, 0); __builtin_amdgcn_s_setprio(0); } while (0)
; #define PG8_WAIT_V(n) asm volatile("s_waitcnt vmcnt(" #n ")" ::: "memory")
; #define PG8_WAIT_L(n) asm volatile("s_waitcnt lgkmcnt(" #n ")" ::: "memory")
; #define PG8_BAR __builtin_amdgcn_s_barrier()
; #define PG8_SCHED __builtin_amdgcn_sched_barrier(0)
; template <class Epi>
; __device__ __forceinline__ void gemm_phase(LAS unsigned char* lds, const Gemm g, const StaticOrder& S, const Epi& E) {
;     ...
;             PG8_LDB(B1, 0, 1); PG8_STAGE(PG8_SB(0, 0), b2, voffB);
;             PG8_BAR; PG8_WAIT_L(0); PG8_MMA(0, 1, At, B1); PG8_BAR;
;             PG8_LDA(At, 0, 1); PG8_STAGE(PG8_SA(0, 0), a2, voffA);
;             PG8_BAR; PG8_WAIT_L(0); PG8_MMA(1, 0, At, B0); PG8_BAR; PG8_SCHED;
;             PG8_STAGE(PG8_SB(0, 1), b2 + hstep, voffB);
;             PG8_WAIT_V(6); PG8_BAR; PG8_MMA(1, 1, At, B1); PG8_BAR;
;             PG8_LDB(B0, 1, 0); PG8_SCHED; PG8_LDA(At, 1, 0); PG8_STAGE(PG8_SA(0, 1), a2 + hstep, voffA);
;             PG8_WAIT_L(8); PG8_BAR; PG8_WAIT_L(0); PG8_MMA(0, 0, At, B0); PG8_BAR; PG8_SCHED;
;             PG8_LDB(B1, 1, 1); PG8_STAGE(PG8_SB(1, 0), b3, voffB);
;             PG8_BAR; PG8_WAIT_L(0); PG8_MMA(0, 1, At, B1); PG8_BAR;
;             PG8_LDA(At, 1, 1); PG8_STAGE(PG8_SA(1, 0), a3, voffA);
;             PG8_BAR; PG8_WAIT_L(0); PG8_MMA(1, 0, At, B0); PG8_BAR; PG8_SCHED;
	s_add_u32 s60, s30, 0x80000
	s_addc_u32 s61, s31, 0
	s_add_i32 s62, s52, s37
	v_lshl_add_u64 v[154:155], s[60:61], 0, v[132:133]
	s_mov_b32 m0, s62
	s_nop 0
	global_load_lds_dwordx4 v[154:155], off
	v_lshl_add_u64 v[154:155], s[60:61], 0, v[128:129]
	s_add_i32 m0, s62, 0x2000
	s_nop 0
	global_load_lds_dwordx4 v[154:155], off
	s_waitcnt vmcnt(6)
	s_barrier
	s_setprio 1
	v_mfma_f32_16x16x32_bf16 v[56:59], v[204:207], v[172:175], v[56:59]
	v_mfma_f32_16x16x32_bf16 v[48:51], v[212:215], v[172:175], v[48:51]
	v_mfma_f32_16x16x32_bf16 v[40:43], v[204:207], v[180:183], v[40:43]
	v_mfma_f32_16x16x32_bf16 v[32:35], v[212:215], v[180:183], v[32:35]
	v_mfma_f32_16x16x32_bf16 v[24:27], v[204:207], v[188:191], v[24:27]
	v_mfma_f32_16x16x32_bf16 v[16:19], v[212:215], v[188:191], v[16:19]
	v_mfma_f32_16x16x32_bf16 v[8:11], v[204:207], v[196:199], v[8:11]
	v_mfma_f32_16x16x32_bf16 v[0:3], v[212:215], v[196:199], v[0:3]
	v_mfma_f32_16x16x32_bf16 v[56:59], v[208:211], v[176:179], v[56:59]
	v_mfma_f32_16x16x32_bf16 v[48:51], v[216:219], v[176:179], v[48:51]
	v_mfma_f32_16x16x32_bf16 v[40:43], v[208:211], v[184:187], v[40:43]
	v_mfma_f32_16x16x32_bf16 v[32:35], v[216:219], v[184:187], v[32:35]
	v_mfma_f32_16x16x32_bf16 v[24:27], v[208:211], v[192:195], v[24:27]
	v_mfma_f32_16x16x32_bf16 v[16:19], v[216:219], v[192:195], v[16:19]
	v_mfma_f32_16x16x32_bf16 v[8:11], v[208:211], v[200:203], v[8:11]
	v_mfma_f32_16x16x32_bf16 v[0:3], v[216:219], v[200:203], v[0:3]
	s_setprio 0
	s_add_i32 s60, 0, 0x18000
	v_add_u32_e32 v153, s60, v145
	s_barrier
	ds_read_b128 v[154:157], v153
	ds_read_b128 v[158:161], v153 offset:1024
	ds_read_b128 v[162:165], v153 offset:2048
	ds_read_b128 v[166:169], v153 offset:3072
	s_add_u32 s34, s34, 0x80000
	s_addc_u32 s35, s35, 0
	s_mov_b32 m0, s41
	v_lshl_add_u64 v[204:205], s[34:35], 0, v[134:135]
	ds_read_b128 v[172:175], v148 offset:32768
	ds_read_b128 v[176:179], v148 offset:33792
	ds_read_b128 v[180:183], v148 offset:34816
	ds_read_b128 v[184:187], v148 offset:35840
	ds_read_b128 v[188:191], v148 offset:36864
	ds_read_b128 v[192:195], v148 offset:37888
	ds_read_b128 v[196:199], v148 offset:38912
	ds_read_b128 v[200:203], v148 offset:39936
	global_load_lds_dwordx4 v[204:205], off
	v_lshl_add_u64 v[204:205], s[34:35], 0, v[130:131]
	s_mov_b32 m0, s42
	s_nop 0
	global_load_lds_dwordx4 v[204:205], off
	s_waitcnt lgkmcnt(8)
	s_barrier
	s_waitcnt lgkmcnt(0)
	s_setprio 1
	s_waitcnt lgkmcnt(0)
	v_mfma_f32_16x16x32_bf16 v[124:127], v[154:157], v[172:175], v[124:127]
	v_mfma_f32_16x16x32_bf16 v[116:119], v[162:165], v[172:175], v[116:119]
	v_mfma_f32_16x16x32_bf16 v[108:111], v[154:157], v[180:183], v[108:111]
	v_mfma_f32_16x16x32_bf16 v[100:103], v[162:165], v[180:183], v[100:103]
	v_mfma_f32_16x16x32_bf16 v[92:95], v[154:157], v[188:191], v[92:95]
	v_mfma_f32_16x16x32_bf16 v[84:87], v[162:165], v[188:191], v[84:87]
	v_mfma_f32_16x16x32_bf16 v[76:79], v[154:157], v[196:199], v[76:79]
	v_mfma_f32_16x16x32_bf16 v[68:71], v[162:165], v[196:199], v[68:71]
	v_mfma_f32_16x16x32_bf16 v[124:127], v[158:161], v[176:179], v[124:127]
	v_mfma_f32_16x16x32_bf16 v[116:119], v[166:169], v[176:179], v[116:119]
	v_mfma_f32_16x16x32_bf16 v[108:111], v[158:161], v[184:187], v[108:111]
	v_mfma_f32_16x16x32_bf16 v[100:103], v[166:169], v[184:187], v[100:103]
	v_mfma_f32_16x16x32_bf16 v[92:95], v[158:161], v[192:195], v[92:95]
	v_mfma_f32_16x16x32_bf16 v[84:87], v[166:169], v[192:195], v[84:87]
	v_mfma_f32_16x16x32_bf16 v[76:79], v[158:161], v[200:203], v[76:79]
	v_mfma_f32_16x16x32_bf16 v[68:71], v[166:169], v[200:203], v[68:71]
	s_setprio 0
	s_barrier
	s_add_i32 s34, 0, 0x1c000
	s_add_i32 s35, s60, s37
	v_add_u32_e32 v153, s34, v145
	v_lshl_add_u64 v[150:151], v[150:151], 0, s[0:1]
	s_mov_b32 m0, s35
	ds_read_b128 v[204:207], v153
	ds_read_b128 v[208:211], v153 offset:1024
	ds_read_b128 v[212:215], v153 offset:2048
	ds_read_b128 v[216:219], v153 offset:3072
	global_load_lds_dwordx4 v[150:151], off
	v_lshl_add_u64 v[150:151], v[220:221], 0, s[0:1]
	s_add_i32 m0, s35, 0x2000
	s_nop 0
	global_load_lds_dwordx4 v[150:151], off
	s_barrier
	s_waitcnt lgkmcnt(0)
	s_setprio 1
	s_waitcnt lgkmcnt(0)
	v_mfma_f32_16x16x32_bf16 v[120:123], v[204:207], v[172:175], v[120:123]
	v_mfma_f32_16x16x32_bf16 v[112:115], v[212:215], v[172:175], v[112:115]
	v_mfma_f32_16x16x32_bf16 v[104:107], v[204:207], v[180:183], v[104:107]
	v_mfma_f32_16x16x32_bf16 v[96:99], v[212:215], v[180:183], v[96:99]
	v_mfma_f32_16x16x32_bf16 v[88:91], v[204:207], v[188:191], v[88:91]
	v_mfma_f32_16x16x32_bf16 v[80:83], v[212:215], v[188:191], v[80:83]
	v_mfma_f32_16x16x32_bf16 v[72:75], v[204:207], v[196:199], v[72:75]
	v_mfma_f32_16x16x32_bf16 v[64:67], v[212:215], v[196:199], v[64:67]
	v_mfma_f32_16x16x32_bf16 v[120:123], v[208:211], v[176:179], v[120:123]
	v_mfma_f32_16x16x32_bf16 v[112:115], v[216:219], v[176:179], v[112:115]
	v_mfma_f32_16x16x32_bf16 v[104:107], v[208:211], v[184:187], v[104:107]
	v_mfma_f32_16x16x32_bf16 v[96:99], v[216:219], v[184:187], v[96:99]
	v_mfma_f32_16x16x32_bf16 v[88:91], v[208:211], v[192:195], v[88:91]
	v_mfma_f32_16x16x32_bf16 v[80:83], v[216:219], v[192:195], v[80:83]
	v_mfma_f32_16x16x32_bf16 v[72:75], v[208:211], v[200:203], v[72:75]
	v_mfma_f32_16x16x32_bf16 v[64:67], v[216:219], v[200:203], v[64:67]
	s_setprio 0
	s_mov_b32 m0, s48
	v_lshl_add_u64 v[150:151], v[222:223], 0, s[0:1]
	s_barrier
	ds_read_b128 v[172:175], v148 offset:49152
	ds_read_b128 v[176:179], v148 offset:50176
	ds_read_b128 v[180:183], v148 offset:51200
	ds_read_b128 v[184:187], v148 offset:52224
	ds_read_b128 v[188:191], v148 offset:53248
	ds_read_b128 v[192:195], v148 offset:54272
	ds_read_b128 v[196:199], v148 offset:55296
	ds_read_b128 v[200:203], v148 offset:56320
	global_load_lds_dwordx4 v[150:151], off
	v_lshl_add_u64 v[150:151], v[224:225], 0, s[0:1]
	s_mov_b32 m0, s49
	s_nop 0
	global_load_lds_dwordx4 v[150:151], off
	s_barrier
; __device__ __forceinline__ unsigned cvt_pk_bf16(float lo, float hi) { unsigned r; asm volatile("v_cvt_pk_bf16_f32 %0, %1, %2" : "=v"(r) : "v"(lo), "v"(hi)); return r; }
; __device__ __forceinline__ float sigmoidf_(float x) { return 1.0f / (1.0f + __expf(-x)); }
; #define PG8_STAGE(bufoff, gbase, voff) do { _Pragma("unroll") for (int _i = 0; _i < 2; ++_i) \
;         __builtin_amdgcn_global_load_lds((const unsigned*)((const char*)(gbase) + (voff)[_i]), (LAS unsigned*)(lds + (bufoff) + ldsw + _i * 8192), 16, 0, 0); } while (0)
; #define PG8_LDA(dst, b, h) do { _Pragma("unroll") for (int m = 0; m < 4; ++m) _Pragma("unroll") for (int k = 0; k < 2; ++k) dst[m][k] = *(const LAS bf16x8*)(lds + PG8_SA(b, h) + aoff + m * 2048 + k * 1024); } while (0)
; #define PG8_MMA(ai, bj, At, Bt) do { __builtin_amdgcn_s_setprio(1); _Pragma("unroll") for (int m = 0; m < 4; ++m) _Pragma("unroll") for (int n = 0; n < 2; ++n) _Pragma("unroll") for (int k = 0; k < 2; ++k) \
;         acc[ai][bj][m][n] = __builtin_amdgcn_mfma_f32_16x16x32_bf16(Bt[n][k], At[m][k], acc[ai][bj][m][n], 0, 0, 0); __builtin_amdgcn_s_setprio(0); } while (0)
; template <class Epi>
; __device__ __forceinline__ void gemm_phase(LAS unsigned char* lds, const Gemm g, const StaticOrder& S, const Epi& E) {
;     ...
;             PG8_BAR; PG8_WAIT_L(0); PG8_MMA(0, 1, At, B1); PG8_BAR;
;             PG8_LDA(At, 1, 1); PG8_STAGE(PG8_SA(1, 0), a3, voffA);
;             PG8_BAR; PG8_WAIT_L(0); PG8_MMA(1, 0, At, B0); PG8_BAR; PG8_SCHED;
;             PG8_STAGE(PG8_SB(1, 1), b3 + hstep, voffB);
;             PG8_WAIT_V(6); PG8_BAR; PG8_MMA(1, 1, At, B1); PG8_BAR;
;     __device__ __forceinline__ void operator()(const f32x4 (&acc)[2][2][4][2], const Unit& u, int wr, int wc, int fr, int fq) const {
;     ...
;         for (int ai = 0; ai < 2; ++ai)
; #pragma unroll
;             for (int m = 0; m < 4; ++m) { float hv[8];
; #pragma unroll
;                 for (int n = 0; n < 2; ++n)
; #pragma unroll
;                     for (int i = 0; i < 4; ++i) { const float gt = acc[ai][0][m][n][i], up = acc[ai][1][m][n][i]; hv[4 * n + i] = gt * sigmoidf_(gt) * up; }
;                 u32x4 o; o[0] = cvt_pk_bf16(hv[0], hv[1]); o[1] = cvt_pk_bf16(hv[2], hv[3]); o[2] = cvt_pk_bf16(hv[4], hv[5]); o[3] = cvt_pk_bf16(hv[6], hv[7]);
;                 *(u32x4*)(O + (size_t)(row0 + ai * 128 + m * 16) * 5632 + col0) = o; }
	s_waitcnt lgkmcnt(0)
	s_setprio 1
	s_waitcnt lgkmcnt(0)
	v_mfma_f32_16x16x32_bf16 v[60:63], v[154:157], v[172:175], v[60:63]
	v_mfma_f32_16x16x32_bf16 v[52:55], v[162:165], v[172:175], v[52:55]
	v_mfma_f32_16x16x32_bf16 v[44:47], v[154:157], v[180:183], v[44:47]
	v_mfma_f32_16x16x32_bf16 v[36:39], v[162:165], v[180:183], v[36:39]
	v_mfma_f32_16x16x32_bf16 v[28:31], v[154:157], v[188:191], v[28:31]
	v_mfma_f32_16x16x32_bf16 v[20:23], v[162:165], v[188:191], v[20:23]
	v_mfma_f32_16x16x32_bf16 v[12:15], v[154:157], v[196:199], v[12:15]
	v_mfma_f32_16x16x32_bf16 v[4:7], v[162:165], v[196:199], v[4:7]
	v_mfma_f32_16x16x32_bf16 v[60:63], v[158:161], v[176:179], v[60:63]
	v_mfma_f32_16x16x32_bf16 v[52:55], v[166:169], v[176:179], v[52:55]
	v_mfma_f32_16x16x32_bf16 v[44:47], v[158:161], v[184:187], v[44:47]
	v_mfma_f32_16x16x32_bf16 v[36:39], v[166:169], v[184:187], v[36:39]
	v_mfma_f32_16x16x32_bf16 v[28:31], v[158:161], v[192:195], v[28:31]
	v_mfma_f32_16x16x32_bf16 v[20:23], v[166:169], v[192:195], v[20:23]
	v_mfma_f32_16x16x32_bf16 v[12:15], v[158:161], v[200:203], v[12:15]
	v_mfma_f32_16x16x32_bf16 v[4:7], v[166:169], v[200:203], v[4:7]
	s_setprio 0
	s_barrier
	s_add_u32 s30, s30, 0x80080
	s_addc_u32 s31, s31, 0
	s_add_i32 s34, s34, s37
	v_lshl_add_u64 v[150:151], s[30:31], 0, v[132:133]
	s_mov_b32 m0, s34
	s_nop 0
	global_load_lds_dwordx4 v[150:151], off
	v_lshl_add_u64 v[150:151], s[30:31], 0, v[128:129]
	s_add_i32 m0, s34, 0x2000
	s_nop 0
	global_load_lds_dwordx4 v[150:151], off
	s_waitcnt vmcnt(6)
	s_barrier
	s_setprio 1
	v_mfma_f32_16x16x32_bf16 v[56:59], v[204:207], v[172:175], v[56:59]
	v_mfma_f32_16x16x32_bf16 v[48:51], v[212:215], v[172:175], v[48:51]
	v_mfma_f32_16x16x32_bf16 v[40:43], v[204:207], v[180:183], v[40:43]
	v_mfma_f32_16x16x32_bf16 v[32:35], v[212:215], v[180:183], v[32:35]
	v_mfma_f32_16x16x32_bf16 v[24:27], v[204:207], v[188:191], v[24:27]
	v_mfma_f32_16x16x32_bf16 v[16:19], v[212:215], v[188:191], v[16:19]
	v_mfma_f32_16x16x32_bf16 v[8:11], v[204:207], v[196:199], v[8:11]
	v_mfma_f32_16x16x32_bf16 v[0:3], v[212:215], v[196:199], v[0:3]
	v_mfma_f32_16x16x32_bf16 v[56:59], v[208:211], v[176:179], v[56:59]
	v_mfma_f32_16x16x32_bf16 v[48:51], v[216:219], v[176:179], v[48:51]
	v_mfma_f32_16x16x32_bf16 v[40:43], v[208:211], v[184:187], v[40:43]
	v_mfma_f32_16x16x32_bf16 v[32:35], v[216:219], v[184:187], v[32:35]
	v_mfma_f32_16x16x32_bf16 v[24:27], v[208:211], v[192:195], v[24:27]
	v_mfma_f32_16x16x32_bf16 v[16:19], v[216:219], v[192:195], v[16:19]
	v_mfma_f32_16x16x32_bf16 v[8:11], v[208:211], v[200:203], v[8:11]
	v_mfma_f32_16x16x32_bf16 v[0:3], v[216:219], v[200:203], v[0:3]
	s_setprio 0
	s_add_i32 s59, s59, 2
	s_add_u32 s26, s26, 0x100
	s_addc_u32 s27, s27, 0
	s_add_u32 s57, s57, 0x100
	s_addc_u32 s58, s58, 0
	s_cmp_gt_u32 s59, 29
	s_barrier
	s_cbranch_scc0 .LBB0_1769
	v_mul_f32_e32 v150, 0xbfb8aa3b, v124
	v_exp_f32_e32 v151, v150
	v_lshl_or_b32 v154, s54, 7, v146
	v_lshl_add_u32 v150, s20, 8, v144
	v_ashrrev_i32_e32 v155, 31, v154
	v_min_f32_e32 v151, 0x7e800000, v151
	v_add_f32_e32 v151, 1.0, v151
	v_rcp_f32_e32 v156, v151
	s_mov_b32 s54, s6
	v_mul_f32_e32 v159, 0xbfb8aa3b, v125
	v_exp_f32_e32 v159, v159
	v_fma_f32 v158, -v151, v156, 1.0
	v_fma_f32 v151, v158, v156, v156
	v_min_f32_e32 v159, 0x7e800000, v159
	v_add_f32_e32 v156, 1.0, v159
	v_rcp_f32_e32 v158, v156
	v_mul_f32_e32 v124, v124, v151
	v_mul_f32_e32 v120, v124, v120
	s_mov_b32 s20, s12
	v_mul_f32_e32 v153, 0xbfb8aa3b, v126
	v_exp_f32_e32 v153, v153
	v_fma_f32 v151, -v156, v158, 1.0
	v_fma_f32 v124, v151, v158, v158
	v_min_f32_e32 v153, 0x7e800000, v153
	v_add_f32_e32 v151, 1.0, v153
	v_rcp_f32_e32 v157, v151
	v_mul_f32_e32 v124, v125, v124
	v_mul_f32_e32 v121, v124, v121
	s_mov_b64 s[30:31], s[16:17]
	v_mul_f32_e32 v156, 0xbfb8aa3b, v127
	v_exp_f32_e32 v156, v156
	v_fma_f32 v125, -v151, v157, 1.0
	v_fma_f32 v124, v125, v157, v157
	v_min_f32_e32 v156, 0x7e800000, v156
	v_add_f32_e32 v125, 1.0, v156
	v_rcp_f32_e32 v156, v125
	v_mul_f32_e32 v124, v126, v124
	v_mul_f32_e32 v122, v124, v122
	v_mul_f32_e32 v151, 0xbfb8aa3b, v116
	v_exp_f32_e32 v151, v151
	v_fma_f32 v126, -v125, v156, 1.0
	v_fma_f32 v124, v126, v156, v156
	v_min_f32_e32 v151, 0x7e800000, v151
	v_add_f32_e32 v126, 1.0, v151
	v_rcp_f32_e32 v153, v126
	v_mul_f32_e32 v124, v127, v124
	v_mul_f32_e32 v123, v124, v123
	v_mul_f32_e32 v127, 0xbfb8aa3b, v117
	v_exp_f32_e32 v127, v127
	v_fma_f32 v125, -v126, v153, 1.0
	v_fma_f32 v124, v125, v153, v153
	v_min_f32_e32 v127, 0x7e800000, v127
	v_add_f32_e32 v125, 1.0, v127
	v_rcp_f32_e32 v151, v125
	v_mul_f32_e32 v116, v116, v124
	v_mul_f32_e32 v112, v116, v112
	v_mul_f32_e32 v126, 0xbfb8aa3b, v118
	v_exp_f32_e32 v126, v126
	v_fma_f32 v124, -v125, v151, 1.0
	v_fma_f32 v116, v124, v151, v151
	v_min_f32_e32 v126, 0x7e800000, v126
	v_add_f32_e32 v124, 1.0, v126
	v_rcp_f32_e32 v127, v124
	v_mul_f32_e32 v116, v117, v116
	v_mul_f32_e32 v113, v116, v113
	v_mul_f32_e32 v125, 0xbfb8aa3b, v119
	v_exp_f32_e32 v125, v125
	v_fma_f32 v117, -v124, v127, 1.0
	v_fma_f32 v116, v117, v127, v127
	v_min_f32_e32 v125, 0x7e800000, v125
	v_add_f32_e32 v117, 1.0, v125
	v_rcp_f32_e32 v126, v117
	v_mul_f32_e32 v116, v118, v116
	v_mul_f32_e32 v114, v116, v114
	v_fma_f32 v118, -v117, v126, 1.0
	v_fma_f32 v116, v118, v126, v126
	v_mul_f32_e32 v116, v119, v116
	v_mul_f32_e32 v115, v116, v115
	v_cvt_pk_bf16_f32 v116, v120, v121
	v_cvt_pk_bf16_f32 v117, v122, v123
	v_cvt_pk_bf16_f32 v118, v112, v113
	v_mul_f32_e32 v112, 0xbfb8aa3b, v108
	v_cvt_pk_bf16_f32 v119, v114, v115
	v_exp_f32_e32 v114, v112
	v_mov_b64_e32 v[112:113], s[96:97]
	v_mad_i64_i32 v[120:121], s[26:27], v150, s53, v[112:113]
; __device__ __forceinline__ unsigned cvt_pk_bf16(float lo, float hi) { unsigned r; asm volatile("v_cvt_pk_bf16_f32 %0, %1, %2" : "=v"(r) : "v"(lo), "v"(hi)); return r; }
; __device__ __forceinline__ float sigmoidf_(float x) { return 1.0f / (1.0f + __expf(-x)); }
;     __device__ __forceinline__ void operator()(const f32x4 (&acc)[2][2][4][2], const Unit& u, int wr, int wc, int fr, int fq) const {
;     ...
;         for (int ai = 0; ai < 2; ++ai)
; #pragma unroll
;             for (int m = 0; m < 4; ++m) { float hv[8];
; #pragma unroll
;                 for (int n = 0; n < 2; ++n)
; #pragma unroll
;                     for (int i = 0; i < 4; ++i) { const float gt = acc[ai][0][m][n][i], up = acc[ai][1][m][n][i]; hv[4 * n + i] = gt * sigmoidf_(gt) * up; }
;                 u32x4 o; o[0] = cvt_pk_bf16(hv[0], hv[1]); o[1] = cvt_pk_bf16(hv[2], hv[3]); o[2] = cvt_pk_bf16(hv[4], hv[5]); o[3] = cvt_pk_bf16(hv[6], hv[7]);
;                 *(u32x4*)(O + (size_t)(row0 + ai * 128 + m * 16) * 5632 + col0) = o; }
	v_min_f32_e32 v114, 0x7e800000, v114
	v_add_f32_e32 v122, 1.0, v114
	v_rcp_f32_e32 v124, v122
	v_lshlrev_b64 v[114:115], 1, v[154:155]
	v_lshl_add_u64 v[120:121], v[120:121], 0, v[114:115]
	global_store_dwordx4 v[120:121], v[116:119], off
	s_nop 1
	v_mul_f32_e32 v118, 0xbfb8aa3b, v109
	v_exp_f32_e32 v118, v118
	v_fma_f32 v117, -v122, v124, 1.0
	v_fma_f32 v116, v117, v124, v124
	v_min_f32_e32 v118, 0x7e800000, v118
	v_add_f32_e32 v117, 1.0, v118
	v_rcp_f32_e32 v119, v117
	v_mul_f32_e32 v108, v108, v116
	v_mul_f32_e32 v104, v108, v104
	v_mul_f32_e32 v120, 0xbfb8aa3b, v110
	v_exp_f32_e32 v120, v120
	v_fma_f32 v116, -v117, v119, 1.0
	v_fma_f32 v108, v116, v119, v119
	v_min_f32_e32 v120, 0x7e800000, v120
	v_add_f32_e32 v116, 1.0, v120
	v_rcp_f32_e32 v119, v116
	v_mul_f32_e32 v108, v109, v108
	v_mul_f32_e32 v105, v108, v105
	v_mul_f32_e32 v117, 0xbfb8aa3b, v111
	v_exp_f32_e32 v117, v117
	v_fma_f32 v109, -v116, v119, 1.0
	v_fma_f32 v108, v109, v119, v119
	v_min_f32_e32 v117, 0x7e800000, v117
	v_add_f32_e32 v109, 1.0, v117
	v_rcp_f32_e32 v118, v109
	v_mul_f32_e32 v108, v110, v108
	v_mul_f32_e32 v106, v108, v106
	v_mul_f32_e32 v116, 0xbfb8aa3b, v100
	v_exp_f32_e32 v116, v116
	v_fma_f32 v110, -v109, v118, 1.0
	v_fma_f32 v108, v110, v118, v118
	v_min_f32_e32 v116, 0x7e800000, v116
	v_add_f32_e32 v110, 1.0, v116
	v_rcp_f32_e32 v117, v110
	v_mul_f32_e32 v108, v111, v108
	v_mul_f32_e32 v107, v108, v107
	v_mul_f32_e32 v111, 0xbfb8aa3b, v101
	v_exp_f32_e32 v111, v111
	v_fma_f32 v109, -v110, v117, 1.0
	v_fma_f32 v108, v109, v117, v117
	v_min_f32_e32 v111, 0x7e800000, v111
	v_add_f32_e32 v109, 1.0, v111
	v_rcp_f32_e32 v116, v109
	v_mul_f32_e32 v100, v100, v108
	v_mul_f32_e32 v100, v100, v96
	v_mul_f32_e32 v110, 0xbfb8aa3b, v102
	v_exp_f32_e32 v110, v110
	v_fma_f32 v108, -v109, v116, 1.0
	v_fma_f32 v96, v108, v116, v116
	v_min_f32_e32 v110, 0x7e800000, v110
	v_add_f32_e32 v108, 1.0, v110
	v_rcp_f32_e32 v111, v108
	v_mul_f32_e32 v96, v101, v96
	v_mul_f32_e32 v101, v96, v97
	v_mul_f32_e32 v109, 0xbfb8aa3b, v103
	v_exp_f32_e32 v109, v109
	v_fma_f32 v97, -v108, v111, 1.0
	v_fma_f32 v96, v97, v111, v111
	v_min_f32_e32 v109, 0x7e800000, v109
	v_add_f32_e32 v97, 1.0, v109
	v_rcp_f32_e32 v110, v97
	v_mul_f32_e32 v96, v102, v96
	v_mul_f32_e32 v102, v96, v98
	v_fma_f32 v98, -v97, v110, 1.0
	v_fma_f32 v96, v98, v110, v110
	v_mul_f32_e32 v98, 0xbfb8aa3b, v92
	v_mul_f32_e32 v96, v103, v96
	v_exp_f32_e32 v103, v98
	v_mul_f32_e32 v99, v96, v99
	v_cvt_pk_bf16_f32 v96, v104, v105
	v_cvt_pk_bf16_f32 v97, v106, v107
	v_cvt_pk_bf16_f32 v98, v100, v101
	v_cvt_pk_bf16_f32 v99, v102, v99
	v_min_f32_e32 v103, 0x7e800000, v103
	v_add_f32_e32 v102, 1.0, v103
	v_rcp_f32_e32 v104, v102
	v_or_b32_e32 v100, 16, v150
	v_mad_i64_i32 v[100:101], s[26:27], v100, s53, v[112:113]
	v_lshl_add_u64 v[100:101], v[100:101], 0, v[114:115]
	global_store_dwordx4 v[100:101], v[96:99], off
	s_nop 1
	v_mul_f32_e32 v98, 0xbfb8aa3b, v93
	v_exp_f32_e32 v98, v98
	v_fma_f32 v97, -v102, v104, 1.0
	v_fma_f32 v96, v97, v104, v104
	v_min_f32_e32 v98, 0x7e800000, v98
	v_add_f32_e32 v97, 1.0, v98
	v_rcp_f32_e32 v99, v97
	v_mul_f32_e32 v92, v92, v96
	v_mul_f32_e32 v88, v92, v88
	v_mul_f32_e32 v100, 0xbfb8aa3b, v94
	v_exp_f32_e32 v100, v100
	v_fma_f32 v96, -v97, v99, 1.0
	v_fma_f32 v92, v96, v99, v99
	v_min_f32_e32 v100, 0x7e800000, v100
	v_add_f32_e32 v96, 1.0, v100
	v_rcp_f32_e32 v99, v96
	v_mul_f32_e32 v92, v93, v92
	v_mul_f32_e32 v89, v92, v89
	v_mul_f32_e32 v97, 0xbfb8aa3b, v95
	v_exp_f32_e32 v97, v97
	v_fma_f32 v93, -v96, v99, 1.0
	v_fma_f32 v92, v93, v99, v99
	v_min_f32_e32 v97, 0x7e800000, v97
	v_add_f32_e32 v93, 1.0, v97
	v_rcp_f32_e32 v98, v93
	v_mul_f32_e32 v92, v94, v92
	v_mul_f32_e32 v90, v92, v90
	v_mul_f32_e32 v96, 0xbfb8aa3b, v84
	v_exp_f32_e32 v96, v96
	v_fma_f32 v94, -v93, v98, 1.0
	v_fma_f32 v92, v94, v98, v98
	v_min_f32_e32 v96, 0x7e800000, v96
	v_add_f32_e32 v94, 1.0, v96
	v_rcp_f32_e32 v97, v94
	v_mul_f32_e32 v92, v95, v92
	v_mul_f32_e32 v91, v92, v91
	v_mul_f32_e32 v95, 0xbfb8aa3b, v85
	v_exp_f32_e32 v95, v95
	v_fma_f32 v93, -v94, v97, 1.0
	v_fma_f32 v92, v93, v97, v97
	v_min_f32_e32 v95, 0x7e800000, v95
	v_add_f32_e32 v93, 1.0, v95
	v_rcp_f32_e32 v96, v93
	v_mul_f32_e32 v84, v84, v92
	v_mul_f32_e32 v84, v84, v80
	v_mul_f32_e32 v94, 0xbfb8aa3b, v86
	v_exp_f32_e32 v94, v94
	v_fma_f32 v92, -v93, v96, 1.0
	v_fma_f32 v80, v92, v96, v96
	v_min_f32_e32 v94, 0x7e800000, v94
	v_add_f32_e32 v92, 1.0, v94
	v_rcp_f32_e32 v95, v92
	v_mul_f32_e32 v80, v85, v80
	v_mul_f32_e32 v85, v80, v81
	v_mul_f32_e32 v93, 0xbfb8aa3b, v87
	v_exp_f32_e32 v93, v93
	v_fma_f32 v81, -v92, v95, 1.0
	v_fma_f32 v80, v81, v95, v95
	v_min_f32_e32 v93, 0x7e800000, v93
	v_add_f32_e32 v81, 1.0, v93
	v_rcp_f32_e32 v94, v81
	v_mul_f32_e32 v80, v86, v80
	v_mul_f32_e32 v86, v80, v82
	v_fma_f32 v82, -v81, v94, 1.0
	v_fma_f32 v80, v82, v94, v94
	v_mul_f32_e32 v82, 0xbfb8aa3b, v76
	v_mul_f32_e32 v80, v87, v80
	v_exp_f32_e32 v87, v82
	v_mul_f32_e32 v83, v80, v83
	v_cvt_pk_bf16_f32 v80, v88, v89
	v_cvt_pk_bf16_f32 v81, v90, v91
	v_cvt_pk_bf16_f32 v82, v84, v85
	v_cvt_pk_bf16_f32 v83, v86, v83
	v_min_f32_e32 v87, 0x7e800000, v87
	v_add_f32_e32 v86, 1.0, v87
	v_rcp_f32_e32 v88, v86
	v_or_b32_e32 v84, 32, v150
	v_mad_i64_i32 v[84:85], s[26:27], v84, s53, v[112:113]
	v_lshl_add_u64 v[84:85], v[84:85], 0, v[114:115]
	global_store_dwordx4 v[84:85], v[80:83], off
	s_nop 1
	v_mul_f32_e32 v82, 0xbfb8aa3b, v77
	v_exp_f32_e32 v82, v82
	v_fma_f32 v81, -v86, v88, 1.0
	v_fma_f32 v80, v81, v88, v88
	v_min_f32_e32 v82, 0x7e800000, v82
	v_add_f32_e32 v81, 1.0, v82
	v_rcp_f32_e32 v83, v81
	v_mul_f32_e32 v76, v76, v80
	v_mul_f32_e32 v72, v76, v72
; __device__ __forceinline__ unsigned cvt_pk_bf16(float lo, float hi) { unsigned r; asm volatile("v_cvt_pk_bf16_f32 %0, %1, %2" : "=v"(r) : "v"(lo), "v"(hi)); return r; }
; __device__ __forceinline__ float sigmoidf_(float x) { return 1.0f / (1.0f + __expf(-x)); }
;     __device__ __forceinline__ void operator()(const f32x4 (&acc)[2][2][4][2], const Unit& u, int wr, int wc, int fr, int fq) const {
;     ...
;         for (int ai = 0; ai < 2; ++ai)
; #pragma unroll
;             for (int m = 0; m < 4; ++m) { float hv[8];
; #pragma unroll
;                 for (int n = 0; n < 2; ++n)
; #pragma unroll
;                     for (int i = 0; i < 4; ++i) { const float gt = acc[ai][0][m][n][i], up = acc[ai][1][m][n][i]; hv[4 * n + i] = gt * sigmoidf_(gt) * up; }
;                 u32x4 o; o[0] = cvt_pk_bf16(hv[0], hv[1]); o[1] = cvt_pk_bf16(hv[2], hv[3]); o[2] = cvt_pk_bf16(hv[4], hv[5]); o[3] = cvt_pk_bf16(hv[6], hv[7]);
;                 *(u32x4*)(O + (size_t)(row0 + ai * 128 + m * 16) * 5632 + col0) = o; }
	v_mul_f32_e32 v84, 0xbfb8aa3b, v78
	v_exp_f32_e32 v84, v84
	v_fma_f32 v80, -v81, v83, 1.0
	v_fma_f32 v76, v80, v83, v83
	v_min_f32_e32 v84, 0x7e800000, v84
	v_add_f32_e32 v80, 1.0, v84
	v_rcp_f32_e32 v83, v80
	v_mul_f32_e32 v76, v77, v76
	v_mul_f32_e32 v73, v76, v73
	v_mul_f32_e32 v81, 0xbfb8aa3b, v79
	v_exp_f32_e32 v81, v81
	v_fma_f32 v77, -v80, v83, 1.0
	v_fma_f32 v76, v77, v83, v83
	v_min_f32_e32 v81, 0x7e800000, v81
	v_add_f32_e32 v77, 1.0, v81
	v_rcp_f32_e32 v82, v77
	v_mul_f32_e32 v76, v78, v76
	v_mul_f32_e32 v74, v76, v74
	v_mul_f32_e32 v80, 0xbfb8aa3b, v68
	v_exp_f32_e32 v80, v80
	v_fma_f32 v78, -v77, v82, 1.0
	v_fma_f32 v76, v78, v82, v82
	v_min_f32_e32 v80, 0x7e800000, v80
	v_add_f32_e32 v78, 1.0, v80
	v_rcp_f32_e32 v81, v78
	v_mul_f32_e32 v76, v79, v76
	v_mul_f32_e32 v75, v76, v75
	v_mul_f32_e32 v79, 0xbfb8aa3b, v69
	v_exp_f32_e32 v79, v79
	v_fma_f32 v77, -v78, v81, 1.0
	v_fma_f32 v76, v77, v81, v81
	v_min_f32_e32 v79, 0x7e800000, v79
	v_add_f32_e32 v77, 1.0, v79
	v_rcp_f32_e32 v80, v77
	v_mul_f32_e32 v68, v68, v76
	v_mul_f32_e32 v68, v68, v64
	v_mul_f32_e32 v78, 0xbfb8aa3b, v70
	v_exp_f32_e32 v78, v78
	v_fma_f32 v76, -v77, v80, 1.0
	v_fma_f32 v64, v76, v80, v80
	v_min_f32_e32 v78, 0x7e800000, v78
	v_add_f32_e32 v76, 1.0, v78
	v_rcp_f32_e32 v79, v76
	v_mul_f32_e32 v64, v69, v64
	v_mul_f32_e32 v69, v64, v65
	v_mul_f32_e32 v77, 0xbfb8aa3b, v71
	v_exp_f32_e32 v77, v77
	v_fma_f32 v65, -v76, v79, 1.0
	v_fma_f32 v64, v65, v79, v79
	v_min_f32_e32 v77, 0x7e800000, v77
	v_add_f32_e32 v65, 1.0, v77
	v_rcp_f32_e32 v78, v65
	v_mul_f32_e32 v64, v70, v64
	v_mul_f32_e32 v70, v64, v66
	v_fma_f32 v66, -v65, v78, 1.0
	v_fma_f32 v64, v66, v78, v78
	v_mul_f32_e32 v64, v71, v64
	v_mul_f32_e32 v67, v64, v67
	v_cvt_pk_bf16_f32 v64, v72, v73
	v_cvt_pk_bf16_f32 v65, v74, v75
	v_cvt_pk_bf16_f32 v66, v68, v69
	v_mul_f32_e32 v68, 0xbfb8aa3b, v60
	v_cvt_pk_bf16_f32 v67, v70, v67
	v_exp_f32_e32 v70, v68
	v_or_b32_e32 v68, 48, v150
	v_mad_i64_i32 v[68:69], s[26:27], v68, s53, v[112:113]
	v_min_f32_e32 v70, 0x7e800000, v70
	v_add_f32_e32 v70, 1.0, v70
	v_rcp_f32_e32 v72, v70
	v_lshl_add_u64 v[68:69], v[68:69], 0, v[114:115]
	global_store_dwordx4 v[68:69], v[64:67], off
	s_nop 1
	v_mul_f32_e32 v67, 0xbfb8aa3b, v61
	v_exp_f32_e32 v67, v67
	v_fma_f32 v66, -v70, v72, 1.0
	v_fma_f32 v65, v66, v72, v72
	v_min_f32_e32 v67, 0x7e800000, v67
	v_add_f32_e32 v66, 1.0, v67
	v_rcp_f32_e32 v68, v66
	v_mul_f32_e32 v60, v60, v65
	v_mul_f32_e32 v56, v60, v56
	v_add_u32_e32 v64, 0x80, v150
	v_mul_f32_e32 v69, 0xbfb8aa3b, v62
	v_exp_f32_e32 v69, v69
	v_fma_f32 v65, -v66, v68, 1.0
	v_fma_f32 v60, v65, v68, v68
	v_min_f32_e32 v69, 0x7e800000, v69
	v_add_f32_e32 v65, 1.0, v69
	v_rcp_f32_e32 v68, v65
	v_mul_f32_e32 v60, v61, v60
	v_mul_f32_e32 v57, v60, v57
	v_mul_f32_e32 v66, 0xbfb8aa3b, v63
	v_exp_f32_e32 v66, v66
	v_fma_f32 v61, -v65, v68, 1.0
	v_fma_f32 v60, v61, v68, v68
	v_min_f32_e32 v66, 0x7e800000, v66
	v_add_f32_e32 v61, 1.0, v66
	v_rcp_f32_e32 v67, v61
	v_mul_f32_e32 v60, v62, v60
	v_mul_f32_e32 v58, v60, v58
	v_mul_f32_e32 v65, 0xbfb8aa3b, v52
	v_exp_f32_e32 v65, v65
	v_fma_f32 v62, -v61, v67, 1.0
	v_fma_f32 v60, v62, v67, v67
	v_min_f32_e32 v65, 0x7e800000, v65
	v_add_f32_e32 v62, 1.0, v65
	v_rcp_f32_e32 v66, v62
	v_mul_f32_e32 v60, v63, v60
	v_mul_f32_e32 v59, v60, v59
	v_mul_f32_e32 v63, 0xbfb8aa3b, v53
	v_exp_f32_e32 v63, v63
	v_fma_f32 v61, -v62, v66, 1.0
	v_fma_f32 v60, v61, v66, v66
	v_min_f32_e32 v63, 0x7e800000, v63
	v_add_f32_e32 v61, 1.0, v63
	v_rcp_f32_e32 v65, v61
	v_mul_f32_e32 v52, v52, v60
	v_mul_f32_e32 v52, v52, v48
	v_mul_f32_e32 v62, 0xbfb8aa3b, v54
	v_exp_f32_e32 v62, v62
	v_fma_f32 v60, -v61, v65, 1.0
	v_fma_f32 v48, v60, v65, v65
	v_min_f32_e32 v62, 0x7e800000, v62
	v_add_f32_e32 v60, 1.0, v62
	v_rcp_f32_e32 v63, v60
	v_mul_f32_e32 v48, v53, v48
	v_mul_f32_e32 v53, v48, v49
	v_mul_f32_e32 v61, 0xbfb8aa3b, v55
	v_exp_f32_e32 v61, v61
	v_fma_f32 v49, -v60, v63, 1.0
	v_fma_f32 v48, v49, v63, v63
	v_min_f32_e32 v61, 0x7e800000, v61
	v_add_f32_e32 v49, 1.0, v61
	v_rcp_f32_e32 v62, v49
	v_mul_f32_e32 v48, v54, v48
	v_mul_f32_e32 v54, v48, v50
	v_fma_f32 v50, -v49, v62, 1.0
	v_fma_f32 v48, v50, v62, v62
	v_mul_f32_e32 v49, 0xbfb8aa3b, v44
	v_mul_f32_e32 v48, v55, v48
	v_exp_f32_e32 v55, v49
	v_mul_f32_e32 v51, v48, v51
	v_cvt_pk_bf16_f32 v48, v56, v57
	v_cvt_pk_bf16_f32 v49, v58, v59
	v_cvt_pk_bf16_f32 v50, v52, v53
	v_cvt_pk_bf16_f32 v51, v54, v51
	v_min_f32_e32 v55, 0x7e800000, v55
	v_add_f32_e32 v54, 1.0, v55
	v_rcp_f32_e32 v56, v54
	v_mad_i64_i32 v[52:53], s[26:27], v64, s53, v[112:113]
	v_lshl_add_u64 v[52:53], v[52:53], 0, v[114:115]
	global_store_dwordx4 v[52:53], v[48:51], off
	s_nop 1
	v_mul_f32_e32 v50, 0xbfb8aa3b, v45
	v_exp_f32_e32 v50, v50
	v_fma_f32 v49, -v54, v56, 1.0
	v_fma_f32 v48, v49, v56, v56
	v_min_f32_e32 v50, 0x7e800000, v50
	v_add_f32_e32 v49, 1.0, v50
	v_rcp_f32_e32 v51, v49
	v_mul_f32_e32 v44, v44, v48
	v_mul_f32_e32 v40, v44, v40
	v_mul_f32_e32 v52, 0xbfb8aa3b, v46
	v_exp_f32_e32 v52, v52
	v_fma_f32 v48, -v49, v51, 1.0
	v_fma_f32 v44, v48, v51, v51
	v_min_f32_e32 v52, 0x7e800000, v52
	v_add_f32_e32 v48, 1.0, v52
	v_rcp_f32_e32 v51, v48
	v_mul_f32_e32 v44, v45, v44
	v_mul_f32_e32 v41, v44, v41
	v_mul_f32_e32 v49, 0xbfb8aa3b, v47
	v_exp_f32_e32 v49, v49
	v_fma_f32 v45, -v48, v51, 1.0
	v_fma_f32 v44, v45, v51, v51
	v_min_f32_e32 v49, 0x7e800000, v49
	v_add_f32_e32 v45, 1.0, v49
	v_rcp_f32_e32 v50, v45
	v_mul_f32_e32 v44, v46, v44
	v_mul_f32_e32 v42, v44, v42
	v_mul_f32_e32 v48, 0xbfb8aa3b, v36
	v_exp_f32_e32 v48, v48
	v_fma_f32 v46, -v45, v50, 1.0
	v_fma_f32 v44, v46, v50, v50
	v_min_f32_e32 v48, 0x7e800000, v48
; __device__ __forceinline__ unsigned cvt_pk_bf16(float lo, float hi) { unsigned r; asm volatile("v_cvt_pk_bf16_f32 %0, %1, %2" : "=v"(r) : "v"(lo), "v"(hi)); return r; }
; __device__ __forceinline__ float sigmoidf_(float x) { return 1.0f / (1.0f + __expf(-x)); }
; #define PG8_WAIT_V(n) asm volatile("s_waitcnt vmcnt(" #n ")" ::: "memory")
; #define PG8_BAR __builtin_amdgcn_s_barrier()
; template <class Epi>
; __device__ __forceinline__ void gemm_phase(LAS unsigned char* lds, const Gemm g, const StaticOrder& S, const Epi& E) {
;     ...
;         cur = nxt; cA = nA; cB = nB; ++ui;
;     }
;     PG8_WAIT_V(0);
;     if (wr == 0) PG8_BAR;
;     PG8_BAR;
;     __device__ __forceinline__ void operator()(const f32x4 (&acc)[2][2][4][2], const Unit& u, int wr, int wc, int fr, int fq) const {
;     ...
;         for (int ai = 0; ai < 2; ++ai)
; #pragma unroll
;             for (int m = 0; m < 4; ++m) { float hv[8];
; #pragma unroll
;                 for (int n = 0; n < 2; ++n)
; #pragma unroll
;                     for (int i = 0; i < 4; ++i) { const float gt = acc[ai][0][m][n][i], up = acc[ai][1][m][n][i]; hv[4 * n + i] = gt * sigmoidf_(gt) * up; }
;                 u32x4 o; o[0] = cvt_pk_bf16(hv[0], hv[1]); o[1] = cvt_pk_bf16(hv[2], hv[3]); o[2] = cvt_pk_bf16(hv[4], hv[5]); o[3] = cvt_pk_bf16(hv[6], hv[7]);
;                 *(u32x4*)(O + (size_t)(row0 + ai * 128 + m * 16) * 5632 + col0) = o; }
	v_add_f32_e32 v46, 1.0, v48
	v_rcp_f32_e32 v49, v46
	v_mul_f32_e32 v44, v47, v44
	v_mul_f32_e32 v43, v44, v43
	v_mul_f32_e32 v47, 0xbfb8aa3b, v37
	v_exp_f32_e32 v47, v47
	v_fma_f32 v45, -v46, v49, 1.0
	v_fma_f32 v44, v45, v49, v49
	v_min_f32_e32 v47, 0x7e800000, v47
	v_add_f32_e32 v45, 1.0, v47
	v_rcp_f32_e32 v48, v45
	v_mul_f32_e32 v36, v36, v44
	v_mul_f32_e32 v36, v36, v32
	v_mul_f32_e32 v46, 0xbfb8aa3b, v38
	v_exp_f32_e32 v46, v46
	v_fma_f32 v44, -v45, v48, 1.0
	v_fma_f32 v32, v44, v48, v48
	v_min_f32_e32 v46, 0x7e800000, v46
	v_add_f32_e32 v44, 1.0, v46
	v_rcp_f32_e32 v47, v44
	v_mul_f32_e32 v32, v37, v32
	v_mul_f32_e32 v37, v32, v33
	v_mul_f32_e32 v45, 0xbfb8aa3b, v39
	v_exp_f32_e32 v45, v45
	v_fma_f32 v33, -v44, v47, 1.0
	v_fma_f32 v32, v33, v47, v47
	v_min_f32_e32 v45, 0x7e800000, v45
	v_add_f32_e32 v33, 1.0, v45
	v_rcp_f32_e32 v46, v33
	v_mul_f32_e32 v32, v38, v32
	v_mul_f32_e32 v38, v32, v34
	v_fma_f32 v34, -v33, v46, 1.0
	v_fma_f32 v32, v34, v46, v46
	v_mul_f32_e32 v34, 0xbfb8aa3b, v28
	v_mul_f32_e32 v32, v39, v32
	v_exp_f32_e32 v39, v34
	v_mul_f32_e32 v35, v32, v35
	v_cvt_pk_bf16_f32 v32, v40, v41
	v_cvt_pk_bf16_f32 v33, v42, v43
	v_cvt_pk_bf16_f32 v34, v36, v37
	v_cvt_pk_bf16_f32 v35, v38, v35
	v_min_f32_e32 v39, 0x7e800000, v39
	v_add_f32_e32 v38, 1.0, v39
	v_rcp_f32_e32 v40, v38
	v_add_u32_e32 v36, 0x90, v150
	v_mad_i64_i32 v[36:37], s[26:27], v36, s53, v[112:113]
	v_lshl_add_u64 v[36:37], v[36:37], 0, v[114:115]
	global_store_dwordx4 v[36:37], v[32:35], off
	s_nop 1
	v_mul_f32_e32 v34, 0xbfb8aa3b, v29
	v_exp_f32_e32 v34, v34
	v_fma_f32 v33, -v38, v40, 1.0
	v_fma_f32 v32, v33, v40, v40
	v_min_f32_e32 v34, 0x7e800000, v34
	v_add_f32_e32 v33, 1.0, v34
	v_rcp_f32_e32 v35, v33
	v_mul_f32_e32 v28, v28, v32
	v_mul_f32_e32 v24, v28, v24
	v_mul_f32_e32 v36, 0xbfb8aa3b, v30
	v_exp_f32_e32 v36, v36
	v_fma_f32 v32, -v33, v35, 1.0
	v_fma_f32 v28, v32, v35, v35
	v_min_f32_e32 v36, 0x7e800000, v36
	v_add_f32_e32 v32, 1.0, v36
	v_rcp_f32_e32 v35, v32
	v_mul_f32_e32 v28, v29, v28
	v_mul_f32_e32 v25, v28, v25
	v_mul_f32_e32 v33, 0xbfb8aa3b, v31
	v_exp_f32_e32 v33, v33
	v_fma_f32 v29, -v32, v35, 1.0
	v_fma_f32 v28, v29, v35, v35
	v_min_f32_e32 v33, 0x7e800000, v33
	v_add_f32_e32 v29, 1.0, v33
	v_rcp_f32_e32 v34, v29
	v_mul_f32_e32 v28, v30, v28
	v_mul_f32_e32 v26, v28, v26
	v_mul_f32_e32 v32, 0xbfb8aa3b, v20
	v_exp_f32_e32 v32, v32
	v_fma_f32 v30, -v29, v34, 1.0
	v_fma_f32 v28, v30, v34, v34
	v_min_f32_e32 v32, 0x7e800000, v32
	v_add_f32_e32 v30, 1.0, v32
	v_rcp_f32_e32 v33, v30
	v_mul_f32_e32 v28, v31, v28
	v_mul_f32_e32 v27, v28, v27
	v_mul_f32_e32 v31, 0xbfb8aa3b, v21
	v_exp_f32_e32 v31, v31
	v_fma_f32 v29, -v30, v33, 1.0
	v_fma_f32 v28, v29, v33, v33
	v_min_f32_e32 v31, 0x7e800000, v31
	v_add_f32_e32 v29, 1.0, v31
	v_rcp_f32_e32 v32, v29
	v_mul_f32_e32 v20, v20, v28
	v_mul_f32_e32 v20, v20, v16
	v_mul_f32_e32 v30, 0xbfb8aa3b, v22
	v_exp_f32_e32 v30, v30
	v_fma_f32 v28, -v29, v32, 1.0
	v_fma_f32 v16, v28, v32, v32
	v_min_f32_e32 v30, 0x7e800000, v30
	v_add_f32_e32 v28, 1.0, v30
	v_rcp_f32_e32 v31, v28
	v_mul_f32_e32 v16, v21, v16
	v_mul_f32_e32 v21, v16, v17
	v_mul_f32_e32 v29, 0xbfb8aa3b, v23
	v_exp_f32_e32 v29, v29
	v_fma_f32 v17, -v28, v31, 1.0
	v_fma_f32 v16, v17, v31, v31
	v_min_f32_e32 v29, 0x7e800000, v29
	v_add_f32_e32 v17, 1.0, v29
	v_rcp_f32_e32 v30, v17
	v_mul_f32_e32 v16, v22, v16
	v_mul_f32_e32 v22, v16, v18
	v_fma_f32 v18, -v17, v30, 1.0
	v_fma_f32 v16, v18, v30, v30
	v_mul_f32_e32 v18, 0xbfb8aa3b, v12
	v_mul_f32_e32 v16, v23, v16
	v_exp_f32_e32 v23, v18
	v_mul_f32_e32 v19, v16, v19
	v_cvt_pk_bf16_f32 v16, v24, v25
	v_cvt_pk_bf16_f32 v17, v26, v27
	v_cvt_pk_bf16_f32 v18, v20, v21
	v_cvt_pk_bf16_f32 v19, v22, v19
	v_min_f32_e32 v23, 0x7e800000, v23
	v_add_f32_e32 v22, 1.0, v23
	v_rcp_f32_e32 v24, v22
	v_add_u32_e32 v20, 0xa0, v150
	v_mad_i64_i32 v[20:21], s[26:27], v20, s53, v[112:113]
	v_lshl_add_u64 v[20:21], v[20:21], 0, v[114:115]
	global_store_dwordx4 v[20:21], v[16:19], off
	s_nop 1
	v_mul_f32_e32 v18, 0xbfb8aa3b, v13
	v_exp_f32_e32 v18, v18
	v_fma_f32 v17, -v22, v24, 1.0
	v_fma_f32 v16, v17, v24, v24
	v_min_f32_e32 v18, 0x7e800000, v18
	v_add_f32_e32 v17, 1.0, v18
	v_rcp_f32_e32 v19, v17
	v_mul_f32_e32 v12, v12, v16
	v_mul_f32_e32 v8, v12, v8
	v_mul_f32_e32 v20, 0xbfb8aa3b, v14
	v_exp_f32_e32 v20, v20
	v_fma_f32 v16, -v17, v19, 1.0
	v_fma_f32 v12, v16, v19, v19
	v_min_f32_e32 v20, 0x7e800000, v20
	v_add_f32_e32 v16, 1.0, v20
	v_rcp_f32_e32 v19, v16
	v_mul_f32_e32 v12, v13, v12
	v_mul_f32_e32 v9, v12, v9
	v_mul_f32_e32 v17, 0xbfb8aa3b, v15
	v_exp_f32_e32 v17, v17
	v_fma_f32 v13, -v16, v19, 1.0
	v_fma_f32 v12, v13, v19, v19
	v_min_f32_e32 v17, 0x7e800000, v17
	v_add_f32_e32 v13, 1.0, v17
	v_rcp_f32_e32 v18, v13
	v_mul_f32_e32 v12, v14, v12
	v_mul_f32_e32 v10, v12, v10
	v_mul_f32_e32 v16, 0xbfb8aa3b, v4
	v_exp_f32_e32 v16, v16
	v_fma_f32 v14, -v13, v18, 1.0
	v_fma_f32 v12, v14, v18, v18
	v_min_f32_e32 v16, 0x7e800000, v16
	v_add_f32_e32 v14, 1.0, v16
	v_rcp_f32_e32 v17, v14
	v_mul_f32_e32 v12, v15, v12
	v_mul_f32_e32 v11, v12, v11
	v_mul_f32_e32 v15, 0xbfb8aa3b, v5
	v_exp_f32_e32 v15, v15
	v_fma_f32 v13, -v14, v17, 1.0
	v_fma_f32 v12, v13, v17, v17
	v_min_f32_e32 v15, 0x7e800000, v15
	v_add_f32_e32 v13, 1.0, v15
	v_rcp_f32_e32 v16, v13
	v_mul_f32_e32 v4, v4, v12
	v_mul_f32_e32 v4, v4, v0
	v_mul_f32_e32 v14, 0xbfb8aa3b, v6
	v_exp_f32_e32 v14, v14
	v_fma_f32 v12, -v13, v16, 1.0
	v_fma_f32 v0, v12, v16, v16
	v_min_f32_e32 v14, 0x7e800000, v14
	v_add_f32_e32 v12, 1.0, v14
	v_rcp_f32_e32 v15, v12
	v_mul_f32_e32 v0, v5, v0
	v_mul_f32_e32 v5, v0, v1
	v_mul_f32_e32 v13, 0xbfb8aa3b, v7
	v_exp_f32_e32 v13, v13
	v_fma_f32 v1, -v12, v15, 1.0
	v_fma_f32 v0, v1, v15, v15
	v_min_f32_e32 v13, 0x7e800000, v13
	v_add_f32_e32 v1, 1.0, v13
	v_rcp_f32_e32 v14, v1
	v_mul_f32_e32 v0, v6, v0
	v_mul_f32_e32 v6, v0, v2
	v_fma_f32 v2, -v1, v14, 1.0
	v_fma_f32 v0, v2, v14, v14
	v_mul_f32_e32 v0, v7, v0
	v_mul_f32_e32 v3, v0, v3
	v_cvt_pk_bf16_f32 v0, v8, v9
	v_cvt_pk_bf16_f32 v1, v10, v11
	v_cvt_pk_bf16_f32 v2, v4, v5
	v_add_u32_e32 v4, 0xb0, v150
	v_mad_i64_i32 v[4:5], s[26:27], v4, s53, v[112:113]
	v_lshl_add_u64 v[4:5], v[4:5], 0, v[114:115]
	s_and_b64 vcc, exec, s[4:5]
	s_mov_b64 s[26:27], s[14:15]
	v_cvt_pk_bf16_f32 v3, v6, v3
	global_store_dwordx4 v[4:5], v[0:3], off
	s_cbranch_vccz .LBB0_1766
	s_waitcnt vmcnt(0)
	s_cmpk_gt_u32 s2, 0xff
	s_cbranch_scc1 .LBB0_1773
	s_barrier

; #define PG8_STAGE(bufoff, gbase, voff) do { _Pragma("unroll") for (int _i = 0; _i < 2; ++_i) \
;         __builtin_amdgcn_global_load_lds((const unsigned*)((const char*)(gbase) + (voff)[_i]), (LAS unsigned*)(lds + (bufoff) + ldsw + _i * 8192), 16, 0, 0); } while (0)
; #define PG8_LDA(dst, b, h) do { _Pragma("unroll") for (int m = 0; m < 4; ++m) _Pragma("unroll") for (int k = 0; k < 2; ++k) dst[m][k] = *(const LAS bf16x8*)(lds + PG8_SA(b, h) + aoff + m * 2048 + k * 1024); } while (0)
; #define PG8_LDB(dst, b, h) do { _Pragma("unroll") for (int n = 0; n < 2; ++n) _Pragma("unroll") for (int k = 0; k < 2; ++k) dst[n][k] = *(const LAS bf16x8*)(lds + PG8_SB(b, h) + boff + n * 2048 + k * 1024); } while (0)
; #define PG8_MMA(ai, bj, At, Bt) do { __builtin_amdgcn_s_setprio(1); _Pragma("unroll") for (int m = 0; m < 4; ++m) _Pragma("unroll") for (int n = 0; n < 2; ++n) _Pragma("unroll") for (int k = 0; k < 2; ++k) \
;         acc[ai][bj][m][n] = __builtin_amdgcn_mfma_f32_16x16x32_bf16(Bt[n][k], At[m][k], acc[ai][bj][m][n], 0, 0, 0); __builtin_amdgcn_s_setprio(0); } while (0)
; #define PG8_WAIT_V(n) asm volatile("s_waitcnt vmcnt(" #n ")" ::: "memory")
; #define PG8_WAIT_L(n) asm volatile("s_waitcnt lgkmcnt(" #n ")" ::: "memory")
; template <class Epi>
; __device__ __forceinline__ void gemm_phase(LAS unsigned char* lds, const Gemm g, const StaticOrder& S, const Epi& E) {
;     ...
;         for (int t = 0; t < nt; t += 2) {
;             const bool last = (t == nt - 2);
;             const char* a1 = cA + (size_t)(t + 1) * kstep;
;             const char* a2 = last ? nA : cA + (size_t)(t + 2) * kstep; const char* b2 = last ? nB : cB + (size_t)(t + 2) * kstep;
;             const char* a3 = a2 + kstep; const char* b3 = b2 + kstep;
;             PG8_LDB(B0, 0, 0); PG8_SCHED; PG8_LDA(At, 0, 0); PG8_STAGE(PG8_SA(1, 1), a1 + hstep, voffA);
;             PG8_WAIT_L(8); PG8_BAR; PG8_WAIT_L(0); PG8_MMA(0, 0, At, B0); PG8_BAR; PG8_SCHED;
;             PG8_LDB(B1, 0, 1); PG8_STAGE(PG8_SB(0, 0), b2, voffB);
;             PG8_BAR; PG8_WAIT_L(0); PG8_MMA(0, 1, At, B1); PG8_BAR;
;             PG8_LDA(At, 0, 1); PG8_STAGE(PG8_SA(0, 0), a2, voffA);
;             PG8_BAR; PG8_WAIT_L(0); PG8_MMA(1, 0, At, B0); PG8_BAR; PG8_SCHED;
;             PG8_STAGE(PG8_SB(0, 1), b2 + hstep, voffB);
;             PG8_WAIT_V(6); PG8_BAR; PG8_MMA(1, 1, At, B1); PG8_BAR;
.LBB0_2209:
	ds_read_b128 v[150:153], v147
	ds_read_b128 v[154:157], v147 offset:1024
	ds_read_b128 v[158:161], v147 offset:2048
	ds_read_b128 v[162:165], v147 offset:3072
	s_add_u32 s22, s20, 0xfff80080
	s_addc_u32 s23, s21, -1
	s_cmp_eq_u32 s55, 28
	s_cselect_b32 s27, s11, s23
	s_cselect_b32 s26, s51, s22
	s_cselect_b32 s23, s7, s54
	s_cselect_b32 s22, s52, s53
	v_lshl_add_u64 v[200:201], s[20:21], 0, v[136:137]
	s_add_i32 m0, s17, 0xc000
	ds_read_b128 v[166:169], v148
	ds_read_b128 v[172:175], v148 offset:1024
	ds_read_b128 v[176:179], v148 offset:2048
	ds_read_b128 v[180:183], v148 offset:3072
	ds_read_b128 v[184:187], v148 offset:4096
	ds_read_b128 v[188:191], v148 offset:5120
	ds_read_b128 v[192:195], v148 offset:6144
	ds_read_b128 v[196:199], v148 offset:7168
	global_load_lds_dwordx4 v[200:201], off
	v_lshl_add_u64 v[200:201], s[20:21], 0, v[138:139]
	s_add_i32 m0, s17, 0xe000
	s_nop 0
	global_load_lds_dwordx4 v[200:201], off
	s_waitcnt lgkmcnt(8)
	s_barrier
	s_waitcnt lgkmcnt(0)
	s_setprio 1
	s_waitcnt lgkmcnt(0)
	v_mfma_f32_16x16x32_bf16 v[124:127], v[150:153], v[166:169], v[124:127]
	v_mfma_f32_16x16x32_bf16 v[116:119], v[158:161], v[166:169], v[116:119]
	v_mfma_f32_16x16x32_bf16 v[108:111], v[150:153], v[176:179], v[108:111]
	v_mfma_f32_16x16x32_bf16 v[100:103], v[158:161], v[176:179], v[100:103]
	v_mfma_f32_16x16x32_bf16 v[92:95], v[150:153], v[184:187], v[92:95]
	v_mfma_f32_16x16x32_bf16 v[84:87], v[158:161], v[184:187], v[84:87]
	v_mfma_f32_16x16x32_bf16 v[76:79], v[150:153], v[192:195], v[76:79]
	v_mfma_f32_16x16x32_bf16 v[68:71], v[158:161], v[192:195], v[68:71]
	v_mfma_f32_16x16x32_bf16 v[124:127], v[154:157], v[172:175], v[124:127]
	v_mfma_f32_16x16x32_bf16 v[116:119], v[162:165], v[172:175], v[116:119]
	v_mfma_f32_16x16x32_bf16 v[108:111], v[154:157], v[180:183], v[108:111]
	v_mfma_f32_16x16x32_bf16 v[100:103], v[162:165], v[180:183], v[100:103]
	v_mfma_f32_16x16x32_bf16 v[92:95], v[154:157], v[188:191], v[92:95]
	v_mfma_f32_16x16x32_bf16 v[84:87], v[162:165], v[188:191], v[84:87]
	v_mfma_f32_16x16x32_bf16 v[76:79], v[154:157], v[196:199], v[76:79]
	v_mfma_f32_16x16x32_bf16 v[68:71], v[162:165], v[196:199], v[68:71]
	s_setprio 0
	s_barrier
	s_add_i32 s56, s43, s31
	v_lshl_add_u64 v[216:217], s[22:23], 0, v[132:133]
	s_mov_b32 m0, s56
	ds_read_b128 v[200:203], v149
	ds_read_b128 v[204:207], v149 offset:1024
	ds_read_b128 v[208:211], v149 offset:2048
	ds_read_b128 v[212:215], v149 offset:3072
	global_load_lds_dwordx4 v[216:217], off
	v_lshl_add_u64 v[218:219], s[22:23], 0, v[128:129]
	s_add_i32 m0, s56, 0x2000
	s_nop 0
	global_load_lds_dwordx4 v[218:219], off
	s_barrier
	s_waitcnt lgkmcnt(0)
	s_setprio 1
	s_waitcnt lgkmcnt(0)
	v_mfma_f32_16x16x32_bf16 v[120:123], v[200:203], v[166:169], v[120:123]
	v_mfma_f32_16x16x32_bf16 v[112:115], v[208:211], v[166:169], v[112:115]
	v_mfma_f32_16x16x32_bf16 v[104:107], v[200:203], v[176:179], v[104:107]
	v_mfma_f32_16x16x32_bf16 v[96:99], v[208:211], v[176:179], v[96:99]
	v_mfma_f32_16x16x32_bf16 v[88:91], v[200:203], v[184:187], v[88:91]
	v_mfma_f32_16x16x32_bf16 v[80:83], v[208:211], v[184:187], v[80:83]
	v_mfma_f32_16x16x32_bf16 v[72:75], v[200:203], v[192:195], v[72:75]
	v_mfma_f32_16x16x32_bf16 v[64:67], v[208:211], v[192:195], v[64:67]
	v_mfma_f32_16x16x32_bf16 v[120:123], v[204:207], v[172:175], v[120:123]
	v_mfma_f32_16x16x32_bf16 v[112:115], v[212:215], v[172:175], v[112:115]
	v_mfma_f32_16x16x32_bf16 v[104:107], v[204:207], v[180:183], v[104:107]
	v_mfma_f32_16x16x32_bf16 v[96:99], v[212:215], v[180:183], v[96:99]
	v_mfma_f32_16x16x32_bf16 v[88:91], v[204:207], v[188:191], v[88:91]
	v_mfma_f32_16x16x32_bf16 v[80:83], v[212:215], v[188:191], v[80:83]
	v_mfma_f32_16x16x32_bf16 v[72:75], v[204:207], v[196:199], v[72:75]
	v_mfma_f32_16x16x32_bf16 v[64:67], v[212:215], v[196:199], v[64:67]
	s_setprio 0
	s_mov_b32 m0, s17
	v_lshl_add_u64 v[220:221], s[26:27], 0, v[134:135]
	s_barrier
	ds_read_b128 v[166:169], v148 offset:16384
	ds_read_b128 v[172:175], v148 offset:17408
	ds_read_b128 v[176:179], v148 offset:18432
	ds_read_b128 v[180:183], v148 offset:19456
	ds_read_b128 v[184:187], v148 offset:20480
	ds_read_b128 v[188:191], v148 offset:21504
	ds_read_b128 v[192:195], v148 offset:22528
	ds_read_b128 v[196:199], v148 offset:23552
	global_load_lds_dwordx4 v[220:221], off
	v_lshl_add_u64 v[222:223], s[26:27], 0, v[130:131]
	s_mov_b32 m0, s36
	s_nop 0
	global_load_lds_dwordx4 v[222:223], off
	s_barrier
	s_waitcnt lgkmcnt(0)
	s_setprio 1
	s_waitcnt lgkmcnt(0)
	v_mfma_f32_16x16x32_bf16 v[60:63], v[150:153], v[166:169], v[60:63]
	v_mfma_f32_16x16x32_bf16 v[52:55], v[158:161], v[166:169], v[52:55]
	v_mfma_f32_16x16x32_bf16 v[44:47], v[150:153], v[176:179], v[44:47]
	v_mfma_f32_16x16x32_bf16 v[36:39], v[158:161], v[176:179], v[36:39]
	v_mfma_f32_16x16x32_bf16 v[28:31], v[150:153], v[184:187], v[28:31]
	v_mfma_f32_16x16x32_bf16 v[20:23], v[158:161], v[184:187], v[20:23]
	v_mfma_f32_16x16x32_bf16 v[12:15], v[150:153], v[192:195], v[12:15]
	v_mfma_f32_16x16x32_bf16 v[4:7], v[158:161], v[192:195], v[4:7]
	v_mfma_f32_16x16x32_bf16 v[60:63], v[154:157], v[172:175], v[60:63]
	v_mfma_f32_16x16x32_bf16 v[52:55], v[162:165], v[172:175], v[52:55]
	v_mfma_f32_16x16x32_bf16 v[44:47], v[154:157], v[180:183], v[44:47]
	v_mfma_f32_16x16x32_bf16 v[36:39], v[162:165], v[180:183], v[36:39]
	v_mfma_f32_16x16x32_bf16 v[28:31], v[154:157], v[188:191], v[28:31]
	v_mfma_f32_16x16x32_bf16 v[20:23], v[162:165], v[188:191], v[20:23]
	v_mfma_f32_16x16x32_bf16 v[12:15], v[154:157], v[196:199], v[12:15]
	v_mfma_f32_16x16x32_bf16 v[4:7], v[162:165], v[196:199], v[4:7]
	s_setprio 0
	s_barrier
; #define PG8_STAGE(bufoff, gbase, voff) do { _Pragma("unroll") for (int _i = 0; _i < 2; ++_i) \
;         __builtin_amdgcn_global_load_lds((const unsigned*)((const char*)(gbase) + (voff)[_i]), (LAS unsigned*)(lds + (bufoff) + ldsw + _i * 8192), 16, 0, 0); } while (0)
; #define PG8_LDA(dst, b, h) do { _Pragma("unroll") for (int m = 0; m < 4; ++m) _Pragma("unroll") for (int k = 0; k < 2; ++k) dst[m][k] = *(const LAS bf16x8*)(lds + PG8_SA(b, h) + aoff + m * 2048 + k * 1024); } while (0)
; #define PG8_LDB(dst, b, h) do { _Pragma("unroll") for (int n = 0; n < 2; ++n) _Pragma("unroll") for (int k = 0; k < 2; ++k) dst[n][k] = *(const LAS bf16x8*)(lds + PG8_SB(b, h) + boff + n * 2048 + k * 1024); } while (0)
; #define PG8_MMA(ai, bj, At, Bt) do { __builtin_amdgcn_s_setprio(1); _Pragma("unroll") for (int m = 0; m < 4; ++m) _Pragma("unroll") for (int n = 0; n < 2; ++n) _Pragma("unroll") for (int k = 0; k < 2; ++k) \
;         acc[ai][bj][m][n] = __builtin_amdgcn_mfma_f32_16x16x32_bf16(Bt[n][k], At[m][k], acc[ai][bj][m][n], 0, 0, 0); __builtin_amdgcn_s_setprio(0); } while (0)
; #define PG8_WAIT_V(n) asm volatile("s_waitcnt vmcnt(" #n ")" ::: "memory")
; #define PG8_WAIT_L(n) asm volatile("s_waitcnt lgkmcnt(" #n ")" ::: "memory")
; #define PG8_BAR __builtin_amdgcn_s_barrier()
; #define PG8_SCHED __builtin_amdgcn_sched_barrier(0)
; template <class Epi>
; __device__ __forceinline__ void gemm_phase(LAS unsigned char* lds, const Gemm g, const StaticOrder& S, const Epi& E) {
;     ...
;             PG8_LDB(B1, 0, 1); PG8_STAGE(PG8_SB(0, 0), b2, voffB);
;             PG8_BAR; PG8_WAIT_L(0); PG8_MMA(0, 1, At, B1); PG8_BAR;
;             PG8_LDA(At, 0, 1); PG8_STAGE(PG8_SA(0, 0), a2, voffA);
;             PG8_BAR; PG8_WAIT_L(0); PG8_MMA(1, 0, At, B0); PG8_BAR; PG8_SCHED;
;             PG8_STAGE(PG8_SB(0, 1), b2 + hstep, voffB);
;             PG8_WAIT_V(6); PG8_BAR; PG8_MMA(1, 1, At, B1); PG8_BAR;
;             PG8_LDB(B0, 1, 0); PG8_SCHED; PG8_LDA(At, 1, 0); PG8_STAGE(PG8_SA(0, 1), a2 + hstep, voffA);
;             PG8_WAIT_L(8); PG8_BAR; PG8_WAIT_L(0); PG8_MMA(0, 0, At, B0); PG8_BAR; PG8_SCHED;
;             PG8_LDB(B1, 1, 1); PG8_STAGE(PG8_SB(1, 0), b3, voffB);
;             PG8_BAR; PG8_WAIT_L(0); PG8_MMA(0, 1, At, B1); PG8_BAR;
;             PG8_LDA(At, 1, 1); PG8_STAGE(PG8_SA(1, 0), a3, voffA);
;             PG8_BAR; PG8_WAIT_L(0); PG8_MMA(1, 0, At, B0); PG8_BAR; PG8_SCHED;
	s_add_u32 s56, s22, 0x80000
	s_addc_u32 s57, s23, 0
	s_add_i32 s58, s48, s31
	v_lshl_add_u64 v[150:151], s[56:57], 0, v[132:133]
	s_mov_b32 m0, s58
	s_nop 0
	global_load_lds_dwordx4 v[150:151], off
	v_lshl_add_u64 v[150:151], s[56:57], 0, v[128:129]
	s_add_i32 m0, s58, 0x2000
	s_nop 0
	global_load_lds_dwordx4 v[150:151], off
	s_waitcnt vmcnt(6)
	s_barrier
	s_setprio 1
	v_mfma_f32_16x16x32_bf16 v[56:59], v[200:203], v[166:169], v[56:59]
	v_mfma_f32_16x16x32_bf16 v[48:51], v[208:211], v[166:169], v[48:51]
	v_mfma_f32_16x16x32_bf16 v[40:43], v[200:203], v[176:179], v[40:43]
	v_mfma_f32_16x16x32_bf16 v[32:35], v[208:211], v[176:179], v[32:35]
	v_mfma_f32_16x16x32_bf16 v[24:27], v[200:203], v[184:187], v[24:27]
	v_mfma_f32_16x16x32_bf16 v[16:19], v[208:211], v[184:187], v[16:19]
	v_mfma_f32_16x16x32_bf16 v[8:11], v[200:203], v[192:195], v[8:11]
	v_mfma_f32_16x16x32_bf16 v[0:3], v[208:211], v[192:195], v[0:3]
	v_mfma_f32_16x16x32_bf16 v[56:59], v[204:207], v[172:175], v[56:59]
	v_mfma_f32_16x16x32_bf16 v[48:51], v[212:215], v[172:175], v[48:51]
	v_mfma_f32_16x16x32_bf16 v[40:43], v[204:207], v[180:183], v[40:43]
	v_mfma_f32_16x16x32_bf16 v[32:35], v[212:215], v[180:183], v[32:35]
	v_mfma_f32_16x16x32_bf16 v[24:27], v[204:207], v[188:191], v[24:27]
	v_mfma_f32_16x16x32_bf16 v[16:19], v[212:215], v[188:191], v[16:19]
	v_mfma_f32_16x16x32_bf16 v[8:11], v[204:207], v[196:199], v[8:11]
	v_mfma_f32_16x16x32_bf16 v[0:3], v[212:215], v[196:199], v[0:3]
	s_setprio 0
	s_add_i32 s56, 0, 0x18000
	v_add_u32_e32 v162, s56, v145
	s_barrier
	ds_read_b128 v[150:153], v162
	ds_read_b128 v[154:157], v162 offset:1024
	ds_read_b128 v[158:161], v162 offset:2048
	ds_read_b128 v[162:165], v162 offset:3072
	s_add_u32 s26, s26, 0x80000
	s_addc_u32 s27, s27, 0
	s_mov_b32 m0, s37
	v_lshl_add_u64 v[200:201], s[26:27], 0, v[134:135]
	ds_read_b128 v[166:169], v148 offset:32768
	ds_read_b128 v[172:175], v148 offset:33792
	ds_read_b128 v[176:179], v148 offset:34816
	ds_read_b128 v[180:183], v148 offset:35840
	ds_read_b128 v[184:187], v148 offset:36864
	ds_read_b128 v[188:191], v148 offset:37888
	ds_read_b128 v[192:195], v148 offset:38912
	ds_read_b128 v[196:199], v148 offset:39936
	global_load_lds_dwordx4 v[200:201], off
	v_lshl_add_u64 v[200:201], s[26:27], 0, v[130:131]
	s_mov_b32 m0, s38
	s_nop 0
	global_load_lds_dwordx4 v[200:201], off
	s_waitcnt lgkmcnt(8)
	s_barrier
	s_waitcnt lgkmcnt(0)
	s_setprio 1
	s_waitcnt lgkmcnt(0)
	v_mfma_f32_16x16x32_bf16 v[124:127], v[150:153], v[166:169], v[124:127]
	v_mfma_f32_16x16x32_bf16 v[116:119], v[158:161], v[166:169], v[116:119]
	v_mfma_f32_16x16x32_bf16 v[108:111], v[150:153], v[176:179], v[108:111]
	v_mfma_f32_16x16x32_bf16 v[100:103], v[158:161], v[176:179], v[100:103]
	v_mfma_f32_16x16x32_bf16 v[92:95], v[150:153], v[184:187], v[92:95]
	v_mfma_f32_16x16x32_bf16 v[84:87], v[158:161], v[184:187], v[84:87]
	v_mfma_f32_16x16x32_bf16 v[76:79], v[150:153], v[192:195], v[76:79]
	v_mfma_f32_16x16x32_bf16 v[68:71], v[158:161], v[192:195], v[68:71]
	v_mfma_f32_16x16x32_bf16 v[124:127], v[154:157], v[172:175], v[124:127]
	v_mfma_f32_16x16x32_bf16 v[116:119], v[162:165], v[172:175], v[116:119]
	v_mfma_f32_16x16x32_bf16 v[108:111], v[154:157], v[180:183], v[108:111]
	v_mfma_f32_16x16x32_bf16 v[100:103], v[162:165], v[180:183], v[100:103]
	v_mfma_f32_16x16x32_bf16 v[92:95], v[154:157], v[188:191], v[92:95]
	v_mfma_f32_16x16x32_bf16 v[84:87], v[162:165], v[188:191], v[84:87]
	v_mfma_f32_16x16x32_bf16 v[76:79], v[154:157], v[196:199], v[76:79]
	v_mfma_f32_16x16x32_bf16 v[68:71], v[162:165], v[196:199], v[68:71]
	s_setprio 0
	s_barrier
	s_add_i32 s26, 0, 0x1c000
	s_add_i32 s27, s56, s31
	v_add_u32_e32 v171, s26, v145
	v_lshl_add_u64 v[216:217], v[216:217], 0, s[0:1]
	s_mov_b32 m0, s27
	ds_read_b128 v[200:203], v171
	ds_read_b128 v[204:207], v171 offset:1024
	ds_read_b128 v[208:211], v171 offset:2048
	ds_read_b128 v[212:215], v171 offset:3072
	global_load_lds_dwordx4 v[216:217], off
	v_lshl_add_u64 v[216:217], v[218:219], 0, s[0:1]
	s_add_i32 m0, s27, 0x2000
	s_nop 0
	global_load_lds_dwordx4 v[216:217], off
	s_barrier
	s_waitcnt lgkmcnt(0)
	s_setprio 1
	s_waitcnt lgkmcnt(0)
	v_mfma_f32_16x16x32_bf16 v[120:123], v[200:203], v[166:169], v[120:123]
	v_mfma_f32_16x16x32_bf16 v[112:115], v[208:211], v[166:169], v[112:115]
	v_mfma_f32_16x16x32_bf16 v[104:107], v[200:203], v[176:179], v[104:107]
	v_mfma_f32_16x16x32_bf16 v[96:99], v[208:211], v[176:179], v[96:99]
	v_mfma_f32_16x16x32_bf16 v[88:91], v[200:203], v[184:187], v[88:91]
	v_mfma_f32_16x16x32_bf16 v[80:83], v[208:211], v[184:187], v[80:83]
	v_mfma_f32_16x16x32_bf16 v[72:75], v[200:203], v[192:195], v[72:75]
	v_mfma_f32_16x16x32_bf16 v[64:67], v[208:211], v[192:195], v[64:67]
	v_mfma_f32_16x16x32_bf16 v[120:123], v[204:207], v[172:175], v[120:123]
	v_mfma_f32_16x16x32_bf16 v[112:115], v[212:215], v[172:175], v[112:115]
	v_mfma_f32_16x16x32_bf16 v[104:107], v[204:207], v[180:183], v[104:107]
	v_mfma_f32_16x16x32_bf16 v[96:99], v[212:215], v[180:183], v[96:99]
	v_mfma_f32_16x16x32_bf16 v[88:91], v[204:207], v[188:191], v[88:91]
	v_mfma_f32_16x16x32_bf16 v[80:83], v[212:215], v[188:191], v[80:83]
	v_mfma_f32_16x16x32_bf16 v[72:75], v[204:207], v[196:199], v[72:75]
	v_mfma_f32_16x16x32_bf16 v[64:67], v[212:215], v[196:199], v[64:67]
	s_setprio 0
	s_mov_b32 m0, s40
	v_lshl_add_u64 v[216:217], v[220:221], 0, s[0:1]
	s_barrier
	ds_read_b128 v[166:169], v148 offset:49152
	ds_read_b128 v[172:175], v148 offset:50176
	ds_read_b128 v[176:179], v148 offset:51200
	ds_read_b128 v[180:183], v148 offset:52224
	ds_read_b128 v[184:187], v148 offset:53248
	ds_read_b128 v[188:191], v148 offset:54272
	ds_read_b128 v[192:195], v148 offset:55296
	ds_read_b128 v[196:199], v148 offset:56320
	global_load_lds_dwordx4 v[216:217], off
	v_lshl_add_u64 v[216:217], v[222:223], 0, s[0:1]
	s_mov_b32 m0, s41
	s_nop 0
	global_load_lds_dwordx4 v[216:217], off
	s_barrier
; __device__ __forceinline__ unsigned cvt_pk_bf16(float lo, float hi) { unsigned r; asm volatile("v_cvt_pk_bf16_f32 %0, %1, %2" : "=v"(r) : "v"(lo), "v"(hi)); return r; }
; __device__ __forceinline__ float sigmoidf_(float x) { return 1.0f / (1.0f + __expf(-x)); }
; #define PG8_STAGE(bufoff, gbase, voff) do { _Pragma("unroll") for (int _i = 0; _i < 2; ++_i) \
;         __builtin_amdgcn_global_load_lds((const unsigned*)((const char*)(gbase) + (voff)[_i]), (LAS unsigned*)(lds + (bufoff) + ldsw + _i * 8192), 16, 0, 0); } while (0)
; #define PG8_LDA(dst, b, h) do { _Pragma("unroll") for (int m = 0; m < 4; ++m) _Pragma("unroll") for (int k = 0; k < 2; ++k) dst[m][k] = *(const LAS bf16x8*)(lds + PG8_SA(b, h) + aoff + m * 2048 + k * 1024); } while (0)
; #define PG8_MMA(ai, bj, At, Bt) do { __builtin_amdgcn_s_setprio(1); _Pragma("unroll") for (int m = 0; m < 4; ++m) _Pragma("unroll") for (int n = 0; n < 2; ++n) _Pragma("unroll") for (int k = 0; k < 2; ++k) \
;         acc[ai][bj][m][n] = __builtin_amdgcn_mfma_f32_16x16x32_bf16(Bt[n][k], At[m][k], acc[ai][bj][m][n], 0, 0, 0); __builtin_amdgcn_s_setprio(0); } while (0)
; template <class Epi>
; __device__ __forceinline__ void gemm_phase(LAS unsigned char* lds, const Gemm g, const StaticOrder& S, const Epi& E) {
;     ...
;             PG8_BAR; PG8_WAIT_L(0); PG8_MMA(0, 1, At, B1); PG8_BAR;
;             PG8_LDA(At, 1, 1); PG8_STAGE(PG8_SA(1, 0), a3, voffA);
;             PG8_BAR; PG8_WAIT_L(0); PG8_MMA(1, 0, At, B0); PG8_BAR; PG8_SCHED;
;             PG8_STAGE(PG8_SB(1, 1), b3 + hstep, voffB);
;             PG8_WAIT_V(6); PG8_BAR; PG8_MMA(1, 1, At, B1); PG8_BAR;
;     __device__ __forceinline__ void operator()(const f32x4 (&acc)[2][2][4][2], const Unit& u, int wr, int wc, int fr, int fq) const {
;     ...
;         for (int ai = 0; ai < 2; ++ai)
; #pragma unroll
;             for (int m = 0; m < 4; ++m) { float hv[8];
; #pragma unroll
;                 for (int n = 0; n < 2; ++n)
; #pragma unroll
;                     for (int i = 0; i < 4; ++i) { const float gt = acc[ai][0][m][n][i], up = acc[ai][1][m][n][i]; hv[4 * n + i] = gt * sigmoidf_(gt) * up; }
;                 u32x4 o; o[0] = cvt_pk_bf16(hv[0], hv[1]); o[1] = cvt_pk_bf16(hv[2], hv[3]); o[2] = cvt_pk_bf16(hv[4], hv[5]); o[3] = cvt_pk_bf16(hv[6], hv[7]);
;                 *(u32x4*)(O + (size_t)(row0 + ai * 128 + m * 16) * 5632 + col0) = o; }
	s_waitcnt lgkmcnt(0)
	s_setprio 1
	s_waitcnt lgkmcnt(0)
	v_mfma_f32_16x16x32_bf16 v[60:63], v[150:153], v[166:169], v[60:63]
	v_mfma_f32_16x16x32_bf16 v[52:55], v[158:161], v[166:169], v[52:55]
	v_mfma_f32_16x16x32_bf16 v[44:47], v[150:153], v[176:179], v[44:47]
	v_mfma_f32_16x16x32_bf16 v[36:39], v[158:161], v[176:179], v[36:39]
	v_mfma_f32_16x16x32_bf16 v[28:31], v[150:153], v[184:187], v[28:31]
	v_mfma_f32_16x16x32_bf16 v[20:23], v[158:161], v[184:187], v[20:23]
	v_mfma_f32_16x16x32_bf16 v[12:15], v[150:153], v[192:195], v[12:15]
	v_mfma_f32_16x16x32_bf16 v[4:7], v[158:161], v[192:195], v[4:7]
	v_mfma_f32_16x16x32_bf16 v[60:63], v[154:157], v[172:175], v[60:63]
	v_mfma_f32_16x16x32_bf16 v[52:55], v[162:165], v[172:175], v[52:55]
	v_mfma_f32_16x16x32_bf16 v[44:47], v[154:157], v[180:183], v[44:47]
	v_mfma_f32_16x16x32_bf16 v[36:39], v[162:165], v[180:183], v[36:39]
	v_mfma_f32_16x16x32_bf16 v[28:31], v[154:157], v[188:191], v[28:31]
	v_mfma_f32_16x16x32_bf16 v[20:23], v[162:165], v[188:191], v[20:23]
	v_mfma_f32_16x16x32_bf16 v[12:15], v[154:157], v[196:199], v[12:15]
	v_mfma_f32_16x16x32_bf16 v[4:7], v[162:165], v[196:199], v[4:7]
	s_setprio 0
	s_barrier
	s_add_u32 s22, s22, 0x80080
	s_addc_u32 s23, s23, 0
	s_add_i32 s26, s26, s31
	v_lshl_add_u64 v[150:151], s[22:23], 0, v[132:133]
	s_mov_b32 m0, s26
	s_nop 0
	global_load_lds_dwordx4 v[150:151], off
	v_lshl_add_u64 v[150:151], s[22:23], 0, v[128:129]
	s_add_i32 m0, s26, 0x2000
	s_nop 0
	global_load_lds_dwordx4 v[150:151], off
	s_waitcnt vmcnt(6)
	s_barrier
	s_setprio 1
	v_mfma_f32_16x16x32_bf16 v[56:59], v[200:203], v[166:169], v[56:59]
	v_mfma_f32_16x16x32_bf16 v[48:51], v[208:211], v[166:169], v[48:51]
	v_mfma_f32_16x16x32_bf16 v[40:43], v[200:203], v[176:179], v[40:43]
	v_mfma_f32_16x16x32_bf16 v[32:35], v[208:211], v[176:179], v[32:35]
	v_mfma_f32_16x16x32_bf16 v[24:27], v[200:203], v[184:187], v[24:27]
	v_mfma_f32_16x16x32_bf16 v[16:19], v[208:211], v[184:187], v[16:19]
	v_mfma_f32_16x16x32_bf16 v[8:11], v[200:203], v[192:195], v[8:11]
	v_mfma_f32_16x16x32_bf16 v[0:3], v[208:211], v[192:195], v[0:3]
	v_mfma_f32_16x16x32_bf16 v[56:59], v[204:207], v[172:175], v[56:59]
	v_mfma_f32_16x16x32_bf16 v[48:51], v[212:215], v[172:175], v[48:51]
	v_mfma_f32_16x16x32_bf16 v[40:43], v[204:207], v[180:183], v[40:43]
	v_mfma_f32_16x16x32_bf16 v[32:35], v[212:215], v[180:183], v[32:35]
	v_mfma_f32_16x16x32_bf16 v[24:27], v[204:207], v[188:191], v[24:27]
	v_mfma_f32_16x16x32_bf16 v[16:19], v[212:215], v[188:191], v[16:19]
	v_mfma_f32_16x16x32_bf16 v[8:11], v[204:207], v[196:199], v[8:11]
	v_mfma_f32_16x16x32_bf16 v[0:3], v[212:215], v[196:199], v[0:3]
	s_setprio 0
	s_add_i32 s55, s55, 2
	s_add_u32 s20, s20, 0x100
	s_addc_u32 s21, s21, 0
	s_add_u32 s53, s53, 0x100
	s_addc_u32 s54, s54, 0
	s_cmp_gt_u32 s55, 29
	s_barrier
	s_cbranch_scc0 .LBB0_2209
	v_mul_f32_e32 v150, 0xbfb8aa3b, v124
	v_exp_f32_e32 v151, v150
	v_lshl_or_b32 v152, s50, 7, v146
	v_lshl_add_u32 v150, s16, 8, v144
	v_ashrrev_i32_e32 v153, 31, v152
	v_min_f32_e32 v151, 0x7e800000, v151
	v_add_f32_e32 v151, 1.0, v151
	v_rcp_f32_e32 v155, v151
	s_mov_b32 s50, s6
	v_mul_f32_e32 v158, 0xbfb8aa3b, v125
	v_exp_f32_e32 v158, v158
	v_fma_f32 v157, -v151, v155, 1.0
	v_fma_f32 v151, v157, v155, v155
	v_min_f32_e32 v158, 0x7e800000, v158
	v_add_f32_e32 v155, 1.0, v158
	v_rcp_f32_e32 v157, v155
	v_mul_f32_e32 v124, v124, v151
	v_mul_f32_e32 v120, v124, v120
	s_mov_b32 s16, s10
	v_mul_f32_e32 v154, 0xbfb8aa3b, v126
	v_exp_f32_e32 v154, v154
	v_fma_f32 v151, -v155, v157, 1.0
	v_fma_f32 v124, v151, v157, v157
	v_min_f32_e32 v154, 0x7e800000, v154
	v_add_f32_e32 v151, 1.0, v154
	v_rcp_f32_e32 v156, v151
	v_mul_f32_e32 v124, v125, v124
	v_mul_f32_e32 v121, v124, v121
	s_mov_b64 s[22:23], s[14:15]
	v_mul_f32_e32 v155, 0xbfb8aa3b, v127
	v_exp_f32_e32 v155, v155
	v_fma_f32 v125, -v151, v156, 1.0
	v_fma_f32 v124, v125, v156, v156
	v_min_f32_e32 v155, 0x7e800000, v155
	v_add_f32_e32 v125, 1.0, v155
	v_rcp_f32_e32 v155, v125
	v_mul_f32_e32 v124, v126, v124
	v_mul_f32_e32 v122, v124, v122
	v_mul_f32_e32 v151, 0xbfb8aa3b, v116
	v_exp_f32_e32 v151, v151
	v_fma_f32 v126, -v125, v155, 1.0
	v_fma_f32 v124, v126, v155, v155
	v_min_f32_e32 v151, 0x7e800000, v151
	v_add_f32_e32 v126, 1.0, v151
	v_rcp_f32_e32 v154, v126
	v_mul_f32_e32 v124, v127, v124
	v_mul_f32_e32 v123, v124, v123
	v_mul_f32_e32 v127, 0xbfb8aa3b, v117
	v_exp_f32_e32 v127, v127
	v_fma_f32 v125, -v126, v154, 1.0
	v_fma_f32 v124, v125, v154, v154
	v_min_f32_e32 v127, 0x7e800000, v127
	v_add_f32_e32 v125, 1.0, v127
	v_rcp_f32_e32 v151, v125
	v_mul_f32_e32 v116, v116, v124
	v_mul_f32_e32 v112, v116, v112
	v_mul_f32_e32 v126, 0xbfb8aa3b, v118
	v_exp_f32_e32 v126, v126
	v_fma_f32 v124, -v125, v151, 1.0
	v_fma_f32 v116, v124, v151, v151
	v_min_f32_e32 v126, 0x7e800000, v126
	v_add_f32_e32 v124, 1.0, v126
	v_rcp_f32_e32 v127, v124
	v_mul_f32_e32 v116, v117, v116
	v_mul_f32_e32 v113, v116, v113
	v_mul_f32_e32 v125, 0xbfb8aa3b, v119
	v_exp_f32_e32 v125, v125
	v_fma_f32 v117, -v124, v127, 1.0
	v_fma_f32 v116, v117, v127, v127
	v_min_f32_e32 v125, 0x7e800000, v125
	v_add_f32_e32 v117, 1.0, v125
	v_rcp_f32_e32 v126, v117
	v_mul_f32_e32 v116, v118, v116
	v_mul_f32_e32 v114, v116, v114
	v_fma_f32 v118, -v117, v126, 1.0
	v_fma_f32 v116, v118, v126, v126
	v_mul_f32_e32 v116, v119, v116
	v_mul_f32_e32 v115, v116, v115
	v_cvt_pk_bf16_f32 v116, v120, v121
	v_cvt_pk_bf16_f32 v117, v122, v123
	v_cvt_pk_bf16_f32 v118, v112, v113
	v_mul_f32_e32 v112, 0xbfb8aa3b, v108
	v_cvt_pk_bf16_f32 v119, v114, v115
	v_exp_f32_e32 v114, v112
	v_mov_b64_e32 v[112:113], s[96:97]
	v_mad_i64_i32 v[120:121], s[20:21], v150, s49, v[112:113]
; __device__ __forceinline__ unsigned cvt_pk_bf16(float lo, float hi) { unsigned r; asm volatile("v_cvt_pk_bf16_f32 %0, %1, %2" : "=v"(r) : "v"(lo), "v"(hi)); return r; }
; __device__ __forceinline__ float sigmoidf_(float x) { return 1.0f / (1.0f + __expf(-x)); }
;     __device__ __forceinline__ void operator()(const f32x4 (&acc)[2][2][4][2], const Unit& u, int wr, int wc, int fr, int fq) const {
;     ...
;         for (int ai = 0; ai < 2; ++ai)
; #pragma unroll
;             for (int m = 0; m < 4; ++m) { float hv[8];
; #pragma unroll
;                 for (int n = 0; n < 2; ++n)
; #pragma unroll
;                     for (int i = 0; i < 4; ++i) { const float gt = acc[ai][0][m][n][i], up = acc[ai][1][m][n][i]; hv[4 * n + i] = gt * sigmoidf_(gt) * up; }
;                 u32x4 o; o[0] = cvt_pk_bf16(hv[0], hv[1]); o[1] = cvt_pk_bf16(hv[2], hv[3]); o[2] = cvt_pk_bf16(hv[4], hv[5]); o[3] = cvt_pk_bf16(hv[6], hv[7]);
;                 *(u32x4*)(O + (size_t)(row0 + ai * 128 + m * 16) * 5632 + col0) = o; }
	v_min_f32_e32 v114, 0x7e800000, v114
	v_add_f32_e32 v122, 1.0, v114
	v_rcp_f32_e32 v124, v122
	v_lshlrev_b64 v[114:115], 1, v[152:153]
	v_lshl_add_u64 v[120:121], v[120:121], 0, v[114:115]
	global_store_dwordx4 v[120:121], v[116:119], off
	s_nop 1
	v_mul_f32_e32 v118, 0xbfb8aa3b, v109
	v_exp_f32_e32 v118, v118
	v_fma_f32 v117, -v122, v124, 1.0
	v_fma_f32 v116, v117, v124, v124
	v_min_f32_e32 v118, 0x7e800000, v118
	v_add_f32_e32 v117, 1.0, v118
	v_rcp_f32_e32 v119, v117
	v_mul_f32_e32 v108, v108, v116
	v_mul_f32_e32 v104, v108, v104
	v_mul_f32_e32 v120, 0xbfb8aa3b, v110
	v_exp_f32_e32 v120, v120
	v_fma_f32 v116, -v117, v119, 1.0
	v_fma_f32 v108, v116, v119, v119
	v_min_f32_e32 v120, 0x7e800000, v120
	v_add_f32_e32 v116, 1.0, v120
	v_rcp_f32_e32 v119, v116
	v_mul_f32_e32 v108, v109, v108
	v_mul_f32_e32 v105, v108, v105
	v_mul_f32_e32 v117, 0xbfb8aa3b, v111
	v_exp_f32_e32 v117, v117
	v_fma_f32 v109, -v116, v119, 1.0
	v_fma_f32 v108, v109, v119, v119
	v_min_f32_e32 v117, 0x7e800000, v117
	v_add_f32_e32 v109, 1.0, v117
	v_rcp_f32_e32 v118, v109
	v_mul_f32_e32 v108, v110, v108
	v_mul_f32_e32 v106, v108, v106
	v_mul_f32_e32 v116, 0xbfb8aa3b, v100
	v_exp_f32_e32 v116, v116
	v_fma_f32 v110, -v109, v118, 1.0
	v_fma_f32 v108, v110, v118, v118
	v_min_f32_e32 v116, 0x7e800000, v116
	v_add_f32_e32 v110, 1.0, v116
	v_rcp_f32_e32 v117, v110
	v_mul_f32_e32 v108, v111, v108
	v_mul_f32_e32 v107, v108, v107
	v_mul_f32_e32 v111, 0xbfb8aa3b, v101
	v_exp_f32_e32 v111, v111
	v_fma_f32 v109, -v110, v117, 1.0
	v_fma_f32 v108, v109, v117, v117
	v_min_f32_e32 v111, 0x7e800000, v111
	v_add_f32_e32 v109, 1.0, v111
	v_rcp_f32_e32 v116, v109
	v_mul_f32_e32 v100, v100, v108
	v_mul_f32_e32 v100, v100, v96
	v_mul_f32_e32 v110, 0xbfb8aa3b, v102
	v_exp_f32_e32 v110, v110
	v_fma_f32 v108, -v109, v116, 1.0
	v_fma_f32 v96, v108, v116, v116
	v_min_f32_e32 v110, 0x7e800000, v110
	v_add_f32_e32 v108, 1.0, v110
	v_rcp_f32_e32 v111, v108
	v_mul_f32_e32 v96, v101, v96
	v_mul_f32_e32 v101, v96, v97
	v_mul_f32_e32 v109, 0xbfb8aa3b, v103
	v_exp_f32_e32 v109, v109
	v_fma_f32 v97, -v108, v111, 1.0
	v_fma_f32 v96, v97, v111, v111
	v_min_f32_e32 v109, 0x7e800000, v109
	v_add_f32_e32 v97, 1.0, v109
	v_rcp_f32_e32 v110, v97
	v_mul_f32_e32 v96, v102, v96
	v_mul_f32_e32 v102, v96, v98
	v_fma_f32 v98, -v97, v110, 1.0
	v_fma_f32 v96, v98, v110, v110
	v_mul_f32_e32 v98, 0xbfb8aa3b, v92
	v_mul_f32_e32 v96, v103, v96
	v_exp_f32_e32 v103, v98
	v_mul_f32_e32 v99, v96, v99
	v_cvt_pk_bf16_f32 v96, v104, v105
	v_cvt_pk_bf16_f32 v97, v106, v107
	v_cvt_pk_bf16_f32 v98, v100, v101
	v_cvt_pk_bf16_f32 v99, v102, v99
	v_min_f32_e32 v103, 0x7e800000, v103
	v_add_f32_e32 v102, 1.0, v103
	v_rcp_f32_e32 v104, v102
	v_or_b32_e32 v100, 16, v150
	v_mad_i64_i32 v[100:101], s[20:21], v100, s49, v[112:113]
	v_lshl_add_u64 v[100:101], v[100:101], 0, v[114:115]
	global_store_dwordx4 v[100:101], v[96:99], off
	s_nop 1
	v_mul_f32_e32 v98, 0xbfb8aa3b, v93
	v_exp_f32_e32 v98, v98
	v_fma_f32 v97, -v102, v104, 1.0
	v_fma_f32 v96, v97, v104, v104
	v_min_f32_e32 v98, 0x7e800000, v98
	v_add_f32_e32 v97, 1.0, v98
	v_rcp_f32_e32 v99, v97
	v_mul_f32_e32 v92, v92, v96
	v_mul_f32_e32 v88, v92, v88
	v_mul_f32_e32 v100, 0xbfb8aa3b, v94
	v_exp_f32_e32 v100, v100
	v_fma_f32 v96, -v97, v99, 1.0
	v_fma_f32 v92, v96, v99, v99
	v_min_f32_e32 v100, 0x7e800000, v100
	v_add_f32_e32 v96, 1.0, v100
	v_rcp_f32_e32 v99, v96
	v_mul_f32_e32 v92, v93, v92
	v_mul_f32_e32 v89, v92, v89
	v_mul_f32_e32 v97, 0xbfb8aa3b, v95
	v_exp_f32_e32 v97, v97
	v_fma_f32 v93, -v96, v99, 1.0
	v_fma_f32 v92, v93, v99, v99
	v_min_f32_e32 v97, 0x7e800000, v97
	v_add_f32_e32 v93, 1.0, v97
	v_rcp_f32_e32 v98, v93
	v_mul_f32_e32 v92, v94, v92
	v_mul_f32_e32 v90, v92, v90
	v_mul_f32_e32 v96, 0xbfb8aa3b, v84
	v_exp_f32_e32 v96, v96
	v_fma_f32 v94, -v93, v98, 1.0
	v_fma_f32 v92, v94, v98, v98
	v_min_f32_e32 v96, 0x7e800000, v96
	v_add_f32_e32 v94, 1.0, v96
	v_rcp_f32_e32 v97, v94
	v_mul_f32_e32 v92, v95, v92
	v_mul_f32_e32 v91, v92, v91
	v_mul_f32_e32 v95, 0xbfb8aa3b, v85
	v_exp_f32_e32 v95, v95
	v_fma_f32 v93, -v94, v97, 1.0
	v_fma_f32 v92, v93, v97, v97
	v_min_f32_e32 v95, 0x7e800000, v95
	v_add_f32_e32 v93, 1.0, v95
	v_rcp_f32_e32 v96, v93
	v_mul_f32_e32 v84, v84, v92
	v_mul_f32_e32 v84, v84, v80
	v_mul_f32_e32 v94, 0xbfb8aa3b, v86
	v_exp_f32_e32 v94, v94
	v_fma_f32 v92, -v93, v96, 1.0
	v_fma_f32 v80, v92, v96, v96
	v_min_f32_e32 v94, 0x7e800000, v94
	v_add_f32_e32 v92, 1.0, v94
	v_rcp_f32_e32 v95, v92
	v_mul_f32_e32 v80, v85, v80
	v_mul_f32_e32 v85, v80, v81
	v_mul_f32_e32 v93, 0xbfb8aa3b, v87
	v_exp_f32_e32 v93, v93
	v_fma_f32 v81, -v92, v95, 1.0
	v_fma_f32 v80, v81, v95, v95
	v_min_f32_e32 v93, 0x7e800000, v93
	v_add_f32_e32 v81, 1.0, v93
	v_rcp_f32_e32 v94, v81
	v_mul_f32_e32 v80, v86, v80
	v_mul_f32_e32 v86, v80, v82
	v_fma_f32 v82, -v81, v94, 1.0
	v_fma_f32 v80, v82, v94, v94
	v_mul_f32_e32 v82, 0xbfb8aa3b, v76
	v_mul_f32_e32 v80, v87, v80
	v_exp_f32_e32 v87, v82
	v_mul_f32_e32 v83, v80, v83
	v_cvt_pk_bf16_f32 v80, v88, v89
	v_cvt_pk_bf16_f32 v81, v90, v91
	v_cvt_pk_bf16_f32 v82, v84, v85
	v_cvt_pk_bf16_f32 v83, v86, v83
	v_min_f32_e32 v87, 0x7e800000, v87
	v_add_f32_e32 v86, 1.0, v87
	v_rcp_f32_e32 v88, v86
	v_or_b32_e32 v84, 32, v150
	v_mad_i64_i32 v[84:85], s[20:21], v84, s49, v[112:113]
	v_lshl_add_u64 v[84:85], v[84:85], 0, v[114:115]
	global_store_dwordx4 v[84:85], v[80:83], off
	s_nop 1
	v_mul_f32_e32 v82, 0xbfb8aa3b, v77
	v_exp_f32_e32 v82, v82
	v_fma_f32 v81, -v86, v88, 1.0
	v_fma_f32 v80, v81, v88, v88
	v_min_f32_e32 v82, 0x7e800000, v82
	v_add_f32_e32 v81, 1.0, v82
	v_rcp_f32_e32 v83, v81
	v_mul_f32_e32 v76, v76, v80
	v_mul_f32_e32 v72, v76, v72
; __device__ __forceinline__ unsigned cvt_pk_bf16(float lo, float hi) { unsigned r; asm volatile("v_cvt_pk_bf16_f32 %0, %1, %2" : "=v"(r) : "v"(lo), "v"(hi)); return r; }
; __device__ __forceinline__ float sigmoidf_(float x) { return 1.0f / (1.0f + __expf(-x)); }
;     __device__ __forceinline__ void operator()(const f32x4 (&acc)[2][2][4][2], const Unit& u, int wr, int wc, int fr, int fq) const {
;     ...
;         for (int ai = 0; ai < 2; ++ai)
; #pragma unroll
;             for (int m = 0; m < 4; ++m) { float hv[8];
; #pragma unroll
;                 for (int n = 0; n < 2; ++n)
; #pragma unroll
;                     for (int i = 0; i < 4; ++i) { const float gt = acc[ai][0][m][n][i], up = acc[ai][1][m][n][i]; hv[4 * n + i] = gt * sigmoidf_(gt) * up; }
;                 u32x4 o; o[0] = cvt_pk_bf16(hv[0], hv[1]); o[1] = cvt_pk_bf16(hv[2], hv[3]); o[2] = cvt_pk_bf16(hv[4], hv[5]); o[3] = cvt_pk_bf16(hv[6], hv[7]);
;                 *(u32x4*)(O + (size_t)(row0 + ai * 128 + m * 16) * 5632 + col0) = o; }
	v_mul_f32_e32 v84, 0xbfb8aa3b, v78
	v_exp_f32_e32 v84, v84
	v_fma_f32 v80, -v81, v83, 1.0
	v_fma_f32 v76, v80, v83, v83
	v_min_f32_e32 v84, 0x7e800000, v84
	v_add_f32_e32 v80, 1.0, v84
	v_rcp_f32_e32 v83, v80
	v_mul_f32_e32 v76, v77, v76
	v_mul_f32_e32 v73, v76, v73
	v_mul_f32_e32 v81, 0xbfb8aa3b, v79
	v_exp_f32_e32 v81, v81
	v_fma_f32 v77, -v80, v83, 1.0
	v_fma_f32 v76, v77, v83, v83
	v_min_f32_e32 v81, 0x7e800000, v81
	v_add_f32_e32 v77, 1.0, v81
	v_rcp_f32_e32 v82, v77
	v_mul_f32_e32 v76, v78, v76
	v_mul_f32_e32 v74, v76, v74
	v_mul_f32_e32 v80, 0xbfb8aa3b, v68
	v_exp_f32_e32 v80, v80
	v_fma_f32 v78, -v77, v82, 1.0
	v_fma_f32 v76, v78, v82, v82
	v_min_f32_e32 v80, 0x7e800000, v80
	v_add_f32_e32 v78, 1.0, v80
	v_rcp_f32_e32 v81, v78
	v_mul_f32_e32 v76, v79, v76
	v_mul_f32_e32 v75, v76, v75
	v_mul_f32_e32 v79, 0xbfb8aa3b, v69
	v_exp_f32_e32 v79, v79
	v_fma_f32 v77, -v78, v81, 1.0
	v_fma_f32 v76, v77, v81, v81
	v_min_f32_e32 v79, 0x7e800000, v79
	v_add_f32_e32 v77, 1.0, v79
	v_rcp_f32_e32 v80, v77
	v_mul_f32_e32 v68, v68, v76
	v_mul_f32_e32 v68, v68, v64
	v_mul_f32_e32 v78, 0xbfb8aa3b, v70
	v_exp_f32_e32 v78, v78
	v_fma_f32 v76, -v77, v80, 1.0
	v_fma_f32 v64, v76, v80, v80
	v_min_f32_e32 v78, 0x7e800000, v78
	v_add_f32_e32 v76, 1.0, v78
	v_rcp_f32_e32 v79, v76
	v_mul_f32_e32 v64, v69, v64
	v_mul_f32_e32 v69, v64, v65
	v_mul_f32_e32 v77, 0xbfb8aa3b, v71
	v_exp_f32_e32 v77, v77
	v_fma_f32 v65, -v76, v79, 1.0
	v_fma_f32 v64, v65, v79, v79
	v_min_f32_e32 v77, 0x7e800000, v77
	v_add_f32_e32 v65, 1.0, v77
	v_rcp_f32_e32 v78, v65
	v_mul_f32_e32 v64, v70, v64
	v_mul_f32_e32 v70, v64, v66
	v_fma_f32 v66, -v65, v78, 1.0
	v_fma_f32 v64, v66, v78, v78
	v_mul_f32_e32 v64, v71, v64
	v_mul_f32_e32 v67, v64, v67
	v_cvt_pk_bf16_f32 v64, v72, v73
	v_cvt_pk_bf16_f32 v65, v74, v75
	v_cvt_pk_bf16_f32 v66, v68, v69
	v_mul_f32_e32 v68, 0xbfb8aa3b, v60
	v_cvt_pk_bf16_f32 v67, v70, v67
	v_exp_f32_e32 v70, v68
	v_or_b32_e32 v68, 48, v150
	v_mad_i64_i32 v[68:69], s[20:21], v68, s49, v[112:113]
	v_min_f32_e32 v70, 0x7e800000, v70
	v_add_f32_e32 v70, 1.0, v70
	v_rcp_f32_e32 v72, v70
	v_lshl_add_u64 v[68:69], v[68:69], 0, v[114:115]
	global_store_dwordx4 v[68:69], v[64:67], off
	s_nop 1
	v_mul_f32_e32 v67, 0xbfb8aa3b, v61
	v_exp_f32_e32 v67, v67
	v_fma_f32 v66, -v70, v72, 1.0
	v_fma_f32 v65, v66, v72, v72
	v_min_f32_e32 v67, 0x7e800000, v67
	v_add_f32_e32 v66, 1.0, v67
	v_rcp_f32_e32 v68, v66
	v_mul_f32_e32 v60, v60, v65
	v_mul_f32_e32 v56, v60, v56
	v_add_u32_e32 v64, 0x80, v150
	v_mul_f32_e32 v69, 0xbfb8aa3b, v62
	v_exp_f32_e32 v69, v69
	v_fma_f32 v65, -v66, v68, 1.0
	v_fma_f32 v60, v65, v68, v68
	v_min_f32_e32 v69, 0x7e800000, v69
	v_add_f32_e32 v65, 1.0, v69
	v_rcp_f32_e32 v68, v65
	v_mul_f32_e32 v60, v61, v60
	v_mul_f32_e32 v57, v60, v57
	v_mul_f32_e32 v66, 0xbfb8aa3b, v63
	v_exp_f32_e32 v66, v66
	v_fma_f32 v61, -v65, v68, 1.0
	v_fma_f32 v60, v61, v68, v68
	v_min_f32_e32 v66, 0x7e800000, v66
	v_add_f32_e32 v61, 1.0, v66
	v_rcp_f32_e32 v67, v61
	v_mul_f32_e32 v60, v62, v60
	v_mul_f32_e32 v58, v60, v58
	v_mul_f32_e32 v65, 0xbfb8aa3b, v52
	v_exp_f32_e32 v65, v65
	v_fma_f32 v62, -v61, v67, 1.0
	v_fma_f32 v60, v62, v67, v67
	v_min_f32_e32 v65, 0x7e800000, v65
	v_add_f32_e32 v62, 1.0, v65
	v_rcp_f32_e32 v66, v62
	v_mul_f32_e32 v60, v63, v60
	v_mul_f32_e32 v59, v60, v59
	v_mul_f32_e32 v63, 0xbfb8aa3b, v53
	v_exp_f32_e32 v63, v63
	v_fma_f32 v61, -v62, v66, 1.0
	v_fma_f32 v60, v61, v66, v66
	v_min_f32_e32 v63, 0x7e800000, v63
	v_add_f32_e32 v61, 1.0, v63
	v_rcp_f32_e32 v65, v61
	v_mul_f32_e32 v52, v52, v60
	v_mul_f32_e32 v52, v52, v48
	v_mul_f32_e32 v62, 0xbfb8aa3b, v54
	v_exp_f32_e32 v62, v62
	v_fma_f32 v60, -v61, v65, 1.0
	v_fma_f32 v48, v60, v65, v65
	v_min_f32_e32 v62, 0x7e800000, v62
	v_add_f32_e32 v60, 1.0, v62
	v_rcp_f32_e32 v63, v60
	v_mul_f32_e32 v48, v53, v48
	v_mul_f32_e32 v53, v48, v49
	v_mul_f32_e32 v61, 0xbfb8aa3b, v55
	v_exp_f32_e32 v61, v61
	v_fma_f32 v49, -v60, v63, 1.0
	v_fma_f32 v48, v49, v63, v63
	v_min_f32_e32 v61, 0x7e800000, v61
	v_add_f32_e32 v49, 1.0, v61
	v_rcp_f32_e32 v62, v49
	v_mul_f32_e32 v48, v54, v48
	v_mul_f32_e32 v54, v48, v50
	v_fma_f32 v50, -v49, v62, 1.0
	v_fma_f32 v48, v50, v62, v62
	v_mul_f32_e32 v49, 0xbfb8aa3b, v44
	v_mul_f32_e32 v48, v55, v48
	v_exp_f32_e32 v55, v49
	v_mul_f32_e32 v51, v48, v51
	v_cvt_pk_bf16_f32 v48, v56, v57
	v_cvt_pk_bf16_f32 v49, v58, v59
	v_cvt_pk_bf16_f32 v50, v52, v53
	v_cvt_pk_bf16_f32 v51, v54, v51
	v_min_f32_e32 v55, 0x7e800000, v55
	v_add_f32_e32 v54, 1.0, v55
	v_rcp_f32_e32 v56, v54
	v_mad_i64_i32 v[52:53], s[20:21], v64, s49, v[112:113]
	v_lshl_add_u64 v[52:53], v[52:53], 0, v[114:115]
	global_store_dwordx4 v[52:53], v[48:51], off
	s_nop 1
	v_mul_f32_e32 v50, 0xbfb8aa3b, v45
	v_exp_f32_e32 v50, v50
	v_fma_f32 v49, -v54, v56, 1.0
	v_fma_f32 v48, v49, v56, v56
	v_min_f32_e32 v50, 0x7e800000, v50
	v_add_f32_e32 v49, 1.0, v50
	v_rcp_f32_e32 v51, v49
	v_mul_f32_e32 v44, v44, v48
	v_mul_f32_e32 v40, v44, v40
	v_mul_f32_e32 v52, 0xbfb8aa3b, v46
	v_exp_f32_e32 v52, v52
	v_fma_f32 v48, -v49, v51, 1.0
	v_fma_f32 v44, v48, v51, v51
	v_min_f32_e32 v52, 0x7e800000, v52
	v_add_f32_e32 v48, 1.0, v52
	v_rcp_f32_e32 v51, v48
	v_mul_f32_e32 v44, v45, v44
	v_mul_f32_e32 v41, v44, v41
	v_mul_f32_e32 v49, 0xbfb8aa3b, v47
	v_exp_f32_e32 v49, v49
	v_fma_f32 v45, -v48, v51, 1.0
	v_fma_f32 v44, v45, v51, v51
	v_min_f32_e32 v49, 0x7e800000, v49
	v_add_f32_e32 v45, 1.0, v49
	v_rcp_f32_e32 v50, v45
	v_mul_f32_e32 v44, v46, v44
	v_mul_f32_e32 v42, v44, v42
	v_mul_f32_e32 v48, 0xbfb8aa3b, v36
	v_exp_f32_e32 v48, v48
	v_fma_f32 v46, -v45, v50, 1.0
	v_fma_f32 v44, v46, v50, v50
	v_min_f32_e32 v48, 0x7e800000, v48
; __device__ __forceinline__ unsigned cvt_pk_bf16(float lo, float hi) { unsigned r; asm volatile("v_cvt_pk_bf16_f32 %0, %1, %2" : "=v"(r) : "v"(lo), "v"(hi)); return r; }
; __device__ __forceinline__ float sigmoidf_(float x) { return 1.0f / (1.0f + __expf(-x)); }
; #define PG8_WAIT_V(n) asm volatile("s_waitcnt vmcnt(" #n ")" ::: "memory")
; #define PG8_BAR __builtin_amdgcn_s_barrier()
; template <class Epi>
; __device__ __forceinline__ void gemm_phase(LAS unsigned char* lds, const Gemm g, const StaticOrder& S, const Epi& E) {
;     ...
;         cur = nxt; cA = nA; cB = nB; ++ui;
;     }
;     PG8_WAIT_V(0);
;     if (wr == 0) PG8_BAR;
;     PG8_BAR;
;     __device__ __forceinline__ void operator()(const f32x4 (&acc)[2][2][4][2], const Unit& u, int wr, int wc, int fr, int fq) const {
;     ...
;         for (int ai = 0; ai < 2; ++ai)
; #pragma unroll
;             for (int m = 0; m < 4; ++m) { float hv[8];
; #pragma unroll
;                 for (int n = 0; n < 2; ++n)
; #pragma unroll
;                     for (int i = 0; i < 4; ++i) { const float gt = acc[ai][0][m][n][i], up = acc[ai][1][m][n][i]; hv[4 * n + i] = gt * sigmoidf_(gt) * up; }
;                 u32x4 o; o[0] = cvt_pk_bf16(hv[0], hv[1]); o[1] = cvt_pk_bf16(hv[2], hv[3]); o[2] = cvt_pk_bf16(hv[4], hv[5]); o[3] = cvt_pk_bf16(hv[6], hv[7]);
;                 *(u32x4*)(O + (size_t)(row0 + ai * 128 + m * 16) * 5632 + col0) = o; }
	v_add_f32_e32 v46, 1.0, v48
	v_rcp_f32_e32 v49, v46
	v_mul_f32_e32 v44, v47, v44
	v_mul_f32_e32 v43, v44, v43
	v_mul_f32_e32 v47, 0xbfb8aa3b, v37
	v_exp_f32_e32 v47, v47
	v_fma_f32 v45, -v46, v49, 1.0
	v_fma_f32 v44, v45, v49, v49
	v_min_f32_e32 v47, 0x7e800000, v47
	v_add_f32_e32 v45, 1.0, v47
	v_rcp_f32_e32 v48, v45
	v_mul_f32_e32 v36, v36, v44
	v_mul_f32_e32 v36, v36, v32
	v_mul_f32_e32 v46, 0xbfb8aa3b, v38
	v_exp_f32_e32 v46, v46
	v_fma_f32 v44, -v45, v48, 1.0
	v_fma_f32 v32, v44, v48, v48
	v_min_f32_e32 v46, 0x7e800000, v46
	v_add_f32_e32 v44, 1.0, v46
	v_rcp_f32_e32 v47, v44
	v_mul_f32_e32 v32, v37, v32
	v_mul_f32_e32 v37, v32, v33
	v_mul_f32_e32 v45, 0xbfb8aa3b, v39
	v_exp_f32_e32 v45, v45
	v_fma_f32 v33, -v44, v47, 1.0
	v_fma_f32 v32, v33, v47, v47
	v_min_f32_e32 v45, 0x7e800000, v45
	v_add_f32_e32 v33, 1.0, v45
	v_rcp_f32_e32 v46, v33
	v_mul_f32_e32 v32, v38, v32
	v_mul_f32_e32 v38, v32, v34
	v_fma_f32 v34, -v33, v46, 1.0
	v_fma_f32 v32, v34, v46, v46
	v_mul_f32_e32 v34, 0xbfb8aa3b, v28
	v_mul_f32_e32 v32, v39, v32
	v_exp_f32_e32 v39, v34
	v_mul_f32_e32 v35, v32, v35
	v_cvt_pk_bf16_f32 v32, v40, v41
	v_cvt_pk_bf16_f32 v33, v42, v43
	v_cvt_pk_bf16_f32 v34, v36, v37
	v_cvt_pk_bf16_f32 v35, v38, v35
	v_min_f32_e32 v39, 0x7e800000, v39
	v_add_f32_e32 v38, 1.0, v39
	v_rcp_f32_e32 v40, v38
	v_add_u32_e32 v36, 0x90, v150
	v_mad_i64_i32 v[36:37], s[20:21], v36, s49, v[112:113]
	v_lshl_add_u64 v[36:37], v[36:37], 0, v[114:115]
	global_store_dwordx4 v[36:37], v[32:35], off
	s_nop 1
	v_mul_f32_e32 v34, 0xbfb8aa3b, v29
	v_exp_f32_e32 v34, v34
	v_fma_f32 v33, -v38, v40, 1.0
	v_fma_f32 v32, v33, v40, v40
	v_min_f32_e32 v34, 0x7e800000, v34
	v_add_f32_e32 v33, 1.0, v34
	v_rcp_f32_e32 v35, v33
	v_mul_f32_e32 v28, v28, v32
	v_mul_f32_e32 v24, v28, v24
	v_mul_f32_e32 v36, 0xbfb8aa3b, v30
	v_exp_f32_e32 v36, v36
	v_fma_f32 v32, -v33, v35, 1.0
	v_fma_f32 v28, v32, v35, v35
	v_min_f32_e32 v36, 0x7e800000, v36
	v_add_f32_e32 v32, 1.0, v36
	v_rcp_f32_e32 v35, v32
	v_mul_f32_e32 v28, v29, v28
	v_mul_f32_e32 v25, v28, v25
	v_mul_f32_e32 v33, 0xbfb8aa3b, v31
	v_exp_f32_e32 v33, v33
	v_fma_f32 v29, -v32, v35, 1.0
	v_fma_f32 v28, v29, v35, v35
	v_min_f32_e32 v33, 0x7e800000, v33
	v_add_f32_e32 v29, 1.0, v33
	v_rcp_f32_e32 v34, v29
	v_mul_f32_e32 v28, v30, v28
	v_mul_f32_e32 v26, v28, v26
	v_mul_f32_e32 v32, 0xbfb8aa3b, v20
	v_exp_f32_e32 v32, v32
	v_fma_f32 v30, -v29, v34, 1.0
	v_fma_f32 v28, v30, v34, v34
	v_min_f32_e32 v32, 0x7e800000, v32
	v_add_f32_e32 v30, 1.0, v32
	v_rcp_f32_e32 v33, v30
	v_mul_f32_e32 v28, v31, v28
	v_mul_f32_e32 v27, v28, v27
	v_mul_f32_e32 v31, 0xbfb8aa3b, v21
	v_exp_f32_e32 v31, v31
	v_fma_f32 v29, -v30, v33, 1.0
	v_fma_f32 v28, v29, v33, v33
	v_min_f32_e32 v31, 0x7e800000, v31
	v_add_f32_e32 v29, 1.0, v31
	v_rcp_f32_e32 v32, v29
	v_mul_f32_e32 v20, v20, v28
	v_mul_f32_e32 v20, v20, v16
	v_mul_f32_e32 v30, 0xbfb8aa3b, v22
	v_exp_f32_e32 v30, v30
	v_fma_f32 v28, -v29, v32, 1.0
	v_fma_f32 v16, v28, v32, v32
	v_min_f32_e32 v30, 0x7e800000, v30
	v_add_f32_e32 v28, 1.0, v30
	v_rcp_f32_e32 v31, v28
	v_mul_f32_e32 v16, v21, v16
	v_mul_f32_e32 v21, v16, v17
	v_mul_f32_e32 v29, 0xbfb8aa3b, v23
	v_exp_f32_e32 v29, v29
	v_fma_f32 v17, -v28, v31, 1.0
	v_fma_f32 v16, v17, v31, v31
	v_min_f32_e32 v29, 0x7e800000, v29
	v_add_f32_e32 v17, 1.0, v29
	v_rcp_f32_e32 v30, v17
	v_mul_f32_e32 v16, v22, v16
	v_mul_f32_e32 v22, v16, v18
	v_fma_f32 v18, -v17, v30, 1.0
	v_fma_f32 v16, v18, v30, v30
	v_mul_f32_e32 v18, 0xbfb8aa3b, v12
	v_mul_f32_e32 v16, v23, v16
	v_exp_f32_e32 v23, v18
	v_mul_f32_e32 v19, v16, v19
	v_cvt_pk_bf16_f32 v16, v24, v25
	v_cvt_pk_bf16_f32 v17, v26, v27
	v_cvt_pk_bf16_f32 v18, v20, v21
	v_cvt_pk_bf16_f32 v19, v22, v19
	v_min_f32_e32 v23, 0x7e800000, v23
	v_add_f32_e32 v22, 1.0, v23
	v_rcp_f32_e32 v24, v22
	v_add_u32_e32 v20, 0xa0, v150
	v_mad_i64_i32 v[20:21], s[20:21], v20, s49, v[112:113]
	v_lshl_add_u64 v[20:21], v[20:21], 0, v[114:115]
	global_store_dwordx4 v[20:21], v[16:19], off
	s_nop 1
	v_mul_f32_e32 v18, 0xbfb8aa3b, v13
	v_exp_f32_e32 v18, v18
	v_fma_f32 v17, -v22, v24, 1.0
	v_fma_f32 v16, v17, v24, v24
	v_min_f32_e32 v18, 0x7e800000, v18
	v_add_f32_e32 v17, 1.0, v18
	v_rcp_f32_e32 v19, v17
	v_mul_f32_e32 v12, v12, v16
	v_mul_f32_e32 v8, v12, v8
	v_mul_f32_e32 v20, 0xbfb8aa3b, v14
	v_exp_f32_e32 v20, v20
	v_fma_f32 v16, -v17, v19, 1.0
	v_fma_f32 v12, v16, v19, v19
	v_min_f32_e32 v20, 0x7e800000, v20
	v_add_f32_e32 v16, 1.0, v20
	v_rcp_f32_e32 v19, v16
	v_mul_f32_e32 v12, v13, v12
	v_mul_f32_e32 v9, v12, v9
	v_mul_f32_e32 v17, 0xbfb8aa3b, v15
	v_exp_f32_e32 v17, v17
	v_fma_f32 v13, -v16, v19, 1.0
	v_fma_f32 v12, v13, v19, v19
	v_min_f32_e32 v17, 0x7e800000, v17
	v_add_f32_e32 v13, 1.0, v17
	v_rcp_f32_e32 v18, v13
	v_mul_f32_e32 v12, v14, v12
	v_mul_f32_e32 v10, v12, v10
	v_mul_f32_e32 v16, 0xbfb8aa3b, v4
	v_exp_f32_e32 v16, v16
	v_fma_f32 v14, -v13, v18, 1.0
	v_fma_f32 v12, v14, v18, v18
	v_min_f32_e32 v16, 0x7e800000, v16
	v_add_f32_e32 v14, 1.0, v16
	v_rcp_f32_e32 v17, v14
	v_mul_f32_e32 v12, v15, v12
	v_mul_f32_e32 v11, v12, v11
	v_mul_f32_e32 v15, 0xbfb8aa3b, v5
	v_exp_f32_e32 v15, v15
	v_fma_f32 v13, -v14, v17, 1.0
	v_fma_f32 v12, v13, v17, v17
	v_min_f32_e32 v15, 0x7e800000, v15
	v_add_f32_e32 v13, 1.0, v15
	v_rcp_f32_e32 v16, v13
	v_mul_f32_e32 v4, v4, v12
	v_mul_f32_e32 v4, v4, v0
	v_mul_f32_e32 v14, 0xbfb8aa3b, v6
	v_exp_f32_e32 v14, v14
	v_fma_f32 v12, -v13, v16, 1.0
	v_fma_f32 v0, v12, v16, v16
	v_min_f32_e32 v14, 0x7e800000, v14
	v_add_f32_e32 v12, 1.0, v14
	v_rcp_f32_e32 v15, v12
	v_mul_f32_e32 v0, v5, v0
	v_mul_f32_e32 v5, v0, v1
	v_mul_f32_e32 v13, 0xbfb8aa3b, v7
	v_exp_f32_e32 v13, v13
	v_fma_f32 v1, -v12, v15, 1.0
	v_fma_f32 v0, v1, v15, v15
	v_min_f32_e32 v13, 0x7e800000, v13
	v_add_f32_e32 v1, 1.0, v13
	v_rcp_f32_e32 v14, v1
	v_mul_f32_e32 v0, v6, v0
	v_mul_f32_e32 v6, v0, v2
	v_fma_f32 v2, -v1, v14, 1.0
	v_fma_f32 v0, v2, v14, v14
	v_mul_f32_e32 v0, v7, v0
	v_mul_f32_e32 v3, v0, v3
	v_cvt_pk_bf16_f32 v0, v8, v9
	v_cvt_pk_bf16_f32 v1, v10, v11
	v_cvt_pk_bf16_f32 v2, v4, v5
	v_add_u32_e32 v4, 0xb0, v150
	v_mad_i64_i32 v[4:5], s[20:21], v4, s49, v[112:113]
	v_lshl_add_u64 v[4:5], v[4:5], 0, v[114:115]
	s_and_b64 vcc, exec, s[4:5]
	s_mov_b64 s[20:21], s[12:13]
	v_cvt_pk_bf16_f32 v3, v6, v3
	global_store_dwordx4 v[4:5], v[0:3], off
	s_cbranch_vccz .LBB0_2206
	s_waitcnt vmcnt(0)
	v_readlane_b32 s36, v241, 18
	s_cmpk_gt_u32 s2, 0xff
	v_readlane_b32 s44, v241, 26
	v_readlane_b32 s45, v241, 27
	v_readlane_b32 s46, v241, 28
	v_readlane_b32 s47, v241, 29
	v_readlane_b32 s37, v241, 19
	v_readlane_b32 s38, v241, 20
	v_readlane_b32 s39, v241, 21
	v_readlane_b32 s40, v241, 22
	v_readlane_b32 s41, v241, 23
	v_readlane_b32 s42, v241, 24
	v_readlane_b32 s43, v241, 25
	v_readlane_b32 s48, v241, 30
	v_readlane_b32 s49, v241, 31
	v_readlane_b32 s50, v241, 32
	v_readlane_b32 s51, v241, 33
	s_cbranch_scc1 .LBB0_2213
	s_barrier
